# 50 more xor 1/2/4/8 butterfly sum steps to v_add_f32_dpp (fourth-row chains of the norm ladders etc.; level tracking through existing DPP adds)
# baseline (speedup 1.0000x reference)
.LBB0_842:
	v_lshl_add_u64 v[18:19], s[38:39], 0, v[94:95]
	v_lshl_add_u64 v[22:23], s[38:39], 0, v[92:93]
	v_add_co_u32_e32 v20, vcc, 0x7800000, v18
	v_add_co_u32_e64 v102, s[6:7], s31, v22
	s_nop 0
	v_addc_co_u32_e32 v21, vcc, 0, v19, vcc
	v_addc_co_u32_e64 v103, s[6:7], 0, v23, s[6:7]
	v_add_co_u32_e64 v104, s[6:7], s33, v22
	v_add_co_u32_e32 v22, vcc, 0x7801000, v18
	s_nop 0
	v_addc_co_u32_e64 v105, s[6:7], 0, v23, s[6:7]
	global_load_dwordx4 v[78:81], v[20:21], off
	global_load_dwordx4 v[74:77], v[20:21], off offset:1024
	global_load_dwordx4 v[70:73], v[20:21], off offset:2048
	global_load_dwordx4 v[66:69], v[20:21], off offset:3072
	v_addc_co_u32_e32 v23, vcc, 0, v19, vcc
	v_add_co_u32_e32 v20, vcc, 0x7802000, v18
	global_load_dwordx4 v[62:65], v[22:23], off
	global_load_dwordx4 v[58:61], v[22:23], off offset:1024
	global_load_dwordx4 v[54:57], v[22:23], off offset:2048
	global_load_dwordx4 v[50:53], v[22:23], off offset:3072
	v_addc_co_u32_e32 v21, vcc, 0, v19, vcc
	global_load_dwordx4 v[46:49], v[20:21], off
	global_load_dwordx4 v[42:45], v[20:21], off offset:1024
	global_load_dwordx4 v[38:41], v[20:21], off offset:2048
	global_load_dwordx4 v[34:37], v[20:21], off offset:3072
	v_add_co_u32_e32 v18, vcc, 0x7803000, v18
	s_ashr_i32 s8, s18, 13
	s_nop 0
	v_addc_co_u32_e32 v19, vcc, 0, v19, vcc
	global_load_dwordx4 v[30:33], v[18:19], off
	global_load_dwordx4 v[26:29], v[18:19], off offset:1024
	global_load_dwordx4 v[22:25], v[18:19], off offset:2048
	s_nop 0
	global_load_dwordx4 v[18:21], v[18:19], off offset:3072
	s_add_i32 s9, s18, 0xffffc002
	s_cmpk_lt_i32 s18, 0x4000
	s_cselect_b32 s6, s8, s9
	s_mul_hi_i32 s7, s6, 0x9000
	s_mul_i32 s6, s6, 0x9000
	s_add_u32 s6, s27, s6
	s_addc_u32 s7, s28, s7
	s_add_u32 s10, s6, 0x1000
	s_addc_u32 s11, s7, 0
	v_lshl_add_u64 v[122:123], s[6:7], 0, v[90:91]
	v_lshl_add_u64 v[86:87], s[10:11], 0, v[90:91]
	global_load_dwordx4 v[82:85], v[122:123], off
	s_add_i32 s6, s18, 0xffffc003
	global_load_dwordx4 v[86:89], v[86:87], off
	s_cmpk_lt_i32 s18, 0x3fff
	s_cselect_b32 s6, s8, s6
	s_mul_hi_i32 s7, s6, 0x9000
	s_mul_i32 s6, s6, 0x9000
	s_add_u32 s6, s27, s6
	s_addc_u32 s7, s28, s7
	v_lshl_add_u64 v[142:143], s[10:11], 0, v[96:97]
	v_lshl_add_u64 v[138:139], s[10:11], 0, v[98:99]
	v_lshl_add_u64 v[128:129], s[10:11], 0, v[100:101]
	s_add_u32 s10, s6, 0x1000
	v_lshl_add_u64 v[110:111], s[6:7], 0, v[90:91]
	s_addc_u32 s11, s7, 0
	s_add_i32 s6, s18, 0xffffc004
	s_cmpk_lt_i32 s18, 0x3ffe
	s_cselect_b32 s6, s8, s6
	s_mul_hi_i32 s7, s6, 0x9000
	s_mul_i32 s6, s6, 0x9000
	v_lshl_add_u64 v[124:125], s[10:11], 0, v[90:91]
	v_lshl_add_u64 v[118:119], s[10:11], 0, v[96:97]
	v_lshl_add_u64 v[114:115], s[10:11], 0, v[98:99]
	v_lshl_add_u64 v[112:113], s[10:11], 0, v[100:101]
	s_add_u32 s10, s27, s6
	s_addc_u32 s11, s28, s7
	s_add_u32 s6, s10, 0x1000
	s_addc_u32 s7, s11, 0
	s_add_i32 s9, s18, 0xffffc005
	s_cmpk_lt_i32 s18, 0x3ffd
	v_lshl_add_u64 v[146:147], s[6:7], 0, v[90:91]
	v_lshl_add_u64 v[144:145], s[6:7], 0, v[96:97]
	v_lshl_add_u64 v[140:141], s[6:7], 0, v[98:99]
	v_lshl_add_u64 v[126:127], s[6:7], 0, v[100:101]
	s_cselect_b32 s6, s8, s9
	s_mul_hi_i32 s7, s6, 0x9000
	s_mul_i32 s6, s6, 0x9000
	s_add_u32 s6, s27, s6
	s_addc_u32 s7, s28, s7
	s_add_u32 s24, s6, 0x1000
	v_lshl_add_u64 v[106:107], s[6:7], 0, v[90:91]
	s_addc_u32 s25, s7, 0
	v_lshl_add_u64 v[108:109], s[10:11], 0, v[90:91]
	v_lshl_add_u64 v[120:121], s[24:25], 0, v[90:91]
	v_lshl_add_u64 v[116:117], s[24:25], 0, v[96:97]
	s_add_i32 s18, s18, 32
	v_lshl_add_u64 v[92:93], v[92:93], 0, s[20:21]
	v_lshl_add_u64 v[94:95], v[94:95], 0, s[22:23]
	s_cmp_lt_i32 s18, s26
	s_waitcnt vmcnt(0) lgkmcnt(0)
	v_pk_mul_f32 v[148:149], v[80:81], v[80:81]
	v_pk_mul_f32 v[150:151], v[78:79], v[78:79]
	v_pk_mul_f32 v[152:153], v[76:77], v[76:77]
	v_pk_mul_f32 v[154:155], v[74:75], v[74:75]
	v_mul_f32_e32 v164, v71, v71
	v_mul_f32_e32 v166, v73, v73
	v_pk_mov_b32 v[168:169], v[150:151], v[148:149] op_sel:[1,0]
	v_mov_b32_e32 v151, v149
	v_pk_mov_b32 v[148:149], v[154:155], v[152:153] op_sel:[1,0]
	v_mov_b32_e32 v155, v153
	v_mul_f32_e32 v177, v68, v68
	v_mul_f32_e32 v179, v69, v69
	v_pk_fma_f32 v[152:153], v[70:71], v[70:71], v[164:165] op_sel_hi:[1,1,0]
	v_pk_fma_f32 v[164:165], v[72:73], v[72:73], v[166:167] op_sel_hi:[1,1,0]
	v_pk_mul_f32 v[166:167], v[64:65], v[64:65]
	v_pk_mul_f32 v[170:171], v[62:63], v[62:63]
	v_pk_mul_f32 v[172:173], v[60:61], v[60:61]
	v_pk_mul_f32 v[174:175], v[58:59], v[58:59]
	v_mul_f32_e32 v176, v55, v55
	v_mul_f32_e32 v178, v57, v57
	v_pk_add_f32 v[150:151], v[168:169], v[150:151]
	v_pk_add_f32 v[148:149], v[148:149], v[154:155]
	v_mul_f32_e32 v163, v66, v66
	v_mul_f32_e32 v187, v67, v67
	v_mov_b32_e32 v153, v177
	v_mov_b32_e32 v165, v179
	v_pk_mov_b32 v[154:155], v[170:171], v[166:167] op_sel:[1,0]
	v_mov_b32_e32 v171, v167
	v_pk_mov_b32 v[166:167], v[174:175], v[172:173] op_sel:[1,0]
	v_mov_b32_e32 v175, v173
	v_pk_fma_f32 v[168:169], v[54:55], v[54:55], v[176:177] op_sel_hi:[1,1,0]
	v_pk_fma_f32 v[172:173], v[56:57], v[56:57], v[178:179] op_sel_hi:[1,1,0]
	v_pk_mul_f32 v[176:177], v[48:49], v[48:49]
	v_pk_mul_f32 v[178:179], v[46:47], v[46:47]
	v_pk_add_f32 v[188:189], v[150:151], v[150:151] op_sel:[0,1] op_sel_hi:[1,0]
	v_pk_add_f32 v[190:191], v[148:149], v[148:149] op_sel:[0,1] op_sel_hi:[1,0]
	v_mul_f32_e32 v185, v52, v52
	v_pk_mul_f32 v[180:181], v[44:45], v[44:45]
	v_pk_mul_f32 v[182:183], v[42:43], v[42:43]
	v_mul_f32_e32 v184, v39, v39
	v_mul_f32_e32 v186, v41, v41
	v_pk_add_f32 v[164:165], v[152:153], v[164:165]
	v_pk_add_f32 v[148:149], v[154:155], v[170:171]
	v_pk_add_f32 v[150:151], v[166:167], v[174:175]
	v_pk_mov_b32 v[152:153], v[178:179], v[176:177] op_sel:[1,0]
	v_mov_b32_e32 v179, v177
	v_mov_b32_e32 v189, v163
	v_mov_b32_e32 v191, v187
	v_mul_f32_e32 v193, v50, v50
	v_mul_f32_e32 v198, v51, v51
	v_mul_f32_e32 v192, v53, v53
	v_mul_f32_e32 v201, v36, v36
	v_mul_f32_e32 v202, v37, v37
	v_pk_mov_b32 v[154:155], v[182:183], v[180:181] op_sel:[1,0]
	v_mov_b32_e32 v183, v181
	v_pk_fma_f32 v[166:167], v[38:39], v[38:39], v[184:185] op_sel_hi:[1,1,0]
	v_pk_fma_f32 v[170:171], v[40:41], v[40:41], v[186:187] op_sel_hi:[1,1,0]
	v_pk_add_f32 v[194:195], v[148:149], v[148:149] op_sel:[0,1] op_sel_hi:[1,0]
	v_pk_add_f32 v[196:197], v[150:151], v[150:151] op_sel:[0,1] op_sel_hi:[1,0]
	v_pk_add_f32 v[152:153], v[152:153], v[178:179]
	v_pk_add_f32 v[178:179], v[188:189], v[190:191]
	v_mov_b32_e32 v169, v185
	v_mov_b32_e32 v173, v192
	v_pk_mul_f32 v[174:175], v[32:33], v[32:33]
	v_pk_mul_f32 v[176:177], v[30:31], v[30:31]
	v_pk_mul_f32 v[180:181], v[28:29], v[28:29]
	v_pk_mul_f32 v[184:185], v[26:27], v[26:27]
	v_pk_add_f32 v[154:155], v[154:155], v[182:183]
	v_mov_b32_e32 v167, v201
	v_mov_b32_e32 v171, v202
	v_mov_b32_e32 v195, v193
	v_mov_b32_e32 v197, v198
	v_pk_add_f32 v[164:165], v[178:179], v[164:165]
	v_mul_f32_e32 v199, v34, v34
	v_mul_f32_e32 v200, v35, v35
	v_pk_add_f32 v[168:169], v[168:169], v[172:173]
	v_pk_mov_b32 v[172:173], v[176:177], v[174:175] op_sel:[1,0]
	v_mov_b32_e32 v177, v175
	v_pk_mov_b32 v[174:175], v[184:185], v[180:181] op_sel:[1,0]
	v_mov_b32_e32 v185, v181
	v_pk_add_f32 v[180:181], v[152:153], v[152:153] op_sel:[0,1] op_sel_hi:[1,0]
	v_pk_add_f32 v[182:183], v[154:155], v[154:155] op_sel:[0,1] op_sel_hi:[1,0]
	v_pk_add_f32 v[166:167], v[166:167], v[170:171]
	v_pk_add_f32 v[170:171], v[194:195], v[196:197]
	v_add_f32_e32 v163, v164, v165
	v_mov_b32_e32 v181, v199
	v_mov_b32_e32 v183, v200
	v_pk_add_f32 v[164:165], v[170:171], v[168:169]
	v_pk_add_f32 v[168:169], v[180:181], v[182:183]
	v_add_f32_e32 v170, v164, v165
	v_pk_add_f32 v[164:165], v[168:169], v[166:167]
	v_add_f32_e32 v164, v164, v165
	s_waitcnt lgkmcnt(0)
	s_nop 1
	v_add_f32_dpp v163, v163, v163 quad_perm:[1,0,3,2] row_mask:0xf bank_mask:0xf
	s_waitcnt lgkmcnt(0)
	s_nop 1
	v_add_f32_dpp v166, v170, v170 quad_perm:[1,0,3,2] row_mask:0xf bank_mask:0xf
	s_waitcnt lgkmcnt(0)
	s_nop 1
	v_add_f32_dpp v164, v164, v164 quad_perm:[1,0,3,2] row_mask:0xf bank_mask:0xf
	s_waitcnt lgkmcnt(0)
	s_nop 1
	v_add_f32_dpp v163, v163, v163 quad_perm:[2,3,0,1] row_mask:0xf bank_mask:0xf
	s_waitcnt lgkmcnt(0)
	s_nop 1
	v_add_f32_dpp v166, v166, v166 quad_perm:[2,3,0,1] row_mask:0xf bank_mask:0xf
	s_waitcnt lgkmcnt(0)
	s_nop 1
	v_add_f32_dpp v164, v164, v164 quad_perm:[2,3,0,1] row_mask:0xf bank_mask:0xf
	s_waitcnt lgkmcnt(0)
	s_nop 1
	v_add_f32_dpp v163, v163, v163 row_half_mirror row_mask:0xf bank_mask:0xf
	s_waitcnt lgkmcnt(0)
	s_nop 1
	v_add_f32_dpp v166, v166, v166 row_half_mirror row_mask:0xf bank_mask:0xf
	s_waitcnt lgkmcnt(0)
	s_nop 1
	v_add_f32_dpp v164, v164, v164 row_half_mirror row_mask:0xf bank_mask:0xf
	s_waitcnt lgkmcnt(0)
	s_nop 1
	v_add_f32_dpp v163, v163, v163 row_mirror row_mask:0xf bank_mask:0xf
	ds_bpermute_b32 v167, v159, v163
	s_waitcnt lgkmcnt(2)
	s_nop 1
	v_add_f32_dpp v166, v166, v166 row_mirror row_mask:0xf bank_mask:0xf
	ds_bpermute_b32 v168, v159, v166
	s_waitcnt lgkmcnt(2)
	s_nop 1
	v_add_f32_dpp v164, v164, v164 row_mirror row_mask:0xf bank_mask:0xf
	ds_bpermute_b32 v165, v159, v164
	s_waitcnt lgkmcnt(2)
	v_add_f32_e32 v163, v163, v167
	ds_bpermute_b32 v167, v160, v163
	s_waitcnt lgkmcnt(2)
	v_add_f32_e32 v166, v166, v168
	ds_bpermute_b32 v168, v160, v166
	s_waitcnt lgkmcnt(2)
	v_add_f32_e32 v164, v164, v165
	ds_bpermute_b32 v165, v160, v164
	s_waitcnt lgkmcnt(2)
	v_add_f32_e32 v163, v163, v167
	v_fmamk_f32 v163, v163, 0x3a800000, v161
	s_waitcnt lgkmcnt(1)
	v_add_f32_e32 v166, v166, v168
	v_mul_f32_e32 v167, 0x4f800000, v163
	v_cmp_gt_f32_e32 vcc, s19, v163
	v_fmamk_f32 v166, v166, 0x3a800000, v161
	s_waitcnt lgkmcnt(0)
	v_add_f32_e32 v164, v164, v165
	v_cndmask_b32_e32 v163, v163, v167, vcc
	v_mul_f32_e32 v165, 0x4f800000, v166
	v_cmp_gt_f32_e64 s[6:7], s19, v166
	v_sqrt_f32_e32 v167, v163
	v_fmamk_f32 v164, v164, 0x3a800000, v161
	v_cndmask_b32_e64 v165, v166, v165, s[6:7]
	v_mul_f32_e32 v166, 0x4f800000, v164
	v_cmp_gt_f32_e64 s[8:9], s19, v164
	v_sqrt_f32_e32 v168, v165
	v_add_u32_e32 v169, -1, v167
	v_cndmask_b32_e64 v164, v164, v166, s[8:9]
	v_sqrt_f32_e32 v166, v164
	v_add_u32_e32 v170, 1, v167
	v_fma_f32 v171, -v169, v167, v163
	v_pk_add_f32 v[152:153], v[172:173], v[176:177]
	v_fma_f32 v172, -v170, v167, v163
	v_add_u32_e32 v173, -1, v168
	v_cmp_ge_f32_e64 s[10:11], 0, v171
	v_pk_add_f32 v[154:155], v[174:175], v[184:185]
	v_add_u32_e32 v174, 1, v168
	v_cndmask_b32_e64 v167, v167, v169, s[10:11]
	v_fma_f32 v169, -v173, v168, v165
	v_cmp_lt_f32_e64 s[10:11], 0, v172
	v_fma_f32 v171, -v174, v168, v165
	v_add_u32_e32 v175, -1, v166
	v_cndmask_b32_e64 v167, v167, v170, s[10:11]
	v_cmp_ge_f32_e64 s[10:11], 0, v169
	v_add_u32_e32 v176, 1, v166
	v_fma_f32 v169, -v175, v166, v164
	v_cndmask_b32_e64 v168, v168, v173, s[10:11]
	v_cmp_lt_f32_e64 s[10:11], 0, v171
	v_fma_f32 v170, -v176, v166, v164
	v_mul_f32_e32 v171, 0x37800000, v167
	v_cndmask_b32_e64 v168, v168, v174, s[10:11]
	v_cmp_ge_f32_e64 s[10:11], 0, v169
	v_cndmask_b32_e32 v167, v167, v171, vcc
	v_cmp_class_f32_e32 vcc, v163, v162
	v_cndmask_b32_e64 v166, v166, v175, s[10:11]
	v_cmp_lt_f32_e64 s[10:11], 0, v170
	v_mul_f32_e32 v169, 0x37800000, v168
	v_cndmask_b32_e32 v163, v167, v163, vcc
	v_cndmask_b32_e64 v166, v166, v176, s[10:11]
	v_cndmask_b32_e64 v167, v168, v169, s[6:7]
	v_cmp_class_f32_e32 vcc, v165, v162
	v_mul_f32_e32 v168, 0x37800000, v166
	v_div_scale_f32 v169, s[6:7], v163, v163, 1.0
	v_cndmask_b32_e32 v165, v167, v165, vcc
	v_cndmask_b32_e64 v166, v166, v168, s[8:9]
	v_cmp_class_f32_e32 vcc, v164, v162
	v_rcp_f32_e32 v167, v169
	v_div_scale_f32 v168, s[8:9], v165, v165, 1.0
	v_cndmask_b32_e32 v166, v166, v164, vcc
	v_rcp_f32_e32 v172, v168
	v_div_scale_f32 v173, s[10:11], v166, v166, 1.0
	v_rcp_f32_e32 v175, v173
	v_fma_f32 v164, -v169, v167, 1.0
	v_div_scale_f32 v170, s[6:7], 1.0, v163, 1.0
	v_fmac_f32_e32 v167, v164, v167
	v_fma_f32 v164, -v168, v172, 1.0
	v_mul_f32_e32 v176, v170, v167
	v_div_scale_f32 v171, s[8:9], 1.0, v165, 1.0
	v_fmac_f32_e32 v172, v164, v172
	v_fma_f32 v164, -v173, v175, 1.0
	v_fma_f32 v177, -v169, v176, v170
	v_div_scale_f32 v174, s[10:11], 1.0, v166, 1.0
	v_mul_f32_e32 v178, v171, v172
	v_fmac_f32_e32 v175, v164, v175
	v_fmac_f32_e32 v176, v177, v167
	v_fma_f32 v164, -v168, v178, v171
	v_mul_f32_e32 v177, v174, v175
	v_fma_f32 v169, -v169, v176, v170
	s_mov_b64 vcc, s[6:7]
	v_fmac_f32_e32 v178, v164, v172
	v_fma_f32 v164, -v173, v177, v174
	v_div_fmas_f32 v167, v169, v167, v176
	v_fma_f32 v168, -v168, v178, v171
	v_fmac_f32_e32 v177, v164, v175
	v_div_fixup_f32 v164, v167, v163, 1.0
	s_mov_b64 vcc, s[8:9]
	v_div_fmas_f32 v163, v168, v172, v178
	v_fma_f32 v167, -v173, v177, v174
	v_pk_mul_f32 v[80:81], v[80:81], v[164:165] op_sel_hi:[1,0]
	v_pk_mul_f32 v[78:79], v[78:79], v[164:165] op_sel_hi:[1,0]
	s_mov_b64 vcc, s[10:11]
	v_pk_add_f32 v[88:89], v[88:89], 1.0 op_sel_hi:[1,0]
	v_pk_add_f32 v[86:87], v[86:87], 1.0 op_sel_hi:[1,0]
	v_pk_mul_f32 v[76:77], v[76:77], v[164:165] op_sel_hi:[1,0]
	v_pk_mul_f32 v[74:75], v[74:75], v[164:165] op_sel_hi:[1,0]
	v_pk_mul_f32 v[72:73], v[72:73], v[164:165] op_sel_hi:[1,0]
	v_pk_mul_f32 v[70:71], v[70:71], v[164:165] op_sel_hi:[1,0]
	v_pk_mul_f32 v[68:69], v[68:69], v[164:165] op_sel_hi:[1,0]
	v_pk_mul_f32 v[66:67], v[66:67], v[164:165] op_sel_hi:[1,0]
	v_div_fixup_f32 v164, v163, v165, 1.0
	v_div_fmas_f32 v163, v167, v175, v177
	v_pk_mul_f32 v[78:79], v[78:79], v[2:3]
	v_pk_mul_f32 v[80:81], v[80:81], v[4:5]
	v_pk_mul_f32 v[64:65], v[64:65], v[164:165] op_sel_hi:[1,0]
	v_pk_mul_f32 v[62:63], v[62:63], v[164:165] op_sel_hi:[1,0]
	v_pk_mul_f32 v[60:61], v[60:61], v[164:165] op_sel_hi:[1,0]
	v_pk_mul_f32 v[58:59], v[58:59], v[164:165] op_sel_hi:[1,0]
	v_pk_mul_f32 v[56:57], v[56:57], v[164:165] op_sel_hi:[1,0]
	v_pk_mul_f32 v[54:55], v[54:55], v[164:165] op_sel_hi:[1,0]
	v_pk_mul_f32 v[52:53], v[52:53], v[164:165] op_sel_hi:[1,0]
	v_pk_mul_f32 v[50:51], v[50:51], v[164:165] op_sel_hi:[1,0]
	v_div_fixup_f32 v164, v163, v166, 1.0
	v_pk_fma_f32 v[80:81], v[80:81], v[88:89], v[84:85]
	v_pk_fma_f32 v[78:79], v[78:79], v[86:87], v[82:83]
	v_pk_mul_f32 v[82:83], v[50:51], v[14:15]
	v_pk_mul_f32 v[84:85], v[52:53], v[16:17]
	v_pk_mul_f32 v[48:49], v[48:49], v[164:165] op_sel_hi:[1,0]
	v_pk_mul_f32 v[46:47], v[46:47], v[164:165] op_sel_hi:[1,0]
	v_pk_mul_f32 v[86:87], v[46:47], v[2:3]
	v_pk_mul_f32 v[88:89], v[48:49], v[4:5]
	v_cvt_pk_bf16_f32 v46, v78, v79
	v_cvt_pk_bf16_f32 v47, v80, v81
	global_store_dwordx2 v[102:103], v[46:47], off
	global_load_dwordx4 v[46:49], v[142:143], off
	s_nop 0
	global_load_dwordx4 v[50:53], v[122:123], off offset:1024
	v_pk_mul_f32 v[74:75], v[74:75], v[6:7]
	v_pk_mul_f32 v[76:77], v[76:77], v[8:9]
	v_pk_mul_f32 v[70:71], v[70:71], v[10:11]
	v_pk_mul_f32 v[72:73], v[72:73], v[12:13]
	v_pk_mul_f32 v[66:67], v[66:67], v[14:15]
	v_pk_mul_f32 v[68:69], v[68:69], v[16:17]
	v_pk_mul_f32 v[62:63], v[62:63], v[2:3]
	v_pk_mul_f32 v[64:65], v[64:65], v[4:5]
	v_pk_mul_f32 v[58:59], v[58:59], v[6:7]
	v_pk_mul_f32 v[60:61], v[60:61], v[8:9]
	v_pk_mul_f32 v[54:55], v[54:55], v[10:11]
	v_pk_mul_f32 v[56:57], v[56:57], v[12:13]
	v_pk_mul_f32 v[44:45], v[44:45], v[164:165] op_sel_hi:[1,0]
	v_pk_mul_f32 v[42:43], v[42:43], v[164:165] op_sel_hi:[1,0]
	v_pk_mul_f32 v[44:45], v[44:45], v[8:9]
	v_pk_mul_f32 v[42:43], v[42:43], v[6:7]
	v_pk_mul_f32 v[40:41], v[40:41], v[164:165] op_sel_hi:[1,0]
	v_pk_mul_f32 v[38:39], v[38:39], v[164:165] op_sel_hi:[1,0]
	v_pk_mul_f32 v[40:41], v[40:41], v[12:13]
	v_pk_mul_f32 v[38:39], v[38:39], v[10:11]
	v_pk_mul_f32 v[36:37], v[36:37], v[164:165] op_sel_hi:[1,0]
	v_pk_mul_f32 v[34:35], v[34:35], v[164:165] op_sel_hi:[1,0]
	v_pk_mul_f32 v[36:37], v[36:37], v[16:17]
	v_pk_mul_f32 v[34:35], v[34:35], v[14:15]
	v_mul_f32_e32 v186, v23, v23
	v_mul_f32_e32 v192, v25, v25
	v_mul_f32_e32 v203, v18, v18
	v_mul_f32_e32 v204, v19, v19
	v_mul_f32_e32 v205, v20, v20
	v_mul_f32_e32 v206, v21, v21
	v_pk_fma_f32 v[148:149], v[22:23], v[22:23], v[186:187] op_sel_hi:[1,1,0]
	v_pk_fma_f32 v[150:151], v[24:25], v[24:25], v[192:193] op_sel_hi:[1,1,0]
	v_mov_b32_e32 v149, v205
	v_mov_b32_e32 v151, v206
	s_waitcnt vmcnt(0) lgkmcnt(0)
	v_pk_add_f32 v[48:49], v[48:49], 1.0 op_sel_hi:[1,0]
	v_pk_add_f32 v[46:47], v[46:47], 1.0 op_sel_hi:[1,0]
	v_pk_fma_f32 v[48:49], v[76:77], v[48:49], v[52:53]
	v_pk_fma_f32 v[46:47], v[74:75], v[46:47], v[50:51]
	v_cvt_pk_bf16_f32 v46, v46, v47
	v_cvt_pk_bf16_f32 v47, v48, v49
	global_store_dwordx2 v[102:103], v[46:47], off offset:512
	global_load_dwordx4 v[46:49], v[138:139], off
	s_nop 0
	global_load_dwordx4 v[50:53], v[122:123], off offset:2048
	s_waitcnt vmcnt(0) lgkmcnt(0)
	v_pk_add_f32 v[48:49], v[48:49], 1.0 op_sel_hi:[1,0]
	v_pk_add_f32 v[46:47], v[46:47], 1.0 op_sel_hi:[1,0]
	v_pk_fma_f32 v[48:49], v[72:73], v[48:49], v[52:53]
	v_pk_fma_f32 v[46:47], v[70:71], v[46:47], v[50:51]
	v_cvt_pk_bf16_f32 v46, v46, v47
	v_cvt_pk_bf16_f32 v47, v48, v49
	global_store_dwordx2 v[102:103], v[46:47], off offset:1024
	global_load_dwordx4 v[46:49], v[128:129], off
	s_nop 0
	global_load_dwordx4 v[50:53], v[122:123], off offset:3072
	s_waitcnt vmcnt(0) lgkmcnt(0)
	v_pk_add_f32 v[48:49], v[48:49], 1.0 op_sel_hi:[1,0]
	v_pk_add_f32 v[46:47], v[46:47], 1.0 op_sel_hi:[1,0]
	v_pk_fma_f32 v[48:49], v[68:69], v[48:49], v[52:53]
	v_pk_fma_f32 v[46:47], v[66:67], v[46:47], v[50:51]
	v_cvt_pk_bf16_f32 v46, v46, v47
	v_cvt_pk_bf16_f32 v47, v48, v49
	global_store_dwordx2 v[102:103], v[46:47], off offset:1536
	global_load_dwordx4 v[46:49], v[124:125], off
	s_nop 0
	global_load_dwordx4 v[50:53], v[110:111], off
	s_waitcnt vmcnt(0) lgkmcnt(0)
	v_pk_add_f32 v[48:49], v[48:49], 1.0 op_sel_hi:[1,0]
	v_pk_add_f32 v[46:47], v[46:47], 1.0 op_sel_hi:[1,0]
	v_pk_fma_f32 v[48:49], v[64:65], v[48:49], v[52:53]
	v_pk_fma_f32 v[46:47], v[62:63], v[46:47], v[50:51]
	v_cvt_pk_bf16_f32 v46, v46, v47
	v_cvt_pk_bf16_f32 v47, v48, v49
	global_store_dwordx2 v[102:103], v[46:47], off offset:2048
	global_load_dwordx4 v[46:49], v[118:119], off
	s_nop 0
	global_load_dwordx4 v[50:53], v[110:111], off offset:1024
	s_waitcnt vmcnt(0) lgkmcnt(0)
	v_pk_add_f32 v[48:49], v[48:49], 1.0 op_sel_hi:[1,0]
	v_pk_add_f32 v[46:47], v[46:47], 1.0 op_sel_hi:[1,0]
	v_pk_fma_f32 v[48:49], v[60:61], v[48:49], v[52:53]
	v_pk_fma_f32 v[46:47], v[58:59], v[46:47], v[50:51]
	v_cvt_pk_bf16_f32 v46, v46, v47
	v_cvt_pk_bf16_f32 v47, v48, v49
	global_store_dwordx2 v[102:103], v[46:47], off offset:2560
	global_load_dwordx4 v[46:49], v[114:115], off
	s_nop 0
	global_load_dwordx4 v[50:53], v[110:111], off offset:2048
	v_pk_add_f32 v[58:59], v[148:149], v[150:151]
	s_waitcnt vmcnt(0) lgkmcnt(0)
	v_pk_add_f32 v[48:49], v[48:49], 1.0 op_sel_hi:[1,0]
	v_pk_add_f32 v[46:47], v[46:47], 1.0 op_sel_hi:[1,0]
	v_pk_fma_f32 v[48:49], v[56:57], v[48:49], v[52:53]
	v_pk_fma_f32 v[46:47], v[54:55], v[46:47], v[50:51]
	v_cvt_pk_bf16_f32 v46, v46, v47
	v_cvt_pk_bf16_f32 v47, v48, v49
	global_store_dwordx2 v[102:103], v[46:47], off offset:3072
	global_load_dwordx4 v[46:49], v[112:113], off
	s_nop 0
	global_load_dwordx4 v[50:53], v[110:111], off offset:3072
	v_pk_add_f32 v[54:55], v[152:153], v[152:153] op_sel:[0,1] op_sel_hi:[1,0]
	v_pk_add_f32 v[56:57], v[154:155], v[154:155] op_sel:[0,1] op_sel_hi:[1,0]
	v_mov_b32_e32 v55, v203
	v_mov_b32_e32 v57, v204
	s_waitcnt vmcnt(0) lgkmcnt(0)
	v_pk_add_f32 v[48:49], v[48:49], 1.0 op_sel_hi:[1,0]
	v_pk_add_f32 v[46:47], v[46:47], 1.0 op_sel_hi:[1,0]
	v_pk_fma_f32 v[48:49], v[84:85], v[48:49], v[52:53]
	v_pk_fma_f32 v[46:47], v[82:83], v[46:47], v[50:51]
	v_cvt_pk_bf16_f32 v46, v46, v47
	v_cvt_pk_bf16_f32 v47, v48, v49
	global_store_dwordx2 v[102:103], v[46:47], off offset:3584
	global_load_dwordx4 v[46:49], v[146:147], off
	s_nop 0
	global_load_dwordx4 v[50:53], v[108:109], off
	s_waitcnt vmcnt(0) lgkmcnt(0)
	v_pk_add_f32 v[48:49], v[48:49], 1.0 op_sel_hi:[1,0]
	v_pk_add_f32 v[46:47], v[46:47], 1.0 op_sel_hi:[1,0]
	v_pk_fma_f32 v[48:49], v[88:89], v[48:49], v[52:53]
	v_pk_fma_f32 v[46:47], v[86:87], v[46:47], v[50:51]
	v_cvt_pk_bf16_f32 v46, v46, v47
	v_cvt_pk_bf16_f32 v47, v48, v49
	global_store_dwordx2 v[104:105], v[46:47], off
	global_load_dwordx4 v[46:49], v[144:145], off
	s_nop 0
	global_load_dwordx4 v[50:53], v[108:109], off offset:1024
	s_waitcnt vmcnt(0) lgkmcnt(0)
	v_pk_add_f32 v[48:49], v[48:49], 1.0 op_sel_hi:[1,0]
	v_pk_add_f32 v[46:47], v[46:47], 1.0 op_sel_hi:[1,0]
	v_pk_fma_f32 v[44:45], v[44:45], v[48:49], v[52:53]
	v_pk_fma_f32 v[42:43], v[42:43], v[46:47], v[50:51]
	v_cvt_pk_bf16_f32 v42, v42, v43
	v_cvt_pk_bf16_f32 v43, v44, v45
	global_store_dwordx2 v[104:105], v[42:43], off offset:512
	global_load_dwordx4 v[42:45], v[140:141], off
	s_nop 0
	global_load_dwordx4 v[46:49], v[108:109], off offset:2048
	v_pk_add_f32 v[50:51], v[54:55], v[56:57]
	s_waitcnt vmcnt(0) lgkmcnt(0)
	v_pk_add_f32 v[44:45], v[44:45], 1.0 op_sel_hi:[1,0]
	v_pk_add_f32 v[42:43], v[42:43], 1.0 op_sel_hi:[1,0]
	v_pk_fma_f32 v[40:41], v[40:41], v[44:45], v[48:49]
	v_pk_fma_f32 v[38:39], v[38:39], v[42:43], v[46:47]
	v_cvt_pk_bf16_f32 v38, v38, v39
	v_cvt_pk_bf16_f32 v39, v40, v41
	global_store_dwordx2 v[104:105], v[38:39], off offset:1024
	global_load_dwordx4 v[38:41], v[126:127], off
	s_nop 0
	global_load_dwordx4 v[42:45], v[108:109], off offset:3072
	v_pk_add_f32 v[50:51], v[50:51], v[58:59]
	s_waitcnt vmcnt(0) lgkmcnt(0)
	v_pk_add_f32 v[40:41], v[40:41], 1.0 op_sel_hi:[1,0]
	v_pk_add_f32 v[38:39], v[38:39], 1.0 op_sel_hi:[1,0]
	v_pk_fma_f32 v[36:37], v[36:37], v[40:41], v[44:45]
	v_pk_fma_f32 v[34:35], v[34:35], v[38:39], v[42:43]
	v_cvt_pk_bf16_f32 v34, v34, v35
	v_cvt_pk_bf16_f32 v35, v36, v37
	global_store_dwordx2 v[104:105], v[34:35], off offset:1536
	global_load_dwordx4 v[34:37], v[120:121], off
	s_nop 0
	global_load_dwordx4 v[38:41], v[106:107], off
	v_add_f32_e32 v50, v50, v51
	s_waitcnt lgkmcnt(0)
	s_nop 1
	v_add_f32_dpp v50, v50, v50 quad_perm:[1,0,3,2] row_mask:0xf bank_mask:0xf
	s_waitcnt lgkmcnt(0)
	s_nop 1
	v_add_f32_dpp v50, v50, v50 quad_perm:[2,3,0,1] row_mask:0xf bank_mask:0xf
	s_waitcnt lgkmcnt(0)
	s_nop 1
	v_add_f32_dpp v46, v50, v50 row_half_mirror row_mask:0xf bank_mask:0xf
	s_waitcnt lgkmcnt(0)
	s_nop 1
	v_add_f32_dpp v46, v46, v46 row_mirror row_mask:0xf bank_mask:0xf
	ds_bpermute_b32 v47, v159, v46
	s_waitcnt lgkmcnt(0)
	v_add_f32_e32 v46, v46, v47
	ds_bpermute_b32 v47, v160, v46
	s_waitcnt lgkmcnt(0)
	v_add_f32_e32 v46, v46, v47
	v_fmamk_f32 v46, v46, 0x3a800000, v161
	v_mul_f32_e32 v47, 0x4f800000, v46
	v_cmp_gt_f32_e32 vcc, s19, v46
	s_waitcnt vmcnt(0)
	v_pk_add_f32 v[36:37], v[36:37], 1.0 op_sel_hi:[1,0]
	v_cndmask_b32_e32 v42, v46, v47, vcc
	v_sqrt_f32_e32 v43, v42
	v_pk_add_f32 v[34:35], v[34:35], 1.0 op_sel_hi:[1,0]
	v_add_u32_e32 v44, -1, v43
	v_add_u32_e32 v45, 1, v43
	v_fma_f32 v46, -v44, v43, v42
	v_fma_f32 v47, -v45, v43, v42
	v_cmp_ge_f32_e64 s[6:7], 0, v46
	s_nop 1
	v_cndmask_b32_e64 v43, v43, v44, s[6:7]
	v_cmp_lt_f32_e64 s[6:7], 0, v47
	s_nop 1
	v_cndmask_b32_e64 v43, v43, v45, s[6:7]
	v_mul_f32_e32 v44, 0x37800000, v43
	v_cndmask_b32_e32 v43, v43, v44, vcc
	v_cmp_class_f32_e32 vcc, v42, v162
	s_nop 1
	v_cndmask_b32_e32 v42, v43, v42, vcc
	v_div_scale_f32 v43, s[6:7], v42, v42, 1.0
	v_rcp_f32_e32 v45, v43
	v_div_scale_f32 v44, vcc, 1.0, v42, 1.0
	v_fma_f32 v46, -v43, v45, 1.0
	v_fmac_f32_e32 v45, v46, v45
	v_mul_f32_e32 v46, v44, v45
	v_fma_f32 v47, -v43, v46, v44
	v_fmac_f32_e32 v46, v47, v45
	v_fma_f32 v43, -v43, v46, v44
	v_div_fmas_f32 v43, v43, v45, v46
	v_div_fixup_f32 v42, v43, v42, 1.0
	v_pk_mul_f32 v[32:33], v[32:33], v[42:43] op_sel_hi:[1,0]
	v_pk_mul_f32 v[30:31], v[30:31], v[42:43] op_sel_hi:[1,0]
	v_pk_mul_f32 v[32:33], v[32:33], v[4:5]
	v_pk_mul_f32 v[30:31], v[30:31], v[2:3]
	v_pk_fma_f32 v[32:33], v[32:33], v[36:37], v[40:41]
	v_pk_fma_f32 v[30:31], v[30:31], v[34:35], v[38:39]
	v_cvt_pk_bf16_f32 v30, v30, v31
	v_cvt_pk_bf16_f32 v31, v32, v33
	global_store_dwordx2 v[104:105], v[30:31], off offset:2048
	global_load_dwordx4 v[30:33], v[116:117], off
	s_nop 0
	global_load_dwordx4 v[34:37], v[106:107], off offset:1024
	v_pk_mul_f32 v[28:29], v[28:29], v[42:43] op_sel_hi:[1,0]
	v_pk_mul_f32 v[26:27], v[26:27], v[42:43] op_sel_hi:[1,0]
	v_pk_mul_f32 v[28:29], v[28:29], v[8:9]
	v_pk_mul_f32 v[26:27], v[26:27], v[6:7]
	v_lshl_add_u64 v[38:39], s[24:25], 0, v[98:99]
	v_pk_mul_f32 v[24:25], v[24:25], v[42:43] op_sel_hi:[1,0]
	v_pk_mul_f32 v[22:23], v[22:23], v[42:43] op_sel_hi:[1,0]
	v_pk_mul_f32 v[24:25], v[24:25], v[12:13]
	v_pk_mul_f32 v[22:23], v[22:23], v[10:11]
	v_pk_mul_f32 v[20:21], v[20:21], v[42:43] op_sel_hi:[1,0]
	v_pk_mul_f32 v[18:19], v[18:19], v[42:43] op_sel_hi:[1,0]
	v_pk_mul_f32 v[20:21], v[20:21], v[16:17]
	v_pk_mul_f32 v[18:19], v[18:19], v[14:15]
	s_waitcnt vmcnt(0) lgkmcnt(0)
	v_pk_add_f32 v[32:33], v[32:33], 1.0 op_sel_hi:[1,0]
	v_pk_add_f32 v[30:31], v[30:31], 1.0 op_sel_hi:[1,0]
	v_pk_fma_f32 v[28:29], v[28:29], v[32:33], v[36:37]
	v_pk_fma_f32 v[26:27], v[26:27], v[30:31], v[34:35]
	v_cvt_pk_bf16_f32 v26, v26, v27
	v_cvt_pk_bf16_f32 v27, v28, v29
	global_store_dwordx2 v[104:105], v[26:27], off offset:2560
	global_load_dwordx4 v[26:29], v[38:39], off
	s_nop 0
	global_load_dwordx4 v[30:33], v[106:107], off offset:2048
	v_lshl_add_u64 v[34:35], s[24:25], 0, v[100:101]
	s_waitcnt vmcnt(0) lgkmcnt(0)
	v_pk_add_f32 v[28:29], v[28:29], 1.0 op_sel_hi:[1,0]
	v_pk_add_f32 v[26:27], v[26:27], 1.0 op_sel_hi:[1,0]
	v_pk_fma_f32 v[24:25], v[24:25], v[28:29], v[32:33]
	v_pk_fma_f32 v[22:23], v[22:23], v[26:27], v[30:31]
	v_cvt_pk_bf16_f32 v22, v22, v23
	v_cvt_pk_bf16_f32 v23, v24, v25
	global_store_dwordx2 v[104:105], v[22:23], off offset:3072
	global_load_dwordx4 v[22:25], v[34:35], off
	s_nop 0
	global_load_dwordx4 v[26:29], v[106:107], off offset:3072
	s_waitcnt vmcnt(0) lgkmcnt(0)
	v_pk_add_f32 v[24:25], v[24:25], 1.0 op_sel_hi:[1,0]
	v_pk_add_f32 v[22:23], v[22:23], 1.0 op_sel_hi:[1,0]
	v_pk_fma_f32 v[20:21], v[20:21], v[24:25], v[28:29]
	v_pk_fma_f32 v[18:19], v[18:19], v[22:23], v[26:27]
	v_cvt_pk_bf16_f32 v18, v18, v19
	v_cvt_pk_bf16_f32 v19, v20, v21
	global_store_dwordx2 v[104:105], v[18:19], off offset:3584
	s_cbranch_scc1 .LBB0_842

.LBB0_1004:
	v_lshl_add_u64 v[18:19], s[38:39], 0, v[94:95]
	v_lshl_add_u64 v[22:23], s[38:39], 0, v[92:93]
	v_add_co_u32_e32 v20, vcc, 0x7800000, v18
	v_add_co_u32_e64 v102, s[6:7], s24, v22
	s_nop 0
	v_addc_co_u32_e32 v21, vcc, 0, v19, vcc
	v_addc_co_u32_e64 v103, s[6:7], 0, v23, s[6:7]
	v_add_co_u32_e64 v104, s[6:7], s25, v22
	v_add_co_u32_e32 v22, vcc, 0x7801000, v18
	s_nop 0
	v_addc_co_u32_e64 v105, s[6:7], 0, v23, s[6:7]
	global_load_dwordx4 v[78:81], v[20:21], off
	global_load_dwordx4 v[74:77], v[20:21], off offset:1024
	global_load_dwordx4 v[70:73], v[20:21], off offset:2048
	global_load_dwordx4 v[66:69], v[20:21], off offset:3072
	v_addc_co_u32_e32 v23, vcc, 0, v19, vcc
	v_add_co_u32_e32 v20, vcc, 0x7802000, v18
	global_load_dwordx4 v[62:65], v[22:23], off
	global_load_dwordx4 v[58:61], v[22:23], off offset:1024
	global_load_dwordx4 v[54:57], v[22:23], off offset:2048
	global_load_dwordx4 v[50:53], v[22:23], off offset:3072
	v_addc_co_u32_e32 v21, vcc, 0, v19, vcc
	global_load_dwordx4 v[46:49], v[20:21], off
	global_load_dwordx4 v[42:45], v[20:21], off offset:1024
	global_load_dwordx4 v[38:41], v[20:21], off offset:2048
	global_load_dwordx4 v[34:37], v[20:21], off offset:3072
	v_add_co_u32_e32 v82, vcc, 0x7803000, v18
	s_add_i32 s26, s8, 32
	s_nop 0
	v_addc_co_u32_e32 v83, vcc, 0, v19, vcc
	global_load_dwordx4 v[30:33], v[82:83], off
	global_load_dwordx4 v[26:29], v[82:83], off offset:1024
	global_load_dwordx4 v[22:25], v[82:83], off offset:2048
	global_load_dwordx4 v[18:21], v[82:83], off offset:3072
	s_add_i32 s10, s8, 0xffffc022
	s_ashr_i32 s9, s26, 13
	s_cmpk_lt_i32 s26, 0x4000
	s_cselect_b32 s6, s9, s10
	s_mul_hi_i32 s7, s6, 0x9000
	s_mul_i32 s6, s6, 0x9000
	s_add_u32 s6, s2, s6
	s_addc_u32 s7, s13, s7
	s_add_u32 s10, s6, 0x1000
	s_addc_u32 s11, s7, 0
	v_lshl_add_u64 v[124:125], s[6:7], 0, v[90:91]
	v_lshl_add_u64 v[86:87], s[10:11], 0, v[90:91]
	global_load_dwordx4 v[82:85], v[124:125], off
	s_add_i32 s6, s8, 0xffffc023
	global_load_dwordx4 v[86:89], v[86:87], off
	s_cmpk_lt_i32 s26, 0x3fff
	s_cselect_b32 s6, s9, s6
	s_mul_hi_i32 s7, s6, 0x9000
	s_mul_i32 s6, s6, 0x9000
	s_add_u32 s6, s2, s6
	s_addc_u32 s7, s13, s7
	v_lshl_add_u64 v[138:139], s[10:11], 0, v[96:97]
	v_lshl_add_u64 v[134:135], s[10:11], 0, v[98:99]
	v_lshl_add_u64 v[128:129], s[10:11], 0, v[100:101]
	s_add_u32 s10, s6, 0x1000
	v_lshl_add_u64 v[110:111], s[6:7], 0, v[90:91]
	s_addc_u32 s11, s7, 0
	s_add_i32 s6, s8, 0xffffc024
	s_cmpk_lt_i32 s26, 0x3ffe
	s_cselect_b32 s6, s9, s6
	s_mul_hi_i32 s7, s6, 0x9000
	s_mul_i32 s6, s6, 0x9000
	v_lshl_add_u64 v[126:127], s[10:11], 0, v[90:91]
	v_lshl_add_u64 v[120:121], s[10:11], 0, v[96:97]
	v_lshl_add_u64 v[116:117], s[10:11], 0, v[98:99]
	v_lshl_add_u64 v[112:113], s[10:11], 0, v[100:101]
	s_add_u32 s10, s2, s6
	s_addc_u32 s11, s13, s7
	s_add_u32 s6, s10, 0x1000
	s_addc_u32 s7, s11, 0
	s_addk_i32 s8, 0xc025
	s_cmpk_lt_i32 s26, 0x3ffd
	v_lshl_add_u64 v[142:143], s[6:7], 0, v[90:91]
	v_lshl_add_u64 v[140:141], s[6:7], 0, v[96:97]
	v_lshl_add_u64 v[136:137], s[6:7], 0, v[98:99]
	v_lshl_add_u64 v[122:123], s[6:7], 0, v[100:101]
	s_cselect_b32 s6, s9, s8
	s_mul_hi_i32 s7, s6, 0x9000
	s_mul_i32 s6, s6, 0x9000
	s_add_u32 s6, s2, s6
	s_addc_u32 s7, s13, s7
	s_add_u32 s20, s6, 0x1000
	v_lshl_add_u64 v[106:107], s[6:7], 0, v[90:91]
	s_addc_u32 s21, s7, 0
	v_lshl_add_u64 v[108:109], s[10:11], 0, v[90:91]
	v_lshl_add_u64 v[118:119], s[20:21], 0, v[90:91]
	v_lshl_add_u64 v[114:115], s[20:21], 0, v[96:97]
	v_lshl_add_u64 v[92:93], v[92:93], 0, s[16:17]
	v_lshl_add_u64 v[94:95], v[94:95], 0, s[18:19]
	s_cmp_lt_i32 s26, s22
	s_waitcnt vmcnt(0) lgkmcnt(0)
	v_pk_mul_f32 v[144:145], v[80:81], v[80:81]
	v_pk_mul_f32 v[146:147], v[78:79], v[78:79]
	v_pk_mul_f32 v[148:149], v[76:77], v[76:77]
	v_pk_mul_f32 v[150:151], v[74:75], v[74:75]
	v_mul_f32_e32 v158, v71, v71
	v_mul_f32_e32 v160, v73, v73
	v_pk_mov_b32 v[162:163], v[146:147], v[144:145] op_sel:[1,0]
	v_mov_b32_e32 v147, v145
	v_pk_mov_b32 v[144:145], v[150:151], v[148:149] op_sel:[1,0]
	v_mov_b32_e32 v151, v149
	v_mul_f32_e32 v171, v68, v68
	v_mul_f32_e32 v173, v69, v69
	v_pk_fma_f32 v[148:149], v[70:71], v[70:71], v[158:159] op_sel_hi:[1,1,0]
	v_pk_fma_f32 v[158:159], v[72:73], v[72:73], v[160:161] op_sel_hi:[1,1,0]
	v_pk_mul_f32 v[160:161], v[64:65], v[64:65]
	v_pk_mul_f32 v[164:165], v[62:63], v[62:63]
	v_pk_mul_f32 v[166:167], v[60:61], v[60:61]
	v_pk_mul_f32 v[168:169], v[58:59], v[58:59]
	v_mul_f32_e32 v170, v55, v55
	v_mul_f32_e32 v172, v57, v57
	v_pk_add_f32 v[146:147], v[162:163], v[146:147]
	v_pk_add_f32 v[144:145], v[144:145], v[150:151]
	v_mul_f32_e32 v157, v66, v66
	v_mul_f32_e32 v181, v67, v67
	v_mov_b32_e32 v149, v171
	v_mov_b32_e32 v159, v173
	v_pk_mov_b32 v[150:151], v[164:165], v[160:161] op_sel:[1,0]
	v_mov_b32_e32 v165, v161
	v_pk_mov_b32 v[160:161], v[168:169], v[166:167] op_sel:[1,0]
	v_mov_b32_e32 v169, v167
	v_pk_fma_f32 v[162:163], v[54:55], v[54:55], v[170:171] op_sel_hi:[1,1,0]
	v_pk_fma_f32 v[166:167], v[56:57], v[56:57], v[172:173] op_sel_hi:[1,1,0]
	v_pk_mul_f32 v[170:171], v[48:49], v[48:49]
	v_pk_mul_f32 v[172:173], v[46:47], v[46:47]
	v_pk_add_f32 v[182:183], v[146:147], v[146:147] op_sel:[0,1] op_sel_hi:[1,0]
	v_pk_add_f32 v[184:185], v[144:145], v[144:145] op_sel:[0,1] op_sel_hi:[1,0]
	v_mul_f32_e32 v179, v52, v52
	v_pk_mul_f32 v[174:175], v[44:45], v[44:45]
	v_pk_mul_f32 v[176:177], v[42:43], v[42:43]
	v_mul_f32_e32 v178, v39, v39
	v_mul_f32_e32 v180, v41, v41
	v_pk_add_f32 v[158:159], v[148:149], v[158:159]
	v_pk_add_f32 v[144:145], v[150:151], v[164:165]
	v_pk_add_f32 v[146:147], v[160:161], v[168:169]
	v_pk_mov_b32 v[148:149], v[172:173], v[170:171] op_sel:[1,0]
	v_mov_b32_e32 v173, v171
	v_mov_b32_e32 v183, v157
	v_mov_b32_e32 v185, v181
	v_mul_f32_e32 v187, v50, v50
	v_mul_f32_e32 v192, v51, v51
	v_mul_f32_e32 v186, v53, v53
	v_mul_f32_e32 v195, v36, v36
	v_mul_f32_e32 v196, v37, v37
	v_pk_mov_b32 v[150:151], v[176:177], v[174:175] op_sel:[1,0]
	v_mov_b32_e32 v177, v175
	v_pk_fma_f32 v[160:161], v[38:39], v[38:39], v[178:179] op_sel_hi:[1,1,0]
	v_pk_fma_f32 v[164:165], v[40:41], v[40:41], v[180:181] op_sel_hi:[1,1,0]
	v_pk_add_f32 v[188:189], v[144:145], v[144:145] op_sel:[0,1] op_sel_hi:[1,0]
	v_pk_add_f32 v[190:191], v[146:147], v[146:147] op_sel:[0,1] op_sel_hi:[1,0]
	v_pk_add_f32 v[148:149], v[148:149], v[172:173]
	v_pk_add_f32 v[172:173], v[182:183], v[184:185]
	v_mov_b32_e32 v163, v179
	v_mov_b32_e32 v167, v186
	v_pk_mul_f32 v[168:169], v[32:33], v[32:33]
	v_pk_mul_f32 v[170:171], v[30:31], v[30:31]
	v_pk_mul_f32 v[174:175], v[28:29], v[28:29]
	v_pk_mul_f32 v[178:179], v[26:27], v[26:27]
	v_pk_add_f32 v[150:151], v[150:151], v[176:177]
	v_mov_b32_e32 v161, v195
	v_mov_b32_e32 v165, v196
	v_mov_b32_e32 v189, v187
	v_mov_b32_e32 v191, v192
	v_pk_add_f32 v[158:159], v[172:173], v[158:159]
	v_mul_f32_e32 v193, v34, v34
	v_mul_f32_e32 v194, v35, v35
	v_pk_add_f32 v[162:163], v[162:163], v[166:167]
	v_pk_mov_b32 v[166:167], v[170:171], v[168:169] op_sel:[1,0]
	v_mov_b32_e32 v171, v169
	v_pk_mov_b32 v[168:169], v[178:179], v[174:175] op_sel:[1,0]
	v_mov_b32_e32 v179, v175
	v_pk_add_f32 v[174:175], v[148:149], v[148:149] op_sel:[0,1] op_sel_hi:[1,0]
	v_pk_add_f32 v[176:177], v[150:151], v[150:151] op_sel:[0,1] op_sel_hi:[1,0]
	v_pk_add_f32 v[160:161], v[160:161], v[164:165]
	v_pk_add_f32 v[164:165], v[188:189], v[190:191]
	v_add_f32_e32 v157, v158, v159
	v_mov_b32_e32 v175, v193
	v_mov_b32_e32 v177, v194
	v_pk_add_f32 v[158:159], v[164:165], v[162:163]
	v_pk_add_f32 v[162:163], v[174:175], v[176:177]
	v_add_f32_e32 v164, v158, v159
	v_pk_add_f32 v[158:159], v[162:163], v[160:161]
	v_add_f32_e32 v158, v158, v159
	s_waitcnt lgkmcnt(0)
	s_nop 1
	v_add_f32_dpp v157, v157, v157 quad_perm:[1,0,3,2] row_mask:0xf bank_mask:0xf
	s_waitcnt lgkmcnt(0)
	s_nop 1
	v_add_f32_dpp v160, v164, v164 quad_perm:[1,0,3,2] row_mask:0xf bank_mask:0xf
	s_waitcnt lgkmcnt(0)
	s_nop 1
	v_add_f32_dpp v158, v158, v158 quad_perm:[1,0,3,2] row_mask:0xf bank_mask:0xf
	s_waitcnt lgkmcnt(0)
	s_nop 1
	v_add_f32_dpp v157, v157, v157 quad_perm:[2,3,0,1] row_mask:0xf bank_mask:0xf
	s_waitcnt lgkmcnt(0)
	s_nop 1
	v_add_f32_dpp v160, v160, v160 quad_perm:[2,3,0,1] row_mask:0xf bank_mask:0xf
	s_waitcnt lgkmcnt(0)
	s_nop 1
	v_add_f32_dpp v158, v158, v158 quad_perm:[2,3,0,1] row_mask:0xf bank_mask:0xf
	s_waitcnt lgkmcnt(0)
	s_nop 1
	v_add_f32_dpp v157, v157, v157 row_half_mirror row_mask:0xf bank_mask:0xf
	s_waitcnt lgkmcnt(0)
	s_nop 1
	v_add_f32_dpp v160, v160, v160 row_half_mirror row_mask:0xf bank_mask:0xf
	s_waitcnt lgkmcnt(0)
	s_nop 1
	v_add_f32_dpp v158, v158, v158 row_half_mirror row_mask:0xf bank_mask:0xf
	s_waitcnt lgkmcnt(0)
	s_nop 1
	v_add_f32_dpp v157, v157, v157 row_mirror row_mask:0xf bank_mask:0xf
	ds_bpermute_b32 v161, v153, v157
	s_waitcnt lgkmcnt(2)
	s_nop 1
	v_add_f32_dpp v160, v160, v160 row_mirror row_mask:0xf bank_mask:0xf
	ds_bpermute_b32 v162, v153, v160
	s_waitcnt lgkmcnt(2)
	s_nop 1
	v_add_f32_dpp v158, v158, v158 row_mirror row_mask:0xf bank_mask:0xf
	ds_bpermute_b32 v159, v153, v158
	s_waitcnt lgkmcnt(2)
	v_add_f32_e32 v157, v157, v161
	ds_bpermute_b32 v161, v154, v157
	s_waitcnt lgkmcnt(2)
	v_add_f32_e32 v160, v160, v162
	ds_bpermute_b32 v162, v154, v160
	s_waitcnt lgkmcnt(2)
	v_add_f32_e32 v158, v158, v159
	ds_bpermute_b32 v159, v154, v158
	s_waitcnt lgkmcnt(2)
	v_add_f32_e32 v157, v157, v161
	v_fmamk_f32 v157, v157, 0x3a800000, v155
	s_waitcnt lgkmcnt(1)
	v_add_f32_e32 v160, v160, v162
	v_mul_f32_e32 v161, 0x4f800000, v157
	v_cmp_gt_f32_e32 vcc, s4, v157
	v_fmamk_f32 v160, v160, 0x3a800000, v155
	s_waitcnt lgkmcnt(0)
	v_add_f32_e32 v158, v158, v159
	v_cndmask_b32_e32 v157, v157, v161, vcc
	v_mul_f32_e32 v159, 0x4f800000, v160
	v_cmp_gt_f32_e64 s[6:7], s4, v160
	v_sqrt_f32_e32 v161, v157
	v_fmamk_f32 v158, v158, 0x3a800000, v155
	v_cndmask_b32_e64 v159, v160, v159, s[6:7]
	v_mul_f32_e32 v160, 0x4f800000, v158
	v_cmp_gt_f32_e64 s[8:9], s4, v158
	v_sqrt_f32_e32 v162, v159
	v_add_u32_e32 v163, -1, v161
	v_cndmask_b32_e64 v158, v158, v160, s[8:9]
	v_sqrt_f32_e32 v160, v158
	v_add_u32_e32 v164, 1, v161
	v_fma_f32 v165, -v163, v161, v157
	v_pk_add_f32 v[148:149], v[166:167], v[170:171]
	v_fma_f32 v166, -v164, v161, v157
	v_add_u32_e32 v167, -1, v162
	v_cmp_ge_f32_e64 s[10:11], 0, v165
	v_pk_add_f32 v[150:151], v[168:169], v[178:179]
	v_add_u32_e32 v168, 1, v162
	v_cndmask_b32_e64 v161, v161, v163, s[10:11]
	v_fma_f32 v163, -v167, v162, v159
	v_cmp_lt_f32_e64 s[10:11], 0, v166
	v_fma_f32 v165, -v168, v162, v159
	v_add_u32_e32 v169, -1, v160
	v_cndmask_b32_e64 v161, v161, v164, s[10:11]
	v_cmp_ge_f32_e64 s[10:11], 0, v163
	v_add_u32_e32 v170, 1, v160
	v_fma_f32 v163, -v169, v160, v158
	v_cndmask_b32_e64 v162, v162, v167, s[10:11]
	v_cmp_lt_f32_e64 s[10:11], 0, v165
	v_fma_f32 v164, -v170, v160, v158
	v_mul_f32_e32 v165, 0x37800000, v161
	v_cndmask_b32_e64 v162, v162, v168, s[10:11]
	v_cmp_ge_f32_e64 s[10:11], 0, v163
	v_cndmask_b32_e32 v161, v161, v165, vcc
	v_cmp_class_f32_e32 vcc, v157, v156
	v_cndmask_b32_e64 v160, v160, v169, s[10:11]
	v_cmp_lt_f32_e64 s[10:11], 0, v164
	v_mul_f32_e32 v163, 0x37800000, v162
	v_cndmask_b32_e32 v157, v161, v157, vcc
	v_cndmask_b32_e64 v160, v160, v170, s[10:11]
	v_cndmask_b32_e64 v161, v162, v163, s[6:7]
	v_cmp_class_f32_e32 vcc, v159, v156
	v_mul_f32_e32 v162, 0x37800000, v160
	v_div_scale_f32 v163, s[6:7], v157, v157, 1.0
	v_cndmask_b32_e32 v159, v161, v159, vcc
	v_cndmask_b32_e64 v160, v160, v162, s[8:9]
	v_cmp_class_f32_e32 vcc, v158, v156
	v_rcp_f32_e32 v161, v163
	v_div_scale_f32 v162, s[8:9], v159, v159, 1.0
	v_cndmask_b32_e32 v160, v160, v158, vcc
	v_rcp_f32_e32 v166, v162
	v_div_scale_f32 v167, s[10:11], v160, v160, 1.0
	v_rcp_f32_e32 v169, v167
	v_fma_f32 v158, -v163, v161, 1.0
	v_div_scale_f32 v164, s[6:7], 1.0, v157, 1.0
	v_fmac_f32_e32 v161, v158, v161
	v_fma_f32 v158, -v162, v166, 1.0
	v_mul_f32_e32 v170, v164, v161
	v_div_scale_f32 v165, s[8:9], 1.0, v159, 1.0
	v_fmac_f32_e32 v166, v158, v166
	v_fma_f32 v158, -v167, v169, 1.0
	v_fma_f32 v171, -v163, v170, v164
	v_div_scale_f32 v168, s[10:11], 1.0, v160, 1.0
	v_mul_f32_e32 v172, v165, v166
	v_fmac_f32_e32 v169, v158, v169
	v_fmac_f32_e32 v170, v171, v161
	v_fma_f32 v158, -v162, v172, v165
	v_mul_f32_e32 v171, v168, v169
	v_fma_f32 v163, -v163, v170, v164
	s_mov_b64 vcc, s[6:7]
	v_fmac_f32_e32 v172, v158, v166
	v_fma_f32 v158, -v167, v171, v168
	v_div_fmas_f32 v161, v163, v161, v170
	v_fma_f32 v162, -v162, v172, v165
	v_fmac_f32_e32 v171, v158, v169
	v_div_fixup_f32 v158, v161, v157, 1.0
	s_mov_b64 vcc, s[8:9]
	v_div_fmas_f32 v157, v162, v166, v172
	v_fma_f32 v161, -v167, v171, v168
	v_pk_mul_f32 v[80:81], v[80:81], v[158:159] op_sel_hi:[1,0]
	v_pk_mul_f32 v[78:79], v[78:79], v[158:159] op_sel_hi:[1,0]
	s_mov_b64 vcc, s[10:11]
	v_pk_add_f32 v[88:89], v[88:89], 1.0 op_sel_hi:[1,0]
	v_pk_add_f32 v[86:87], v[86:87], 1.0 op_sel_hi:[1,0]
	v_pk_mul_f32 v[76:77], v[76:77], v[158:159] op_sel_hi:[1,0]
	v_pk_mul_f32 v[74:75], v[74:75], v[158:159] op_sel_hi:[1,0]
	v_pk_mul_f32 v[72:73], v[72:73], v[158:159] op_sel_hi:[1,0]
	v_pk_mul_f32 v[70:71], v[70:71], v[158:159] op_sel_hi:[1,0]
	v_pk_mul_f32 v[68:69], v[68:69], v[158:159] op_sel_hi:[1,0]
	v_pk_mul_f32 v[66:67], v[66:67], v[158:159] op_sel_hi:[1,0]
	v_div_fixup_f32 v158, v157, v159, 1.0
	v_div_fmas_f32 v157, v161, v169, v171
	v_pk_mul_f32 v[78:79], v[78:79], v[2:3]
	v_pk_mul_f32 v[80:81], v[80:81], v[4:5]
	v_pk_mul_f32 v[64:65], v[64:65], v[158:159] op_sel_hi:[1,0]
	v_pk_mul_f32 v[62:63], v[62:63], v[158:159] op_sel_hi:[1,0]
	v_pk_mul_f32 v[60:61], v[60:61], v[158:159] op_sel_hi:[1,0]
	v_pk_mul_f32 v[58:59], v[58:59], v[158:159] op_sel_hi:[1,0]
	v_pk_mul_f32 v[56:57], v[56:57], v[158:159] op_sel_hi:[1,0]
	v_pk_mul_f32 v[54:55], v[54:55], v[158:159] op_sel_hi:[1,0]
	v_pk_mul_f32 v[52:53], v[52:53], v[158:159] op_sel_hi:[1,0]
	v_pk_mul_f32 v[158:159], v[50:51], v[158:159] op_sel_hi:[1,0]
	v_div_fixup_f32 v50, v157, v160, 1.0
	v_pk_fma_f32 v[80:81], v[80:81], v[88:89], v[84:85]
	v_pk_fma_f32 v[78:79], v[78:79], v[86:87], v[82:83]
	v_pk_mul_f32 v[86:87], v[52:53], v[16:17]
	v_pk_mul_f32 v[48:49], v[48:49], v[50:51] op_sel_hi:[1,0]
	v_pk_mul_f32 v[46:47], v[46:47], v[50:51] op_sel_hi:[1,0]
	v_pk_mul_f32 v[82:83], v[54:55], v[10:11]
	v_pk_mul_f32 v[84:85], v[158:159], v[14:15]
	v_pk_mul_f32 v[88:89], v[46:47], v[2:3]
	v_pk_mul_f32 v[158:159], v[48:49], v[4:5]
	v_cvt_pk_bf16_f32 v46, v78, v79
	v_cvt_pk_bf16_f32 v47, v80, v81
	global_store_dwordx2 v[102:103], v[46:47], off
	global_load_dwordx4 v[46:49], v[138:139], off
	s_nop 0
	global_load_dwordx4 v[52:55], v[124:125], off offset:1024
	v_pk_mul_f32 v[74:75], v[74:75], v[6:7]
	v_pk_mul_f32 v[76:77], v[76:77], v[8:9]
	v_pk_mul_f32 v[70:71], v[70:71], v[10:11]
	v_pk_mul_f32 v[72:73], v[72:73], v[12:13]
	v_pk_mul_f32 v[66:67], v[66:67], v[14:15]
	v_pk_mul_f32 v[68:69], v[68:69], v[16:17]
	v_pk_mul_f32 v[62:63], v[62:63], v[2:3]
	v_pk_mul_f32 v[64:65], v[64:65], v[4:5]
	v_pk_mul_f32 v[58:59], v[58:59], v[6:7]
	v_pk_mul_f32 v[60:61], v[60:61], v[8:9]
	v_pk_mul_f32 v[56:57], v[56:57], v[12:13]
	v_mul_f32_e32 v180, v23, v23
	v_mul_f32_e32 v186, v25, v25
	v_mul_f32_e32 v197, v18, v18
	v_mul_f32_e32 v198, v19, v19
	v_mul_f32_e32 v199, v20, v20
	v_mul_f32_e32 v200, v21, v21
	v_pk_fma_f32 v[144:145], v[22:23], v[22:23], v[180:181] op_sel_hi:[1,1,0]
	v_pk_fma_f32 v[146:147], v[24:25], v[24:25], v[186:187] op_sel_hi:[1,1,0]
	v_mov_b32_e32 v145, v199
	v_mov_b32_e32 v147, v200
	s_mov_b32 s8, s26
	s_waitcnt vmcnt(0) lgkmcnt(0)
	v_pk_add_f32 v[48:49], v[48:49], 1.0 op_sel_hi:[1,0]
	v_pk_add_f32 v[46:47], v[46:47], 1.0 op_sel_hi:[1,0]
	v_pk_fma_f32 v[48:49], v[76:77], v[48:49], v[54:55]
	v_pk_fma_f32 v[46:47], v[74:75], v[46:47], v[52:53]
	v_cvt_pk_bf16_f32 v46, v46, v47
	v_cvt_pk_bf16_f32 v47, v48, v49
	global_store_dwordx2 v[102:103], v[46:47], off offset:512
	global_load_dwordx4 v[46:49], v[134:135], off
	s_nop 0
	global_load_dwordx4 v[52:55], v[124:125], off offset:2048
	s_waitcnt vmcnt(0) lgkmcnt(0)
	v_pk_add_f32 v[48:49], v[48:49], 1.0 op_sel_hi:[1,0]
	v_pk_add_f32 v[46:47], v[46:47], 1.0 op_sel_hi:[1,0]
	v_pk_fma_f32 v[48:49], v[72:73], v[48:49], v[54:55]
	v_pk_fma_f32 v[46:47], v[70:71], v[46:47], v[52:53]
	v_cvt_pk_bf16_f32 v46, v46, v47
	v_cvt_pk_bf16_f32 v47, v48, v49
	global_store_dwordx2 v[102:103], v[46:47], off offset:1024
	global_load_dwordx4 v[46:49], v[128:129], off
	s_nop 0
	global_load_dwordx4 v[52:55], v[124:125], off offset:3072
	s_waitcnt vmcnt(0) lgkmcnt(0)
	v_pk_add_f32 v[48:49], v[48:49], 1.0 op_sel_hi:[1,0]
	v_pk_add_f32 v[46:47], v[46:47], 1.0 op_sel_hi:[1,0]
	v_pk_fma_f32 v[48:49], v[68:69], v[48:49], v[54:55]
	v_pk_fma_f32 v[46:47], v[66:67], v[46:47], v[52:53]
	v_cvt_pk_bf16_f32 v46, v46, v47
	v_cvt_pk_bf16_f32 v47, v48, v49
	global_store_dwordx2 v[102:103], v[46:47], off offset:1536
	global_load_dwordx4 v[46:49], v[126:127], off
	s_nop 0
	global_load_dwordx4 v[52:55], v[110:111], off
	s_waitcnt vmcnt(0) lgkmcnt(0)
	v_pk_add_f32 v[48:49], v[48:49], 1.0 op_sel_hi:[1,0]
	v_pk_add_f32 v[46:47], v[46:47], 1.0 op_sel_hi:[1,0]
	v_pk_fma_f32 v[48:49], v[64:65], v[48:49], v[54:55]
	v_pk_fma_f32 v[46:47], v[62:63], v[46:47], v[52:53]
	v_cvt_pk_bf16_f32 v46, v46, v47
	v_cvt_pk_bf16_f32 v47, v48, v49
	global_store_dwordx2 v[102:103], v[46:47], off offset:2048
	global_load_dwordx4 v[46:49], v[120:121], off
	s_nop 0
	global_load_dwordx4 v[52:55], v[110:111], off offset:1024
	s_waitcnt vmcnt(0) lgkmcnt(0)
	v_pk_add_f32 v[48:49], v[48:49], 1.0 op_sel_hi:[1,0]
	v_pk_add_f32 v[46:47], v[46:47], 1.0 op_sel_hi:[1,0]
	v_pk_fma_f32 v[48:49], v[60:61], v[48:49], v[54:55]
	v_pk_fma_f32 v[46:47], v[58:59], v[46:47], v[52:53]
	v_cvt_pk_bf16_f32 v46, v46, v47
	v_cvt_pk_bf16_f32 v47, v48, v49
	global_store_dwordx2 v[102:103], v[46:47], off offset:2560
	global_load_dwordx4 v[46:49], v[116:117], off
	s_nop 0
	global_load_dwordx4 v[52:55], v[110:111], off offset:2048
	v_pk_add_f32 v[58:59], v[150:151], v[150:151] op_sel:[0,1] op_sel_hi:[1,0]
	v_pk_add_f32 v[60:61], v[144:145], v[146:147]
	v_mov_b32_e32 v59, v198
	s_waitcnt vmcnt(0) lgkmcnt(0)
	v_pk_add_f32 v[48:49], v[48:49], 1.0 op_sel_hi:[1,0]
	v_pk_add_f32 v[46:47], v[46:47], 1.0 op_sel_hi:[1,0]
	v_pk_fma_f32 v[48:49], v[56:57], v[48:49], v[54:55]
	v_pk_fma_f32 v[46:47], v[82:83], v[46:47], v[52:53]
	v_cvt_pk_bf16_f32 v46, v46, v47
	v_cvt_pk_bf16_f32 v47, v48, v49
	global_store_dwordx2 v[102:103], v[46:47], off offset:3072
	global_load_dwordx4 v[46:49], v[112:113], off
	s_nop 0
	global_load_dwordx4 v[52:55], v[110:111], off offset:3072
	v_pk_add_f32 v[56:57], v[148:149], v[148:149] op_sel:[0,1] op_sel_hi:[1,0]
	s_waitcnt vmcnt(0) lgkmcnt(0)
	v_pk_add_f32 v[48:49], v[48:49], 1.0 op_sel_hi:[1,0]
	v_pk_add_f32 v[46:47], v[46:47], 1.0 op_sel_hi:[1,0]
	v_pk_fma_f32 v[48:49], v[86:87], v[48:49], v[54:55]
	v_pk_fma_f32 v[46:47], v[84:85], v[46:47], v[52:53]
	v_cvt_pk_bf16_f32 v46, v46, v47
	v_cvt_pk_bf16_f32 v47, v48, v49
	global_store_dwordx2 v[102:103], v[46:47], off offset:3584
	global_load_dwordx4 v[46:49], v[142:143], off
	s_nop 0
	global_load_dwordx4 v[52:55], v[108:109], off
	v_mov_b32_e32 v57, v197
	s_waitcnt vmcnt(0) lgkmcnt(0)
	v_pk_add_f32 v[48:49], v[48:49], 1.0 op_sel_hi:[1,0]
	v_pk_add_f32 v[46:47], v[46:47], 1.0 op_sel_hi:[1,0]
	v_pk_fma_f32 v[48:49], v[158:159], v[48:49], v[54:55]
	v_pk_fma_f32 v[46:47], v[88:89], v[46:47], v[52:53]
	v_bfe_u32 v51, v46, 16, 1
	v_bfe_u32 v52, v47, 16, 1
	v_add3_u32 v46, v46, v51, s5
	v_add3_u32 v47, v47, v52, s5
	v_lshrrev_b32_e32 v46, 16, v46
	v_and_or_b32 v46, v47, s23, v46
	v_cvt_pk_bf16_f32 v47, v48, v49
	global_store_dwordx2 v[104:105], v[46:47], off
	global_load_dwordx4 v[46:49], v[140:141], off
	s_nop 0
	global_load_dwordx4 v[52:55], v[108:109], off offset:1024
	v_pk_mul_f32 v[44:45], v[44:45], v[50:51] op_sel_hi:[1,0]
	v_pk_mul_f32 v[42:43], v[42:43], v[50:51] op_sel_hi:[1,0]
	v_pk_mul_f32 v[44:45], v[44:45], v[8:9]
	v_pk_mul_f32 v[42:43], v[42:43], v[6:7]
	s_waitcnt vmcnt(0) lgkmcnt(0)
	v_pk_add_f32 v[48:49], v[48:49], 1.0 op_sel_hi:[1,0]
	v_pk_add_f32 v[46:47], v[46:47], 1.0 op_sel_hi:[1,0]
	v_pk_fma_f32 v[44:45], v[44:45], v[48:49], v[54:55]
	v_pk_fma_f32 v[42:43], v[42:43], v[46:47], v[52:53]
	v_cvt_pk_bf16_f32 v42, v42, v43
	v_cvt_pk_bf16_f32 v43, v44, v45
	global_store_dwordx2 v[104:105], v[42:43], off offset:512
	global_load_dwordx4 v[42:45], v[136:137], off
	s_nop 0
	global_load_dwordx4 v[46:49], v[108:109], off offset:2048
	v_pk_add_f32 v[52:53], v[56:57], v[58:59]
	s_waitcnt vmcnt(0) lgkmcnt(0)
	v_pk_add_f32 v[44:45], v[44:45], 1.0 op_sel_hi:[1,0]
	v_pk_add_f32 v[52:53], v[52:53], v[60:61]
	v_pk_add_f32 v[42:43], v[42:43], 1.0 op_sel_hi:[1,0]
	v_add_f32_e32 v51, v52, v53
	s_waitcnt lgkmcnt(0)
	s_nop 1
	v_add_f32_dpp v51, v51, v51 quad_perm:[1,0,3,2] row_mask:0xf bank_mask:0xf
	s_waitcnt lgkmcnt(0)
	s_nop 1
	v_add_f32_dpp v51, v51, v51 quad_perm:[2,3,0,1] row_mask:0xf bank_mask:0xf
	v_pk_mul_f32 v[40:41], v[40:41], v[50:51] op_sel_hi:[1,0]
	v_pk_mul_f32 v[38:39], v[38:39], v[50:51] op_sel_hi:[1,0]
	v_pk_mul_f32 v[40:41], v[40:41], v[12:13]
	v_pk_mul_f32 v[38:39], v[38:39], v[10:11]
	v_pk_fma_f32 v[40:41], v[40:41], v[44:45], v[48:49]
	v_pk_fma_f32 v[38:39], v[38:39], v[42:43], v[46:47]
	v_cvt_pk_bf16_f32 v38, v38, v39
	v_cvt_pk_bf16_f32 v39, v40, v41
	global_store_dwordx2 v[104:105], v[38:39], off offset:1024
	global_load_dwordx4 v[38:41], v[122:123], off
	s_nop 0
	global_load_dwordx4 v[42:45], v[108:109], off offset:3072
	v_pk_mul_f32 v[36:37], v[36:37], v[50:51] op_sel_hi:[1,0]
	v_pk_mul_f32 v[34:35], v[34:35], v[50:51] op_sel_hi:[1,0]
	v_pk_mul_f32 v[36:37], v[36:37], v[16:17]
	v_pk_mul_f32 v[34:35], v[34:35], v[14:15]
	s_waitcnt lgkmcnt(0)
	s_nop 1
	v_add_f32_dpp v46, v51, v51 row_half_mirror row_mask:0xf bank_mask:0xf
	s_waitcnt lgkmcnt(0)
	s_nop 1
	v_add_f32_dpp v46, v46, v46 row_mirror row_mask:0xf bank_mask:0xf
	ds_bpermute_b32 v47, v153, v46
	s_waitcnt lgkmcnt(0)
	v_add_f32_e32 v46, v46, v47
	ds_bpermute_b32 v47, v154, v46
	s_waitcnt lgkmcnt(0)
	v_add_f32_e32 v46, v46, v47
	v_fmamk_f32 v46, v46, 0x3a800000, v155
	v_mul_f32_e32 v47, 0x4f800000, v46
	v_cmp_gt_f32_e32 vcc, s4, v46
	s_waitcnt vmcnt(0)
	v_pk_add_f32 v[40:41], v[40:41], 1.0 op_sel_hi:[1,0]
	v_pk_add_f32 v[38:39], v[38:39], 1.0 op_sel_hi:[1,0]
	v_pk_fma_f32 v[36:37], v[36:37], v[40:41], v[44:45]
	v_pk_fma_f32 v[34:35], v[34:35], v[38:39], v[42:43]
	v_cvt_pk_bf16_f32 v34, v34, v35
	v_cvt_pk_bf16_f32 v35, v36, v37
	global_store_dwordx2 v[104:105], v[34:35], off offset:1536
	global_load_dwordx4 v[34:37], v[118:119], off
	s_nop 0
	global_load_dwordx4 v[38:41], v[106:107], off
	v_cndmask_b32_e32 v42, v46, v47, vcc
	v_sqrt_f32_e32 v43, v42
	s_waitcnt vmcnt(0) lgkmcnt(0)
	v_pk_add_f32 v[36:37], v[36:37], 1.0 op_sel_hi:[1,0]
	v_add_u32_e32 v44, -1, v43
	v_add_u32_e32 v45, 1, v43
	v_fma_f32 v46, -v44, v43, v42
	v_fma_f32 v47, -v45, v43, v42
	v_cmp_ge_f32_e64 s[6:7], 0, v46
	v_pk_add_f32 v[34:35], v[34:35], 1.0 op_sel_hi:[1,0]
	s_nop 0
	v_cndmask_b32_e64 v43, v43, v44, s[6:7]
	v_cmp_lt_f32_e64 s[6:7], 0, v47
	s_nop 1
	v_cndmask_b32_e64 v43, v43, v45, s[6:7]
	v_mul_f32_e32 v44, 0x37800000, v43
	v_cndmask_b32_e32 v43, v43, v44, vcc
	v_cmp_class_f32_e32 vcc, v42, v156
	s_nop 1
	v_cndmask_b32_e32 v42, v43, v42, vcc
	v_div_scale_f32 v43, s[6:7], v42, v42, 1.0
	v_rcp_f32_e32 v45, v43
	v_div_scale_f32 v44, vcc, 1.0, v42, 1.0
	v_fma_f32 v46, -v43, v45, 1.0
	v_fmac_f32_e32 v45, v46, v45
	v_mul_f32_e32 v46, v44, v45
	v_fma_f32 v47, -v43, v46, v44
	v_fmac_f32_e32 v46, v47, v45
	v_fma_f32 v43, -v43, v46, v44
	v_div_fmas_f32 v43, v43, v45, v46
	v_div_fixup_f32 v42, v43, v42, 1.0
	v_pk_mul_f32 v[32:33], v[32:33], v[42:43] op_sel_hi:[1,0]
	v_pk_mul_f32 v[30:31], v[30:31], v[42:43] op_sel_hi:[1,0]
	v_pk_mul_f32 v[32:33], v[32:33], v[4:5]
	v_pk_mul_f32 v[30:31], v[30:31], v[2:3]
	v_pk_fma_f32 v[32:33], v[32:33], v[36:37], v[40:41]
	v_pk_fma_f32 v[30:31], v[30:31], v[34:35], v[38:39]
	v_cvt_pk_bf16_f32 v30, v30, v31
	v_cvt_pk_bf16_f32 v31, v32, v33
	global_store_dwordx2 v[104:105], v[30:31], off offset:2048
	global_load_dwordx4 v[30:33], v[114:115], off
	s_nop 0
	global_load_dwordx4 v[34:37], v[106:107], off offset:1024
	v_pk_mul_f32 v[28:29], v[28:29], v[42:43] op_sel_hi:[1,0]
	v_pk_mul_f32 v[26:27], v[26:27], v[42:43] op_sel_hi:[1,0]
	v_pk_mul_f32 v[28:29], v[28:29], v[8:9]
	v_pk_mul_f32 v[26:27], v[26:27], v[6:7]
	v_lshl_add_u64 v[38:39], s[20:21], 0, v[98:99]
	v_pk_mul_f32 v[24:25], v[24:25], v[42:43] op_sel_hi:[1,0]
	v_pk_mul_f32 v[22:23], v[22:23], v[42:43] op_sel_hi:[1,0]
	v_pk_mul_f32 v[24:25], v[24:25], v[12:13]
	v_pk_mul_f32 v[22:23], v[22:23], v[10:11]
	v_pk_mul_f32 v[20:21], v[20:21], v[42:43] op_sel_hi:[1,0]
	v_pk_mul_f32 v[18:19], v[18:19], v[42:43] op_sel_hi:[1,0]
	v_pk_mul_f32 v[20:21], v[20:21], v[16:17]
	v_pk_mul_f32 v[18:19], v[18:19], v[14:15]
	s_waitcnt vmcnt(0) lgkmcnt(0)
	v_pk_add_f32 v[32:33], v[32:33], 1.0 op_sel_hi:[1,0]
	v_pk_add_f32 v[30:31], v[30:31], 1.0 op_sel_hi:[1,0]
	v_pk_fma_f32 v[28:29], v[28:29], v[32:33], v[36:37]
	v_pk_fma_f32 v[26:27], v[26:27], v[30:31], v[34:35]
	v_cvt_pk_bf16_f32 v26, v26, v27
	v_cvt_pk_bf16_f32 v27, v28, v29
	global_store_dwordx2 v[104:105], v[26:27], off offset:2560
	global_load_dwordx4 v[26:29], v[38:39], off
	s_nop 0
	global_load_dwordx4 v[30:33], v[106:107], off offset:2048
	v_lshl_add_u64 v[34:35], s[20:21], 0, v[100:101]
	s_waitcnt vmcnt(0) lgkmcnt(0)
	v_pk_add_f32 v[28:29], v[28:29], 1.0 op_sel_hi:[1,0]
	v_pk_add_f32 v[26:27], v[26:27], 1.0 op_sel_hi:[1,0]
	v_pk_fma_f32 v[24:25], v[24:25], v[28:29], v[32:33]
	v_pk_fma_f32 v[22:23], v[22:23], v[26:27], v[30:31]
	v_cvt_pk_bf16_f32 v22, v22, v23
	v_cvt_pk_bf16_f32 v23, v24, v25
	global_store_dwordx2 v[104:105], v[22:23], off offset:3072
	global_load_dwordx4 v[22:25], v[34:35], off
	s_nop 0
	global_load_dwordx4 v[26:29], v[106:107], off offset:3072
	s_waitcnt vmcnt(0) lgkmcnt(0)
	v_pk_add_f32 v[24:25], v[24:25], 1.0 op_sel_hi:[1,0]
	v_pk_add_f32 v[22:23], v[22:23], 1.0 op_sel_hi:[1,0]
	v_pk_fma_f32 v[20:21], v[20:21], v[24:25], v[28:29]
	v_pk_fma_f32 v[18:19], v[18:19], v[22:23], v[26:27]
	v_cvt_pk_bf16_f32 v18, v18, v19
	v_cvt_pk_bf16_f32 v19, v20, v21
	global_store_dwordx2 v[104:105], v[18:19], off offset:3584
	s_cbranch_scc1 .LBB0_1004

.LBB0_2762:
	v_mul_f32_e32 v149, v11, v95
	v_fmac_f32_e32 v149, v10, v94
	v_fmac_f32_e32 v149, v12, v96
	v_fmac_f32_e32 v149, v13, v97
	v_sub_u32_e32 v148, 0x800, v144
	v_cvt_f32_u32_e32 v148, v148
	v_cmp_gt_i32_e32 vcc, s45, v144
	s_waitcnt vmcnt(0)
	v_pk_mul_f32 v[154:155], v[12:13], v[92:93]
	s_waitcnt lgkmcnt(0)
	v_add_f32_dpp v149, v149, v149 quad_perm:[1,0,3,2] row_mask:0xf bank_mask:0xf
	v_cmp_gt_i32_e64 s[10:11], s45, v147
	v_pk_mul_f32 v[158:159], v[12:13], v[88:89]
	v_cmp_gt_i32_e64 s[12:13], s45, v146
	v_pk_mul_f32 v[160:161], v[10:11], v[82:83]
	s_waitcnt lgkmcnt(0)
	v_add_f32_dpp v149, v149, v149 quad_perm:[2,3,0,1] row_mask:0xf bank_mask:0xf
	v_cmp_gt_i32_e64 s[14:15], s45, v145
	s_waitcnt lgkmcnt(0)
	v_add_f32_dpp v149, v149, v149 row_half_mirror row_mask:0xf bank_mask:0xf
	s_waitcnt lgkmcnt(0)
	s_nop 0
	v_add_f32_dpp v149, v149, v149 row_mirror row_mask:0xf bank_mask:0xf
	v_fma_f32 v149, -v127, v148, v149
	v_cndmask_b32_e32 v153, v135, v149, vcc
	v_mul_f32_e32 v149, v15, v95
	v_fmac_f32_e32 v149, v14, v94
	v_fmac_f32_e32 v149, v16, v96
	v_fmac_f32_e32 v149, v17, v97
	s_waitcnt lgkmcnt(0)
	s_nop 0
	v_add_f32_dpp v149, v149, v149 quad_perm:[1,0,3,2] row_mask:0xf bank_mask:0xf
	s_waitcnt lgkmcnt(0)
	s_nop 0
	v_add_f32_dpp v149, v149, v149 quad_perm:[2,3,0,1] row_mask:0xf bank_mask:0xf
	s_waitcnt lgkmcnt(0)
	s_nop 0
	v_add_f32_dpp v151, v149, v149 row_half_mirror row_mask:0xf bank_mask:0xf
	v_mul_f32_e32 v149, v19, v95
	v_mul_f32_e32 v95, v23, v95
	v_fmac_f32_e32 v149, v18, v94
	v_fmac_f32_e32 v95, v22, v94
	v_fmac_f32_e32 v149, v20, v96
	v_fmac_f32_e32 v95, v24, v96
	v_fmac_f32_e32 v149, v21, v97
	v_fmac_f32_e32 v95, v25, v97
	v_mul_f32_e32 v97, v11, v91
	v_fmac_f32_e32 v97, v10, v90
	v_add_f32_e32 v97, v154, v97
	v_add_f32_e32 v97, v155, v97
	ds_bpermute_b32 v152, v141, v151
	s_waitcnt lgkmcnt(0)
	v_add_f32_dpp v97, v97, v97 quad_perm:[1,0,3,2] row_mask:0xf bank_mask:0xf
	s_waitcnt lgkmcnt(0)
	s_nop 1
	v_add_f32_dpp v94, v95, v95 quad_perm:[1,0,3,2] row_mask:0xf bank_mask:0xf
	s_waitcnt lgkmcnt(0)
	v_add_f32_dpp v149, v149, v149 quad_perm:[1,0,3,2] row_mask:0xf bank_mask:0xf
	s_waitcnt lgkmcnt(0)
	v_add_f32_dpp v97, v97, v97 quad_perm:[2,3,0,1] row_mask:0xf bank_mask:0xf
	s_waitcnt lgkmcnt(0)
	v_add_f32_dpp v94, v94, v94 quad_perm:[2,3,0,1] row_mask:0xf bank_mask:0xf
	s_waitcnt lgkmcnt(0)
	v_add_f32_dpp v149, v149, v149 quad_perm:[2,3,0,1] row_mask:0xf bank_mask:0xf
	s_waitcnt lgkmcnt(0)
	v_add_f32_dpp v97, v97, v97 row_half_mirror row_mask:0xf bank_mask:0xf
	s_waitcnt lgkmcnt(0)
	v_add_f32_dpp v94, v94, v94 row_half_mirror row_mask:0xf bank_mask:0xf
	v_sub_u32_e32 v95, 0x7fc, v144
	v_cvt_f32_u32_e32 v95, v95
	s_waitcnt lgkmcnt(0)
	v_add_f32_dpp v149, v149, v149 row_half_mirror row_mask:0xf bank_mask:0xf
	s_waitcnt lgkmcnt(0)
	v_add_f32_dpp v97, v97, v97 row_mirror row_mask:0xf bank_mask:0xf
	ds_bpermute_b32 v150, v141, v149
	v_fma_f32 v97, -v127, v95, v97
	v_cndmask_b32_e64 v156, v135, v97, s[10:11]
	v_mul_f32_e32 v97, v15, v91
	v_fmac_f32_e32 v97, v14, v90
	v_fmac_f32_e32 v97, v16, v92
	v_fmac_f32_e32 v97, v17, v93
	v_max3_f32 v162, v153, s35, v156
	ds_bpermute_b32 v96, v141, v94
	s_waitcnt lgkmcnt(0)
	v_add_f32_dpp v97, v97, v97 quad_perm:[1,0,3,2] row_mask:0xf bank_mask:0xf
	s_waitcnt lgkmcnt(0)
	s_nop 0
	v_add_f32_dpp v97, v97, v97 quad_perm:[2,3,0,1] row_mask:0xf bank_mask:0xf
	s_waitcnt lgkmcnt(0)
	s_nop 0
	v_add_f32_dpp v154, v97, v97 row_half_mirror row_mask:0xf bank_mask:0xf
	v_mul_f32_e32 v97, v19, v91
	v_mul_f32_e32 v91, v23, v91
	v_fmac_f32_e32 v97, v18, v90
	v_fmac_f32_e32 v91, v22, v90
	v_fmac_f32_e32 v97, v20, v92
	v_fmac_f32_e32 v91, v24, v92
	v_fmac_f32_e32 v97, v21, v93
	v_fmac_f32_e32 v91, v25, v93
	v_mul_f32_e32 v93, v11, v87
	v_fmac_f32_e32 v93, v10, v86
	v_add_f32_e32 v93, v158, v93
	v_add_f32_e32 v93, v159, v93
	ds_bpermute_b32 v155, v141, v154
	s_waitcnt lgkmcnt(0)
	v_add_f32_dpp v93, v93, v93 quad_perm:[1,0,3,2] row_mask:0xf bank_mask:0xf
	s_waitcnt lgkmcnt(0)
	s_nop 1
	v_add_f32_dpp v90, v91, v91 quad_perm:[1,0,3,2] row_mask:0xf bank_mask:0xf
	s_waitcnt lgkmcnt(0)
	v_add_f32_dpp v97, v97, v97 quad_perm:[1,0,3,2] row_mask:0xf bank_mask:0xf
	s_waitcnt lgkmcnt(0)
	v_add_f32_dpp v93, v93, v93 quad_perm:[2,3,0,1] row_mask:0xf bank_mask:0xf
	s_waitcnt lgkmcnt(0)
	v_add_f32_dpp v90, v90, v90 quad_perm:[2,3,0,1] row_mask:0xf bank_mask:0xf
	s_waitcnt lgkmcnt(0)
	v_add_f32_dpp v97, v97, v97 quad_perm:[2,3,0,1] row_mask:0xf bank_mask:0xf
	s_waitcnt lgkmcnt(0)
	v_add_f32_dpp v93, v93, v93 row_half_mirror row_mask:0xf bank_mask:0xf
	s_waitcnt lgkmcnt(0)
	s_nop 1
	v_add_f32_dpp v91, v90, v90 row_half_mirror row_mask:0xf bank_mask:0xf
	v_sub_u32_e32 v90, 0x7f8, v144
	v_cvt_f32_u32_e32 v90, v90
	s_waitcnt lgkmcnt(0)
	v_add_f32_dpp v97, v97, v97 row_half_mirror row_mask:0xf bank_mask:0xf
	s_waitcnt lgkmcnt(0)
	v_add_f32_dpp v93, v93, v93 row_mirror row_mask:0xf bank_mask:0xf
	ds_bpermute_b32 v147, v141, v97
	v_fma_f32 v93, -v127, v90, v93
	v_cndmask_b32_e64 v159, v135, v93, s[12:13]
	v_mul_f32_e32 v93, v15, v87
	v_fmac_f32_e32 v93, v14, v86
	v_fmac_f32_e32 v93, v16, v88
	v_fmac_f32_e32 v93, v17, v89
	ds_bpermute_b32 v92, v141, v91
	s_waitcnt lgkmcnt(0)
	v_add_f32_dpp v93, v93, v93 quad_perm:[1,0,3,2] row_mask:0xf bank_mask:0xf
	s_waitcnt lgkmcnt(0)
	s_nop 0
	v_add_f32_dpp v93, v93, v93 quad_perm:[2,3,0,1] row_mask:0xf bank_mask:0xf
	s_waitcnt lgkmcnt(0)
	s_nop 0
	v_add_f32_dpp v157, v93, v93 row_half_mirror row_mask:0xf bank_mask:0xf
	v_mul_f32_e32 v93, v19, v87
	v_mul_f32_e32 v87, v23, v87
	v_fmac_f32_e32 v87, v22, v86
	v_fmac_f32_e32 v87, v24, v88
	v_fmac_f32_e32 v87, v25, v89
	v_fmac_f32_e32 v93, v18, v86
	v_fmac_f32_e32 v93, v20, v88
	v_fmac_f32_e32 v93, v21, v89
	v_add_f32_e32 v89, v160, v161
	s_waitcnt lgkmcnt(0)
	s_nop 1
	v_add_f32_dpp v86, v87, v87 quad_perm:[1,0,3,2] row_mask:0xf bank_mask:0xf
	ds_bpermute_b32 v158, v141, v157
	s_waitcnt lgkmcnt(0)
	v_add_f32_dpp v93, v93, v93 quad_perm:[1,0,3,2] row_mask:0xf bank_mask:0xf
	s_waitcnt lgkmcnt(0)
	v_add_f32_dpp v86, v86, v86 quad_perm:[2,3,0,1] row_mask:0xf bank_mask:0xf
	s_waitcnt lgkmcnt(0)
	v_add_f32_dpp v93, v93, v93 quad_perm:[2,3,0,1] row_mask:0xf bank_mask:0xf
	s_waitcnt lgkmcnt(0)
	v_add_f32_dpp v86, v86, v86 row_half_mirror row_mask:0xf bank_mask:0xf
	v_sub_u32_e32 v87, 0x7f4, v144
	v_pk_mul_f32 v[144:145], v[12:13], v[84:85]
	v_cvt_f32_u32_e32 v87, v87
	v_add_f32_e32 v89, v144, v89
	v_add_f32_e32 v89, v145, v89
	s_waitcnt lgkmcnt(0)
	v_add_f32_dpp v93, v93, v93 row_half_mirror row_mask:0xf bank_mask:0xf
	ds_bpermute_b32 v146, v141, v93
	ds_bpermute_b32 v88, v141, v86
	s_waitcnt lgkmcnt(0)
	v_add_f32_dpp v89, v89, v89 quad_perm:[1,0,3,2] row_mask:0xf bank_mask:0xf
	s_waitcnt lgkmcnt(0)
	s_nop 0
	v_add_f32_dpp v89, v89, v89 quad_perm:[2,3,0,1] row_mask:0xf bank_mask:0xf
	s_waitcnt lgkmcnt(0)
	s_nop 0
	v_add_f32_dpp v89, v89, v89 row_half_mirror row_mask:0xf bank_mask:0xf
	s_waitcnt lgkmcnt(0)
	s_nop 0
	v_add_f32_dpp v89, v89, v89 row_mirror row_mask:0xf bank_mask:0xf
	v_fma_f32 v89, -v127, v87, v89
	v_cndmask_b32_e64 v161, v135, v89, s[14:15]
	v_mul_f32_e32 v89, v15, v83
	v_fmac_f32_e32 v89, v14, v82
	v_fmac_f32_e32 v89, v16, v84
	v_fmac_f32_e32 v89, v17, v85
	v_max3_f32 v162, v162, v159, v161
	s_waitcnt lgkmcnt(0)
	v_add_f32_dpp v89, v89, v89 quad_perm:[1,0,3,2] row_mask:0xf bank_mask:0xf
	s_waitcnt lgkmcnt(0)
	s_nop 0
	v_add_f32_dpp v89, v89, v89 quad_perm:[2,3,0,1] row_mask:0xf bank_mask:0xf
	s_waitcnt lgkmcnt(0)
	s_nop 0
	v_add_f32_dpp v145, v89, v89 row_half_mirror row_mask:0xf bank_mask:0xf
	v_mul_f32_e32 v89, v19, v83
	v_mul_f32_e32 v83, v23, v83
	v_fmac_f32_e32 v89, v18, v82
	v_fmac_f32_e32 v83, v22, v82
	v_fmac_f32_e32 v89, v20, v84
	v_fmac_f32_e32 v83, v24, v84
	v_fmac_f32_e32 v89, v21, v85
	v_fmac_f32_e32 v83, v25, v85
	ds_bpermute_b32 v84, v142, v162
	ds_bpermute_b32 v160, v141, v145
	s_waitcnt lgkmcnt(0)
	v_add_f32_dpp v89, v89, v89 quad_perm:[1,0,3,2] row_mask:0xf bank_mask:0xf
	s_waitcnt lgkmcnt(0)
	s_nop 1
	v_add_f32_dpp v82, v83, v83 quad_perm:[1,0,3,2] row_mask:0xf bank_mask:0xf
	s_waitcnt lgkmcnt(0)
	v_max_f32_e32 v84, v84, v84
	v_max_f32_e32 v84, v162, v84
	ds_bpermute_b32 v85, v143, v84
	s_waitcnt lgkmcnt(0)
	v_add_f32_dpp v89, v89, v89 quad_perm:[2,3,0,1] row_mask:0xf bank_mask:0xf
	s_waitcnt lgkmcnt(0)
	v_add_f32_dpp v82, v82, v82 quad_perm:[2,3,0,1] row_mask:0xf bank_mask:0xf
	s_waitcnt lgkmcnt(0)
	v_max_f32_e32 v85, v85, v85
	v_max_f32_e32 v84, v84, v85
	v_cmp_neq_f32_e64 s[16:17], s35, v84
	s_waitcnt lgkmcnt(0)
	v_add_f32_dpp v89, v89, v89 row_half_mirror row_mask:0xf bank_mask:0xf
	s_waitcnt lgkmcnt(0)
	v_add_f32_dpp v82, v82, v82 row_half_mirror row_mask:0xf bank_mask:0xf
	ds_bpermute_b32 v144, v141, v89
	ds_bpermute_b32 v83, v141, v82
	s_and_saveexec_b64 s[24:25], s[16:17]
	s_cbranch_execz .LBB0_2764
	v_max_f32_e32 v84, v84, v84
	v_max_f32_e32 v85, v113, v113
	v_max_f32_e32 v119, v85, v84
	v_sub_f32_e32 v84, v113, v119
	v_mul_f32_e32 v113, 0x3fb8aa3b, v84
	v_sub_f32_e32 v84, v153, v119
	v_mul_f32_e32 v84, 0x3fb8aa3b, v84
	v_sub_f32_e32 v118, v156, v119
	v_exp_f32_e32 v84, v84
	v_mul_f32_e32 v118, 0x3fb8aa3b, v118
	v_exp_f32_e32 v118, v118
	v_exp_f32_e32 v156, v113
	v_add_f32_e32 v153, 0, v84
	v_pk_fma_f32 v[162:163], v[76:77], v[84:85], 0 op_sel_hi:[1,0,0]
	v_pk_fma_f32 v[84:85], v[74:75], v[84:85], 0 op_sel_hi:[1,0,0]
	v_add_f32_e32 v153, v118, v153
	v_pk_fma_f32 v[162:163], v[68:69], v[118:119], v[162:163] op_sel_hi:[1,0,1]
	v_pk_fma_f32 v[84:85], v[66:67], v[118:119], v[84:85] op_sel_hi:[1,0,1]
	v_sub_f32_e32 v118, v159, v119
	v_mul_f32_e32 v118, 0x3fb8aa3b, v118
	v_exp_f32_e32 v118, v118
	s_nop 0
	v_add_f32_e32 v153, v118, v153
	v_pk_fma_f32 v[84:85], v[70:71], v[118:119], v[84:85] op_sel_hi:[1,0,1]
	v_pk_fma_f32 v[162:163], v[72:73], v[118:119], v[162:163] op_sel_hi:[1,0,1]
	v_sub_f32_e32 v118, v161, v119
	v_mul_f32_e32 v118, 0x3fb8aa3b, v118
	v_exp_f32_e32 v118, v118
	s_nop 0
	v_add_f32_e32 v153, v118, v153
	ds_bpermute_b32 v113, v142, v153
	v_pk_fma_f32 v[162:163], v[80:81], v[118:119], v[162:163] op_sel_hi:[1,0,1]
	v_pk_fma_f32 v[84:85], v[78:79], v[118:119], v[84:85] op_sel_hi:[1,0,1]
	ds_bpermute_b32 v164, v142, v162
	ds_bpermute_b32 v165, v142, v163
	s_waitcnt lgkmcnt(0)
	v_add_f32_e32 v113, v153, v113
	ds_bpermute_b32 v118, v143, v113
	s_waitcnt lgkmcnt(0)
	v_pk_add_f32 v[162:163], v[162:163], v[164:165]
	ds_bpermute_b32 v164, v143, v162
	s_waitcnt lgkmcnt(0)
	v_add_f32_e32 v118, v113, v118
	v_fmac_f32_e32 v118, v112, v156
	ds_bpermute_b32 v112, v142, v84
	ds_bpermute_b32 v113, v142, v85
	ds_bpermute_b32 v165, v143, v163
	s_waitcnt lgkmcnt(0)
	v_pk_add_f32 v[84:85], v[84:85], v[112:113]
	ds_bpermute_b32 v112, v143, v84
	ds_bpermute_b32 v113, v143, v85
	s_waitcnt lgkmcnt(0)
	v_pk_add_f32 v[84:85], v[84:85], v[112:113]
	v_pk_add_f32 v[112:113], v[162:163], v[164:165]
	v_pk_fma_f32 v[62:63], v[62:63], v[156:157], v[84:85] op_sel_hi:[1,0,1]
	v_pk_fma_f32 v[64:65], v[64:65], v[156:157], v[112:113] op_sel_hi:[1,0,1]
	v_mov_b32_e32 v112, v118
	v_mov_b32_e32 v113, v119

.LBB0_2937:
	v_lshl_add_u64 v[18:19], s[68:69], 0, v[94:95]
	v_lshl_add_u64 v[22:23], s[68:69], 0, v[92:93]
	v_add_co_u32_e32 v20, vcc, 0x7800000, v18
	v_add_co_u32_e64 v102, s[6:7], s24, v22
	s_nop 0
	v_addc_co_u32_e32 v21, vcc, 0, v19, vcc
	v_addc_co_u32_e64 v103, s[6:7], 0, v23, s[6:7]
	v_add_co_u32_e64 v104, s[6:7], s25, v22
	v_add_co_u32_e32 v22, vcc, 0x7801000, v18
	s_nop 0
	v_addc_co_u32_e64 v105, s[6:7], 0, v23, s[6:7]
	global_load_dwordx4 v[78:81], v[20:21], off
	global_load_dwordx4 v[74:77], v[20:21], off offset:1024
	global_load_dwordx4 v[70:73], v[20:21], off offset:2048
	global_load_dwordx4 v[66:69], v[20:21], off offset:3072
	v_addc_co_u32_e32 v23, vcc, 0, v19, vcc
	v_add_co_u32_e32 v20, vcc, 0x7802000, v18
	global_load_dwordx4 v[62:65], v[22:23], off
	global_load_dwordx4 v[58:61], v[22:23], off offset:1024
	global_load_dwordx4 v[54:57], v[22:23], off offset:2048
	global_load_dwordx4 v[50:53], v[22:23], off offset:3072
	v_addc_co_u32_e32 v21, vcc, 0, v19, vcc
	v_add_co_u32_e32 v82, vcc, 0x7803000, v18
	global_load_dwordx4 v[46:49], v[20:21], off
	global_load_dwordx4 v[42:45], v[20:21], off offset:1024
	global_load_dwordx4 v[38:41], v[20:21], off offset:2048
	global_load_dwordx4 v[34:37], v[20:21], off offset:3072
	v_addc_co_u32_e32 v83, vcc, 0, v19, vcc
	global_load_dwordx4 v[30:33], v[82:83], off
	global_load_dwordx4 v[26:29], v[82:83], off offset:1024
	global_load_dwordx4 v[22:25], v[82:83], off offset:2048
	global_load_dwordx4 v[18:21], v[82:83], off offset:3072
	s_ashr_i32 s8, s12, 13
	s_add_i32 s9, s12, 0xffffc002
	s_cmpk_lt_i32 s12, 0x4000
	s_cselect_b32 s6, s8, s9
	s_mul_hi_i32 s7, s6, 0x9000
	s_mul_i32 s6, s6, 0x9000
	s_add_u32 s9, s3, s6
	s_addc_u32 s11, s4, s7
	s_add_u32 s6, s9, 0x6000
	s_addc_u32 s7, s11, 0
	s_add_u32 s10, s9, 0x7000
	s_addc_u32 s11, s11, 0
	v_lshl_add_u64 v[82:83], s[6:7], 0, v[90:91]
	v_lshl_add_u64 v[86:87], s[10:11], 0, v[90:91]
	global_load_dwordx4 v[82:85], v[82:83], off
	v_lshl_add_u64 v[148:149], s[6:7], 0, v[96:97]
	global_load_dwordx4 v[86:89], v[86:87], off
	v_lshl_add_u64 v[142:143], s[6:7], 0, v[98:99]
	v_lshl_add_u64 v[134:135], s[6:7], 0, v[100:101]
	s_add_i32 s6, s12, 0xffffc003
	s_cmpk_lt_i32 s12, 0x3fff
	s_cselect_b32 s6, s8, s6
	s_mul_hi_i32 s7, s6, 0x9000
	s_mul_i32 s6, s6, 0x9000
	s_add_u32 s9, s3, s6
	v_lshl_add_u64 v[152:153], s[10:11], 0, v[96:97]
	v_lshl_add_u64 v[146:147], s[10:11], 0, v[98:99]
	v_lshl_add_u64 v[140:141], s[10:11], 0, v[100:101]
	s_addc_u32 s11, s4, s7
	s_add_u32 s6, s9, 0x6000
	s_addc_u32 s7, s11, 0
	s_add_u32 s10, s9, 0x7000
	v_lshl_add_u64 v[132:133], s[6:7], 0, v[90:91]
	v_lshl_add_u64 v[126:127], s[6:7], 0, v[96:97]
	v_lshl_add_u64 v[118:119], s[6:7], 0, v[98:99]
	v_lshl_add_u64 v[114:115], s[6:7], 0, v[100:101]
	s_addc_u32 s11, s11, 0
	s_add_i32 s6, s12, 0xffffc004
	s_cmpk_lt_i32 s12, 0x3ffe
	s_cselect_b32 s6, s8, s6
	s_mul_hi_i32 s7, s6, 0x9000
	s_mul_i32 s6, s6, 0x9000
	s_add_u32 s6, s3, s6
	s_addc_u32 s7, s4, s7
	v_lshl_add_u64 v[138:139], s[10:11], 0, v[90:91]
	v_lshl_add_u64 v[130:131], s[10:11], 0, v[96:97]
	v_lshl_add_u64 v[122:123], s[10:11], 0, v[98:99]
	v_lshl_add_u64 v[116:117], s[10:11], 0, v[100:101]
	s_add_u32 s10, s6, 0x6000
	s_addc_u32 s11, s7, 0
	s_add_u32 s6, s6, 0x7000
	s_addc_u32 s7, s7, 0
	s_add_i32 s9, s12, 0xffffc005
	s_cmpk_lt_i32 s12, 0x3ffd
	v_lshl_add_u64 v[156:157], s[6:7], 0, v[90:91]
	v_lshl_add_u64 v[154:155], s[6:7], 0, v[96:97]
	v_lshl_add_u64 v[150:151], s[6:7], 0, v[98:99]
	v_lshl_add_u64 v[136:137], s[6:7], 0, v[100:101]
	s_cselect_b32 s6, s8, s9
	s_mul_hi_i32 s7, s6, 0x9000
	s_mul_i32 s6, s6, 0x9000
	s_add_u32 s6, s3, s6
	s_addc_u32 s7, s4, s7
	s_waitcnt vmcnt(0) lgkmcnt(0)
	v_pk_mul_f32 v[158:159], v[80:81], v[80:81]
	v_pk_mul_f32 v[160:161], v[78:79], v[78:79]
	v_pk_mul_f32 v[162:163], v[76:77], v[76:77]
	v_pk_mul_f32 v[164:165], v[74:75], v[74:75]
	v_mul_f32_e32 v174, v71, v71
	v_mul_f32_e32 v176, v73, v73
	v_mul_f32_e32 v187, v68, v68
	v_mul_f32_e32 v189, v69, v69
	v_pk_mov_b32 v[178:179], v[160:161], v[158:159] op_sel:[1,0]
	v_mov_b32_e32 v161, v159
	v_pk_mov_b32 v[158:159], v[164:165], v[162:163] op_sel:[1,0]
	v_mov_b32_e32 v165, v163
	v_pk_fma_f32 v[162:163], v[70:71], v[70:71], v[174:175] op_sel_hi:[1,1,0]
	v_pk_fma_f32 v[174:175], v[72:73], v[72:73], v[176:177] op_sel_hi:[1,1,0]
	v_pk_mul_f32 v[176:177], v[64:65], v[64:65]
	v_pk_mul_f32 v[180:181], v[62:63], v[62:63]
	v_pk_mul_f32 v[182:183], v[60:61], v[60:61]
	v_pk_mul_f32 v[184:185], v[58:59], v[58:59]
	v_mul_f32_e32 v186, v55, v55
	v_mul_f32_e32 v188, v57, v57
	v_pk_add_f32 v[160:161], v[178:179], v[160:161]
	v_pk_add_f32 v[158:159], v[158:159], v[164:165]
	v_mov_b32_e32 v163, v187
	v_mov_b32_e32 v175, v189
	v_pk_mov_b32 v[164:165], v[180:181], v[176:177] op_sel:[1,0]
	v_mov_b32_e32 v181, v177
	v_pk_mov_b32 v[176:177], v[184:185], v[182:183] op_sel:[1,0]
	v_mov_b32_e32 v185, v183
	v_pk_fma_f32 v[178:179], v[54:55], v[54:55], v[186:187] op_sel_hi:[1,1,0]
	v_pk_fma_f32 v[182:183], v[56:57], v[56:57], v[188:189] op_sel_hi:[1,1,0]
	v_pk_mul_f32 v[186:187], v[48:49], v[48:49]
	v_pk_mul_f32 v[188:189], v[46:47], v[46:47]
	v_pk_mul_f32 v[190:191], v[44:45], v[44:45]
	v_pk_mul_f32 v[192:193], v[42:43], v[42:43]
	v_mul_f32_e32 v197, v66, v66
	v_mul_f32_e32 v203, v67, v67
	v_mul_f32_e32 v195, v52, v52
	v_mul_f32_e32 v202, v53, v53
	v_mul_f32_e32 v194, v39, v39
	v_mul_f32_e32 v196, v41, v41
	v_pk_add_f32 v[198:199], v[160:161], v[160:161] op_sel:[0,1] op_sel_hi:[1,0]
	v_pk_add_f32 v[200:201], v[158:159], v[158:159] op_sel:[0,1] op_sel_hi:[1,0]
	v_pk_add_f32 v[174:175], v[162:163], v[174:175]
	v_pk_add_f32 v[158:159], v[164:165], v[180:181]
	v_pk_add_f32 v[160:161], v[176:177], v[184:185]
	v_pk_mov_b32 v[162:163], v[188:189], v[186:187] op_sel:[1,0]
	v_mov_b32_e32 v189, v187
	v_pk_mov_b32 v[164:165], v[192:193], v[190:191] op_sel:[1,0]
	v_mov_b32_e32 v193, v191
	v_mul_f32_e32 v208, v50, v50
	v_mul_f32_e32 v209, v51, v51
	v_mul_f32_e32 v212, v36, v36
	v_mul_f32_e32 v213, v37, v37
	v_mov_b32_e32 v179, v195
	v_mov_b32_e32 v183, v202
	v_pk_fma_f32 v[176:177], v[38:39], v[38:39], v[194:195] op_sel_hi:[1,1,0]
	v_pk_fma_f32 v[180:181], v[40:41], v[40:41], v[196:197] op_sel_hi:[1,1,0]
	v_pk_mul_f32 v[184:185], v[32:33], v[32:33]
	v_pk_mul_f32 v[186:187], v[30:31], v[30:31]
	v_pk_mul_f32 v[190:191], v[28:29], v[28:29]
	v_pk_mul_f32 v[194:195], v[26:27], v[26:27]
	v_mov_b32_e32 v199, v197
	v_mov_b32_e32 v201, v203
	v_pk_add_f32 v[204:205], v[158:159], v[158:159] op_sel:[0,1] op_sel_hi:[1,0]
	v_pk_add_f32 v[206:207], v[160:161], v[160:161] op_sel:[0,1] op_sel_hi:[1,0]
	v_pk_add_f32 v[162:163], v[162:163], v[188:189]
	v_pk_add_f32 v[164:165], v[164:165], v[192:193]
	v_mul_f32_e32 v210, v34, v34
	v_mul_f32_e32 v211, v35, v35
	v_pk_add_f32 v[178:179], v[178:179], v[182:183]
	v_mov_b32_e32 v177, v212
	v_mov_b32_e32 v181, v213
	v_pk_mov_b32 v[182:183], v[186:187], v[184:185] op_sel:[1,0]
	v_mov_b32_e32 v187, v185
	v_pk_mov_b32 v[184:185], v[194:195], v[190:191] op_sel:[1,0]
	v_mov_b32_e32 v195, v191
	v_pk_add_f32 v[188:189], v[198:199], v[200:201]
	v_mov_b32_e32 v205, v208
	v_mov_b32_e32 v207, v209
	v_pk_add_f32 v[190:191], v[162:163], v[162:163] op_sel:[0,1] op_sel_hi:[1,0]
	v_pk_add_f32 v[192:193], v[164:165], v[164:165] op_sel:[0,1] op_sel_hi:[1,0]
	v_pk_add_f32 v[176:177], v[176:177], v[180:181]
	v_pk_add_f32 v[174:175], v[188:189], v[174:175]
	v_pk_add_f32 v[180:181], v[204:205], v[206:207]
	v_mov_b32_e32 v191, v210
	v_mov_b32_e32 v193, v211
	v_pk_add_f32 v[162:163], v[182:183], v[186:187]
	v_add_f32_e32 v182, v174, v175
	v_pk_add_f32 v[174:175], v[180:181], v[178:179]
	v_pk_add_f32 v[178:179], v[190:191], v[192:193]
	v_add_f32_e32 v180, v174, v175
	v_pk_add_f32 v[174:175], v[178:179], v[176:177]
	v_add_f32_e32 v174, v174, v175
	s_add_u32 s18, s6, 0x6000
	s_waitcnt lgkmcnt(0)
	s_nop 1
	v_add_f32_dpp v176, v182, v182 quad_perm:[1,0,3,2] row_mask:0xf bank_mask:0xf
	s_waitcnt lgkmcnt(0)
	s_nop 1
	v_add_f32_dpp v177, v180, v180 quad_perm:[1,0,3,2] row_mask:0xf bank_mask:0xf
	s_waitcnt lgkmcnt(0)
	s_nop 1
	v_add_f32_dpp v174, v174, v174 quad_perm:[1,0,3,2] row_mask:0xf bank_mask:0xf
	s_waitcnt lgkmcnt(0)
	s_nop 1
	v_add_f32_dpp v176, v176, v176 quad_perm:[2,3,0,1] row_mask:0xf bank_mask:0xf
	s_waitcnt lgkmcnt(0)
	s_nop 1
	v_add_f32_dpp v177, v177, v177 quad_perm:[2,3,0,1] row_mask:0xf bank_mask:0xf
	s_waitcnt lgkmcnt(0)
	s_nop 1
	v_add_f32_dpp v174, v174, v174 quad_perm:[2,3,0,1] row_mask:0xf bank_mask:0xf
	s_waitcnt lgkmcnt(0)
	s_nop 1
	v_add_f32_dpp v176, v176, v176 row_half_mirror row_mask:0xf bank_mask:0xf
	s_waitcnt lgkmcnt(0)
	s_nop 1
	v_add_f32_dpp v177, v177, v177 row_half_mirror row_mask:0xf bank_mask:0xf
	s_waitcnt lgkmcnt(0)
	s_nop 1
	v_add_f32_dpp v174, v174, v174 row_half_mirror row_mask:0xf bank_mask:0xf
	s_waitcnt lgkmcnt(0)
	s_nop 1
	v_add_f32_dpp v176, v176, v176 row_mirror row_mask:0xf bank_mask:0xf
	ds_bpermute_b32 v178, v170, v176
	s_waitcnt lgkmcnt(2)
	s_nop 1
	v_add_f32_dpp v177, v177, v177 row_mirror row_mask:0xf bank_mask:0xf
	ds_bpermute_b32 v179, v170, v177
	s_waitcnt lgkmcnt(2)
	s_nop 1
	v_add_f32_dpp v174, v174, v174 row_mirror row_mask:0xf bank_mask:0xf
	ds_bpermute_b32 v175, v170, v174
	s_waitcnt lgkmcnt(2)
	v_add_f32_e32 v176, v176, v178
	ds_bpermute_b32 v178, v171, v176
	s_waitcnt lgkmcnt(2)
	v_add_f32_e32 v177, v177, v179
	ds_bpermute_b32 v179, v171, v177
	s_waitcnt lgkmcnt(2)
	v_add_f32_e32 v174, v174, v175
	ds_bpermute_b32 v175, v171, v174
	s_waitcnt lgkmcnt(2)
	v_add_f32_e32 v176, v176, v178
	v_fmamk_f32 v176, v176, 0x3a800000, v172
	s_addc_u32 s19, s7, 0
	s_waitcnt lgkmcnt(1)
	v_add_f32_e32 v177, v177, v179
	v_mul_f32_e32 v178, 0x4f800000, v176
	v_cmp_gt_f32_e32 vcc, s13, v176
	s_add_u32 s20, s6, 0x7000
	v_fmamk_f32 v177, v177, 0x3a800000, v172
	s_waitcnt lgkmcnt(0)
	v_add_f32_e32 v174, v174, v175
	v_cndmask_b32_e32 v175, v176, v178, vcc
	s_addc_u32 s21, s7, 0
	v_mul_f32_e32 v176, 0x4f800000, v177
	v_cmp_gt_f32_e64 s[6:7], s13, v177
	v_sqrt_f32_e32 v178, v175
	v_fmamk_f32 v174, v174, 0x3a800000, v172
	v_cndmask_b32_e64 v176, v177, v176, s[6:7]
	v_mul_f32_e32 v177, 0x4f800000, v174
	v_cmp_gt_f32_e64 s[8:9], s13, v174
	v_sqrt_f32_e32 v179, v176
	v_add_u32_e32 v180, -1, v178
	v_cndmask_b32_e64 v174, v174, v177, s[8:9]
	v_sqrt_f32_e32 v177, v174
	v_add_u32_e32 v181, 1, v178
	v_fma_f32 v182, -v180, v178, v175
	v_lshl_add_u64 v[112:113], s[10:11], 0, v[90:91]
	v_lshl_add_u64 v[106:107], s[10:11], 0, v[96:97]
	v_lshl_add_u64 v[110:111], s[10:11], 0, v[98:99]
	v_lshl_add_u64 v[108:109], s[10:11], 0, v[100:101]
	v_pk_add_f32 v[164:165], v[184:185], v[194:195]
	v_fma_f32 v183, -v181, v178, v175
	v_add_u32_e32 v184, -1, v179
	v_cmp_ge_f32_e64 s[10:11], 0, v182
	v_add_u32_e32 v185, 1, v179
	v_fma_f32 v182, -v185, v179, v176
	v_cndmask_b32_e64 v178, v178, v180, s[10:11]
	v_fma_f32 v180, -v184, v179, v176
	v_cmp_lt_f32_e64 s[10:11], 0, v183
	v_add_u32_e32 v186, -1, v177
	v_add_u32_e32 v187, 1, v177
	v_cndmask_b32_e64 v178, v178, v181, s[10:11]
	v_cmp_ge_f32_e64 s[10:11], 0, v180
	v_fma_f32 v180, -v186, v177, v174
	v_fma_f32 v181, -v187, v177, v174
	v_cndmask_b32_e64 v179, v179, v184, s[10:11]
	v_cmp_lt_f32_e64 s[10:11], 0, v182
	v_mul_f32_e32 v182, 0x37800000, v178
	v_cndmask_b32_e32 v178, v178, v182, vcc
	v_cndmask_b32_e64 v179, v179, v185, s[10:11]
	v_cmp_ge_f32_e64 s[10:11], 0, v180
	v_mul_f32_e32 v180, 0x37800000, v179
	v_cmp_class_f32_e32 vcc, v175, v173
	v_cndmask_b32_e64 v177, v177, v186, s[10:11]
	v_cmp_lt_f32_e64 s[10:11], 0, v181
	v_cndmask_b32_e32 v175, v178, v175, vcc
	v_cndmask_b32_e64 v178, v179, v180, s[6:7]
	v_cndmask_b32_e64 v177, v177, v187, s[10:11]
	v_cmp_class_f32_e32 vcc, v176, v173
	v_mul_f32_e32 v179, 0x37800000, v177
	v_div_scale_f32 v180, s[6:7], v175, v175, 1.0
	v_cndmask_b32_e32 v176, v178, v176, vcc
	v_cndmask_b32_e64 v177, v177, v179, s[8:9]
	v_cmp_class_f32_e32 vcc, v174, v173
	v_rcp_f32_e32 v178, v180
	v_div_scale_f32 v179, s[8:9], v176, v176, 1.0
	v_cndmask_b32_e32 v177, v177, v174, vcc
	v_rcp_f32_e32 v183, v179
	v_div_scale_f32 v184, s[10:11], v177, v177, 1.0
	v_rcp_f32_e32 v186, v184
	v_fma_f32 v174, -v180, v178, 1.0
	v_div_scale_f32 v181, s[6:7], 1.0, v175, 1.0
	v_fmac_f32_e32 v178, v174, v178
	v_fma_f32 v174, -v179, v183, 1.0
	v_div_scale_f32 v182, s[8:9], 1.0, v176, 1.0
	v_mul_f32_e32 v187, v181, v178
	v_fmac_f32_e32 v183, v174, v183
	v_fma_f32 v174, -v184, v186, 1.0
	v_fma_f32 v188, -v180, v187, v181
	v_mul_f32_e32 v189, v182, v183
	v_div_scale_f32 v185, s[10:11], 1.0, v177, 1.0
	v_fmac_f32_e32 v186, v174, v186
	v_fmac_f32_e32 v187, v188, v178
	v_fma_f32 v174, -v179, v189, v182
	v_mul_f32_e32 v188, v185, v186
	v_fma_f32 v180, -v180, v187, v181
	v_fmac_f32_e32 v189, v174, v183
	s_mov_b64 vcc, s[6:7]
	v_fma_f32 v174, -v184, v188, v185
	v_div_fmas_f32 v178, v180, v178, v187
	v_fma_f32 v179, -v179, v189, v182
	s_mov_b64 vcc, s[8:9]
	v_fmac_f32_e32 v188, v174, v186
	v_div_fixup_f32 v174, v178, v175, 1.0
	v_div_fmas_f32 v175, v179, v183, v189
	v_fma_f32 v178, -v184, v188, v185
	v_pk_mul_f32 v[80:81], v[80:81], v[174:175] op_sel_hi:[1,0]
	v_pk_mul_f32 v[78:79], v[78:79], v[174:175] op_sel_hi:[1,0]
	s_mov_b64 vcc, s[10:11]
	v_pk_add_f32 v[88:89], v[88:89], 1.0 op_sel_hi:[1,0]
	v_pk_add_f32 v[86:87], v[86:87], 1.0 op_sel_hi:[1,0]
	v_pk_mul_f32 v[76:77], v[76:77], v[174:175] op_sel_hi:[1,0]
	v_pk_mul_f32 v[74:75], v[74:75], v[174:175] op_sel_hi:[1,0]
	v_pk_mul_f32 v[72:73], v[72:73], v[174:175] op_sel_hi:[1,0]
	v_pk_mul_f32 v[70:71], v[70:71], v[174:175] op_sel_hi:[1,0]
	v_pk_mul_f32 v[68:69], v[68:69], v[174:175] op_sel_hi:[1,0]
	v_pk_mul_f32 v[66:67], v[66:67], v[174:175] op_sel_hi:[1,0]
	v_div_fixup_f32 v174, v175, v176, 1.0
	v_div_fmas_f32 v176, v178, v186, v188
	v_pk_mul_f32 v[78:79], v[2:3], v[78:79]
	v_pk_mul_f32 v[80:81], v[4:5], v[80:81]
	v_pk_mul_f32 v[64:65], v[64:65], v[174:175] op_sel_hi:[1,0]
	v_pk_mul_f32 v[62:63], v[62:63], v[174:175] op_sel_hi:[1,0]
	v_pk_mul_f32 v[60:61], v[60:61], v[174:175] op_sel_hi:[1,0]
	v_pk_mul_f32 v[58:59], v[58:59], v[174:175] op_sel_hi:[1,0]
	v_pk_mul_f32 v[56:57], v[56:57], v[174:175] op_sel_hi:[1,0]
	v_pk_mul_f32 v[54:55], v[54:55], v[174:175] op_sel_hi:[1,0]
	v_pk_mul_f32 v[52:53], v[52:53], v[174:175] op_sel_hi:[1,0]
	v_pk_mul_f32 v[174:175], v[50:51], v[174:175] op_sel_hi:[1,0]
	v_div_fixup_f32 v50, v176, v177, 1.0
	v_pk_fma_f32 v[80:81], v[88:89], v[80:81], v[84:85]
	v_pk_fma_f32 v[78:79], v[86:87], v[78:79], v[82:83]
	v_pk_mul_f32 v[86:87], v[16:17], v[52:53]
	v_pk_mul_f32 v[48:49], v[48:49], v[50:51] op_sel_hi:[1,0]
	v_pk_mul_f32 v[46:47], v[46:47], v[50:51] op_sel_hi:[1,0]
	v_pk_mul_f32 v[82:83], v[10:11], v[54:55]
	v_pk_mul_f32 v[84:85], v[14:15], v[174:175]
	v_pk_mul_f32 v[88:89], v[2:3], v[46:47]
	v_pk_mul_f32 v[174:175], v[4:5], v[48:49]
	v_cvt_pk_bf16_f32 v46, v78, v79
	v_cvt_pk_bf16_f32 v47, v80, v81
	global_store_dwordx2 v[102:103], v[46:47], off
	global_load_dwordx4 v[46:49], v[152:153], off
	s_nop 0
	global_load_dwordx4 v[52:55], v[148:149], off
	v_pk_mul_f32 v[74:75], v[6:7], v[74:75]
	v_pk_mul_f32 v[76:77], v[8:9], v[76:77]
	v_pk_mul_f32 v[70:71], v[10:11], v[70:71]
	v_pk_mul_f32 v[72:73], v[12:13], v[72:73]
	v_pk_mul_f32 v[66:67], v[66:67], v[14:15]
	v_pk_mul_f32 v[68:69], v[68:69], v[16:17]
	v_pk_mul_f32 v[62:63], v[2:3], v[62:63]
	v_pk_mul_f32 v[64:65], v[4:5], v[64:65]
	v_pk_mul_f32 v[58:59], v[6:7], v[58:59]
	v_pk_mul_f32 v[60:61], v[8:9], v[60:61]
	v_pk_mul_f32 v[56:57], v[12:13], v[56:57]
	v_mul_f32_e32 v196, v23, v23
	v_mul_f32_e32 v202, v25, v25
	v_mul_f32_e32 v214, v18, v18
	v_mul_f32_e32 v215, v19, v19
	v_mul_f32_e32 v216, v20, v20
	v_mul_f32_e32 v217, v21, v21
	v_pk_fma_f32 v[158:159], v[22:23], v[22:23], v[196:197] op_sel_hi:[1,1,0]
	v_pk_fma_f32 v[160:161], v[24:25], v[24:25], v[202:203] op_sel_hi:[1,1,0]
	v_mov_b32_e32 v159, v216
	v_mov_b32_e32 v161, v217
	v_lshl_add_u64 v[144:145], s[20:21], 0, v[90:91]
	v_lshl_add_u64 v[128:129], s[18:19], 0, v[90:91]
	v_lshl_add_u64 v[124:125], s[20:21], 0, v[96:97]
	v_lshl_add_u64 v[120:121], s[18:19], 0, v[96:97]
	s_add_i32 s12, s12, 32
	v_lshl_add_u64 v[92:93], v[92:93], 0, s[14:15]
	v_lshl_add_u64 v[94:95], v[94:95], 0, s[16:17]
	s_cmp_lt_i32 s12, s2
	s_waitcnt vmcnt(0) lgkmcnt(0)
	v_pk_add_f32 v[48:49], v[48:49], 1.0 op_sel_hi:[1,0]
	v_pk_add_f32 v[46:47], v[46:47], 1.0 op_sel_hi:[1,0]
	v_pk_fma_f32 v[48:49], v[48:49], v[76:77], v[54:55]
	v_pk_fma_f32 v[46:47], v[46:47], v[74:75], v[52:53]
	v_cvt_pk_bf16_f32 v46, v46, v47
	v_cvt_pk_bf16_f32 v47, v48, v49
	global_store_dwordx2 v[102:103], v[46:47], off offset:512
	global_load_dwordx4 v[46:49], v[146:147], off
	s_nop 0
	global_load_dwordx4 v[52:55], v[142:143], off
	s_waitcnt vmcnt(0) lgkmcnt(0)
	v_pk_add_f32 v[48:49], v[48:49], 1.0 op_sel_hi:[1,0]
	v_pk_add_f32 v[46:47], v[46:47], 1.0 op_sel_hi:[1,0]
	v_pk_fma_f32 v[48:49], v[72:73], v[48:49], v[54:55]
	v_pk_fma_f32 v[46:47], v[70:71], v[46:47], v[52:53]
	v_cvt_pk_bf16_f32 v46, v46, v47
	v_cvt_pk_bf16_f32 v47, v48, v49
	global_store_dwordx2 v[102:103], v[46:47], off offset:1024
	global_load_dwordx4 v[46:49], v[140:141], off
	s_nop 0
	global_load_dwordx4 v[52:55], v[134:135], off
	s_waitcnt vmcnt(0) lgkmcnt(0)
	v_pk_add_f32 v[48:49], v[48:49], 1.0 op_sel_hi:[1,0]
	v_pk_add_f32 v[46:47], v[46:47], 1.0 op_sel_hi:[1,0]
	v_pk_fma_f32 v[48:49], v[68:69], v[48:49], v[54:55]
	v_pk_fma_f32 v[46:47], v[66:67], v[46:47], v[52:53]
	v_cvt_pk_bf16_f32 v46, v46, v47
	v_cvt_pk_bf16_f32 v47, v48, v49
	global_store_dwordx2 v[102:103], v[46:47], off offset:1536
	global_load_dwordx4 v[46:49], v[138:139], off
	s_nop 0
	global_load_dwordx4 v[52:55], v[132:133], off
	s_waitcnt vmcnt(0) lgkmcnt(0)
	v_pk_add_f32 v[48:49], v[48:49], 1.0 op_sel_hi:[1,0]
	v_pk_add_f32 v[46:47], v[46:47], 1.0 op_sel_hi:[1,0]
	v_pk_fma_f32 v[48:49], v[48:49], v[64:65], v[54:55]
	v_pk_fma_f32 v[46:47], v[46:47], v[62:63], v[52:53]
	v_cvt_pk_bf16_f32 v46, v46, v47
	v_cvt_pk_bf16_f32 v47, v48, v49
	global_store_dwordx2 v[102:103], v[46:47], off offset:2048
	global_load_dwordx4 v[46:49], v[130:131], off
	s_nop 0
	global_load_dwordx4 v[52:55], v[126:127], off
	s_waitcnt vmcnt(0) lgkmcnt(0)
	v_pk_add_f32 v[48:49], v[48:49], 1.0 op_sel_hi:[1,0]
	v_pk_add_f32 v[46:47], v[46:47], 1.0 op_sel_hi:[1,0]
	v_pk_fma_f32 v[48:49], v[48:49], v[60:61], v[54:55]
	v_pk_fma_f32 v[46:47], v[46:47], v[58:59], v[52:53]
	v_cvt_pk_bf16_f32 v46, v46, v47
	v_cvt_pk_bf16_f32 v47, v48, v49
	global_store_dwordx2 v[102:103], v[46:47], off offset:2560
	global_load_dwordx4 v[46:49], v[122:123], off
	s_nop 0
	global_load_dwordx4 v[52:55], v[118:119], off
	v_pk_add_f32 v[58:59], v[164:165], v[164:165] op_sel:[0,1] op_sel_hi:[1,0]
	v_pk_add_f32 v[60:61], v[158:159], v[160:161]
	v_mov_b32_e32 v59, v215
	s_waitcnt vmcnt(0) lgkmcnt(0)
	v_pk_add_f32 v[48:49], v[48:49], 1.0 op_sel_hi:[1,0]
	v_pk_add_f32 v[46:47], v[46:47], 1.0 op_sel_hi:[1,0]
	v_pk_fma_f32 v[48:49], v[48:49], v[56:57], v[54:55]
	v_pk_fma_f32 v[46:47], v[46:47], v[82:83], v[52:53]
	v_cvt_pk_bf16_f32 v46, v46, v47
	v_cvt_pk_bf16_f32 v47, v48, v49
	global_store_dwordx2 v[102:103], v[46:47], off offset:3072
	global_load_dwordx4 v[46:49], v[116:117], off
	s_nop 0
	global_load_dwordx4 v[52:55], v[114:115], off
	v_pk_add_f32 v[56:57], v[162:163], v[162:163] op_sel:[0,1] op_sel_hi:[1,0]
	s_waitcnt vmcnt(0) lgkmcnt(0)
	v_pk_add_f32 v[48:49], v[48:49], 1.0 op_sel_hi:[1,0]
	v_pk_add_f32 v[46:47], v[46:47], 1.0 op_sel_hi:[1,0]
	v_pk_fma_f32 v[48:49], v[86:87], v[48:49], v[54:55]
	v_pk_fma_f32 v[46:47], v[84:85], v[46:47], v[52:53]
	v_cvt_pk_bf16_f32 v46, v46, v47
	v_cvt_pk_bf16_f32 v47, v48, v49
	global_store_dwordx2 v[102:103], v[46:47], off offset:3584
	global_load_dwordx4 v[46:49], v[156:157], off
	s_nop 0
	global_load_dwordx4 v[52:55], v[112:113], off
	v_mov_b32_e32 v57, v214
	s_waitcnt vmcnt(0) lgkmcnt(0)
	v_pk_add_f32 v[48:49], v[48:49], 1.0 op_sel_hi:[1,0]
	v_pk_add_f32 v[46:47], v[46:47], 1.0 op_sel_hi:[1,0]
	v_pk_fma_f32 v[48:49], v[48:49], v[174:175], v[54:55]
	v_pk_fma_f32 v[46:47], v[46:47], v[88:89], v[52:53]
	v_bfe_u32 v51, v46, 16, 1
	v_bfe_u32 v52, v47, 16, 1
	v_add3_u32 v46, v46, v51, s22
	v_add3_u32 v47, v47, v52, s22
	v_lshrrev_b32_e32 v46, 16, v46
	v_and_or_b32 v46, v47, s23, v46
	v_cvt_pk_bf16_f32 v47, v48, v49
	global_store_dwordx2 v[104:105], v[46:47], off
	global_load_dwordx4 v[46:49], v[154:155], off
	s_nop 0
	global_load_dwordx4 v[52:55], v[106:107], off
	v_pk_mul_f32 v[44:45], v[44:45], v[50:51] op_sel_hi:[1,0]
	v_pk_mul_f32 v[42:43], v[42:43], v[50:51] op_sel_hi:[1,0]
	v_pk_mul_f32 v[44:45], v[8:9], v[44:45]
	v_pk_mul_f32 v[42:43], v[6:7], v[42:43]
	s_waitcnt vmcnt(0) lgkmcnt(0)
	v_pk_add_f32 v[48:49], v[48:49], 1.0 op_sel_hi:[1,0]
	v_pk_add_f32 v[46:47], v[46:47], 1.0 op_sel_hi:[1,0]
	v_pk_fma_f32 v[44:45], v[48:49], v[44:45], v[54:55]
	v_pk_fma_f32 v[42:43], v[46:47], v[42:43], v[52:53]
	v_cvt_pk_bf16_f32 v42, v42, v43
	v_cvt_pk_bf16_f32 v43, v44, v45
	global_store_dwordx2 v[104:105], v[42:43], off offset:512
	global_load_dwordx4 v[42:45], v[150:151], off
	s_nop 0
	global_load_dwordx4 v[46:49], v[110:111], off
	v_pk_add_f32 v[52:53], v[56:57], v[58:59]
	s_waitcnt vmcnt(0) lgkmcnt(0)
	v_pk_add_f32 v[44:45], v[44:45], 1.0 op_sel_hi:[1,0]
	v_pk_add_f32 v[52:53], v[52:53], v[60:61]
	v_pk_add_f32 v[42:43], v[42:43], 1.0 op_sel_hi:[1,0]
	v_add_f32_e32 v51, v52, v53
	s_waitcnt lgkmcnt(0)
	s_nop 1
	v_add_f32_dpp v51, v51, v51 quad_perm:[1,0,3,2] row_mask:0xf bank_mask:0xf
	s_waitcnt lgkmcnt(0)
	s_nop 1
	v_add_f32_dpp v51, v51, v51 quad_perm:[2,3,0,1] row_mask:0xf bank_mask:0xf
	v_pk_mul_f32 v[40:41], v[40:41], v[50:51] op_sel_hi:[1,0]
	v_pk_mul_f32 v[38:39], v[38:39], v[50:51] op_sel_hi:[1,0]
	v_pk_mul_f32 v[40:41], v[12:13], v[40:41]
	v_pk_mul_f32 v[38:39], v[10:11], v[38:39]
	v_pk_fma_f32 v[40:41], v[44:45], v[40:41], v[48:49]
	v_pk_fma_f32 v[38:39], v[42:43], v[38:39], v[46:47]
	v_cvt_pk_bf16_f32 v38, v38, v39
	v_cvt_pk_bf16_f32 v39, v40, v41
	global_store_dwordx2 v[104:105], v[38:39], off offset:1024
	global_load_dwordx4 v[38:41], v[136:137], off
	s_nop 0
	global_load_dwordx4 v[42:45], v[108:109], off
	v_pk_mul_f32 v[36:37], v[36:37], v[50:51] op_sel_hi:[1,0]
	v_pk_mul_f32 v[34:35], v[34:35], v[50:51] op_sel_hi:[1,0]
	v_pk_mul_f32 v[36:37], v[16:17], v[36:37]
	v_pk_mul_f32 v[34:35], v[14:15], v[34:35]
	s_waitcnt lgkmcnt(0)
	s_nop 1
	v_add_f32_dpp v46, v51, v51 row_half_mirror row_mask:0xf bank_mask:0xf
	s_waitcnt lgkmcnt(0)
	s_nop 1
	v_add_f32_dpp v46, v46, v46 row_mirror row_mask:0xf bank_mask:0xf
	ds_bpermute_b32 v47, v170, v46
	s_waitcnt lgkmcnt(0)
	v_add_f32_e32 v46, v46, v47
	ds_bpermute_b32 v47, v171, v46
	s_waitcnt lgkmcnt(0)
	v_add_f32_e32 v46, v46, v47
	v_fmamk_f32 v46, v46, 0x3a800000, v172
	v_mul_f32_e32 v47, 0x4f800000, v46
	v_cmp_gt_f32_e32 vcc, s13, v46
	s_waitcnt vmcnt(0)
	v_pk_add_f32 v[40:41], v[40:41], 1.0 op_sel_hi:[1,0]
	v_pk_add_f32 v[38:39], v[38:39], 1.0 op_sel_hi:[1,0]
	v_pk_fma_f32 v[36:37], v[36:37], v[40:41], v[44:45]
	v_pk_fma_f32 v[34:35], v[34:35], v[38:39], v[42:43]
	v_cvt_pk_bf16_f32 v34, v34, v35
	v_cvt_pk_bf16_f32 v35, v36, v37
	global_store_dwordx2 v[104:105], v[34:35], off offset:1536
	global_load_dwordx4 v[34:37], v[144:145], off
	s_nop 0
	global_load_dwordx4 v[38:41], v[128:129], off
	v_cndmask_b32_e32 v42, v46, v47, vcc
	v_sqrt_f32_e32 v43, v42
	s_waitcnt vmcnt(0) lgkmcnt(0)
	v_pk_add_f32 v[36:37], v[36:37], 1.0 op_sel_hi:[1,0]
	v_add_u32_e32 v44, -1, v43
	v_add_u32_e32 v45, 1, v43
	v_fma_f32 v46, -v44, v43, v42
	v_fma_f32 v47, -v45, v43, v42
	v_cmp_ge_f32_e64 s[6:7], 0, v46
	v_pk_add_f32 v[34:35], v[34:35], 1.0 op_sel_hi:[1,0]
	s_nop 0
	v_cndmask_b32_e64 v43, v43, v44, s[6:7]
	v_cmp_lt_f32_e64 s[6:7], 0, v47
	s_nop 1
	v_cndmask_b32_e64 v43, v43, v45, s[6:7]
	v_mul_f32_e32 v44, 0x37800000, v43
	v_cndmask_b32_e32 v43, v43, v44, vcc
	v_cmp_class_f32_e32 vcc, v42, v173
	s_nop 1
	v_cndmask_b32_e32 v42, v43, v42, vcc
	v_div_scale_f32 v43, s[6:7], v42, v42, 1.0
	v_rcp_f32_e32 v45, v43
	v_div_scale_f32 v44, vcc, 1.0, v42, 1.0
	v_fma_f32 v46, -v43, v45, 1.0
	v_fmac_f32_e32 v45, v46, v45
	v_mul_f32_e32 v46, v44, v45
	v_fma_f32 v47, -v43, v46, v44
	v_fmac_f32_e32 v46, v47, v45
	v_fma_f32 v43, -v43, v46, v44
	v_div_fmas_f32 v43, v43, v45, v46
	v_div_fixup_f32 v42, v43, v42, 1.0
	v_pk_mul_f32 v[32:33], v[32:33], v[42:43] op_sel_hi:[1,0]
	v_pk_mul_f32 v[30:31], v[30:31], v[42:43] op_sel_hi:[1,0]
	v_pk_mul_f32 v[32:33], v[4:5], v[32:33]
	v_pk_mul_f32 v[30:31], v[2:3], v[30:31]
	v_pk_fma_f32 v[32:33], v[36:37], v[32:33], v[40:41]
	v_pk_fma_f32 v[30:31], v[34:35], v[30:31], v[38:39]
	v_cvt_pk_bf16_f32 v30, v30, v31
	v_cvt_pk_bf16_f32 v31, v32, v33
	global_store_dwordx2 v[104:105], v[30:31], off offset:2048
	global_load_dwordx4 v[30:33], v[124:125], off
	s_nop 0
	global_load_dwordx4 v[34:37], v[120:121], off
	v_pk_mul_f32 v[28:29], v[28:29], v[42:43] op_sel_hi:[1,0]
	v_pk_mul_f32 v[26:27], v[26:27], v[42:43] op_sel_hi:[1,0]
	v_pk_mul_f32 v[28:29], v[8:9], v[28:29]
	v_pk_mul_f32 v[26:27], v[6:7], v[26:27]
	v_lshl_add_u64 v[40:41], s[20:21], 0, v[98:99]
	v_lshl_add_u64 v[38:39], s[18:19], 0, v[98:99]
	v_pk_mul_f32 v[24:25], v[24:25], v[42:43] op_sel_hi:[1,0]
	v_pk_mul_f32 v[22:23], v[22:23], v[42:43] op_sel_hi:[1,0]
	v_pk_mul_f32 v[24:25], v[12:13], v[24:25]
	v_pk_mul_f32 v[22:23], v[10:11], v[22:23]
	v_pk_mul_f32 v[20:21], v[20:21], v[42:43] op_sel_hi:[1,0]
	v_pk_mul_f32 v[18:19], v[18:19], v[42:43] op_sel_hi:[1,0]
	v_pk_mul_f32 v[20:21], v[16:17], v[20:21]
	v_pk_mul_f32 v[18:19], v[14:15], v[18:19]
	s_waitcnt vmcnt(0) lgkmcnt(0)
	v_pk_add_f32 v[32:33], v[32:33], 1.0 op_sel_hi:[1,0]
	v_pk_add_f32 v[30:31], v[30:31], 1.0 op_sel_hi:[1,0]
	v_pk_fma_f32 v[28:29], v[32:33], v[28:29], v[36:37]
	v_pk_fma_f32 v[26:27], v[30:31], v[26:27], v[34:35]
	v_cvt_pk_bf16_f32 v26, v26, v27
	v_cvt_pk_bf16_f32 v27, v28, v29
	global_store_dwordx2 v[104:105], v[26:27], off offset:2560
	global_load_dwordx4 v[26:29], v[40:41], off
	s_nop 0
	global_load_dwordx4 v[30:33], v[38:39], off
	v_lshl_add_u64 v[36:37], s[20:21], 0, v[100:101]
	v_lshl_add_u64 v[34:35], s[18:19], 0, v[100:101]
	s_waitcnt vmcnt(0) lgkmcnt(0)
	v_pk_add_f32 v[28:29], v[28:29], 1.0 op_sel_hi:[1,0]
	v_pk_add_f32 v[26:27], v[26:27], 1.0 op_sel_hi:[1,0]
	v_pk_fma_f32 v[24:25], v[28:29], v[24:25], v[32:33]
	v_pk_fma_f32 v[22:23], v[26:27], v[22:23], v[30:31]
	v_cvt_pk_bf16_f32 v22, v22, v23
	v_cvt_pk_bf16_f32 v23, v24, v25
	global_store_dwordx2 v[104:105], v[22:23], off offset:3072
	global_load_dwordx4 v[22:25], v[36:37], off
	s_nop 0
	global_load_dwordx4 v[26:29], v[34:35], off
	s_waitcnt vmcnt(0) lgkmcnt(0)
	v_pk_add_f32 v[24:25], v[24:25], 1.0 op_sel_hi:[1,0]
	v_pk_add_f32 v[22:23], v[22:23], 1.0 op_sel_hi:[1,0]
	v_pk_fma_f32 v[20:21], v[20:21], v[24:25], v[28:29]
	v_pk_fma_f32 v[18:19], v[18:19], v[22:23], v[26:27]
	v_cvt_pk_bf16_f32 v18, v18, v19
	v_cvt_pk_bf16_f32 v19, v20, v21
	global_store_dwordx2 v[104:105], v[18:19], off offset:3584
	s_cbranch_scc1 .LBB0_2937

.LBB0_3086:
	v_lshl_add_u64 v[18:19], s[68:69], 0, v[94:95]
	v_lshl_add_u64 v[22:23], s[68:69], 0, v[92:93]
	v_add_co_u32_e32 v20, vcc, 0x7800000, v18
	v_add_co_u32_e64 v102, s[6:7], s22, v22
	s_nop 0
	v_addc_co_u32_e32 v21, vcc, 0, v19, vcc
	v_addc_co_u32_e64 v103, s[6:7], 0, v23, s[6:7]
	v_add_co_u32_e64 v104, s[6:7], s23, v22
	v_add_co_u32_e32 v22, vcc, 0x7801000, v18
	s_nop 0
	v_addc_co_u32_e64 v105, s[6:7], 0, v23, s[6:7]
	global_load_dwordx4 v[78:81], v[20:21], off
	global_load_dwordx4 v[74:77], v[20:21], off offset:1024
	global_load_dwordx4 v[70:73], v[20:21], off offset:2048
	global_load_dwordx4 v[66:69], v[20:21], off offset:3072
	v_addc_co_u32_e32 v23, vcc, 0, v19, vcc
	v_add_co_u32_e32 v20, vcc, 0x7802000, v18
	global_load_dwordx4 v[62:65], v[22:23], off
	global_load_dwordx4 v[58:61], v[22:23], off offset:1024
	global_load_dwordx4 v[54:57], v[22:23], off offset:2048
	global_load_dwordx4 v[50:53], v[22:23], off offset:3072
	v_addc_co_u32_e32 v21, vcc, 0, v19, vcc
	v_add_co_u32_e32 v82, vcc, 0x7803000, v18
	global_load_dwordx4 v[46:49], v[20:21], off
	global_load_dwordx4 v[42:45], v[20:21], off offset:1024
	global_load_dwordx4 v[38:41], v[20:21], off offset:2048
	global_load_dwordx4 v[34:37], v[20:21], off offset:3072
	v_addc_co_u32_e32 v83, vcc, 0, v19, vcc
	global_load_dwordx4 v[30:33], v[82:83], off
	global_load_dwordx4 v[26:29], v[82:83], off offset:1024
	global_load_dwordx4 v[22:25], v[82:83], off offset:2048
	global_load_dwordx4 v[18:21], v[82:83], off offset:3072
	s_add_i32 s24, s8, 32
	s_add_i32 s10, s8, 0xffffc022
	s_ashr_i32 s9, s24, 13
	s_cmpk_lt_i32 s24, 0x4000
	s_cselect_b32 s6, s9, s10
	s_mul_hi_i32 s7, s6, 0x9000
	s_mul_i32 s6, s6, 0x9000
	s_add_u32 s10, s4, s6
	s_addc_u32 s11, s5, s7
	s_add_u32 s6, s10, 0x6000
	s_addc_u32 s7, s11, 0
	s_add_u32 s10, s10, 0x7000
	s_addc_u32 s11, s11, 0
	v_lshl_add_u64 v[82:83], s[6:7], 0, v[90:91]
	v_lshl_add_u64 v[86:87], s[10:11], 0, v[90:91]
	global_load_dwordx4 v[82:85], v[82:83], off
	v_lshl_add_u64 v[148:149], s[6:7], 0, v[96:97]
	global_load_dwordx4 v[86:89], v[86:87], off
	v_lshl_add_u64 v[142:143], s[6:7], 0, v[98:99]
	v_lshl_add_u64 v[134:135], s[6:7], 0, v[100:101]
	s_add_i32 s6, s8, 0xffffc023
	s_cmpk_lt_i32 s24, 0x3fff
	s_cselect_b32 s6, s9, s6
	s_mul_hi_i32 s7, s6, 0x9000
	s_mul_i32 s6, s6, 0x9000
	v_lshl_add_u64 v[152:153], s[10:11], 0, v[96:97]
	v_lshl_add_u64 v[146:147], s[10:11], 0, v[98:99]
	v_lshl_add_u64 v[140:141], s[10:11], 0, v[100:101]
	s_add_u32 s10, s4, s6
	s_addc_u32 s11, s5, s7
	s_add_u32 s6, s10, 0x6000
	s_addc_u32 s7, s11, 0
	s_add_u32 s10, s10, 0x7000
	v_lshl_add_u64 v[132:133], s[6:7], 0, v[90:91]
	v_lshl_add_u64 v[126:127], s[6:7], 0, v[96:97]
	v_lshl_add_u64 v[118:119], s[6:7], 0, v[98:99]
	v_lshl_add_u64 v[114:115], s[6:7], 0, v[100:101]
	s_addc_u32 s11, s11, 0
	s_add_i32 s6, s8, 0xffffc024
	s_cmpk_lt_i32 s24, 0x3ffe
	s_cselect_b32 s6, s9, s6
	s_mul_hi_i32 s7, s6, 0x9000
	s_mul_i32 s6, s6, 0x9000
	s_add_u32 s6, s4, s6
	s_addc_u32 s7, s5, s7
	v_lshl_add_u64 v[138:139], s[10:11], 0, v[90:91]
	v_lshl_add_u64 v[130:131], s[10:11], 0, v[96:97]
	v_lshl_add_u64 v[124:125], s[10:11], 0, v[98:99]
	v_lshl_add_u64 v[116:117], s[10:11], 0, v[100:101]
	s_add_u32 s10, s6, 0x6000
	s_addc_u32 s11, s7, 0
	s_add_u32 s6, s6, 0x7000
	s_addc_u32 s7, s7, 0
	s_addk_i32 s8, 0xc025
	s_cmpk_lt_i32 s24, 0x3ffd
	v_lshl_add_u64 v[156:157], s[6:7], 0, v[90:91]
	v_lshl_add_u64 v[154:155], s[6:7], 0, v[96:97]
	v_lshl_add_u64 v[150:151], s[6:7], 0, v[98:99]
	v_lshl_add_u64 v[136:137], s[6:7], 0, v[100:101]
	s_cselect_b32 s6, s9, s8
	s_mul_hi_i32 s7, s6, 0x9000
	s_mul_i32 s6, s6, 0x9000
	s_add_u32 s6, s4, s6
	s_waitcnt vmcnt(0) lgkmcnt(0)
	v_pk_mul_f32 v[158:159], v[80:81], v[80:81]
	v_pk_mul_f32 v[160:161], v[78:79], v[78:79]
	v_pk_mul_f32 v[162:163], v[76:77], v[76:77]
	v_pk_mul_f32 v[164:165], v[74:75], v[74:75]
	v_mul_f32_e32 v174, v71, v71
	v_mul_f32_e32 v176, v73, v73
	v_mul_f32_e32 v187, v68, v68
	v_mul_f32_e32 v189, v69, v69
	v_pk_mov_b32 v[178:179], v[160:161], v[158:159] op_sel:[1,0]
	v_mov_b32_e32 v161, v159
	v_pk_mov_b32 v[158:159], v[164:165], v[162:163] op_sel:[1,0]
	v_mov_b32_e32 v165, v163
	v_pk_fma_f32 v[162:163], v[70:71], v[70:71], v[174:175] op_sel_hi:[1,1,0]
	v_pk_fma_f32 v[174:175], v[72:73], v[72:73], v[176:177] op_sel_hi:[1,1,0]
	v_pk_mul_f32 v[176:177], v[64:65], v[64:65]
	v_pk_mul_f32 v[180:181], v[62:63], v[62:63]
	v_pk_mul_f32 v[182:183], v[60:61], v[60:61]
	v_pk_mul_f32 v[184:185], v[58:59], v[58:59]
	v_mul_f32_e32 v186, v55, v55
	v_mul_f32_e32 v188, v57, v57
	v_pk_add_f32 v[160:161], v[178:179], v[160:161]
	v_pk_add_f32 v[158:159], v[158:159], v[164:165]
	v_mov_b32_e32 v163, v187
	v_mov_b32_e32 v175, v189
	v_pk_mov_b32 v[164:165], v[180:181], v[176:177] op_sel:[1,0]
	v_mov_b32_e32 v181, v177
	v_pk_mov_b32 v[176:177], v[184:185], v[182:183] op_sel:[1,0]
	v_mov_b32_e32 v185, v183
	v_pk_fma_f32 v[178:179], v[54:55], v[54:55], v[186:187] op_sel_hi:[1,1,0]
	v_pk_fma_f32 v[182:183], v[56:57], v[56:57], v[188:189] op_sel_hi:[1,1,0]
	v_pk_mul_f32 v[186:187], v[48:49], v[48:49]
	v_pk_mul_f32 v[188:189], v[46:47], v[46:47]
	v_pk_mul_f32 v[190:191], v[44:45], v[44:45]
	v_pk_mul_f32 v[192:193], v[42:43], v[42:43]
	v_mul_f32_e32 v173, v66, v66
	v_mul_f32_e32 v197, v67, v67
	v_mul_f32_e32 v195, v52, v52
	v_mul_f32_e32 v202, v53, v53
	v_mul_f32_e32 v194, v39, v39
	v_mul_f32_e32 v196, v41, v41
	v_pk_add_f32 v[198:199], v[160:161], v[160:161] op_sel:[0,1] op_sel_hi:[1,0]
	v_pk_add_f32 v[200:201], v[158:159], v[158:159] op_sel:[0,1] op_sel_hi:[1,0]
	v_pk_add_f32 v[174:175], v[162:163], v[174:175]
	v_pk_add_f32 v[158:159], v[164:165], v[180:181]
	v_pk_add_f32 v[160:161], v[176:177], v[184:185]
	v_pk_mov_b32 v[162:163], v[188:189], v[186:187] op_sel:[1,0]
	v_mov_b32_e32 v189, v187
	v_pk_mov_b32 v[164:165], v[192:193], v[190:191] op_sel:[1,0]
	v_mov_b32_e32 v193, v191
	v_mul_f32_e32 v203, v50, v50
	v_mul_f32_e32 v208, v51, v51
	v_mul_f32_e32 v211, v36, v36
	v_mul_f32_e32 v212, v37, v37
	v_mov_b32_e32 v179, v195
	v_mov_b32_e32 v183, v202
	v_pk_fma_f32 v[176:177], v[38:39], v[38:39], v[194:195] op_sel_hi:[1,1,0]
	v_pk_fma_f32 v[180:181], v[40:41], v[40:41], v[196:197] op_sel_hi:[1,1,0]
	v_pk_mul_f32 v[184:185], v[32:33], v[32:33]
	v_pk_mul_f32 v[186:187], v[30:31], v[30:31]
	v_pk_mul_f32 v[190:191], v[28:29], v[28:29]
	v_pk_mul_f32 v[194:195], v[26:27], v[26:27]
	v_mov_b32_e32 v199, v173
	v_mov_b32_e32 v201, v197
	v_pk_add_f32 v[204:205], v[158:159], v[158:159] op_sel:[0,1] op_sel_hi:[1,0]
	v_pk_add_f32 v[206:207], v[160:161], v[160:161] op_sel:[0,1] op_sel_hi:[1,0]
	v_pk_add_f32 v[162:163], v[162:163], v[188:189]
	v_pk_add_f32 v[164:165], v[164:165], v[192:193]
	v_mul_f32_e32 v209, v34, v34
	v_mul_f32_e32 v210, v35, v35
	v_pk_add_f32 v[178:179], v[178:179], v[182:183]
	v_mov_b32_e32 v177, v211
	v_mov_b32_e32 v181, v212
	v_pk_mov_b32 v[182:183], v[186:187], v[184:185] op_sel:[1,0]
	v_mov_b32_e32 v187, v185
	v_pk_mov_b32 v[184:185], v[194:195], v[190:191] op_sel:[1,0]
	v_mov_b32_e32 v195, v191
	v_pk_add_f32 v[188:189], v[198:199], v[200:201]
	v_mov_b32_e32 v205, v203
	v_mov_b32_e32 v207, v208
	v_pk_add_f32 v[190:191], v[162:163], v[162:163] op_sel:[0,1] op_sel_hi:[1,0]
	v_pk_add_f32 v[192:193], v[164:165], v[164:165] op_sel:[0,1] op_sel_hi:[1,0]
	v_pk_add_f32 v[176:177], v[176:177], v[180:181]
	v_pk_add_f32 v[174:175], v[188:189], v[174:175]
	v_pk_add_f32 v[180:181], v[204:205], v[206:207]
	v_mov_b32_e32 v191, v209
	v_mov_b32_e32 v193, v210
	v_add_f32_e32 v173, v174, v175
	v_pk_add_f32 v[174:175], v[180:181], v[178:179]
	v_pk_add_f32 v[178:179], v[190:191], v[192:193]
	v_add_f32_e32 v180, v174, v175
	v_pk_add_f32 v[174:175], v[178:179], v[176:177]
	v_add_f32_e32 v174, v174, v175
	s_addc_u32 s7, s5, s7
	s_waitcnt lgkmcnt(0)
	s_nop 1
	v_add_f32_dpp v173, v173, v173 quad_perm:[1,0,3,2] row_mask:0xf bank_mask:0xf
	s_waitcnt lgkmcnt(0)
	s_nop 1
	v_add_f32_dpp v175, v180, v180 quad_perm:[1,0,3,2] row_mask:0xf bank_mask:0xf
	s_waitcnt lgkmcnt(0)
	s_nop 1
	v_add_f32_dpp v174, v174, v174 quad_perm:[1,0,3,2] row_mask:0xf bank_mask:0xf
	s_waitcnt lgkmcnt(0)
	s_nop 1
	v_add_f32_dpp v173, v173, v173 quad_perm:[2,3,0,1] row_mask:0xf bank_mask:0xf
	s_waitcnt lgkmcnt(0)
	s_nop 1
	v_add_f32_dpp v175, v175, v175 quad_perm:[2,3,0,1] row_mask:0xf bank_mask:0xf
	s_waitcnt lgkmcnt(0)
	s_nop 1
	v_add_f32_dpp v174, v174, v174 quad_perm:[2,3,0,1] row_mask:0xf bank_mask:0xf
	s_waitcnt lgkmcnt(0)
	s_nop 1
	v_add_f32_dpp v173, v173, v173 row_half_mirror row_mask:0xf bank_mask:0xf
	s_waitcnt lgkmcnt(0)
	s_nop 1
	v_add_f32_dpp v175, v175, v175 row_half_mirror row_mask:0xf bank_mask:0xf
	s_waitcnt lgkmcnt(0)
	s_nop 1
	v_add_f32_dpp v174, v174, v174 row_half_mirror row_mask:0xf bank_mask:0xf
	s_waitcnt lgkmcnt(0)
	s_nop 1
	v_add_f32_dpp v173, v173, v173 row_mirror row_mask:0xf bank_mask:0xf
	ds_bpermute_b32 v176, v169, v173
	s_waitcnt lgkmcnt(2)
	s_nop 1
	v_add_f32_dpp v175, v175, v175 row_mirror row_mask:0xf bank_mask:0xf
	ds_bpermute_b32 v178, v169, v175
	s_waitcnt lgkmcnt(2)
	s_nop 1
	v_add_f32_dpp v174, v174, v174 row_mirror row_mask:0xf bank_mask:0xf
	ds_bpermute_b32 v177, v169, v174
	s_waitcnt lgkmcnt(2)
	v_add_f32_e32 v173, v173, v176
	ds_bpermute_b32 v176, v170, v173
	s_waitcnt lgkmcnt(2)
	v_add_f32_e32 v175, v175, v178
	ds_bpermute_b32 v178, v170, v175
	s_waitcnt lgkmcnt(2)
	v_add_f32_e32 v174, v174, v177
	ds_bpermute_b32 v177, v170, v174
	s_waitcnt lgkmcnt(2)
	v_add_f32_e32 v173, v173, v176
	s_add_u32 s16, s6, 0x6000
	v_fmamk_f32 v173, v173, 0x3a800000, v171
	s_addc_u32 s17, s7, 0
	s_waitcnt lgkmcnt(1)
	v_add_f32_e32 v175, v175, v178
	v_mul_f32_e32 v176, 0x4f800000, v173
	v_cmp_gt_f32_e32 vcc, s2, v173
	s_add_u32 s18, s6, 0x7000
	v_fmamk_f32 v175, v175, 0x3a800000, v171
	v_cndmask_b32_e32 v173, v173, v176, vcc
	s_addc_u32 s19, s7, 0
	s_waitcnt lgkmcnt(0)
	v_add_f32_e32 v174, v174, v177
	v_mul_f32_e32 v176, 0x4f800000, v175
	v_cmp_gt_f32_e64 s[6:7], s2, v175
	v_sqrt_f32_e32 v177, v173
	v_fmamk_f32 v174, v174, 0x3a800000, v171
	v_cndmask_b32_e64 v175, v175, v176, s[6:7]
	v_mul_f32_e32 v176, 0x4f800000, v174
	v_cmp_gt_f32_e64 s[8:9], s2, v174
	v_sqrt_f32_e32 v178, v175
	v_add_u32_e32 v179, -1, v177
	v_cndmask_b32_e64 v174, v174, v176, s[8:9]
	v_sqrt_f32_e32 v176, v174
	v_add_u32_e32 v180, 1, v177
	v_fma_f32 v181, -v179, v177, v173
	v_lshl_add_u64 v[112:113], s[10:11], 0, v[90:91]
	v_lshl_add_u64 v[106:107], s[10:11], 0, v[96:97]
	v_lshl_add_u64 v[108:109], s[10:11], 0, v[98:99]
	v_lshl_add_u64 v[110:111], s[10:11], 0, v[100:101]
	v_pk_add_f32 v[162:163], v[182:183], v[186:187]
	v_fma_f32 v182, -v180, v177, v173
	v_add_u32_e32 v183, -1, v178
	v_cmp_ge_f32_e64 s[10:11], 0, v181
	v_pk_add_f32 v[164:165], v[184:185], v[194:195]
	v_add_u32_e32 v184, 1, v178
	v_cndmask_b32_e64 v177, v177, v179, s[10:11]
	v_fma_f32 v179, -v183, v178, v175
	v_cmp_lt_f32_e64 s[10:11], 0, v182
	v_fma_f32 v181, -v184, v178, v175
	v_add_u32_e32 v185, -1, v176
	v_cndmask_b32_e64 v177, v177, v180, s[10:11]
	v_cmp_ge_f32_e64 s[10:11], 0, v179
	v_add_u32_e32 v186, 1, v176
	v_fma_f32 v179, -v185, v176, v174
	v_cndmask_b32_e64 v178, v178, v183, s[10:11]
	v_cmp_lt_f32_e64 s[10:11], 0, v181
	v_fma_f32 v180, -v186, v176, v174
	v_mul_f32_e32 v181, 0x37800000, v177
	v_cndmask_b32_e64 v178, v178, v184, s[10:11]
	v_cmp_ge_f32_e64 s[10:11], 0, v179
	v_cndmask_b32_e32 v177, v177, v181, vcc
	v_cmp_class_f32_e32 vcc, v173, v172
	v_cndmask_b32_e64 v176, v176, v185, s[10:11]
	v_cmp_lt_f32_e64 s[10:11], 0, v180
	v_mul_f32_e32 v179, 0x37800000, v178
	v_cndmask_b32_e32 v173, v177, v173, vcc
	v_cndmask_b32_e64 v176, v176, v186, s[10:11]
	v_cndmask_b32_e64 v177, v178, v179, s[6:7]
	v_cmp_class_f32_e32 vcc, v175, v172
	v_mul_f32_e32 v178, 0x37800000, v176
	v_div_scale_f32 v179, s[6:7], v173, v173, 1.0
	v_cndmask_b32_e32 v175, v177, v175, vcc
	v_cndmask_b32_e64 v176, v176, v178, s[8:9]
	v_cmp_class_f32_e32 vcc, v174, v172
	v_rcp_f32_e32 v177, v179
	v_div_scale_f32 v178, s[8:9], v175, v175, 1.0
	v_cndmask_b32_e32 v176, v176, v174, vcc
	v_rcp_f32_e32 v182, v178
	v_div_scale_f32 v183, s[10:11], v176, v176, 1.0
	v_rcp_f32_e32 v185, v183
	v_fma_f32 v174, -v179, v177, 1.0
	v_div_scale_f32 v180, s[6:7], 1.0, v173, 1.0
	v_fmac_f32_e32 v177, v174, v177
	v_fma_f32 v174, -v178, v182, 1.0
	v_mul_f32_e32 v186, v180, v177
	v_div_scale_f32 v181, s[8:9], 1.0, v175, 1.0
	v_fmac_f32_e32 v182, v174, v182
	v_fma_f32 v174, -v183, v185, 1.0
	v_fma_f32 v187, -v179, v186, v180
	v_div_scale_f32 v184, s[10:11], 1.0, v176, 1.0
	v_mul_f32_e32 v188, v181, v182
	v_fmac_f32_e32 v185, v174, v185
	v_fmac_f32_e32 v186, v187, v177
	v_fma_f32 v174, -v178, v188, v181
	v_mul_f32_e32 v187, v184, v185
	v_fma_f32 v179, -v179, v186, v180
	s_mov_b64 vcc, s[6:7]
	v_fmac_f32_e32 v188, v174, v182
	v_fma_f32 v174, -v183, v187, v184
	v_div_fmas_f32 v177, v179, v177, v186
	v_fma_f32 v178, -v178, v188, v181
	v_fmac_f32_e32 v187, v174, v185
	v_div_fixup_f32 v174, v177, v173, 1.0
	s_mov_b64 vcc, s[8:9]
	v_div_fmas_f32 v173, v178, v182, v188
	v_fma_f32 v177, -v183, v187, v184
	v_pk_mul_f32 v[80:81], v[80:81], v[174:175] op_sel_hi:[1,0]
	v_pk_mul_f32 v[78:79], v[78:79], v[174:175] op_sel_hi:[1,0]
	s_mov_b64 vcc, s[10:11]
	v_pk_add_f32 v[88:89], v[88:89], 1.0 op_sel_hi:[1,0]
	v_pk_add_f32 v[86:87], v[86:87], 1.0 op_sel_hi:[1,0]
	v_pk_mul_f32 v[76:77], v[76:77], v[174:175] op_sel_hi:[1,0]
	v_pk_mul_f32 v[74:75], v[74:75], v[174:175] op_sel_hi:[1,0]
	v_pk_mul_f32 v[72:73], v[72:73], v[174:175] op_sel_hi:[1,0]
	v_pk_mul_f32 v[70:71], v[70:71], v[174:175] op_sel_hi:[1,0]
	v_pk_mul_f32 v[68:69], v[68:69], v[174:175] op_sel_hi:[1,0]
	v_pk_mul_f32 v[66:67], v[66:67], v[174:175] op_sel_hi:[1,0]
	v_div_fixup_f32 v174, v173, v175, 1.0
	v_div_fmas_f32 v173, v177, v185, v187
	v_pk_mul_f32 v[78:79], v[2:3], v[78:79]
	v_pk_mul_f32 v[80:81], v[4:5], v[80:81]
	v_pk_mul_f32 v[64:65], v[64:65], v[174:175] op_sel_hi:[1,0]
	v_pk_mul_f32 v[62:63], v[62:63], v[174:175] op_sel_hi:[1,0]
	v_pk_mul_f32 v[60:61], v[60:61], v[174:175] op_sel_hi:[1,0]
	v_pk_mul_f32 v[58:59], v[58:59], v[174:175] op_sel_hi:[1,0]
	v_pk_mul_f32 v[56:57], v[56:57], v[174:175] op_sel_hi:[1,0]
	v_pk_mul_f32 v[54:55], v[54:55], v[174:175] op_sel_hi:[1,0]
	v_pk_mul_f32 v[52:53], v[52:53], v[174:175] op_sel_hi:[1,0]
	v_pk_mul_f32 v[174:175], v[50:51], v[174:175] op_sel_hi:[1,0]
	v_div_fixup_f32 v50, v173, v176, 1.0
	v_pk_fma_f32 v[80:81], v[88:89], v[80:81], v[84:85]
	v_pk_fma_f32 v[78:79], v[86:87], v[78:79], v[82:83]
	v_pk_mul_f32 v[86:87], v[16:17], v[52:53]
	v_pk_mul_f32 v[48:49], v[48:49], v[50:51] op_sel_hi:[1,0]
	v_pk_mul_f32 v[46:47], v[46:47], v[50:51] op_sel_hi:[1,0]
	v_pk_mul_f32 v[82:83], v[10:11], v[54:55]
	v_pk_mul_f32 v[84:85], v[14:15], v[174:175]
	v_pk_mul_f32 v[88:89], v[2:3], v[46:47]
	v_pk_mul_f32 v[174:175], v[4:5], v[48:49]
	v_cvt_pk_bf16_f32 v46, v78, v79
	v_cvt_pk_bf16_f32 v47, v80, v81
	global_store_dwordx2 v[102:103], v[46:47], off
	global_load_dwordx4 v[46:49], v[152:153], off
	s_nop 0
	global_load_dwordx4 v[52:55], v[148:149], off
	v_pk_mul_f32 v[74:75], v[6:7], v[74:75]
	v_pk_mul_f32 v[76:77], v[8:9], v[76:77]
	v_pk_mul_f32 v[70:71], v[10:11], v[70:71]
	v_pk_mul_f32 v[72:73], v[12:13], v[72:73]
	v_pk_mul_f32 v[66:67], v[66:67], v[14:15]
	v_pk_mul_f32 v[68:69], v[68:69], v[16:17]
	v_pk_mul_f32 v[62:63], v[2:3], v[62:63]
	v_pk_mul_f32 v[64:65], v[4:5], v[64:65]
	v_pk_mul_f32 v[58:59], v[6:7], v[58:59]
	v_pk_mul_f32 v[60:61], v[8:9], v[60:61]
	v_pk_mul_f32 v[56:57], v[12:13], v[56:57]
	v_mul_f32_e32 v196, v23, v23
	v_mul_f32_e32 v202, v25, v25
	v_mul_f32_e32 v213, v18, v18
	v_mul_f32_e32 v214, v19, v19
	v_mul_f32_e32 v215, v20, v20
	v_mul_f32_e32 v216, v21, v21
	v_pk_fma_f32 v[158:159], v[22:23], v[22:23], v[196:197] op_sel_hi:[1,1,0]
	v_pk_fma_f32 v[160:161], v[24:25], v[24:25], v[202:203] op_sel_hi:[1,1,0]
	v_mov_b32_e32 v159, v215
	v_mov_b32_e32 v161, v216
	v_lshl_add_u64 v[144:145], s[18:19], 0, v[90:91]
	v_lshl_add_u64 v[128:129], s[16:17], 0, v[90:91]
	v_lshl_add_u64 v[122:123], s[18:19], 0, v[96:97]
	v_lshl_add_u64 v[120:121], s[16:17], 0, v[96:97]
	v_lshl_add_u64 v[92:93], v[92:93], 0, s[12:13]
	v_lshl_add_u64 v[94:95], v[94:95], 0, s[14:15]
	s_mov_b32 s8, s24
	s_cmp_lt_i32 s24, s20
	s_waitcnt vmcnt(0) lgkmcnt(0)
	v_pk_add_f32 v[48:49], v[48:49], 1.0 op_sel_hi:[1,0]
	v_pk_add_f32 v[46:47], v[46:47], 1.0 op_sel_hi:[1,0]
	v_pk_fma_f32 v[48:49], v[48:49], v[76:77], v[54:55]
	v_pk_fma_f32 v[46:47], v[46:47], v[74:75], v[52:53]
	v_cvt_pk_bf16_f32 v46, v46, v47
	v_cvt_pk_bf16_f32 v47, v48, v49
	global_store_dwordx2 v[102:103], v[46:47], off offset:512
	global_load_dwordx4 v[46:49], v[146:147], off
	s_nop 0
	global_load_dwordx4 v[52:55], v[142:143], off
	s_waitcnt vmcnt(0) lgkmcnt(0)
	v_pk_add_f32 v[48:49], v[48:49], 1.0 op_sel_hi:[1,0]
	v_pk_add_f32 v[46:47], v[46:47], 1.0 op_sel_hi:[1,0]
	v_pk_fma_f32 v[48:49], v[72:73], v[48:49], v[54:55]
	v_pk_fma_f32 v[46:47], v[70:71], v[46:47], v[52:53]
	v_cvt_pk_bf16_f32 v46, v46, v47
	v_cvt_pk_bf16_f32 v47, v48, v49
	global_store_dwordx2 v[102:103], v[46:47], off offset:1024
	global_load_dwordx4 v[46:49], v[140:141], off
	s_nop 0
	global_load_dwordx4 v[52:55], v[134:135], off
	s_waitcnt vmcnt(0) lgkmcnt(0)
	v_pk_add_f32 v[48:49], v[48:49], 1.0 op_sel_hi:[1,0]
	v_pk_add_f32 v[46:47], v[46:47], 1.0 op_sel_hi:[1,0]
	v_pk_fma_f32 v[48:49], v[68:69], v[48:49], v[54:55]
	v_pk_fma_f32 v[46:47], v[66:67], v[46:47], v[52:53]
	v_cvt_pk_bf16_f32 v46, v46, v47
	v_cvt_pk_bf16_f32 v47, v48, v49
	global_store_dwordx2 v[102:103], v[46:47], off offset:1536
	global_load_dwordx4 v[46:49], v[138:139], off
	s_nop 0
	global_load_dwordx4 v[52:55], v[132:133], off
	s_waitcnt vmcnt(0) lgkmcnt(0)
	v_pk_add_f32 v[48:49], v[48:49], 1.0 op_sel_hi:[1,0]
	v_pk_add_f32 v[46:47], v[46:47], 1.0 op_sel_hi:[1,0]
	v_pk_fma_f32 v[48:49], v[48:49], v[64:65], v[54:55]
	v_pk_fma_f32 v[46:47], v[46:47], v[62:63], v[52:53]
	v_cvt_pk_bf16_f32 v46, v46, v47
	v_cvt_pk_bf16_f32 v47, v48, v49
	global_store_dwordx2 v[102:103], v[46:47], off offset:2048
	global_load_dwordx4 v[46:49], v[130:131], off
	s_nop 0
	global_load_dwordx4 v[52:55], v[126:127], off
	s_waitcnt vmcnt(0) lgkmcnt(0)
	v_pk_add_f32 v[48:49], v[48:49], 1.0 op_sel_hi:[1,0]
	v_pk_add_f32 v[46:47], v[46:47], 1.0 op_sel_hi:[1,0]
	v_pk_fma_f32 v[48:49], v[48:49], v[60:61], v[54:55]
	v_pk_fma_f32 v[46:47], v[46:47], v[58:59], v[52:53]
	v_cvt_pk_bf16_f32 v46, v46, v47
	v_cvt_pk_bf16_f32 v47, v48, v49
	global_store_dwordx2 v[102:103], v[46:47], off offset:2560
	global_load_dwordx4 v[46:49], v[124:125], off
	s_nop 0
	global_load_dwordx4 v[52:55], v[118:119], off
	v_pk_add_f32 v[58:59], v[164:165], v[164:165] op_sel:[0,1] op_sel_hi:[1,0]
	v_pk_add_f32 v[60:61], v[158:159], v[160:161]
	v_mov_b32_e32 v59, v214
	s_waitcnt vmcnt(0) lgkmcnt(0)
	v_pk_add_f32 v[48:49], v[48:49], 1.0 op_sel_hi:[1,0]
	v_pk_add_f32 v[46:47], v[46:47], 1.0 op_sel_hi:[1,0]
	v_pk_fma_f32 v[48:49], v[48:49], v[56:57], v[54:55]
	v_pk_fma_f32 v[46:47], v[46:47], v[82:83], v[52:53]
	v_cvt_pk_bf16_f32 v46, v46, v47
	v_cvt_pk_bf16_f32 v47, v48, v49
	global_store_dwordx2 v[102:103], v[46:47], off offset:3072
	global_load_dwordx4 v[46:49], v[116:117], off
	s_nop 0
	global_load_dwordx4 v[52:55], v[114:115], off
	v_pk_add_f32 v[56:57], v[162:163], v[162:163] op_sel:[0,1] op_sel_hi:[1,0]
	s_waitcnt vmcnt(0) lgkmcnt(0)
	v_pk_add_f32 v[48:49], v[48:49], 1.0 op_sel_hi:[1,0]
	v_pk_add_f32 v[46:47], v[46:47], 1.0 op_sel_hi:[1,0]
	v_pk_fma_f32 v[48:49], v[86:87], v[48:49], v[54:55]
	v_pk_fma_f32 v[46:47], v[84:85], v[46:47], v[52:53]
	v_cvt_pk_bf16_f32 v46, v46, v47
	v_cvt_pk_bf16_f32 v47, v48, v49
	global_store_dwordx2 v[102:103], v[46:47], off offset:3584
	global_load_dwordx4 v[46:49], v[156:157], off
	s_nop 0
	global_load_dwordx4 v[52:55], v[112:113], off
	v_mov_b32_e32 v57, v213
	s_waitcnt vmcnt(0) lgkmcnt(0)
	v_pk_add_f32 v[48:49], v[48:49], 1.0 op_sel_hi:[1,0]
	v_pk_add_f32 v[46:47], v[46:47], 1.0 op_sel_hi:[1,0]
	v_pk_fma_f32 v[48:49], v[48:49], v[174:175], v[54:55]
	v_pk_fma_f32 v[46:47], v[46:47], v[88:89], v[52:53]
	v_bfe_u32 v51, v46, 16, 1
	v_bfe_u32 v52, v47, 16, 1
	v_add3_u32 v46, v46, v51, s3
	v_add3_u32 v47, v47, v52, s3
	v_lshrrev_b32_e32 v46, 16, v46
	v_and_or_b32 v46, v47, s21, v46
	v_cvt_pk_bf16_f32 v47, v48, v49
	global_store_dwordx2 v[104:105], v[46:47], off
	global_load_dwordx4 v[46:49], v[154:155], off
	s_nop 0
	global_load_dwordx4 v[52:55], v[106:107], off
	v_pk_mul_f32 v[44:45], v[44:45], v[50:51] op_sel_hi:[1,0]
	v_pk_mul_f32 v[42:43], v[42:43], v[50:51] op_sel_hi:[1,0]
	v_pk_mul_f32 v[44:45], v[8:9], v[44:45]
	v_pk_mul_f32 v[42:43], v[6:7], v[42:43]
	s_waitcnt vmcnt(0) lgkmcnt(0)
	v_pk_add_f32 v[48:49], v[48:49], 1.0 op_sel_hi:[1,0]
	v_pk_add_f32 v[46:47], v[46:47], 1.0 op_sel_hi:[1,0]
	v_pk_fma_f32 v[44:45], v[48:49], v[44:45], v[54:55]
	v_pk_fma_f32 v[42:43], v[46:47], v[42:43], v[52:53]
	v_cvt_pk_bf16_f32 v42, v42, v43
	v_cvt_pk_bf16_f32 v43, v44, v45
	global_store_dwordx2 v[104:105], v[42:43], off offset:512
	global_load_dwordx4 v[42:45], v[150:151], off
	s_nop 0
	global_load_dwordx4 v[46:49], v[108:109], off
	v_pk_add_f32 v[52:53], v[56:57], v[58:59]
	s_waitcnt vmcnt(0) lgkmcnt(0)
	v_pk_add_f32 v[44:45], v[44:45], 1.0 op_sel_hi:[1,0]
	v_pk_add_f32 v[52:53], v[52:53], v[60:61]
	v_pk_add_f32 v[42:43], v[42:43], 1.0 op_sel_hi:[1,0]
	v_add_f32_e32 v51, v52, v53
	s_waitcnt lgkmcnt(0)
	s_nop 1
	v_add_f32_dpp v51, v51, v51 quad_perm:[1,0,3,2] row_mask:0xf bank_mask:0xf
	s_waitcnt lgkmcnt(0)
	s_nop 1
	v_add_f32_dpp v51, v51, v51 quad_perm:[2,3,0,1] row_mask:0xf bank_mask:0xf
	v_pk_mul_f32 v[40:41], v[40:41], v[50:51] op_sel_hi:[1,0]
	v_pk_mul_f32 v[38:39], v[38:39], v[50:51] op_sel_hi:[1,0]
	v_pk_mul_f32 v[40:41], v[12:13], v[40:41]
	v_pk_mul_f32 v[38:39], v[10:11], v[38:39]
	v_pk_fma_f32 v[40:41], v[44:45], v[40:41], v[48:49]
	v_pk_fma_f32 v[38:39], v[42:43], v[38:39], v[46:47]
	v_cvt_pk_bf16_f32 v38, v38, v39
	v_cvt_pk_bf16_f32 v39, v40, v41
	global_store_dwordx2 v[104:105], v[38:39], off offset:1024
	global_load_dwordx4 v[38:41], v[136:137], off
	s_nop 0
	global_load_dwordx4 v[42:45], v[110:111], off
	v_pk_mul_f32 v[36:37], v[36:37], v[50:51] op_sel_hi:[1,0]
	v_pk_mul_f32 v[34:35], v[34:35], v[50:51] op_sel_hi:[1,0]
	v_pk_mul_f32 v[36:37], v[16:17], v[36:37]
	v_pk_mul_f32 v[34:35], v[14:15], v[34:35]
	s_waitcnt lgkmcnt(0)
	s_nop 1
	v_add_f32_dpp v46, v51, v51 row_half_mirror row_mask:0xf bank_mask:0xf
	s_waitcnt lgkmcnt(0)
	s_nop 1
	v_add_f32_dpp v46, v46, v46 row_mirror row_mask:0xf bank_mask:0xf
	ds_bpermute_b32 v47, v169, v46
	s_waitcnt lgkmcnt(0)
	v_add_f32_e32 v46, v46, v47
	ds_bpermute_b32 v47, v170, v46
	s_waitcnt lgkmcnt(0)
	v_add_f32_e32 v46, v46, v47
	v_fmamk_f32 v46, v46, 0x3a800000, v171
	v_mul_f32_e32 v47, 0x4f800000, v46
	v_cmp_gt_f32_e32 vcc, s2, v46
	s_waitcnt vmcnt(0)
	v_pk_add_f32 v[40:41], v[40:41], 1.0 op_sel_hi:[1,0]
	v_pk_add_f32 v[38:39], v[38:39], 1.0 op_sel_hi:[1,0]
	v_pk_fma_f32 v[36:37], v[36:37], v[40:41], v[44:45]
	v_pk_fma_f32 v[34:35], v[34:35], v[38:39], v[42:43]
	v_cvt_pk_bf16_f32 v34, v34, v35
	v_cvt_pk_bf16_f32 v35, v36, v37
	global_store_dwordx2 v[104:105], v[34:35], off offset:1536
	global_load_dwordx4 v[34:37], v[144:145], off
	s_nop 0
	global_load_dwordx4 v[38:41], v[128:129], off
	v_cndmask_b32_e32 v42, v46, v47, vcc
	v_sqrt_f32_e32 v43, v42
	s_waitcnt vmcnt(0) lgkmcnt(0)
	v_pk_add_f32 v[36:37], v[36:37], 1.0 op_sel_hi:[1,0]
	v_add_u32_e32 v44, -1, v43
	v_add_u32_e32 v45, 1, v43
	v_fma_f32 v46, -v44, v43, v42
	v_fma_f32 v47, -v45, v43, v42
	v_cmp_ge_f32_e64 s[6:7], 0, v46
	v_pk_add_f32 v[34:35], v[34:35], 1.0 op_sel_hi:[1,0]
	s_nop 0
	v_cndmask_b32_e64 v43, v43, v44, s[6:7]
	v_cmp_lt_f32_e64 s[6:7], 0, v47
	s_nop 1
	v_cndmask_b32_e64 v43, v43, v45, s[6:7]
	v_mul_f32_e32 v44, 0x37800000, v43
	v_cndmask_b32_e32 v43, v43, v44, vcc
	v_cmp_class_f32_e32 vcc, v42, v172
	s_nop 1
	v_cndmask_b32_e32 v42, v43, v42, vcc
	v_div_scale_f32 v43, s[6:7], v42, v42, 1.0
	v_rcp_f32_e32 v45, v43
	v_div_scale_f32 v44, vcc, 1.0, v42, 1.0
	v_fma_f32 v46, -v43, v45, 1.0
	v_fmac_f32_e32 v45, v46, v45
	v_mul_f32_e32 v46, v44, v45
	v_fma_f32 v47, -v43, v46, v44
	v_fmac_f32_e32 v46, v47, v45
	v_fma_f32 v43, -v43, v46, v44
	v_div_fmas_f32 v43, v43, v45, v46
	v_div_fixup_f32 v42, v43, v42, 1.0
	v_pk_mul_f32 v[32:33], v[32:33], v[42:43] op_sel_hi:[1,0]
	v_pk_mul_f32 v[30:31], v[30:31], v[42:43] op_sel_hi:[1,0]
	v_pk_mul_f32 v[32:33], v[4:5], v[32:33]
	v_pk_mul_f32 v[30:31], v[2:3], v[30:31]
	v_pk_fma_f32 v[32:33], v[36:37], v[32:33], v[40:41]
	v_pk_fma_f32 v[30:31], v[34:35], v[30:31], v[38:39]
	v_cvt_pk_bf16_f32 v30, v30, v31
	v_cvt_pk_bf16_f32 v31, v32, v33
	global_store_dwordx2 v[104:105], v[30:31], off offset:2048
	global_load_dwordx4 v[30:33], v[122:123], off
	s_nop 0
	global_load_dwordx4 v[34:37], v[120:121], off
	v_pk_mul_f32 v[28:29], v[28:29], v[42:43] op_sel_hi:[1,0]
	v_pk_mul_f32 v[26:27], v[26:27], v[42:43] op_sel_hi:[1,0]
	v_pk_mul_f32 v[28:29], v[8:9], v[28:29]
	v_pk_mul_f32 v[26:27], v[6:7], v[26:27]
	v_lshl_add_u64 v[40:41], s[18:19], 0, v[98:99]
	v_lshl_add_u64 v[38:39], s[16:17], 0, v[98:99]
	v_pk_mul_f32 v[24:25], v[24:25], v[42:43] op_sel_hi:[1,0]
	v_pk_mul_f32 v[22:23], v[22:23], v[42:43] op_sel_hi:[1,0]
	v_pk_mul_f32 v[24:25], v[12:13], v[24:25]
	v_pk_mul_f32 v[22:23], v[10:11], v[22:23]
	v_pk_mul_f32 v[20:21], v[20:21], v[42:43] op_sel_hi:[1,0]
	v_pk_mul_f32 v[18:19], v[18:19], v[42:43] op_sel_hi:[1,0]
	v_pk_mul_f32 v[20:21], v[16:17], v[20:21]
	v_pk_mul_f32 v[18:19], v[14:15], v[18:19]
	s_waitcnt vmcnt(0) lgkmcnt(0)
	v_pk_add_f32 v[32:33], v[32:33], 1.0 op_sel_hi:[1,0]
	v_pk_add_f32 v[30:31], v[30:31], 1.0 op_sel_hi:[1,0]
	v_pk_fma_f32 v[28:29], v[32:33], v[28:29], v[36:37]
	v_pk_fma_f32 v[26:27], v[30:31], v[26:27], v[34:35]
	v_cvt_pk_bf16_f32 v26, v26, v27
	v_cvt_pk_bf16_f32 v27, v28, v29
	global_store_dwordx2 v[104:105], v[26:27], off offset:2560
	global_load_dwordx4 v[26:29], v[40:41], off
	s_nop 0
	global_load_dwordx4 v[30:33], v[38:39], off
	v_lshl_add_u64 v[36:37], s[18:19], 0, v[100:101]
	v_lshl_add_u64 v[34:35], s[16:17], 0, v[100:101]
	s_waitcnt vmcnt(0) lgkmcnt(0)
	v_pk_add_f32 v[28:29], v[28:29], 1.0 op_sel_hi:[1,0]
	v_pk_add_f32 v[26:27], v[26:27], 1.0 op_sel_hi:[1,0]
	v_pk_fma_f32 v[24:25], v[28:29], v[24:25], v[32:33]
	v_pk_fma_f32 v[22:23], v[26:27], v[22:23], v[30:31]
	v_cvt_pk_bf16_f32 v22, v22, v23
	v_cvt_pk_bf16_f32 v23, v24, v25
	global_store_dwordx2 v[104:105], v[22:23], off offset:3072
	global_load_dwordx4 v[22:25], v[36:37], off
	s_nop 0
	global_load_dwordx4 v[26:29], v[34:35], off
	s_waitcnt vmcnt(0) lgkmcnt(0)
	v_pk_add_f32 v[24:25], v[24:25], 1.0 op_sel_hi:[1,0]
	v_pk_add_f32 v[22:23], v[22:23], 1.0 op_sel_hi:[1,0]
	v_pk_fma_f32 v[20:21], v[20:21], v[24:25], v[28:29]
	v_pk_fma_f32 v[18:19], v[18:19], v[22:23], v[26:27]
	v_cvt_pk_bf16_f32 v18, v18, v19
	v_cvt_pk_bf16_f32 v19, v20, v21
	global_store_dwordx2 v[104:105], v[18:19], off offset:3584
	s_cbranch_scc1 .LBB0_3086

.LBB0_3194:
	v_lshl_add_u64 v[18:19], s[12:13], 0, v[94:95]
	v_lshl_add_u64 v[22:23], s[12:13], 0, v[92:93]
	v_add_co_u32_e32 v20, vcc, 0x7800000, v18
	v_add_co_u32_e64 v102, s[6:7], s29, v22
	s_nop 0
	v_addc_co_u32_e32 v21, vcc, 0, v19, vcc
	v_addc_co_u32_e64 v103, s[6:7], 0, v23, s[6:7]
	v_add_co_u32_e64 v104, s[6:7], s30, v22
	v_add_co_u32_e32 v22, vcc, 0x7801000, v18
	s_nop 0
	v_addc_co_u32_e64 v105, s[6:7], 0, v23, s[6:7]
	global_load_dwordx4 v[78:81], v[20:21], off
	global_load_dwordx4 v[74:77], v[20:21], off offset:1024
	global_load_dwordx4 v[70:73], v[20:21], off offset:2048
	global_load_dwordx4 v[66:69], v[20:21], off offset:3072
	v_addc_co_u32_e32 v23, vcc, 0, v19, vcc
	v_add_co_u32_e32 v20, vcc, 0x7802000, v18
	global_load_dwordx4 v[62:65], v[22:23], off
	global_load_dwordx4 v[58:61], v[22:23], off offset:1024
	global_load_dwordx4 v[54:57], v[22:23], off offset:2048
	global_load_dwordx4 v[50:53], v[22:23], off offset:3072
	v_addc_co_u32_e32 v21, vcc, 0, v19, vcc
	global_load_dwordx4 v[46:49], v[20:21], off
	global_load_dwordx4 v[42:45], v[20:21], off offset:1024
	global_load_dwordx4 v[38:41], v[20:21], off offset:2048
	global_load_dwordx4 v[34:37], v[20:21], off offset:3072
	v_add_co_u32_e32 v82, vcc, 0x7803000, v18
	s_ashr_i32 s8, s24, 13
	s_nop 0
	v_addc_co_u32_e32 v83, vcc, 0, v19, vcc
	global_load_dwordx4 v[30:33], v[82:83], off
	global_load_dwordx4 v[26:29], v[82:83], off offset:1024
	global_load_dwordx4 v[22:25], v[82:83], off offset:2048
	global_load_dwordx4 v[18:21], v[82:83], off offset:3072
	s_add_i32 s9, s24, 0xffffc002
	s_cmpk_lt_i32 s24, 0x4000
	s_cselect_b32 s6, s8, s9
	s_addk_i32 s6, 0x82
	s_mul_hi_i32 s7, s6, 0x9000
	s_mul_i32 s6, s6, 0x9000
	s_add_u32 s6, s14, s6
	s_addc_u32 s7, s15, s7
	s_add_u32 s10, s6, 0x1000
	s_addc_u32 s11, s7, 0
	v_lshl_add_u64 v[124:125], s[6:7], 0, v[90:91]
	v_lshl_add_u64 v[86:87], s[10:11], 0, v[90:91]
	global_load_dwordx4 v[82:85], v[124:125], off
	s_add_i32 s6, s24, 0xffffc003
	global_load_dwordx4 v[86:89], v[86:87], off
	s_cmpk_lt_i32 s24, 0x3fff
	s_cselect_b32 s6, s8, s6
	s_addk_i32 s6, 0x82
	s_mul_hi_i32 s7, s6, 0x9000
	s_mul_i32 s6, s6, 0x9000
	s_add_u32 s6, s14, s6
	s_addc_u32 s7, s15, s7
	v_lshl_add_u64 v[134:135], s[10:11], 0, v[96:97]
	v_lshl_add_u64 v[130:131], s[10:11], 0, v[98:99]
	v_lshl_add_u64 v[128:129], s[10:11], 0, v[100:101]
	s_add_u32 s10, s6, 0x1000
	v_lshl_add_u64 v[110:111], s[6:7], 0, v[90:91]
	s_addc_u32 s11, s7, 0
	s_add_i32 s6, s24, 0xffffc004
	s_cmpk_lt_i32 s24, 0x3ffe
	s_cselect_b32 s6, s8, s6
	s_addk_i32 s6, 0x82
	s_mul_hi_i32 s7, s6, 0x9000
	s_mul_i32 s6, s6, 0x9000
	v_lshl_add_u64 v[126:127], s[10:11], 0, v[90:91]
	v_lshl_add_u64 v[120:121], s[10:11], 0, v[96:97]
	v_lshl_add_u64 v[116:117], s[10:11], 0, v[98:99]
	v_lshl_add_u64 v[112:113], s[10:11], 0, v[100:101]
	s_add_u32 s10, s14, s6
	s_addc_u32 s11, s15, s7
	s_add_u32 s6, s10, 0x1000
	s_addc_u32 s7, s11, 0
	s_add_i32 s9, s24, 0xffffc005
	s_cmpk_lt_i32 s24, 0x3ffd
	v_lshl_add_u64 v[138:139], s[6:7], 0, v[90:91]
	v_lshl_add_u64 v[136:137], s[6:7], 0, v[96:97]
	v_lshl_add_u64 v[132:133], s[6:7], 0, v[98:99]
	v_lshl_add_u64 v[122:123], s[6:7], 0, v[100:101]
	s_cselect_b32 s6, s8, s9
	s_addk_i32 s6, 0x82
	s_mul_hi_i32 s7, s6, 0x9000
	s_mul_i32 s6, s6, 0x9000
	s_add_u32 s6, s14, s6
	s_addc_u32 s7, s15, s7
	s_add_u32 s40, s6, 0x1000
	v_lshl_add_u64 v[106:107], s[6:7], 0, v[90:91]
	s_addc_u32 s41, s7, 0
	v_lshl_add_u64 v[108:109], s[10:11], 0, v[90:91]
	v_lshl_add_u64 v[118:119], s[40:41], 0, v[90:91]
	v_lshl_add_u64 v[114:115], s[40:41], 0, v[96:97]
	s_add_i32 s24, s24, 32
	v_lshl_add_u64 v[92:93], v[92:93], 0, s[26:27]
	s_waitcnt vmcnt(0) lgkmcnt(0)
	v_pk_mul_f32 v[140:141], v[80:81], v[80:81]
	v_pk_mul_f32 v[142:143], v[78:79], v[78:79]
	v_pk_mul_f32 v[144:145], v[76:77], v[76:77]
	v_pk_mul_f32 v[146:147], v[74:75], v[74:75]
	v_mul_f32_e32 v156, v71, v71
	v_mul_f32_e32 v158, v73, v73
	v_pk_mov_b32 v[160:161], v[142:143], v[140:141] op_sel:[1,0]
	v_mov_b32_e32 v143, v141
	v_pk_mov_b32 v[140:141], v[146:147], v[144:145] op_sel:[1,0]
	v_mov_b32_e32 v147, v145
	v_mul_f32_e32 v169, v68, v68
	v_mul_f32_e32 v171, v69, v69
	v_pk_fma_f32 v[144:145], v[70:71], v[70:71], v[156:157] op_sel_hi:[1,1,0]
	v_pk_fma_f32 v[156:157], v[72:73], v[72:73], v[158:159] op_sel_hi:[1,1,0]
	v_pk_mul_f32 v[158:159], v[64:65], v[64:65]
	v_pk_mul_f32 v[162:163], v[62:63], v[62:63]
	v_pk_mul_f32 v[164:165], v[60:61], v[60:61]
	v_pk_mul_f32 v[166:167], v[58:59], v[58:59]
	v_mul_f32_e32 v168, v55, v55
	v_mul_f32_e32 v170, v57, v57
	v_pk_add_f32 v[142:143], v[160:161], v[142:143]
	v_pk_add_f32 v[140:141], v[140:141], v[146:147]
	v_mul_f32_e32 v155, v66, v66
	v_mul_f32_e32 v179, v67, v67
	v_mov_b32_e32 v145, v169
	v_mov_b32_e32 v157, v171
	v_pk_mov_b32 v[146:147], v[162:163], v[158:159] op_sel:[1,0]
	v_mov_b32_e32 v163, v159
	v_pk_mov_b32 v[158:159], v[166:167], v[164:165] op_sel:[1,0]
	v_mov_b32_e32 v167, v165
	v_pk_fma_f32 v[160:161], v[54:55], v[54:55], v[168:169] op_sel_hi:[1,1,0]
	v_pk_fma_f32 v[164:165], v[56:57], v[56:57], v[170:171] op_sel_hi:[1,1,0]
	v_pk_mul_f32 v[168:169], v[48:49], v[48:49]
	v_pk_mul_f32 v[170:171], v[46:47], v[46:47]
	v_pk_add_f32 v[180:181], v[142:143], v[142:143] op_sel:[0,1] op_sel_hi:[1,0]
	v_pk_add_f32 v[182:183], v[140:141], v[140:141] op_sel:[0,1] op_sel_hi:[1,0]
	v_mul_f32_e32 v177, v52, v52
	v_pk_mul_f32 v[172:173], v[44:45], v[44:45]
	v_pk_mul_f32 v[174:175], v[42:43], v[42:43]
	v_mul_f32_e32 v176, v39, v39
	v_mul_f32_e32 v178, v41, v41
	v_pk_add_f32 v[156:157], v[144:145], v[156:157]
	v_pk_add_f32 v[140:141], v[146:147], v[162:163]
	v_pk_add_f32 v[142:143], v[158:159], v[166:167]
	v_pk_mov_b32 v[144:145], v[170:171], v[168:169] op_sel:[1,0]
	v_mov_b32_e32 v171, v169
	v_mov_b32_e32 v181, v155
	v_mov_b32_e32 v183, v179
	v_mul_f32_e32 v185, v50, v50
	v_mul_f32_e32 v190, v51, v51
	v_mul_f32_e32 v184, v53, v53
	v_mul_f32_e32 v193, v36, v36
	v_mul_f32_e32 v194, v37, v37
	v_pk_mov_b32 v[146:147], v[174:175], v[172:173] op_sel:[1,0]
	v_mov_b32_e32 v175, v173
	v_pk_fma_f32 v[158:159], v[38:39], v[38:39], v[176:177] op_sel_hi:[1,1,0]
	v_pk_fma_f32 v[162:163], v[40:41], v[40:41], v[178:179] op_sel_hi:[1,1,0]
	v_pk_add_f32 v[186:187], v[140:141], v[140:141] op_sel:[0,1] op_sel_hi:[1,0]
	v_pk_add_f32 v[188:189], v[142:143], v[142:143] op_sel:[0,1] op_sel_hi:[1,0]
	v_pk_add_f32 v[144:145], v[144:145], v[170:171]
	v_pk_add_f32 v[170:171], v[180:181], v[182:183]
	v_mov_b32_e32 v161, v177
	v_mov_b32_e32 v165, v184
	v_pk_mul_f32 v[166:167], v[32:33], v[32:33]
	v_pk_mul_f32 v[168:169], v[30:31], v[30:31]
	v_pk_mul_f32 v[172:173], v[28:29], v[28:29]
	v_pk_mul_f32 v[176:177], v[26:27], v[26:27]
	v_pk_add_f32 v[146:147], v[146:147], v[174:175]
	v_mov_b32_e32 v159, v193
	v_mov_b32_e32 v163, v194
	v_mov_b32_e32 v187, v185
	v_mov_b32_e32 v189, v190
	v_pk_add_f32 v[156:157], v[170:171], v[156:157]
	v_mul_f32_e32 v191, v34, v34
	v_mul_f32_e32 v192, v35, v35
	v_pk_add_f32 v[160:161], v[160:161], v[164:165]
	v_pk_mov_b32 v[164:165], v[168:169], v[166:167] op_sel:[1,0]
	v_mov_b32_e32 v169, v167
	v_pk_mov_b32 v[166:167], v[176:177], v[172:173] op_sel:[1,0]
	v_mov_b32_e32 v177, v173
	v_pk_add_f32 v[172:173], v[144:145], v[144:145] op_sel:[0,1] op_sel_hi:[1,0]
	v_pk_add_f32 v[174:175], v[146:147], v[146:147] op_sel:[0,1] op_sel_hi:[1,0]
	v_pk_add_f32 v[158:159], v[158:159], v[162:163]
	v_pk_add_f32 v[162:163], v[186:187], v[188:189]
	v_add_f32_e32 v155, v156, v157
	v_mov_b32_e32 v173, v191
	v_mov_b32_e32 v175, v192
	v_pk_add_f32 v[156:157], v[162:163], v[160:161]
	v_pk_add_f32 v[160:161], v[172:173], v[174:175]
	v_add_f32_e32 v162, v156, v157
	v_pk_add_f32 v[156:157], v[160:161], v[158:159]
	v_add_f32_e32 v156, v156, v157
	s_waitcnt lgkmcnt(0)
	s_nop 1
	v_add_f32_dpp v155, v155, v155 quad_perm:[1,0,3,2] row_mask:0xf bank_mask:0xf
	s_waitcnt lgkmcnt(0)
	s_nop 1
	v_add_f32_dpp v158, v162, v162 quad_perm:[1,0,3,2] row_mask:0xf bank_mask:0xf
	s_waitcnt lgkmcnt(0)
	s_nop 1
	v_add_f32_dpp v156, v156, v156 quad_perm:[1,0,3,2] row_mask:0xf bank_mask:0xf
	s_waitcnt lgkmcnt(0)
	s_nop 1
	v_add_f32_dpp v155, v155, v155 quad_perm:[2,3,0,1] row_mask:0xf bank_mask:0xf
	s_waitcnt lgkmcnt(0)
	s_nop 1
	v_add_f32_dpp v158, v158, v158 quad_perm:[2,3,0,1] row_mask:0xf bank_mask:0xf
	s_waitcnt lgkmcnt(0)
	s_nop 1
	v_add_f32_dpp v156, v156, v156 quad_perm:[2,3,0,1] row_mask:0xf bank_mask:0xf
	s_waitcnt lgkmcnt(0)
	s_nop 1
	v_add_f32_dpp v155, v155, v155 row_half_mirror row_mask:0xf bank_mask:0xf
	s_waitcnt lgkmcnt(0)
	s_nop 1
	v_add_f32_dpp v158, v158, v158 row_half_mirror row_mask:0xf bank_mask:0xf
	s_waitcnt lgkmcnt(0)
	s_nop 1
	v_add_f32_dpp v156, v156, v156 row_half_mirror row_mask:0xf bank_mask:0xf
	s_waitcnt lgkmcnt(0)
	s_nop 1
	v_add_f32_dpp v155, v155, v155 row_mirror row_mask:0xf bank_mask:0xf
	ds_bpermute_b32 v159, v151, v155
	s_waitcnt lgkmcnt(2)
	s_nop 1
	v_add_f32_dpp v158, v158, v158 row_mirror row_mask:0xf bank_mask:0xf
	ds_bpermute_b32 v160, v151, v158
	s_waitcnt lgkmcnt(2)
	s_nop 1
	v_add_f32_dpp v156, v156, v156 row_mirror row_mask:0xf bank_mask:0xf
	ds_bpermute_b32 v157, v151, v156
	s_waitcnt lgkmcnt(2)
	v_add_f32_e32 v155, v155, v159
	ds_bpermute_b32 v159, v152, v155
	s_waitcnt lgkmcnt(2)
	v_add_f32_e32 v158, v158, v160
	ds_bpermute_b32 v160, v152, v158
	s_waitcnt lgkmcnt(2)
	v_add_f32_e32 v156, v156, v157
	ds_bpermute_b32 v157, v152, v156
	s_waitcnt lgkmcnt(2)
	v_add_f32_e32 v155, v155, v159
	v_fmamk_f32 v155, v155, 0x3a800000, v153
	s_waitcnt lgkmcnt(1)
	v_add_f32_e32 v158, v158, v160
	v_mul_f32_e32 v159, 0x4f800000, v155
	v_cmp_gt_f32_e32 vcc, s17, v155
	v_fmamk_f32 v158, v158, 0x3a800000, v153
	s_waitcnt lgkmcnt(0)
	v_add_f32_e32 v156, v156, v157
	v_cndmask_b32_e32 v155, v155, v159, vcc
	v_mul_f32_e32 v157, 0x4f800000, v158
	v_cmp_gt_f32_e64 s[6:7], s17, v158
	v_sqrt_f32_e32 v159, v155
	v_fmamk_f32 v156, v156, 0x3a800000, v153
	v_cndmask_b32_e64 v157, v158, v157, s[6:7]
	v_mul_f32_e32 v158, 0x4f800000, v156
	v_cmp_gt_f32_e64 s[8:9], s17, v156
	v_sqrt_f32_e32 v160, v157
	v_add_u32_e32 v161, -1, v159
	v_cndmask_b32_e64 v156, v156, v158, s[8:9]
	v_sqrt_f32_e32 v158, v156
	v_add_u32_e32 v162, 1, v159
	v_fma_f32 v163, -v161, v159, v155
	v_pk_add_f32 v[144:145], v[164:165], v[168:169]
	v_fma_f32 v164, -v162, v159, v155
	v_add_u32_e32 v165, -1, v160
	v_cmp_ge_f32_e64 s[10:11], 0, v163
	v_pk_add_f32 v[146:147], v[166:167], v[176:177]
	v_add_u32_e32 v166, 1, v160
	v_cndmask_b32_e64 v159, v159, v161, s[10:11]
	v_fma_f32 v161, -v165, v160, v157
	v_cmp_lt_f32_e64 s[10:11], 0, v164
	v_fma_f32 v163, -v166, v160, v157
	v_add_u32_e32 v167, -1, v158
	v_cndmask_b32_e64 v159, v159, v162, s[10:11]
	v_cmp_ge_f32_e64 s[10:11], 0, v161
	v_add_u32_e32 v168, 1, v158
	v_fma_f32 v161, -v167, v158, v156
	v_cndmask_b32_e64 v160, v160, v165, s[10:11]
	v_cmp_lt_f32_e64 s[10:11], 0, v163
	v_fma_f32 v162, -v168, v158, v156
	v_mul_f32_e32 v163, 0x37800000, v159
	v_cndmask_b32_e64 v160, v160, v166, s[10:11]
	v_cmp_ge_f32_e64 s[10:11], 0, v161
	v_cndmask_b32_e32 v159, v159, v163, vcc
	v_cmp_class_f32_e32 vcc, v155, v154
	v_cndmask_b32_e64 v158, v158, v167, s[10:11]
	v_cmp_lt_f32_e64 s[10:11], 0, v162
	v_mul_f32_e32 v161, 0x37800000, v160
	v_cndmask_b32_e32 v155, v159, v155, vcc
	v_cndmask_b32_e64 v158, v158, v168, s[10:11]
	v_cndmask_b32_e64 v159, v160, v161, s[6:7]
	v_cmp_class_f32_e32 vcc, v157, v154
	v_mul_f32_e32 v160, 0x37800000, v158
	v_div_scale_f32 v161, s[6:7], v155, v155, 1.0
	v_cndmask_b32_e32 v157, v159, v157, vcc
	v_cndmask_b32_e64 v158, v158, v160, s[8:9]
	v_cmp_class_f32_e32 vcc, v156, v154
	v_rcp_f32_e32 v159, v161
	v_div_scale_f32 v160, s[8:9], v157, v157, 1.0
	v_cndmask_b32_e32 v158, v158, v156, vcc
	v_rcp_f32_e32 v164, v160
	v_div_scale_f32 v165, s[10:11], v158, v158, 1.0
	v_rcp_f32_e32 v167, v165
	v_fma_f32 v156, -v161, v159, 1.0
	v_div_scale_f32 v162, s[6:7], 1.0, v155, 1.0
	v_fmac_f32_e32 v159, v156, v159
	v_fma_f32 v156, -v160, v164, 1.0
	v_mul_f32_e32 v168, v162, v159
	v_div_scale_f32 v163, s[8:9], 1.0, v157, 1.0
	v_fmac_f32_e32 v164, v156, v164
	v_fma_f32 v156, -v165, v167, 1.0
	v_fma_f32 v169, -v161, v168, v162
	v_div_scale_f32 v166, s[10:11], 1.0, v158, 1.0
	v_mul_f32_e32 v170, v163, v164
	v_fmac_f32_e32 v167, v156, v167
	v_fmac_f32_e32 v168, v169, v159
	v_fma_f32 v156, -v160, v170, v163
	v_mul_f32_e32 v169, v166, v167
	v_fma_f32 v161, -v161, v168, v162
	s_mov_b64 vcc, s[6:7]
	v_fmac_f32_e32 v170, v156, v164
	v_fma_f32 v156, -v165, v169, v166
	v_div_fmas_f32 v159, v161, v159, v168
	v_fma_f32 v160, -v160, v170, v163
	v_fmac_f32_e32 v169, v156, v167
	v_div_fixup_f32 v156, v159, v155, 1.0
	s_mov_b64 vcc, s[8:9]
	v_div_fmas_f32 v155, v160, v164, v170
	v_fma_f32 v159, -v165, v169, v166
	v_pk_mul_f32 v[80:81], v[80:81], v[156:157] op_sel_hi:[1,0]
	v_pk_mul_f32 v[78:79], v[78:79], v[156:157] op_sel_hi:[1,0]
	s_mov_b64 vcc, s[10:11]
	v_pk_add_f32 v[88:89], v[88:89], 1.0 op_sel_hi:[1,0]
	v_pk_add_f32 v[86:87], v[86:87], 1.0 op_sel_hi:[1,0]
	v_pk_mul_f32 v[76:77], v[76:77], v[156:157] op_sel_hi:[1,0]
	v_pk_mul_f32 v[74:75], v[74:75], v[156:157] op_sel_hi:[1,0]
	v_pk_mul_f32 v[72:73], v[72:73], v[156:157] op_sel_hi:[1,0]
	v_pk_mul_f32 v[70:71], v[70:71], v[156:157] op_sel_hi:[1,0]
	v_pk_mul_f32 v[68:69], v[68:69], v[156:157] op_sel_hi:[1,0]
	v_pk_mul_f32 v[66:67], v[66:67], v[156:157] op_sel_hi:[1,0]
	v_div_fixup_f32 v156, v155, v157, 1.0
	v_div_fmas_f32 v155, v159, v167, v169
	v_pk_mul_f32 v[78:79], v[78:79], v[2:3]
	v_pk_mul_f32 v[80:81], v[80:81], v[4:5]
	v_pk_mul_f32 v[64:65], v[64:65], v[156:157] op_sel_hi:[1,0]
	v_pk_mul_f32 v[62:63], v[62:63], v[156:157] op_sel_hi:[1,0]
	v_pk_mul_f32 v[60:61], v[60:61], v[156:157] op_sel_hi:[1,0]
	v_pk_mul_f32 v[58:59], v[58:59], v[156:157] op_sel_hi:[1,0]
	v_pk_mul_f32 v[56:57], v[56:57], v[156:157] op_sel_hi:[1,0]
	v_pk_mul_f32 v[54:55], v[54:55], v[156:157] op_sel_hi:[1,0]
	v_pk_mul_f32 v[52:53], v[52:53], v[156:157] op_sel_hi:[1,0]
	v_pk_mul_f32 v[156:157], v[50:51], v[156:157] op_sel_hi:[1,0]
	v_div_fixup_f32 v50, v155, v158, 1.0
	v_pk_fma_f32 v[80:81], v[80:81], v[88:89], v[84:85]
	v_pk_fma_f32 v[78:79], v[78:79], v[86:87], v[82:83]
	v_pk_mul_f32 v[86:87], v[52:53], v[16:17]
	v_pk_mul_f32 v[48:49], v[48:49], v[50:51] op_sel_hi:[1,0]
	v_pk_mul_f32 v[46:47], v[46:47], v[50:51] op_sel_hi:[1,0]
	v_pk_mul_f32 v[82:83], v[54:55], v[10:11]
	v_pk_mul_f32 v[84:85], v[156:157], v[14:15]
	v_pk_mul_f32 v[88:89], v[46:47], v[2:3]
	v_pk_mul_f32 v[156:157], v[48:49], v[4:5]
	v_cvt_pk_bf16_f32 v46, v78, v79
	v_cvt_pk_bf16_f32 v47, v80, v81
	global_store_dwordx2 v[102:103], v[46:47], off
	global_load_dwordx4 v[46:49], v[134:135], off
	s_nop 0
	global_load_dwordx4 v[52:55], v[124:125], off offset:1024
	v_pk_mul_f32 v[74:75], v[74:75], v[6:7]
	v_pk_mul_f32 v[76:77], v[76:77], v[8:9]
	v_pk_mul_f32 v[70:71], v[70:71], v[10:11]
	v_pk_mul_f32 v[72:73], v[72:73], v[12:13]
	v_pk_mul_f32 v[66:67], v[66:67], v[14:15]
	v_pk_mul_f32 v[68:69], v[68:69], v[16:17]
	v_pk_mul_f32 v[62:63], v[62:63], v[2:3]
	v_pk_mul_f32 v[64:65], v[64:65], v[4:5]
	v_pk_mul_f32 v[58:59], v[58:59], v[6:7]
	v_pk_mul_f32 v[60:61], v[60:61], v[8:9]
	v_pk_mul_f32 v[56:57], v[56:57], v[12:13]
	v_mul_f32_e32 v178, v23, v23
	v_mul_f32_e32 v184, v25, v25
	v_mul_f32_e32 v195, v18, v18
	v_mul_f32_e32 v196, v19, v19
	v_mul_f32_e32 v197, v20, v20
	v_mul_f32_e32 v198, v21, v21
	v_pk_fma_f32 v[140:141], v[22:23], v[22:23], v[178:179] op_sel_hi:[1,1,0]
	v_pk_fma_f32 v[142:143], v[24:25], v[24:25], v[184:185] op_sel_hi:[1,1,0]
	v_mov_b32_e32 v141, v197
	v_mov_b32_e32 v143, v198
	v_lshl_add_u64 v[94:95], v[94:95], 0, s[38:39]
	s_cmp_lt_i32 s24, s5
	s_waitcnt vmcnt(0) lgkmcnt(0)
	v_pk_add_f32 v[48:49], v[48:49], 1.0 op_sel_hi:[1,0]
	v_pk_add_f32 v[46:47], v[46:47], 1.0 op_sel_hi:[1,0]
	v_pk_fma_f32 v[48:49], v[76:77], v[48:49], v[54:55]
	v_pk_fma_f32 v[46:47], v[74:75], v[46:47], v[52:53]
	v_cvt_pk_bf16_f32 v46, v46, v47
	v_cvt_pk_bf16_f32 v47, v48, v49
	global_store_dwordx2 v[102:103], v[46:47], off offset:512
	global_load_dwordx4 v[46:49], v[130:131], off
	s_nop 0
	global_load_dwordx4 v[52:55], v[124:125], off offset:2048
	s_waitcnt vmcnt(0) lgkmcnt(0)
	v_pk_add_f32 v[48:49], v[48:49], 1.0 op_sel_hi:[1,0]
	v_pk_add_f32 v[46:47], v[46:47], 1.0 op_sel_hi:[1,0]
	v_pk_fma_f32 v[48:49], v[72:73], v[48:49], v[54:55]
	v_pk_fma_f32 v[46:47], v[70:71], v[46:47], v[52:53]
	v_cvt_pk_bf16_f32 v46, v46, v47
	v_cvt_pk_bf16_f32 v47, v48, v49
	global_store_dwordx2 v[102:103], v[46:47], off offset:1024
	global_load_dwordx4 v[46:49], v[128:129], off
	s_nop 0
	global_load_dwordx4 v[52:55], v[124:125], off offset:3072
	s_waitcnt vmcnt(0) lgkmcnt(0)
	v_pk_add_f32 v[48:49], v[48:49], 1.0 op_sel_hi:[1,0]
	v_pk_add_f32 v[46:47], v[46:47], 1.0 op_sel_hi:[1,0]
	v_pk_fma_f32 v[48:49], v[68:69], v[48:49], v[54:55]
	v_pk_fma_f32 v[46:47], v[66:67], v[46:47], v[52:53]
	v_cvt_pk_bf16_f32 v46, v46, v47
	v_cvt_pk_bf16_f32 v47, v48, v49
	global_store_dwordx2 v[102:103], v[46:47], off offset:1536
	global_load_dwordx4 v[46:49], v[126:127], off
	s_nop 0
	global_load_dwordx4 v[52:55], v[110:111], off
	s_waitcnt vmcnt(0) lgkmcnt(0)
	v_pk_add_f32 v[48:49], v[48:49], 1.0 op_sel_hi:[1,0]
	v_pk_add_f32 v[46:47], v[46:47], 1.0 op_sel_hi:[1,0]
	v_pk_fma_f32 v[48:49], v[64:65], v[48:49], v[54:55]
	v_pk_fma_f32 v[46:47], v[62:63], v[46:47], v[52:53]
	v_cvt_pk_bf16_f32 v46, v46, v47
	v_cvt_pk_bf16_f32 v47, v48, v49
	global_store_dwordx2 v[102:103], v[46:47], off offset:2048
	global_load_dwordx4 v[46:49], v[120:121], off
	s_nop 0
	global_load_dwordx4 v[52:55], v[110:111], off offset:1024
	s_waitcnt vmcnt(0) lgkmcnt(0)
	v_pk_add_f32 v[48:49], v[48:49], 1.0 op_sel_hi:[1,0]
	v_pk_add_f32 v[46:47], v[46:47], 1.0 op_sel_hi:[1,0]
	v_pk_fma_f32 v[48:49], v[60:61], v[48:49], v[54:55]
	v_pk_fma_f32 v[46:47], v[58:59], v[46:47], v[52:53]
	v_cvt_pk_bf16_f32 v46, v46, v47
	v_cvt_pk_bf16_f32 v47, v48, v49
	global_store_dwordx2 v[102:103], v[46:47], off offset:2560
	global_load_dwordx4 v[46:49], v[116:117], off
	s_nop 0
	global_load_dwordx4 v[52:55], v[110:111], off offset:2048
	v_pk_add_f32 v[58:59], v[146:147], v[146:147] op_sel:[0,1] op_sel_hi:[1,0]
	v_pk_add_f32 v[60:61], v[140:141], v[142:143]
	v_mov_b32_e32 v59, v196
	s_waitcnt vmcnt(0) lgkmcnt(0)
	v_pk_add_f32 v[48:49], v[48:49], 1.0 op_sel_hi:[1,0]
	v_pk_add_f32 v[46:47], v[46:47], 1.0 op_sel_hi:[1,0]
	v_pk_fma_f32 v[48:49], v[56:57], v[48:49], v[54:55]
	v_pk_fma_f32 v[46:47], v[82:83], v[46:47], v[52:53]
	v_cvt_pk_bf16_f32 v46, v46, v47
	v_cvt_pk_bf16_f32 v47, v48, v49
	global_store_dwordx2 v[102:103], v[46:47], off offset:3072
	global_load_dwordx4 v[46:49], v[112:113], off
	s_nop 0
	global_load_dwordx4 v[52:55], v[110:111], off offset:3072
	v_pk_add_f32 v[56:57], v[144:145], v[144:145] op_sel:[0,1] op_sel_hi:[1,0]
	s_waitcnt vmcnt(0) lgkmcnt(0)
	v_pk_add_f32 v[48:49], v[48:49], 1.0 op_sel_hi:[1,0]
	v_pk_add_f32 v[46:47], v[46:47], 1.0 op_sel_hi:[1,0]
	v_pk_fma_f32 v[48:49], v[86:87], v[48:49], v[54:55]
	v_pk_fma_f32 v[46:47], v[84:85], v[46:47], v[52:53]
	v_cvt_pk_bf16_f32 v46, v46, v47
	v_cvt_pk_bf16_f32 v47, v48, v49
	global_store_dwordx2 v[102:103], v[46:47], off offset:3584
	global_load_dwordx4 v[46:49], v[138:139], off
	s_nop 0
	global_load_dwordx4 v[52:55], v[108:109], off
	v_mov_b32_e32 v57, v195
	s_waitcnt vmcnt(0) lgkmcnt(0)
	v_pk_add_f32 v[48:49], v[48:49], 1.0 op_sel_hi:[1,0]
	v_pk_add_f32 v[46:47], v[46:47], 1.0 op_sel_hi:[1,0]
	v_pk_fma_f32 v[48:49], v[156:157], v[48:49], v[54:55]
	v_pk_fma_f32 v[46:47], v[88:89], v[46:47], v[52:53]
	v_bfe_u32 v51, v46, 16, 1
	v_bfe_u32 v52, v47, 16, 1
	v_add3_u32 v46, v46, v51, s25
	v_add3_u32 v47, v47, v52, s25
	v_lshrrev_b32_e32 v46, 16, v46
	v_and_or_b32 v46, v47, s28, v46
	v_cvt_pk_bf16_f32 v47, v48, v49
	global_store_dwordx2 v[104:105], v[46:47], off
	global_load_dwordx4 v[46:49], v[136:137], off
	s_nop 0
	global_load_dwordx4 v[52:55], v[108:109], off offset:1024
	v_pk_mul_f32 v[44:45], v[44:45], v[50:51] op_sel_hi:[1,0]
	v_pk_mul_f32 v[42:43], v[42:43], v[50:51] op_sel_hi:[1,0]
	v_pk_mul_f32 v[44:45], v[44:45], v[8:9]
	v_pk_mul_f32 v[42:43], v[42:43], v[6:7]
	s_waitcnt vmcnt(0) lgkmcnt(0)
	v_pk_add_f32 v[48:49], v[48:49], 1.0 op_sel_hi:[1,0]
	v_pk_add_f32 v[46:47], v[46:47], 1.0 op_sel_hi:[1,0]
	v_pk_fma_f32 v[44:45], v[44:45], v[48:49], v[54:55]
	v_pk_fma_f32 v[42:43], v[42:43], v[46:47], v[52:53]
	v_cvt_pk_bf16_f32 v42, v42, v43
	v_cvt_pk_bf16_f32 v43, v44, v45
	global_store_dwordx2 v[104:105], v[42:43], off offset:512
	global_load_dwordx4 v[42:45], v[132:133], off
	s_nop 0
	global_load_dwordx4 v[46:49], v[108:109], off offset:2048
	v_pk_add_f32 v[52:53], v[56:57], v[58:59]
	s_waitcnt vmcnt(0) lgkmcnt(0)
	v_pk_add_f32 v[44:45], v[44:45], 1.0 op_sel_hi:[1,0]
	v_pk_add_f32 v[52:53], v[52:53], v[60:61]
	v_pk_add_f32 v[42:43], v[42:43], 1.0 op_sel_hi:[1,0]
	v_add_f32_e32 v51, v52, v53
	s_waitcnt lgkmcnt(0)
	s_nop 1
	v_add_f32_dpp v51, v51, v51 quad_perm:[1,0,3,2] row_mask:0xf bank_mask:0xf
	s_waitcnt lgkmcnt(0)
	s_nop 1
	v_add_f32_dpp v51, v51, v51 quad_perm:[2,3,0,1] row_mask:0xf bank_mask:0xf
	v_pk_mul_f32 v[40:41], v[40:41], v[50:51] op_sel_hi:[1,0]
	v_pk_mul_f32 v[38:39], v[38:39], v[50:51] op_sel_hi:[1,0]
	v_pk_mul_f32 v[40:41], v[40:41], v[12:13]
	v_pk_mul_f32 v[38:39], v[38:39], v[10:11]
	v_pk_fma_f32 v[40:41], v[40:41], v[44:45], v[48:49]
	v_pk_fma_f32 v[38:39], v[38:39], v[42:43], v[46:47]
	v_cvt_pk_bf16_f32 v38, v38, v39
	v_cvt_pk_bf16_f32 v39, v40, v41
	global_store_dwordx2 v[104:105], v[38:39], off offset:1024
	global_load_dwordx4 v[38:41], v[122:123], off
	s_nop 0
	global_load_dwordx4 v[42:45], v[108:109], off offset:3072
	v_pk_mul_f32 v[36:37], v[36:37], v[50:51] op_sel_hi:[1,0]
	v_pk_mul_f32 v[34:35], v[34:35], v[50:51] op_sel_hi:[1,0]
	v_pk_mul_f32 v[36:37], v[36:37], v[16:17]
	v_pk_mul_f32 v[34:35], v[34:35], v[14:15]
	s_waitcnt lgkmcnt(0)
	s_nop 1
	v_add_f32_dpp v46, v51, v51 row_half_mirror row_mask:0xf bank_mask:0xf
	s_waitcnt lgkmcnt(0)
	s_nop 1
	v_add_f32_dpp v46, v46, v46 row_mirror row_mask:0xf bank_mask:0xf
	ds_bpermute_b32 v47, v151, v46
	s_waitcnt lgkmcnt(0)
	v_add_f32_e32 v46, v46, v47
	ds_bpermute_b32 v47, v152, v46
	s_waitcnt lgkmcnt(0)
	v_add_f32_e32 v46, v46, v47
	v_fmamk_f32 v46, v46, 0x3a800000, v153
	v_mul_f32_e32 v47, 0x4f800000, v46
	v_cmp_gt_f32_e32 vcc, s17, v46
	s_waitcnt vmcnt(0)
	v_pk_add_f32 v[40:41], v[40:41], 1.0 op_sel_hi:[1,0]
	v_pk_add_f32 v[38:39], v[38:39], 1.0 op_sel_hi:[1,0]
	v_pk_fma_f32 v[36:37], v[36:37], v[40:41], v[44:45]
	v_pk_fma_f32 v[34:35], v[34:35], v[38:39], v[42:43]
	v_cvt_pk_bf16_f32 v34, v34, v35
	v_cvt_pk_bf16_f32 v35, v36, v37
	global_store_dwordx2 v[104:105], v[34:35], off offset:1536
	global_load_dwordx4 v[34:37], v[118:119], off
	s_nop 0
	global_load_dwordx4 v[38:41], v[106:107], off
	v_cndmask_b32_e32 v42, v46, v47, vcc
	v_sqrt_f32_e32 v43, v42
	s_waitcnt vmcnt(0) lgkmcnt(0)
	v_pk_add_f32 v[36:37], v[36:37], 1.0 op_sel_hi:[1,0]
	v_add_u32_e32 v44, -1, v43
	v_add_u32_e32 v45, 1, v43
	v_fma_f32 v46, -v44, v43, v42
	v_fma_f32 v47, -v45, v43, v42
	v_cmp_ge_f32_e64 s[6:7], 0, v46
	v_pk_add_f32 v[34:35], v[34:35], 1.0 op_sel_hi:[1,0]
	s_nop 0
	v_cndmask_b32_e64 v43, v43, v44, s[6:7]
	v_cmp_lt_f32_e64 s[6:7], 0, v47
	s_nop 1
	v_cndmask_b32_e64 v43, v43, v45, s[6:7]
	v_mul_f32_e32 v44, 0x37800000, v43
	v_cndmask_b32_e32 v43, v43, v44, vcc
	v_cmp_class_f32_e32 vcc, v42, v154
	s_nop 1
	v_cndmask_b32_e32 v42, v43, v42, vcc
	v_div_scale_f32 v43, s[6:7], v42, v42, 1.0
	v_rcp_f32_e32 v45, v43
	v_div_scale_f32 v44, vcc, 1.0, v42, 1.0
	v_fma_f32 v46, -v43, v45, 1.0
	v_fmac_f32_e32 v45, v46, v45
	v_mul_f32_e32 v46, v44, v45
	v_fma_f32 v47, -v43, v46, v44
	v_fmac_f32_e32 v46, v47, v45
	v_fma_f32 v43, -v43, v46, v44
	v_div_fmas_f32 v43, v43, v45, v46
	v_div_fixup_f32 v42, v43, v42, 1.0
	v_pk_mul_f32 v[32:33], v[32:33], v[42:43] op_sel_hi:[1,0]
	v_pk_mul_f32 v[30:31], v[30:31], v[42:43] op_sel_hi:[1,0]
	v_pk_mul_f32 v[32:33], v[32:33], v[4:5]
	v_pk_mul_f32 v[30:31], v[30:31], v[2:3]
	v_pk_fma_f32 v[32:33], v[32:33], v[36:37], v[40:41]
	v_pk_fma_f32 v[30:31], v[30:31], v[34:35], v[38:39]
	v_cvt_pk_bf16_f32 v30, v30, v31
	v_cvt_pk_bf16_f32 v31, v32, v33
	global_store_dwordx2 v[104:105], v[30:31], off offset:2048
	global_load_dwordx4 v[30:33], v[114:115], off
	s_nop 0
	global_load_dwordx4 v[34:37], v[106:107], off offset:1024
	v_pk_mul_f32 v[28:29], v[28:29], v[42:43] op_sel_hi:[1,0]
	v_pk_mul_f32 v[26:27], v[26:27], v[42:43] op_sel_hi:[1,0]
	v_pk_mul_f32 v[28:29], v[28:29], v[8:9]
	v_pk_mul_f32 v[26:27], v[26:27], v[6:7]
	v_lshl_add_u64 v[38:39], s[40:41], 0, v[98:99]
	v_pk_mul_f32 v[24:25], v[24:25], v[42:43] op_sel_hi:[1,0]
	v_pk_mul_f32 v[22:23], v[22:23], v[42:43] op_sel_hi:[1,0]
	v_pk_mul_f32 v[24:25], v[24:25], v[12:13]
	v_pk_mul_f32 v[22:23], v[22:23], v[10:11]
	v_pk_mul_f32 v[20:21], v[20:21], v[42:43] op_sel_hi:[1,0]
	v_pk_mul_f32 v[18:19], v[18:19], v[42:43] op_sel_hi:[1,0]
	v_pk_mul_f32 v[20:21], v[20:21], v[16:17]
	v_pk_mul_f32 v[18:19], v[18:19], v[14:15]
	s_waitcnt vmcnt(0) lgkmcnt(0)
	v_pk_add_f32 v[32:33], v[32:33], 1.0 op_sel_hi:[1,0]
	v_pk_add_f32 v[30:31], v[30:31], 1.0 op_sel_hi:[1,0]
	v_pk_fma_f32 v[28:29], v[28:29], v[32:33], v[36:37]
	v_pk_fma_f32 v[26:27], v[26:27], v[30:31], v[34:35]
	v_cvt_pk_bf16_f32 v26, v26, v27
	v_cvt_pk_bf16_f32 v27, v28, v29
	global_store_dwordx2 v[104:105], v[26:27], off offset:2560
	global_load_dwordx4 v[26:29], v[38:39], off
	s_nop 0
	global_load_dwordx4 v[30:33], v[106:107], off offset:2048
	v_lshl_add_u64 v[34:35], s[40:41], 0, v[100:101]
	s_waitcnt vmcnt(0) lgkmcnt(0)
	v_pk_add_f32 v[28:29], v[28:29], 1.0 op_sel_hi:[1,0]
	v_pk_add_f32 v[26:27], v[26:27], 1.0 op_sel_hi:[1,0]
	v_pk_fma_f32 v[24:25], v[24:25], v[28:29], v[32:33]
	v_pk_fma_f32 v[22:23], v[22:23], v[26:27], v[30:31]
	v_cvt_pk_bf16_f32 v22, v22, v23
	v_cvt_pk_bf16_f32 v23, v24, v25
	global_store_dwordx2 v[104:105], v[22:23], off offset:3072
	global_load_dwordx4 v[22:25], v[34:35], off
	s_nop 0
	global_load_dwordx4 v[26:29], v[106:107], off offset:3072
	s_waitcnt vmcnt(0) lgkmcnt(0)
	v_pk_add_f32 v[24:25], v[24:25], 1.0 op_sel_hi:[1,0]
	v_pk_add_f32 v[22:23], v[22:23], 1.0 op_sel_hi:[1,0]
	v_pk_fma_f32 v[20:21], v[20:21], v[24:25], v[28:29]
	v_pk_fma_f32 v[18:19], v[18:19], v[22:23], v[26:27]
	v_cvt_pk_bf16_f32 v18, v18, v19
	v_cvt_pk_bf16_f32 v19, v20, v21
	global_store_dwordx2 v[104:105], v[18:19], off offset:3584
	s_cbranch_scc1 .LBB0_3194

.LBB0_3341:
	v_lshl_add_u64 v[18:19], s[12:13], 0, v[94:95]
	v_lshl_add_u64 v[22:23], s[12:13], 0, v[92:93]
	v_add_co_u32_e32 v20, vcc, 0x7800000, v18
	v_add_co_u32_e64 v102, s[6:7], s28, v22
	s_nop 0
	v_addc_co_u32_e32 v21, vcc, 0, v19, vcc
	v_addc_co_u32_e64 v103, s[6:7], 0, v23, s[6:7]
	v_add_co_u32_e64 v104, s[6:7], s29, v22
	v_add_co_u32_e32 v22, vcc, 0x7801000, v18
	s_nop 0
	v_addc_co_u32_e64 v105, s[6:7], 0, v23, s[6:7]
	global_load_dwordx4 v[78:81], v[20:21], off
	global_load_dwordx4 v[74:77], v[20:21], off offset:1024
	global_load_dwordx4 v[70:73], v[20:21], off offset:2048
	global_load_dwordx4 v[66:69], v[20:21], off offset:3072
	v_addc_co_u32_e32 v23, vcc, 0, v19, vcc
	v_add_co_u32_e32 v20, vcc, 0x7802000, v18
	global_load_dwordx4 v[62:65], v[22:23], off
	global_load_dwordx4 v[58:61], v[22:23], off offset:1024
	global_load_dwordx4 v[54:57], v[22:23], off offset:2048
	global_load_dwordx4 v[50:53], v[22:23], off offset:3072
	v_addc_co_u32_e32 v21, vcc, 0, v19, vcc
	v_add_co_u32_e32 v82, vcc, 0x7803000, v18
	global_load_dwordx4 v[46:49], v[20:21], off
	global_load_dwordx4 v[42:45], v[20:21], off offset:1024
	global_load_dwordx4 v[38:41], v[20:21], off offset:2048
	global_load_dwordx4 v[34:37], v[20:21], off offset:3072
	v_addc_co_u32_e32 v83, vcc, 0, v19, vcc
	global_load_dwordx4 v[30:33], v[82:83], off
	global_load_dwordx4 v[26:29], v[82:83], off offset:1024
	global_load_dwordx4 v[22:25], v[82:83], off offset:2048
	global_load_dwordx4 v[18:21], v[82:83], off offset:3072
	s_add_i32 s30, s8, 32
	s_add_i32 s10, s8, 0xffffc022
	s_ashr_i32 s9, s30, 13
	s_cmpk_lt_i32 s30, 0x4000
	s_cselect_b32 s6, s9, s10
	s_addk_i32 s6, 0x82
	s_mul_hi_i32 s7, s6, 0x9000
	s_mul_i32 s6, s6, 0x9000
	s_add_u32 s6, s14, s6
	s_addc_u32 s7, s15, s7
	s_add_u32 s10, s6, 0x1000
	s_addc_u32 s11, s7, 0
	v_lshl_add_u64 v[124:125], s[6:7], 0, v[90:91]
	v_lshl_add_u64 v[86:87], s[10:11], 0, v[90:91]
	global_load_dwordx4 v[82:85], v[124:125], off
	s_add_i32 s6, s8, 0xffffc023
	global_load_dwordx4 v[86:89], v[86:87], off
	s_cmpk_lt_i32 s30, 0x3fff
	s_cselect_b32 s6, s9, s6
	s_addk_i32 s6, 0x82
	s_mul_hi_i32 s7, s6, 0x9000
	s_mul_i32 s6, s6, 0x9000
	s_add_u32 s6, s14, s6
	s_addc_u32 s7, s15, s7
	v_lshl_add_u64 v[134:135], s[10:11], 0, v[96:97]
	v_lshl_add_u64 v[130:131], s[10:11], 0, v[98:99]
	v_lshl_add_u64 v[128:129], s[10:11], 0, v[100:101]
	s_add_u32 s10, s6, 0x1000
	v_lshl_add_u64 v[110:111], s[6:7], 0, v[90:91]
	s_addc_u32 s11, s7, 0
	s_add_i32 s6, s8, 0xffffc024
	s_cmpk_lt_i32 s30, 0x3ffe
	s_cselect_b32 s6, s9, s6
	s_addk_i32 s6, 0x82
	s_mul_hi_i32 s7, s6, 0x9000
	s_mul_i32 s6, s6, 0x9000
	v_lshl_add_u64 v[126:127], s[10:11], 0, v[90:91]
	v_lshl_add_u64 v[120:121], s[10:11], 0, v[96:97]
	v_lshl_add_u64 v[116:117], s[10:11], 0, v[98:99]
	v_lshl_add_u64 v[112:113], s[10:11], 0, v[100:101]
	s_add_u32 s10, s14, s6
	s_addc_u32 s11, s15, s7
	s_add_u32 s6, s10, 0x1000
	s_addc_u32 s7, s11, 0
	s_addk_i32 s8, 0xc025
	s_cmpk_lt_i32 s30, 0x3ffd
	v_lshl_add_u64 v[138:139], s[6:7], 0, v[90:91]
	v_lshl_add_u64 v[136:137], s[6:7], 0, v[96:97]
	v_lshl_add_u64 v[132:133], s[6:7], 0, v[98:99]
	v_lshl_add_u64 v[122:123], s[6:7], 0, v[100:101]
	s_cselect_b32 s6, s9, s8
	s_addk_i32 s6, 0x82
	s_mul_hi_i32 s7, s6, 0x9000
	s_mul_i32 s6, s6, 0x9000
	s_add_u32 s6, s14, s6
	s_addc_u32 s7, s15, s7
	s_add_u32 s22, s6, 0x1000
	v_lshl_add_u64 v[106:107], s[6:7], 0, v[90:91]
	s_addc_u32 s23, s7, 0
	v_lshl_add_u64 v[108:109], s[10:11], 0, v[90:91]
	v_lshl_add_u64 v[118:119], s[22:23], 0, v[90:91]
	v_lshl_add_u64 v[114:115], s[22:23], 0, v[96:97]
	v_lshl_add_u64 v[92:93], v[92:93], 0, s[16:17]
	s_waitcnt vmcnt(0) lgkmcnt(0)
	v_pk_mul_f32 v[140:141], v[80:81], v[80:81]
	v_pk_mul_f32 v[142:143], v[78:79], v[78:79]
	v_pk_mul_f32 v[144:145], v[76:77], v[76:77]
	v_pk_mul_f32 v[146:147], v[74:75], v[74:75]
	v_mul_f32_e32 v156, v71, v71
	v_mul_f32_e32 v158, v73, v73
	v_mul_f32_e32 v169, v68, v68
	v_mul_f32_e32 v171, v69, v69
	v_pk_mov_b32 v[160:161], v[142:143], v[140:141] op_sel:[1,0]
	v_mov_b32_e32 v143, v141
	v_pk_mov_b32 v[140:141], v[146:147], v[144:145] op_sel:[1,0]
	v_mov_b32_e32 v147, v145
	v_pk_fma_f32 v[144:145], v[70:71], v[70:71], v[156:157] op_sel_hi:[1,1,0]
	v_pk_fma_f32 v[156:157], v[72:73], v[72:73], v[158:159] op_sel_hi:[1,1,0]
	v_pk_mul_f32 v[158:159], v[64:65], v[64:65]
	v_pk_mul_f32 v[162:163], v[62:63], v[62:63]
	v_pk_mul_f32 v[164:165], v[60:61], v[60:61]
	v_pk_mul_f32 v[166:167], v[58:59], v[58:59]
	v_mul_f32_e32 v168, v55, v55
	v_mul_f32_e32 v170, v57, v57
	v_pk_add_f32 v[142:143], v[160:161], v[142:143]
	v_pk_add_f32 v[140:141], v[140:141], v[146:147]
	v_mov_b32_e32 v145, v169
	v_mov_b32_e32 v157, v171
	v_pk_mov_b32 v[146:147], v[162:163], v[158:159] op_sel:[1,0]
	v_mov_b32_e32 v163, v159
	v_pk_mov_b32 v[158:159], v[166:167], v[164:165] op_sel:[1,0]
	v_mov_b32_e32 v167, v165
	v_pk_fma_f32 v[160:161], v[54:55], v[54:55], v[168:169] op_sel_hi:[1,1,0]
	v_pk_fma_f32 v[164:165], v[56:57], v[56:57], v[170:171] op_sel_hi:[1,1,0]
	v_pk_mul_f32 v[168:169], v[48:49], v[48:49]
	v_pk_mul_f32 v[170:171], v[46:47], v[46:47]
	v_pk_mul_f32 v[172:173], v[44:45], v[44:45]
	v_pk_mul_f32 v[174:175], v[42:43], v[42:43]
	v_mul_f32_e32 v155, v66, v66
	v_mul_f32_e32 v179, v67, v67
	v_mul_f32_e32 v177, v52, v52
	v_mul_f32_e32 v184, v53, v53
	v_mul_f32_e32 v176, v39, v39
	v_mul_f32_e32 v178, v41, v41
	v_pk_add_f32 v[180:181], v[142:143], v[142:143] op_sel:[0,1] op_sel_hi:[1,0]
	v_pk_add_f32 v[182:183], v[140:141], v[140:141] op_sel:[0,1] op_sel_hi:[1,0]
	v_pk_add_f32 v[156:157], v[144:145], v[156:157]
	v_pk_add_f32 v[140:141], v[146:147], v[162:163]
	v_pk_add_f32 v[142:143], v[158:159], v[166:167]
	v_pk_mov_b32 v[144:145], v[170:171], v[168:169] op_sel:[1,0]
	v_mov_b32_e32 v171, v169
	v_pk_mov_b32 v[146:147], v[174:175], v[172:173] op_sel:[1,0]
	v_mov_b32_e32 v175, v173
	v_mul_f32_e32 v185, v50, v50
	v_mul_f32_e32 v190, v51, v51
	v_mul_f32_e32 v193, v36, v36
	v_mul_f32_e32 v194, v37, v37
	v_mov_b32_e32 v161, v177
	v_mov_b32_e32 v165, v184
	v_pk_fma_f32 v[158:159], v[38:39], v[38:39], v[176:177] op_sel_hi:[1,1,0]
	v_pk_fma_f32 v[162:163], v[40:41], v[40:41], v[178:179] op_sel_hi:[1,1,0]
	v_pk_mul_f32 v[166:167], v[32:33], v[32:33]
	v_pk_mul_f32 v[168:169], v[30:31], v[30:31]
	v_pk_mul_f32 v[172:173], v[28:29], v[28:29]
	v_pk_mul_f32 v[176:177], v[26:27], v[26:27]
	v_mov_b32_e32 v181, v155
	v_mov_b32_e32 v183, v179
	v_pk_add_f32 v[186:187], v[140:141], v[140:141] op_sel:[0,1] op_sel_hi:[1,0]
	v_pk_add_f32 v[188:189], v[142:143], v[142:143] op_sel:[0,1] op_sel_hi:[1,0]
	v_pk_add_f32 v[144:145], v[144:145], v[170:171]
	v_pk_add_f32 v[146:147], v[146:147], v[174:175]
	v_mul_f32_e32 v191, v34, v34
	v_mul_f32_e32 v192, v35, v35
	v_pk_add_f32 v[160:161], v[160:161], v[164:165]
	v_mov_b32_e32 v159, v193
	v_mov_b32_e32 v163, v194
	v_pk_mov_b32 v[164:165], v[168:169], v[166:167] op_sel:[1,0]
	v_mov_b32_e32 v169, v167
	v_pk_mov_b32 v[166:167], v[176:177], v[172:173] op_sel:[1,0]
	v_mov_b32_e32 v177, v173
	v_pk_add_f32 v[170:171], v[180:181], v[182:183]
	v_mov_b32_e32 v187, v185
	v_mov_b32_e32 v189, v190
	v_pk_add_f32 v[172:173], v[144:145], v[144:145] op_sel:[0,1] op_sel_hi:[1,0]
	v_pk_add_f32 v[174:175], v[146:147], v[146:147] op_sel:[0,1] op_sel_hi:[1,0]
	v_pk_add_f32 v[158:159], v[158:159], v[162:163]
	v_pk_add_f32 v[156:157], v[170:171], v[156:157]
	v_pk_add_f32 v[162:163], v[186:187], v[188:189]
	v_mov_b32_e32 v173, v191
	v_mov_b32_e32 v175, v192
	v_add_f32_e32 v155, v156, v157
	v_pk_add_f32 v[156:157], v[162:163], v[160:161]
	v_pk_add_f32 v[160:161], v[172:173], v[174:175]
	v_add_f32_e32 v162, v156, v157
	v_pk_add_f32 v[156:157], v[160:161], v[158:159]
	v_add_f32_e32 v156, v156, v157
	v_pk_add_f32 v[144:145], v[164:165], v[168:169]
	s_waitcnt lgkmcnt(0)
	s_nop 1
	v_add_f32_dpp v155, v155, v155 quad_perm:[1,0,3,2] row_mask:0xf bank_mask:0xf
	s_waitcnt lgkmcnt(0)
	s_nop 1
	v_add_f32_dpp v159, v162, v162 quad_perm:[1,0,3,2] row_mask:0xf bank_mask:0xf
	s_waitcnt lgkmcnt(0)
	s_nop 1
	v_add_f32_dpp v156, v156, v156 quad_perm:[1,0,3,2] row_mask:0xf bank_mask:0xf
	s_waitcnt lgkmcnt(0)
	s_nop 1
	v_add_f32_dpp v155, v155, v155 quad_perm:[2,3,0,1] row_mask:0xf bank_mask:0xf
	s_waitcnt lgkmcnt(0)
	s_nop 1
	v_add_f32_dpp v159, v159, v159 quad_perm:[2,3,0,1] row_mask:0xf bank_mask:0xf
	s_waitcnt lgkmcnt(0)
	s_nop 1
	v_add_f32_dpp v156, v156, v156 quad_perm:[2,3,0,1] row_mask:0xf bank_mask:0xf
	s_waitcnt lgkmcnt(0)
	s_nop 1
	v_add_f32_dpp v155, v155, v155 row_half_mirror row_mask:0xf bank_mask:0xf
	s_waitcnt lgkmcnt(0)
	s_nop 1
	v_add_f32_dpp v159, v159, v159 row_half_mirror row_mask:0xf bank_mask:0xf
	s_waitcnt lgkmcnt(0)
	s_nop 1
	v_add_f32_dpp v156, v156, v156 row_half_mirror row_mask:0xf bank_mask:0xf
	s_waitcnt lgkmcnt(0)
	s_nop 1
	v_add_f32_dpp v155, v155, v155 row_mirror row_mask:0xf bank_mask:0xf
	ds_bpermute_b32 v158, v151, v155
	s_waitcnt lgkmcnt(2)
	s_nop 1
	v_add_f32_dpp v159, v159, v159 row_mirror row_mask:0xf bank_mask:0xf
	ds_bpermute_b32 v160, v151, v159
	s_waitcnt lgkmcnt(2)
	s_nop 1
	v_add_f32_dpp v156, v156, v156 row_mirror row_mask:0xf bank_mask:0xf
	ds_bpermute_b32 v157, v151, v156
	s_waitcnt lgkmcnt(2)
	v_add_f32_e32 v155, v155, v158
	ds_bpermute_b32 v158, v152, v155
	s_waitcnt lgkmcnt(2)
	v_add_f32_e32 v159, v159, v160
	ds_bpermute_b32 v160, v152, v159
	s_waitcnt lgkmcnt(2)
	v_add_f32_e32 v156, v156, v157
	ds_bpermute_b32 v157, v152, v156
	s_waitcnt lgkmcnt(2)
	v_add_f32_e32 v155, v155, v158
	v_fmamk_f32 v155, v155, 0x3a800000, v153
	s_waitcnt lgkmcnt(1)
	v_add_f32_e32 v158, v159, v160
	v_mul_f32_e32 v159, 0x4f800000, v155
	v_cmp_gt_f32_e32 vcc, s25, v155
	v_fmamk_f32 v158, v158, 0x3a800000, v153
	s_waitcnt lgkmcnt(0)
	v_add_f32_e32 v156, v156, v157
	v_cndmask_b32_e32 v155, v155, v159, vcc
	v_mul_f32_e32 v157, 0x4f800000, v158
	v_cmp_gt_f32_e64 s[6:7], s25, v158
	v_sqrt_f32_e32 v159, v155
	v_fmamk_f32 v156, v156, 0x3a800000, v153
	v_cndmask_b32_e64 v157, v158, v157, s[6:7]
	v_mul_f32_e32 v158, 0x4f800000, v156
	v_cmp_gt_f32_e64 s[8:9], s25, v156
	v_sqrt_f32_e32 v160, v157
	v_add_u32_e32 v161, -1, v159
	v_cndmask_b32_e64 v156, v156, v158, s[8:9]
	v_sqrt_f32_e32 v158, v156
	v_add_u32_e32 v162, 1, v159
	v_fma_f32 v163, -v161, v159, v155
	v_fma_f32 v164, -v162, v159, v155
	v_add_u32_e32 v165, -1, v160
	v_cmp_ge_f32_e64 s[10:11], 0, v163
	v_pk_add_f32 v[146:147], v[166:167], v[176:177]
	v_add_u32_e32 v166, 1, v160
	v_cndmask_b32_e64 v159, v159, v161, s[10:11]
	v_fma_f32 v161, -v165, v160, v157
	v_cmp_lt_f32_e64 s[10:11], 0, v164
	v_fma_f32 v163, -v166, v160, v157
	v_add_u32_e32 v167, -1, v158
	v_cndmask_b32_e64 v159, v159, v162, s[10:11]
	v_cmp_ge_f32_e64 s[10:11], 0, v161
	v_add_u32_e32 v168, 1, v158
	v_fma_f32 v161, -v167, v158, v156
	v_cndmask_b32_e64 v160, v160, v165, s[10:11]
	v_cmp_lt_f32_e64 s[10:11], 0, v163
	v_fma_f32 v162, -v168, v158, v156
	v_mul_f32_e32 v163, 0x37800000, v159
	v_cndmask_b32_e64 v160, v160, v166, s[10:11]
	v_cmp_ge_f32_e64 s[10:11], 0, v161
	v_cndmask_b32_e32 v159, v159, v163, vcc
	v_cmp_class_f32_e32 vcc, v155, v154
	v_cndmask_b32_e64 v158, v158, v167, s[10:11]
	v_cmp_lt_f32_e64 s[10:11], 0, v162
	v_mul_f32_e32 v161, 0x37800000, v160
	v_cndmask_b32_e32 v155, v159, v155, vcc
	v_cndmask_b32_e64 v158, v158, v168, s[10:11]
	v_cndmask_b32_e64 v159, v160, v161, s[6:7]
	v_cmp_class_f32_e32 vcc, v157, v154
	v_mul_f32_e32 v160, 0x37800000, v158
	v_div_scale_f32 v161, s[6:7], v155, v155, 1.0
	v_cndmask_b32_e32 v157, v159, v157, vcc
	v_cndmask_b32_e64 v158, v158, v160, s[8:9]
	v_cmp_class_f32_e32 vcc, v156, v154
	v_rcp_f32_e32 v159, v161
	v_div_scale_f32 v160, s[8:9], v157, v157, 1.0
	v_cndmask_b32_e32 v158, v158, v156, vcc
	v_rcp_f32_e32 v164, v160
	v_div_scale_f32 v165, s[10:11], v158, v158, 1.0
	v_rcp_f32_e32 v167, v165
	v_fma_f32 v156, -v161, v159, 1.0
	v_div_scale_f32 v162, s[6:7], 1.0, v155, 1.0
	v_fmac_f32_e32 v159, v156, v159
	v_fma_f32 v156, -v160, v164, 1.0
	v_mul_f32_e32 v168, v162, v159
	v_div_scale_f32 v163, s[8:9], 1.0, v157, 1.0
	v_fmac_f32_e32 v164, v156, v164
	v_fma_f32 v156, -v165, v167, 1.0
	v_fma_f32 v169, -v161, v168, v162
	v_div_scale_f32 v166, s[10:11], 1.0, v158, 1.0
	v_mul_f32_e32 v170, v163, v164
	v_fmac_f32_e32 v167, v156, v167
	v_fmac_f32_e32 v168, v169, v159
	v_fma_f32 v156, -v160, v170, v163
	v_mul_f32_e32 v169, v166, v167
	v_fma_f32 v161, -v161, v168, v162
	s_mov_b64 vcc, s[6:7]
	v_fmac_f32_e32 v170, v156, v164
	v_fma_f32 v156, -v165, v169, v166
	v_div_fmas_f32 v159, v161, v159, v168
	v_fma_f32 v160, -v160, v170, v163
	v_fmac_f32_e32 v169, v156, v167
	v_div_fixup_f32 v156, v159, v155, 1.0
	s_mov_b64 vcc, s[8:9]
	v_div_fmas_f32 v155, v160, v164, v170
	v_fma_f32 v159, -v165, v169, v166
	v_pk_mul_f32 v[80:81], v[80:81], v[156:157] op_sel_hi:[1,0]
	v_pk_mul_f32 v[78:79], v[78:79], v[156:157] op_sel_hi:[1,0]
	s_mov_b64 vcc, s[10:11]
	v_pk_add_f32 v[88:89], v[88:89], 1.0 op_sel_hi:[1,0]
	v_pk_add_f32 v[86:87], v[86:87], 1.0 op_sel_hi:[1,0]
	v_pk_mul_f32 v[76:77], v[76:77], v[156:157] op_sel_hi:[1,0]
	v_pk_mul_f32 v[74:75], v[74:75], v[156:157] op_sel_hi:[1,0]
	v_pk_mul_f32 v[72:73], v[72:73], v[156:157] op_sel_hi:[1,0]
	v_pk_mul_f32 v[70:71], v[70:71], v[156:157] op_sel_hi:[1,0]
	v_pk_mul_f32 v[68:69], v[68:69], v[156:157] op_sel_hi:[1,0]
	v_pk_mul_f32 v[66:67], v[66:67], v[156:157] op_sel_hi:[1,0]
	v_div_fixup_f32 v156, v155, v157, 1.0
	v_div_fmas_f32 v155, v159, v167, v169
	v_pk_mul_f32 v[78:79], v[78:79], v[2:3]
	v_pk_mul_f32 v[80:81], v[80:81], v[4:5]
	v_pk_mul_f32 v[64:65], v[64:65], v[156:157] op_sel_hi:[1,0]
	v_pk_mul_f32 v[62:63], v[62:63], v[156:157] op_sel_hi:[1,0]
	v_pk_mul_f32 v[60:61], v[60:61], v[156:157] op_sel_hi:[1,0]
	v_pk_mul_f32 v[58:59], v[58:59], v[156:157] op_sel_hi:[1,0]
	v_pk_mul_f32 v[56:57], v[56:57], v[156:157] op_sel_hi:[1,0]
	v_pk_mul_f32 v[54:55], v[54:55], v[156:157] op_sel_hi:[1,0]
	v_pk_mul_f32 v[52:53], v[52:53], v[156:157] op_sel_hi:[1,0]
	v_pk_mul_f32 v[156:157], v[50:51], v[156:157] op_sel_hi:[1,0]
	v_div_fixup_f32 v50, v155, v158, 1.0
	v_pk_fma_f32 v[80:81], v[80:81], v[88:89], v[84:85]
	v_pk_fma_f32 v[78:79], v[78:79], v[86:87], v[82:83]
	v_pk_mul_f32 v[86:87], v[52:53], v[16:17]
	v_pk_mul_f32 v[48:49], v[48:49], v[50:51] op_sel_hi:[1,0]
	v_pk_mul_f32 v[46:47], v[46:47], v[50:51] op_sel_hi:[1,0]
	v_pk_mul_f32 v[82:83], v[54:55], v[10:11]
	v_pk_mul_f32 v[84:85], v[156:157], v[14:15]
	v_pk_mul_f32 v[88:89], v[46:47], v[2:3]
	v_pk_mul_f32 v[156:157], v[48:49], v[4:5]
	v_cvt_pk_bf16_f32 v46, v78, v79
	v_cvt_pk_bf16_f32 v47, v80, v81
	global_store_dwordx2 v[102:103], v[46:47], off
	global_load_dwordx4 v[46:49], v[134:135], off
	s_nop 0
	global_load_dwordx4 v[52:55], v[124:125], off offset:1024
	v_pk_mul_f32 v[74:75], v[74:75], v[6:7]
	v_pk_mul_f32 v[76:77], v[76:77], v[8:9]
	v_pk_mul_f32 v[70:71], v[70:71], v[10:11]
	v_pk_mul_f32 v[72:73], v[72:73], v[12:13]
	v_pk_mul_f32 v[66:67], v[66:67], v[14:15]
	v_pk_mul_f32 v[68:69], v[68:69], v[16:17]
	v_pk_mul_f32 v[62:63], v[62:63], v[2:3]
	v_pk_mul_f32 v[64:65], v[64:65], v[4:5]
	v_pk_mul_f32 v[58:59], v[58:59], v[6:7]
	v_pk_mul_f32 v[60:61], v[60:61], v[8:9]
	v_pk_mul_f32 v[56:57], v[56:57], v[12:13]
	v_mul_f32_e32 v178, v23, v23
	v_mul_f32_e32 v184, v25, v25
	v_mul_f32_e32 v195, v18, v18
	v_mul_f32_e32 v196, v19, v19
	v_mul_f32_e32 v197, v20, v20
	v_mul_f32_e32 v198, v21, v21
	v_pk_fma_f32 v[140:141], v[22:23], v[22:23], v[178:179] op_sel_hi:[1,1,0]
	v_pk_fma_f32 v[142:143], v[24:25], v[24:25], v[184:185] op_sel_hi:[1,1,0]
	v_mov_b32_e32 v141, v197
	v_mov_b32_e32 v143, v198
	v_lshl_add_u64 v[94:95], v[94:95], 0, s[18:19]
	s_mov_b32 s8, s30
	s_cmp_lt_i32 s30, s24
	s_waitcnt vmcnt(0) lgkmcnt(0)
	v_pk_add_f32 v[48:49], v[48:49], 1.0 op_sel_hi:[1,0]
	v_pk_add_f32 v[46:47], v[46:47], 1.0 op_sel_hi:[1,0]
	v_pk_fma_f32 v[48:49], v[76:77], v[48:49], v[54:55]
	v_pk_fma_f32 v[46:47], v[74:75], v[46:47], v[52:53]
	v_cvt_pk_bf16_f32 v46, v46, v47
	v_cvt_pk_bf16_f32 v47, v48, v49
	global_store_dwordx2 v[102:103], v[46:47], off offset:512
	global_load_dwordx4 v[46:49], v[130:131], off
	s_nop 0
	global_load_dwordx4 v[52:55], v[124:125], off offset:2048
	s_waitcnt vmcnt(0) lgkmcnt(0)
	v_pk_add_f32 v[48:49], v[48:49], 1.0 op_sel_hi:[1,0]
	v_pk_add_f32 v[46:47], v[46:47], 1.0 op_sel_hi:[1,0]
	v_pk_fma_f32 v[48:49], v[72:73], v[48:49], v[54:55]
	v_pk_fma_f32 v[46:47], v[70:71], v[46:47], v[52:53]
	v_cvt_pk_bf16_f32 v46, v46, v47
	v_cvt_pk_bf16_f32 v47, v48, v49
	global_store_dwordx2 v[102:103], v[46:47], off offset:1024
	global_load_dwordx4 v[46:49], v[128:129], off
	s_nop 0
	global_load_dwordx4 v[52:55], v[124:125], off offset:3072
	s_waitcnt vmcnt(0) lgkmcnt(0)
	v_pk_add_f32 v[48:49], v[48:49], 1.0 op_sel_hi:[1,0]
	v_pk_add_f32 v[46:47], v[46:47], 1.0 op_sel_hi:[1,0]
	v_pk_fma_f32 v[48:49], v[68:69], v[48:49], v[54:55]
	v_pk_fma_f32 v[46:47], v[66:67], v[46:47], v[52:53]
	v_cvt_pk_bf16_f32 v46, v46, v47
	v_cvt_pk_bf16_f32 v47, v48, v49
	global_store_dwordx2 v[102:103], v[46:47], off offset:1536
	global_load_dwordx4 v[46:49], v[126:127], off
	s_nop 0
	global_load_dwordx4 v[52:55], v[110:111], off
	s_waitcnt vmcnt(0) lgkmcnt(0)
	v_pk_add_f32 v[48:49], v[48:49], 1.0 op_sel_hi:[1,0]
	v_pk_add_f32 v[46:47], v[46:47], 1.0 op_sel_hi:[1,0]
	v_pk_fma_f32 v[48:49], v[64:65], v[48:49], v[54:55]
	v_pk_fma_f32 v[46:47], v[62:63], v[46:47], v[52:53]
	v_cvt_pk_bf16_f32 v46, v46, v47
	v_cvt_pk_bf16_f32 v47, v48, v49
	global_store_dwordx2 v[102:103], v[46:47], off offset:2048
	global_load_dwordx4 v[46:49], v[120:121], off
	s_nop 0
	global_load_dwordx4 v[52:55], v[110:111], off offset:1024
	s_waitcnt vmcnt(0) lgkmcnt(0)
	v_pk_add_f32 v[48:49], v[48:49], 1.0 op_sel_hi:[1,0]
	v_pk_add_f32 v[46:47], v[46:47], 1.0 op_sel_hi:[1,0]
	v_pk_fma_f32 v[48:49], v[60:61], v[48:49], v[54:55]
	v_pk_fma_f32 v[46:47], v[58:59], v[46:47], v[52:53]
	v_cvt_pk_bf16_f32 v46, v46, v47
	v_cvt_pk_bf16_f32 v47, v48, v49
	global_store_dwordx2 v[102:103], v[46:47], off offset:2560
	global_load_dwordx4 v[46:49], v[116:117], off
	s_nop 0
	global_load_dwordx4 v[52:55], v[110:111], off offset:2048
	v_pk_add_f32 v[58:59], v[146:147], v[146:147] op_sel:[0,1] op_sel_hi:[1,0]
	v_pk_add_f32 v[60:61], v[140:141], v[142:143]
	v_mov_b32_e32 v59, v196
	s_waitcnt vmcnt(0) lgkmcnt(0)
	v_pk_add_f32 v[48:49], v[48:49], 1.0 op_sel_hi:[1,0]
	v_pk_add_f32 v[46:47], v[46:47], 1.0 op_sel_hi:[1,0]
	v_pk_fma_f32 v[48:49], v[56:57], v[48:49], v[54:55]
	v_pk_fma_f32 v[46:47], v[82:83], v[46:47], v[52:53]
	v_cvt_pk_bf16_f32 v46, v46, v47
	v_cvt_pk_bf16_f32 v47, v48, v49
	global_store_dwordx2 v[102:103], v[46:47], off offset:3072
	global_load_dwordx4 v[46:49], v[112:113], off
	s_nop 0
	global_load_dwordx4 v[52:55], v[110:111], off offset:3072
	v_pk_add_f32 v[56:57], v[144:145], v[144:145] op_sel:[0,1] op_sel_hi:[1,0]
	s_waitcnt vmcnt(0) lgkmcnt(0)
	v_pk_add_f32 v[48:49], v[48:49], 1.0 op_sel_hi:[1,0]
	v_pk_add_f32 v[46:47], v[46:47], 1.0 op_sel_hi:[1,0]
	v_pk_fma_f32 v[48:49], v[86:87], v[48:49], v[54:55]
	v_pk_fma_f32 v[46:47], v[84:85], v[46:47], v[52:53]
	v_cvt_pk_bf16_f32 v46, v46, v47
	v_cvt_pk_bf16_f32 v47, v48, v49
	global_store_dwordx2 v[102:103], v[46:47], off offset:3584
	global_load_dwordx4 v[46:49], v[138:139], off
	s_nop 0
	global_load_dwordx4 v[52:55], v[108:109], off
	v_mov_b32_e32 v57, v195
	s_waitcnt vmcnt(0) lgkmcnt(0)
	v_pk_add_f32 v[48:49], v[48:49], 1.0 op_sel_hi:[1,0]
	v_pk_add_f32 v[46:47], v[46:47], 1.0 op_sel_hi:[1,0]
	v_pk_fma_f32 v[48:49], v[156:157], v[48:49], v[54:55]
	v_pk_fma_f32 v[46:47], v[88:89], v[46:47], v[52:53]
	v_bfe_u32 v51, v46, 16, 1
	v_bfe_u32 v52, v47, 16, 1
	v_add3_u32 v46, v46, v51, s26
	v_add3_u32 v47, v47, v52, s26
	v_lshrrev_b32_e32 v46, 16, v46
	v_and_or_b32 v46, v47, s27, v46
	v_cvt_pk_bf16_f32 v47, v48, v49
	global_store_dwordx2 v[104:105], v[46:47], off
	global_load_dwordx4 v[46:49], v[136:137], off
	s_nop 0
	global_load_dwordx4 v[52:55], v[108:109], off offset:1024
	v_pk_mul_f32 v[44:45], v[44:45], v[50:51] op_sel_hi:[1,0]
	v_pk_mul_f32 v[42:43], v[42:43], v[50:51] op_sel_hi:[1,0]
	v_pk_mul_f32 v[44:45], v[44:45], v[8:9]
	v_pk_mul_f32 v[42:43], v[42:43], v[6:7]
	s_waitcnt vmcnt(0) lgkmcnt(0)
	v_pk_add_f32 v[48:49], v[48:49], 1.0 op_sel_hi:[1,0]
	v_pk_add_f32 v[46:47], v[46:47], 1.0 op_sel_hi:[1,0]
	v_pk_fma_f32 v[44:45], v[44:45], v[48:49], v[54:55]
	v_pk_fma_f32 v[42:43], v[42:43], v[46:47], v[52:53]
	v_cvt_pk_bf16_f32 v42, v42, v43
	v_cvt_pk_bf16_f32 v43, v44, v45
	global_store_dwordx2 v[104:105], v[42:43], off offset:512
	global_load_dwordx4 v[42:45], v[132:133], off
	s_nop 0
	global_load_dwordx4 v[46:49], v[108:109], off offset:2048
	v_pk_add_f32 v[52:53], v[56:57], v[58:59]
	s_waitcnt vmcnt(0) lgkmcnt(0)
	v_pk_add_f32 v[44:45], v[44:45], 1.0 op_sel_hi:[1,0]
	v_pk_add_f32 v[52:53], v[52:53], v[60:61]
	v_pk_add_f32 v[42:43], v[42:43], 1.0 op_sel_hi:[1,0]
	v_add_f32_e32 v51, v52, v53
	s_waitcnt lgkmcnt(0)
	s_nop 1
	v_add_f32_dpp v51, v51, v51 quad_perm:[1,0,3,2] row_mask:0xf bank_mask:0xf
	s_waitcnt lgkmcnt(0)
	s_nop 1
	v_add_f32_dpp v51, v51, v51 quad_perm:[2,3,0,1] row_mask:0xf bank_mask:0xf
	v_pk_mul_f32 v[40:41], v[40:41], v[50:51] op_sel_hi:[1,0]
	v_pk_mul_f32 v[38:39], v[38:39], v[50:51] op_sel_hi:[1,0]
	v_pk_mul_f32 v[40:41], v[40:41], v[12:13]
	v_pk_mul_f32 v[38:39], v[38:39], v[10:11]
	v_pk_fma_f32 v[40:41], v[40:41], v[44:45], v[48:49]
	v_pk_fma_f32 v[38:39], v[38:39], v[42:43], v[46:47]
	v_cvt_pk_bf16_f32 v38, v38, v39
	v_cvt_pk_bf16_f32 v39, v40, v41
	global_store_dwordx2 v[104:105], v[38:39], off offset:1024
	global_load_dwordx4 v[38:41], v[122:123], off
	s_nop 0
	global_load_dwordx4 v[42:45], v[108:109], off offset:3072
	v_pk_mul_f32 v[36:37], v[36:37], v[50:51] op_sel_hi:[1,0]
	v_pk_mul_f32 v[34:35], v[34:35], v[50:51] op_sel_hi:[1,0]
	v_pk_mul_f32 v[36:37], v[36:37], v[16:17]
	v_pk_mul_f32 v[34:35], v[34:35], v[14:15]
	s_waitcnt lgkmcnt(0)
	s_nop 1
	v_add_f32_dpp v46, v51, v51 row_half_mirror row_mask:0xf bank_mask:0xf
	s_waitcnt lgkmcnt(0)
	s_nop 1
	v_add_f32_dpp v46, v46, v46 row_mirror row_mask:0xf bank_mask:0xf
	ds_bpermute_b32 v47, v151, v46
	s_waitcnt lgkmcnt(0)
	v_add_f32_e32 v46, v46, v47
	ds_bpermute_b32 v47, v152, v46
	s_waitcnt lgkmcnt(0)
	v_add_f32_e32 v46, v46, v47
	v_fmamk_f32 v46, v46, 0x3a800000, v153
	v_mul_f32_e32 v47, 0x4f800000, v46
	v_cmp_gt_f32_e32 vcc, s25, v46
	s_waitcnt vmcnt(0)
	v_pk_add_f32 v[40:41], v[40:41], 1.0 op_sel_hi:[1,0]
	v_pk_add_f32 v[38:39], v[38:39], 1.0 op_sel_hi:[1,0]
	v_pk_fma_f32 v[36:37], v[36:37], v[40:41], v[44:45]
	v_pk_fma_f32 v[34:35], v[34:35], v[38:39], v[42:43]
	v_cvt_pk_bf16_f32 v34, v34, v35
	v_cvt_pk_bf16_f32 v35, v36, v37
	global_store_dwordx2 v[104:105], v[34:35], off offset:1536
	global_load_dwordx4 v[34:37], v[118:119], off
	s_nop 0
	global_load_dwordx4 v[38:41], v[106:107], off
	v_cndmask_b32_e32 v42, v46, v47, vcc
	v_sqrt_f32_e32 v43, v42
	s_waitcnt vmcnt(0) lgkmcnt(0)
	v_pk_add_f32 v[36:37], v[36:37], 1.0 op_sel_hi:[1,0]
	v_add_u32_e32 v44, -1, v43
	v_add_u32_e32 v45, 1, v43
	v_fma_f32 v46, -v44, v43, v42
	v_fma_f32 v47, -v45, v43, v42
	v_cmp_ge_f32_e64 s[6:7], 0, v46
	v_pk_add_f32 v[34:35], v[34:35], 1.0 op_sel_hi:[1,0]
	s_nop 0
	v_cndmask_b32_e64 v43, v43, v44, s[6:7]
	v_cmp_lt_f32_e64 s[6:7], 0, v47
	s_nop 1
	v_cndmask_b32_e64 v43, v43, v45, s[6:7]
	v_mul_f32_e32 v44, 0x37800000, v43
	v_cndmask_b32_e32 v43, v43, v44, vcc
	v_cmp_class_f32_e32 vcc, v42, v154
	s_nop 1
	v_cndmask_b32_e32 v42, v43, v42, vcc
	v_div_scale_f32 v43, s[6:7], v42, v42, 1.0
	v_rcp_f32_e32 v45, v43
	v_div_scale_f32 v44, vcc, 1.0, v42, 1.0
	v_fma_f32 v46, -v43, v45, 1.0
	v_fmac_f32_e32 v45, v46, v45
	v_mul_f32_e32 v46, v44, v45
	v_fma_f32 v47, -v43, v46, v44
	v_fmac_f32_e32 v46, v47, v45
	v_fma_f32 v43, -v43, v46, v44
	v_div_fmas_f32 v43, v43, v45, v46
	v_div_fixup_f32 v42, v43, v42, 1.0
	v_pk_mul_f32 v[32:33], v[32:33], v[42:43] op_sel_hi:[1,0]
	v_pk_mul_f32 v[30:31], v[30:31], v[42:43] op_sel_hi:[1,0]
	v_pk_mul_f32 v[32:33], v[32:33], v[4:5]
	v_pk_mul_f32 v[30:31], v[30:31], v[2:3]
	v_pk_fma_f32 v[32:33], v[32:33], v[36:37], v[40:41]
	v_pk_fma_f32 v[30:31], v[30:31], v[34:35], v[38:39]
	v_cvt_pk_bf16_f32 v30, v30, v31
	v_cvt_pk_bf16_f32 v31, v32, v33
	global_store_dwordx2 v[104:105], v[30:31], off offset:2048
	global_load_dwordx4 v[30:33], v[114:115], off
	s_nop 0
	global_load_dwordx4 v[34:37], v[106:107], off offset:1024
	v_pk_mul_f32 v[28:29], v[28:29], v[42:43] op_sel_hi:[1,0]
	v_pk_mul_f32 v[26:27], v[26:27], v[42:43] op_sel_hi:[1,0]
	v_pk_mul_f32 v[28:29], v[28:29], v[8:9]
	v_pk_mul_f32 v[26:27], v[26:27], v[6:7]
	v_lshl_add_u64 v[38:39], s[22:23], 0, v[98:99]
	v_pk_mul_f32 v[24:25], v[24:25], v[42:43] op_sel_hi:[1,0]
	v_pk_mul_f32 v[22:23], v[22:23], v[42:43] op_sel_hi:[1,0]
	v_pk_mul_f32 v[24:25], v[24:25], v[12:13]
	v_pk_mul_f32 v[22:23], v[22:23], v[10:11]
	v_pk_mul_f32 v[20:21], v[20:21], v[42:43] op_sel_hi:[1,0]
	v_pk_mul_f32 v[18:19], v[18:19], v[42:43] op_sel_hi:[1,0]
	v_pk_mul_f32 v[20:21], v[20:21], v[16:17]
	v_pk_mul_f32 v[18:19], v[18:19], v[14:15]
	s_waitcnt vmcnt(0) lgkmcnt(0)
	v_pk_add_f32 v[32:33], v[32:33], 1.0 op_sel_hi:[1,0]
	v_pk_add_f32 v[30:31], v[30:31], 1.0 op_sel_hi:[1,0]
	v_pk_fma_f32 v[28:29], v[28:29], v[32:33], v[36:37]
	v_pk_fma_f32 v[26:27], v[26:27], v[30:31], v[34:35]
	v_cvt_pk_bf16_f32 v26, v26, v27
	v_cvt_pk_bf16_f32 v27, v28, v29
	global_store_dwordx2 v[104:105], v[26:27], off offset:2560
	global_load_dwordx4 v[26:29], v[38:39], off
	s_nop 0
	global_load_dwordx4 v[30:33], v[106:107], off offset:2048
	v_lshl_add_u64 v[34:35], s[22:23], 0, v[100:101]
	s_waitcnt vmcnt(0) lgkmcnt(0)
	v_pk_add_f32 v[28:29], v[28:29], 1.0 op_sel_hi:[1,0]
	v_pk_add_f32 v[26:27], v[26:27], 1.0 op_sel_hi:[1,0]
	v_pk_fma_f32 v[24:25], v[24:25], v[28:29], v[32:33]
	v_pk_fma_f32 v[22:23], v[22:23], v[26:27], v[30:31]
	v_cvt_pk_bf16_f32 v22, v22, v23
	v_cvt_pk_bf16_f32 v23, v24, v25
	global_store_dwordx2 v[104:105], v[22:23], off offset:3072
	global_load_dwordx4 v[22:25], v[34:35], off
	s_nop 0
	global_load_dwordx4 v[26:29], v[106:107], off offset:3072
	s_waitcnt vmcnt(0) lgkmcnt(0)
	v_pk_add_f32 v[24:25], v[24:25], 1.0 op_sel_hi:[1,0]
	v_pk_add_f32 v[22:23], v[22:23], 1.0 op_sel_hi:[1,0]
	v_pk_fma_f32 v[20:21], v[20:21], v[24:25], v[28:29]
	v_pk_fma_f32 v[18:19], v[18:19], v[22:23], v[26:27]
	v_cvt_pk_bf16_f32 v18, v18, v19
	v_cvt_pk_bf16_f32 v19, v20, v21
	global_store_dwordx2 v[104:105], v[18:19], off offset:3584
	s_cbranch_scc1 .LBB0_3341

.LBB0_3449:
	v_lshl_add_u64 v[18:19], s[38:39], 0, v[94:95]
	v_lshl_add_u64 v[22:23], s[38:39], 0, v[92:93]
	v_add_co_u32_e32 v20, vcc, 0x7800000, v18
	v_add_co_u32_e64 v102, s[6:7], s30, v22
	s_nop 0
	v_addc_co_u32_e32 v21, vcc, 0, v19, vcc
	v_addc_co_u32_e64 v103, s[6:7], 0, v23, s[6:7]
	v_add_co_u32_e64 v104, s[6:7], s31, v22
	v_add_co_u32_e32 v22, vcc, 0x7801000, v18
	s_nop 0
	v_addc_co_u32_e64 v105, s[6:7], 0, v23, s[6:7]
	global_load_dwordx4 v[78:81], v[20:21], off
	global_load_dwordx4 v[74:77], v[20:21], off offset:1024
	global_load_dwordx4 v[70:73], v[20:21], off offset:2048
	global_load_dwordx4 v[66:69], v[20:21], off offset:3072
	v_addc_co_u32_e32 v23, vcc, 0, v19, vcc
	v_add_co_u32_e32 v20, vcc, 0x7802000, v18
	global_load_dwordx4 v[62:65], v[22:23], off
	global_load_dwordx4 v[58:61], v[22:23], off offset:1024
	global_load_dwordx4 v[54:57], v[22:23], off offset:2048
	global_load_dwordx4 v[50:53], v[22:23], off offset:3072
	v_addc_co_u32_e32 v21, vcc, 0, v19, vcc
	global_load_dwordx4 v[46:49], v[20:21], off
	global_load_dwordx4 v[42:45], v[20:21], off offset:1024
	global_load_dwordx4 v[38:41], v[20:21], off offset:2048
	global_load_dwordx4 v[34:37], v[20:21], off offset:3072
	v_add_co_u32_e32 v18, vcc, 0x7803000, v18
	s_ashr_i32 s8, s20, 13
	s_nop 0
	v_addc_co_u32_e32 v19, vcc, 0, v19, vcc
	global_load_dwordx4 v[30:33], v[18:19], off
	global_load_dwordx4 v[26:29], v[18:19], off offset:1024
	global_load_dwordx4 v[22:25], v[18:19], off offset:2048
	s_nop 0
	global_load_dwordx4 v[18:21], v[18:19], off offset:3072
	s_add_i32 s9, s20, 0xffffc002
	s_cmpk_lt_i32 s20, 0x4000
	s_cselect_b32 s6, s8, s9
	s_addk_i32 s6, 0x82
	s_mul_hi_i32 s7, s6, 0x9000
	s_mul_i32 s6, s6, 0x9000
	s_add_u32 s6, s26, s6
	s_addc_u32 s7, s27, s7
	s_add_u32 s10, s6, 0x1000
	s_addc_u32 s11, s7, 0
	v_lshl_add_u64 v[122:123], s[6:7], 0, v[90:91]
	v_lshl_add_u64 v[86:87], s[10:11], 0, v[90:91]
	global_load_dwordx4 v[82:85], v[122:123], off
	s_add_i32 s6, s20, 0xffffc003
	global_load_dwordx4 v[86:89], v[86:87], off
	s_cmpk_lt_i32 s20, 0x3fff
	s_cselect_b32 s6, s8, s6
	s_addk_i32 s6, 0x82
	s_mul_hi_i32 s7, s6, 0x9000
	s_mul_i32 s6, s6, 0x9000
	s_add_u32 s6, s26, s6
	s_addc_u32 s7, s27, s7
	v_lshl_add_u64 v[138:139], s[10:11], 0, v[96:97]
	v_lshl_add_u64 v[134:135], s[10:11], 0, v[98:99]
	v_lshl_add_u64 v[128:129], s[10:11], 0, v[100:101]
	s_add_u32 s10, s6, 0x1000
	v_lshl_add_u64 v[110:111], s[6:7], 0, v[90:91]
	s_addc_u32 s11, s7, 0
	s_add_i32 s6, s20, 0xffffc004
	s_cmpk_lt_i32 s20, 0x3ffe
	s_cselect_b32 s6, s8, s6
	s_addk_i32 s6, 0x82
	s_mul_hi_i32 s7, s6, 0x9000
	s_mul_i32 s6, s6, 0x9000
	v_lshl_add_u64 v[124:125], s[10:11], 0, v[90:91]
	v_lshl_add_u64 v[118:119], s[10:11], 0, v[96:97]
	v_lshl_add_u64 v[114:115], s[10:11], 0, v[98:99]
	v_lshl_add_u64 v[112:113], s[10:11], 0, v[100:101]
	s_add_u32 s10, s26, s6
	s_addc_u32 s11, s27, s7
	s_add_u32 s6, s10, 0x1000
	s_addc_u32 s7, s11, 0
	s_add_i32 s9, s20, 0xffffc005
	s_cmpk_lt_i32 s20, 0x3ffd
	v_lshl_add_u64 v[142:143], s[6:7], 0, v[90:91]
	v_lshl_add_u64 v[140:141], s[6:7], 0, v[96:97]
	v_lshl_add_u64 v[136:137], s[6:7], 0, v[98:99]
	v_lshl_add_u64 v[126:127], s[6:7], 0, v[100:101]
	s_cselect_b32 s6, s8, s9
	s_addk_i32 s6, 0x82
	s_mul_hi_i32 s7, s6, 0x9000
	s_mul_i32 s6, s6, 0x9000
	s_add_u32 s6, s26, s6
	s_addc_u32 s7, s27, s7
	s_add_u32 s44, s6, 0x1000
	v_lshl_add_u64 v[106:107], s[6:7], 0, v[90:91]
	s_addc_u32 s45, s7, 0
	v_lshl_add_u64 v[108:109], s[10:11], 0, v[90:91]
	v_lshl_add_u64 v[120:121], s[44:45], 0, v[90:91]
	v_lshl_add_u64 v[116:117], s[44:45], 0, v[96:97]
	s_add_i32 s20, s20, 32
	v_lshl_add_u64 v[92:93], v[92:93], 0, s[22:23]
	s_waitcnt vmcnt(0) lgkmcnt(0)
	v_pk_mul_f32 v[144:145], v[80:81], v[80:81]
	v_pk_mul_f32 v[146:147], v[78:79], v[78:79]
	v_pk_mul_f32 v[148:149], v[76:77], v[76:77]
	v_pk_mul_f32 v[150:151], v[74:75], v[74:75]
	v_mul_f32_e32 v160, v71, v71
	v_mul_f32_e32 v162, v73, v73
	v_pk_mov_b32 v[164:165], v[146:147], v[144:145] op_sel:[1,0]
	v_mov_b32_e32 v147, v145
	v_pk_mov_b32 v[144:145], v[150:151], v[148:149] op_sel:[1,0]
	v_mov_b32_e32 v151, v149
	v_mul_f32_e32 v173, v68, v68
	v_mul_f32_e32 v175, v69, v69
	v_pk_fma_f32 v[148:149], v[70:71], v[70:71], v[160:161] op_sel_hi:[1,1,0]
	v_pk_fma_f32 v[160:161], v[72:73], v[72:73], v[162:163] op_sel_hi:[1,1,0]
	v_pk_mul_f32 v[162:163], v[64:65], v[64:65]
	v_pk_mul_f32 v[166:167], v[62:63], v[62:63]
	v_pk_mul_f32 v[168:169], v[60:61], v[60:61]
	v_pk_mul_f32 v[170:171], v[58:59], v[58:59]
	v_mul_f32_e32 v172, v55, v55
	v_mul_f32_e32 v174, v57, v57
	v_pk_add_f32 v[146:147], v[164:165], v[146:147]
	v_pk_add_f32 v[144:145], v[144:145], v[150:151]
	v_mul_f32_e32 v159, v66, v66
	v_mul_f32_e32 v183, v67, v67
	v_mov_b32_e32 v149, v173
	v_mov_b32_e32 v161, v175
	v_pk_mov_b32 v[150:151], v[166:167], v[162:163] op_sel:[1,0]
	v_mov_b32_e32 v167, v163
	v_pk_mov_b32 v[162:163], v[170:171], v[168:169] op_sel:[1,0]
	v_mov_b32_e32 v171, v169
	v_pk_fma_f32 v[164:165], v[54:55], v[54:55], v[172:173] op_sel_hi:[1,1,0]
	v_pk_fma_f32 v[168:169], v[56:57], v[56:57], v[174:175] op_sel_hi:[1,1,0]
	v_pk_mul_f32 v[172:173], v[48:49], v[48:49]
	v_pk_mul_f32 v[174:175], v[46:47], v[46:47]
	v_pk_add_f32 v[184:185], v[146:147], v[146:147] op_sel:[0,1] op_sel_hi:[1,0]
	v_pk_add_f32 v[186:187], v[144:145], v[144:145] op_sel:[0,1] op_sel_hi:[1,0]
	v_mul_f32_e32 v181, v52, v52
	v_pk_mul_f32 v[176:177], v[44:45], v[44:45]
	v_pk_mul_f32 v[178:179], v[42:43], v[42:43]
	v_mul_f32_e32 v180, v39, v39
	v_mul_f32_e32 v182, v41, v41
	v_pk_add_f32 v[160:161], v[148:149], v[160:161]
	v_pk_add_f32 v[144:145], v[150:151], v[166:167]
	v_pk_add_f32 v[146:147], v[162:163], v[170:171]
	v_pk_mov_b32 v[148:149], v[174:175], v[172:173] op_sel:[1,0]
	v_mov_b32_e32 v175, v173
	v_mov_b32_e32 v185, v159
	v_mov_b32_e32 v187, v183
	v_mul_f32_e32 v189, v50, v50
	v_mul_f32_e32 v194, v51, v51
	v_mul_f32_e32 v188, v53, v53
	v_mul_f32_e32 v197, v36, v36
	v_mul_f32_e32 v198, v37, v37
	v_pk_mov_b32 v[150:151], v[178:179], v[176:177] op_sel:[1,0]
	v_mov_b32_e32 v179, v177
	v_pk_fma_f32 v[162:163], v[38:39], v[38:39], v[180:181] op_sel_hi:[1,1,0]
	v_pk_fma_f32 v[166:167], v[40:41], v[40:41], v[182:183] op_sel_hi:[1,1,0]
	v_pk_add_f32 v[190:191], v[144:145], v[144:145] op_sel:[0,1] op_sel_hi:[1,0]
	v_pk_add_f32 v[192:193], v[146:147], v[146:147] op_sel:[0,1] op_sel_hi:[1,0]
	v_pk_add_f32 v[148:149], v[148:149], v[174:175]
	v_pk_add_f32 v[174:175], v[184:185], v[186:187]
	v_mov_b32_e32 v165, v181
	v_mov_b32_e32 v169, v188
	v_pk_mul_f32 v[170:171], v[32:33], v[32:33]
	v_pk_mul_f32 v[172:173], v[30:31], v[30:31]
	v_pk_mul_f32 v[176:177], v[28:29], v[28:29]
	v_pk_mul_f32 v[180:181], v[26:27], v[26:27]
	v_pk_add_f32 v[150:151], v[150:151], v[178:179]
	v_mov_b32_e32 v163, v197
	v_mov_b32_e32 v167, v198
	v_mov_b32_e32 v191, v189
	v_mov_b32_e32 v193, v194
	v_pk_add_f32 v[160:161], v[174:175], v[160:161]
	v_mul_f32_e32 v195, v34, v34
	v_mul_f32_e32 v196, v35, v35
	v_pk_add_f32 v[164:165], v[164:165], v[168:169]
	v_pk_mov_b32 v[168:169], v[172:173], v[170:171] op_sel:[1,0]
	v_mov_b32_e32 v173, v171
	v_pk_mov_b32 v[170:171], v[180:181], v[176:177] op_sel:[1,0]
	v_mov_b32_e32 v181, v177
	v_pk_add_f32 v[176:177], v[148:149], v[148:149] op_sel:[0,1] op_sel_hi:[1,0]
	v_pk_add_f32 v[178:179], v[150:151], v[150:151] op_sel:[0,1] op_sel_hi:[1,0]
	v_pk_add_f32 v[162:163], v[162:163], v[166:167]
	v_pk_add_f32 v[166:167], v[190:191], v[192:193]
	v_add_f32_e32 v159, v160, v161
	v_mov_b32_e32 v177, v195
	v_mov_b32_e32 v179, v196
	v_pk_add_f32 v[160:161], v[166:167], v[164:165]
	v_pk_add_f32 v[164:165], v[176:177], v[178:179]
	v_add_f32_e32 v166, v160, v161
	v_pk_add_f32 v[160:161], v[164:165], v[162:163]
	v_add_f32_e32 v160, v160, v161
	s_waitcnt lgkmcnt(0)
	s_nop 1
	v_add_f32_dpp v159, v159, v159 quad_perm:[1,0,3,2] row_mask:0xf bank_mask:0xf
	s_waitcnt lgkmcnt(0)
	s_nop 1
	v_add_f32_dpp v162, v166, v166 quad_perm:[1,0,3,2] row_mask:0xf bank_mask:0xf
	s_waitcnt lgkmcnt(0)
	s_nop 1
	v_add_f32_dpp v160, v160, v160 quad_perm:[1,0,3,2] row_mask:0xf bank_mask:0xf
	s_waitcnt lgkmcnt(0)
	s_nop 1
	v_add_f32_dpp v159, v159, v159 quad_perm:[2,3,0,1] row_mask:0xf bank_mask:0xf
	s_waitcnt lgkmcnt(0)
	s_nop 1
	v_add_f32_dpp v162, v162, v162 quad_perm:[2,3,0,1] row_mask:0xf bank_mask:0xf
	s_waitcnt lgkmcnt(0)
	s_nop 1
	v_add_f32_dpp v160, v160, v160 quad_perm:[2,3,0,1] row_mask:0xf bank_mask:0xf
	s_waitcnt lgkmcnt(0)
	s_nop 1
	v_add_f32_dpp v159, v159, v159 row_half_mirror row_mask:0xf bank_mask:0xf
	s_waitcnt lgkmcnt(0)
	s_nop 1
	v_add_f32_dpp v162, v162, v162 row_half_mirror row_mask:0xf bank_mask:0xf
	s_waitcnt lgkmcnt(0)
	s_nop 1
	v_add_f32_dpp v160, v160, v160 row_half_mirror row_mask:0xf bank_mask:0xf
	s_waitcnt lgkmcnt(0)
	s_nop 1
	v_add_f32_dpp v159, v159, v159 row_mirror row_mask:0xf bank_mask:0xf
	ds_bpermute_b32 v163, v155, v159
	s_waitcnt lgkmcnt(2)
	s_nop 1
	v_add_f32_dpp v162, v162, v162 row_mirror row_mask:0xf bank_mask:0xf
	ds_bpermute_b32 v164, v155, v162
	s_waitcnt lgkmcnt(2)
	s_nop 1
	v_add_f32_dpp v160, v160, v160 row_mirror row_mask:0xf bank_mask:0xf
	ds_bpermute_b32 v161, v155, v160
	s_waitcnt lgkmcnt(2)
	v_add_f32_e32 v159, v159, v163
	ds_bpermute_b32 v163, v156, v159
	s_waitcnt lgkmcnt(2)
	v_add_f32_e32 v162, v162, v164
	ds_bpermute_b32 v164, v156, v162
	s_waitcnt lgkmcnt(2)
	v_add_f32_e32 v160, v160, v161
	ds_bpermute_b32 v161, v156, v160
	s_waitcnt lgkmcnt(2)
	v_add_f32_e32 v159, v159, v163
	v_fmamk_f32 v159, v159, 0x3a800000, v157
	s_waitcnt lgkmcnt(1)
	v_add_f32_e32 v162, v162, v164
	v_mul_f32_e32 v163, 0x4f800000, v159
	v_cmp_gt_f32_e32 vcc, s21, v159
	v_fmamk_f32 v162, v162, 0x3a800000, v157
	s_waitcnt lgkmcnt(0)
	v_add_f32_e32 v160, v160, v161
	v_cndmask_b32_e32 v159, v159, v163, vcc
	v_mul_f32_e32 v161, 0x4f800000, v162
	v_cmp_gt_f32_e64 s[6:7], s21, v162
	v_sqrt_f32_e32 v163, v159
	v_fmamk_f32 v160, v160, 0x3a800000, v157
	v_cndmask_b32_e64 v161, v162, v161, s[6:7]
	v_mul_f32_e32 v162, 0x4f800000, v160
	v_cmp_gt_f32_e64 s[8:9], s21, v160
	v_sqrt_f32_e32 v164, v161
	v_add_u32_e32 v165, -1, v163
	v_cndmask_b32_e64 v160, v160, v162, s[8:9]
	v_sqrt_f32_e32 v162, v160
	v_add_u32_e32 v166, 1, v163
	v_fma_f32 v167, -v165, v163, v159
	v_pk_add_f32 v[148:149], v[168:169], v[172:173]
	v_fma_f32 v168, -v166, v163, v159
	v_add_u32_e32 v169, -1, v164
	v_cmp_ge_f32_e64 s[10:11], 0, v167
	v_pk_add_f32 v[150:151], v[170:171], v[180:181]
	v_add_u32_e32 v170, 1, v164
	v_cndmask_b32_e64 v163, v163, v165, s[10:11]
	v_fma_f32 v165, -v169, v164, v161
	v_cmp_lt_f32_e64 s[10:11], 0, v168
	v_fma_f32 v167, -v170, v164, v161
	v_add_u32_e32 v171, -1, v162
	v_cndmask_b32_e64 v163, v163, v166, s[10:11]
	v_cmp_ge_f32_e64 s[10:11], 0, v165
	v_add_u32_e32 v172, 1, v162
	v_fma_f32 v165, -v171, v162, v160
	v_cndmask_b32_e64 v164, v164, v169, s[10:11]
	v_cmp_lt_f32_e64 s[10:11], 0, v167
	v_fma_f32 v166, -v172, v162, v160
	v_mul_f32_e32 v167, 0x37800000, v163
	v_cndmask_b32_e64 v164, v164, v170, s[10:11]
	v_cmp_ge_f32_e64 s[10:11], 0, v165
	v_cndmask_b32_e32 v163, v163, v167, vcc
	v_cmp_class_f32_e32 vcc, v159, v158
	v_cndmask_b32_e64 v162, v162, v171, s[10:11]
	v_cmp_lt_f32_e64 s[10:11], 0, v166
	v_mul_f32_e32 v165, 0x37800000, v164
	v_cndmask_b32_e32 v159, v163, v159, vcc
	v_cndmask_b32_e64 v162, v162, v172, s[10:11]
	v_cndmask_b32_e64 v163, v164, v165, s[6:7]
	v_cmp_class_f32_e32 vcc, v161, v158
	v_mul_f32_e32 v164, 0x37800000, v162
	v_div_scale_f32 v165, s[6:7], v159, v159, 1.0
	v_cndmask_b32_e32 v161, v163, v161, vcc
	v_cndmask_b32_e64 v162, v162, v164, s[8:9]
	v_cmp_class_f32_e32 vcc, v160, v158
	v_rcp_f32_e32 v163, v165
	v_div_scale_f32 v164, s[8:9], v161, v161, 1.0
	v_cndmask_b32_e32 v162, v162, v160, vcc
	v_rcp_f32_e32 v168, v164
	v_div_scale_f32 v169, s[10:11], v162, v162, 1.0
	v_rcp_f32_e32 v171, v169
	v_fma_f32 v160, -v165, v163, 1.0
	v_div_scale_f32 v166, s[6:7], 1.0, v159, 1.0
	v_fmac_f32_e32 v163, v160, v163
	v_fma_f32 v160, -v164, v168, 1.0
	v_mul_f32_e32 v172, v166, v163
	v_div_scale_f32 v167, s[8:9], 1.0, v161, 1.0
	v_fmac_f32_e32 v168, v160, v168
	v_fma_f32 v160, -v169, v171, 1.0
	v_fma_f32 v173, -v165, v172, v166
	v_div_scale_f32 v170, s[10:11], 1.0, v162, 1.0
	v_mul_f32_e32 v174, v167, v168
	v_fmac_f32_e32 v171, v160, v171
	v_fmac_f32_e32 v172, v173, v163
	v_fma_f32 v160, -v164, v174, v167
	v_mul_f32_e32 v173, v170, v171
	v_fma_f32 v165, -v165, v172, v166
	s_mov_b64 vcc, s[6:7]
	v_fmac_f32_e32 v174, v160, v168
	v_fma_f32 v160, -v169, v173, v170
	v_div_fmas_f32 v163, v165, v163, v172
	v_fma_f32 v164, -v164, v174, v167
	v_fmac_f32_e32 v173, v160, v171
	v_div_fixup_f32 v160, v163, v159, 1.0
	s_mov_b64 vcc, s[8:9]
	v_div_fmas_f32 v159, v164, v168, v174
	v_fma_f32 v163, -v169, v173, v170
	v_pk_mul_f32 v[80:81], v[80:81], v[160:161] op_sel_hi:[1,0]
	v_pk_mul_f32 v[78:79], v[78:79], v[160:161] op_sel_hi:[1,0]
	s_mov_b64 vcc, s[10:11]
	v_pk_add_f32 v[88:89], v[88:89], 1.0 op_sel_hi:[1,0]
	v_pk_add_f32 v[86:87], v[86:87], 1.0 op_sel_hi:[1,0]
	v_pk_mul_f32 v[76:77], v[76:77], v[160:161] op_sel_hi:[1,0]
	v_pk_mul_f32 v[74:75], v[74:75], v[160:161] op_sel_hi:[1,0]
	v_pk_mul_f32 v[72:73], v[72:73], v[160:161] op_sel_hi:[1,0]
	v_pk_mul_f32 v[70:71], v[70:71], v[160:161] op_sel_hi:[1,0]
	v_pk_mul_f32 v[68:69], v[68:69], v[160:161] op_sel_hi:[1,0]
	v_pk_mul_f32 v[66:67], v[66:67], v[160:161] op_sel_hi:[1,0]
	v_div_fixup_f32 v160, v159, v161, 1.0
	v_div_fmas_f32 v159, v163, v171, v173
	v_pk_mul_f32 v[78:79], v[78:79], v[2:3]
	v_pk_mul_f32 v[80:81], v[80:81], v[4:5]
	v_pk_mul_f32 v[64:65], v[64:65], v[160:161] op_sel_hi:[1,0]
	v_pk_mul_f32 v[62:63], v[62:63], v[160:161] op_sel_hi:[1,0]
	v_pk_mul_f32 v[60:61], v[60:61], v[160:161] op_sel_hi:[1,0]
	v_pk_mul_f32 v[58:59], v[58:59], v[160:161] op_sel_hi:[1,0]
	v_pk_mul_f32 v[56:57], v[56:57], v[160:161] op_sel_hi:[1,0]
	v_pk_mul_f32 v[54:55], v[54:55], v[160:161] op_sel_hi:[1,0]
	v_pk_mul_f32 v[52:53], v[52:53], v[160:161] op_sel_hi:[1,0]
	v_pk_mul_f32 v[50:51], v[50:51], v[160:161] op_sel_hi:[1,0]
	v_div_fixup_f32 v160, v159, v162, 1.0
	v_pk_fma_f32 v[80:81], v[80:81], v[88:89], v[84:85]
	v_pk_fma_f32 v[78:79], v[78:79], v[86:87], v[82:83]
	v_pk_mul_f32 v[82:83], v[50:51], v[14:15]
	v_pk_mul_f32 v[84:85], v[52:53], v[16:17]
	v_pk_mul_f32 v[48:49], v[48:49], v[160:161] op_sel_hi:[1,0]
	v_pk_mul_f32 v[46:47], v[46:47], v[160:161] op_sel_hi:[1,0]
	v_pk_mul_f32 v[86:87], v[46:47], v[2:3]
	v_pk_mul_f32 v[88:89], v[48:49], v[4:5]
	v_cvt_pk_bf16_f32 v46, v78, v79
	v_cvt_pk_bf16_f32 v47, v80, v81
	global_store_dwordx2 v[102:103], v[46:47], off
	global_load_dwordx4 v[46:49], v[138:139], off
	s_nop 0
	global_load_dwordx4 v[50:53], v[122:123], off offset:1024
	v_pk_mul_f32 v[74:75], v[74:75], v[6:7]
	v_pk_mul_f32 v[76:77], v[76:77], v[8:9]
	v_pk_mul_f32 v[70:71], v[70:71], v[10:11]
	v_pk_mul_f32 v[72:73], v[72:73], v[12:13]
	v_pk_mul_f32 v[66:67], v[66:67], v[14:15]
	v_pk_mul_f32 v[68:69], v[68:69], v[16:17]
	v_pk_mul_f32 v[62:63], v[62:63], v[2:3]
	v_pk_mul_f32 v[64:65], v[64:65], v[4:5]
	v_pk_mul_f32 v[58:59], v[58:59], v[6:7]
	v_pk_mul_f32 v[60:61], v[60:61], v[8:9]
	v_pk_mul_f32 v[54:55], v[54:55], v[10:11]
	v_pk_mul_f32 v[56:57], v[56:57], v[12:13]
	v_pk_mul_f32 v[44:45], v[44:45], v[160:161] op_sel_hi:[1,0]
	v_pk_mul_f32 v[42:43], v[42:43], v[160:161] op_sel_hi:[1,0]
	v_pk_mul_f32 v[44:45], v[44:45], v[8:9]
	v_pk_mul_f32 v[42:43], v[42:43], v[6:7]
	v_pk_mul_f32 v[40:41], v[40:41], v[160:161] op_sel_hi:[1,0]
	v_pk_mul_f32 v[38:39], v[38:39], v[160:161] op_sel_hi:[1,0]
	v_pk_mul_f32 v[40:41], v[40:41], v[12:13]
	v_pk_mul_f32 v[38:39], v[38:39], v[10:11]
	v_pk_mul_f32 v[36:37], v[36:37], v[160:161] op_sel_hi:[1,0]
	v_pk_mul_f32 v[34:35], v[34:35], v[160:161] op_sel_hi:[1,0]
	v_pk_mul_f32 v[36:37], v[36:37], v[16:17]
	v_pk_mul_f32 v[34:35], v[34:35], v[14:15]
	v_mul_f32_e32 v182, v23, v23
	v_mul_f32_e32 v188, v25, v25
	v_mul_f32_e32 v199, v18, v18
	v_mul_f32_e32 v200, v19, v19
	v_mul_f32_e32 v201, v20, v20
	v_mul_f32_e32 v202, v21, v21
	v_pk_fma_f32 v[144:145], v[22:23], v[22:23], v[182:183] op_sel_hi:[1,1,0]
	v_pk_fma_f32 v[146:147], v[24:25], v[24:25], v[188:189] op_sel_hi:[1,1,0]
	v_mov_b32_e32 v145, v201
	v_mov_b32_e32 v147, v202
	v_lshl_add_u64 v[94:95], v[94:95], 0, s[24:25]
	s_cmp_lt_i32 s20, s13
	s_waitcnt vmcnt(0) lgkmcnt(0)
	v_pk_add_f32 v[48:49], v[48:49], 1.0 op_sel_hi:[1,0]
	v_pk_add_f32 v[46:47], v[46:47], 1.0 op_sel_hi:[1,0]
	v_pk_fma_f32 v[48:49], v[76:77], v[48:49], v[52:53]
	v_pk_fma_f32 v[46:47], v[74:75], v[46:47], v[50:51]
	v_cvt_pk_bf16_f32 v46, v46, v47
	v_cvt_pk_bf16_f32 v47, v48, v49
	global_store_dwordx2 v[102:103], v[46:47], off offset:512
	global_load_dwordx4 v[46:49], v[134:135], off
	s_nop 0
	global_load_dwordx4 v[50:53], v[122:123], off offset:2048
	s_waitcnt vmcnt(0) lgkmcnt(0)
	v_pk_add_f32 v[48:49], v[48:49], 1.0 op_sel_hi:[1,0]
	v_pk_add_f32 v[46:47], v[46:47], 1.0 op_sel_hi:[1,0]
	v_pk_fma_f32 v[48:49], v[72:73], v[48:49], v[52:53]
	v_pk_fma_f32 v[46:47], v[70:71], v[46:47], v[50:51]
	v_cvt_pk_bf16_f32 v46, v46, v47
	v_cvt_pk_bf16_f32 v47, v48, v49
	global_store_dwordx2 v[102:103], v[46:47], off offset:1024
	global_load_dwordx4 v[46:49], v[128:129], off
	s_nop 0
	global_load_dwordx4 v[50:53], v[122:123], off offset:3072
	s_waitcnt vmcnt(0) lgkmcnt(0)
	v_pk_add_f32 v[48:49], v[48:49], 1.0 op_sel_hi:[1,0]
	v_pk_add_f32 v[46:47], v[46:47], 1.0 op_sel_hi:[1,0]
	v_pk_fma_f32 v[48:49], v[68:69], v[48:49], v[52:53]
	v_pk_fma_f32 v[46:47], v[66:67], v[46:47], v[50:51]
	v_cvt_pk_bf16_f32 v46, v46, v47
	v_cvt_pk_bf16_f32 v47, v48, v49
	global_store_dwordx2 v[102:103], v[46:47], off offset:1536
	global_load_dwordx4 v[46:49], v[124:125], off
	s_nop 0
	global_load_dwordx4 v[50:53], v[110:111], off
	s_waitcnt vmcnt(0) lgkmcnt(0)
	v_pk_add_f32 v[48:49], v[48:49], 1.0 op_sel_hi:[1,0]
	v_pk_add_f32 v[46:47], v[46:47], 1.0 op_sel_hi:[1,0]
	v_pk_fma_f32 v[48:49], v[64:65], v[48:49], v[52:53]
	v_pk_fma_f32 v[46:47], v[62:63], v[46:47], v[50:51]
	v_cvt_pk_bf16_f32 v46, v46, v47
	v_cvt_pk_bf16_f32 v47, v48, v49
	global_store_dwordx2 v[102:103], v[46:47], off offset:2048
	global_load_dwordx4 v[46:49], v[118:119], off
	s_nop 0
	global_load_dwordx4 v[50:53], v[110:111], off offset:1024
	s_waitcnt vmcnt(0) lgkmcnt(0)
	v_pk_add_f32 v[48:49], v[48:49], 1.0 op_sel_hi:[1,0]
	v_pk_add_f32 v[46:47], v[46:47], 1.0 op_sel_hi:[1,0]
	v_pk_fma_f32 v[48:49], v[60:61], v[48:49], v[52:53]
	v_pk_fma_f32 v[46:47], v[58:59], v[46:47], v[50:51]
	v_cvt_pk_bf16_f32 v46, v46, v47
	v_cvt_pk_bf16_f32 v47, v48, v49
	global_store_dwordx2 v[102:103], v[46:47], off offset:2560
	global_load_dwordx4 v[46:49], v[114:115], off
	s_nop 0
	global_load_dwordx4 v[50:53], v[110:111], off offset:2048
	v_pk_add_f32 v[58:59], v[144:145], v[146:147]
	s_waitcnt vmcnt(0) lgkmcnt(0)
	v_pk_add_f32 v[48:49], v[48:49], 1.0 op_sel_hi:[1,0]
	v_pk_add_f32 v[46:47], v[46:47], 1.0 op_sel_hi:[1,0]
	v_pk_fma_f32 v[48:49], v[56:57], v[48:49], v[52:53]
	v_pk_fma_f32 v[46:47], v[54:55], v[46:47], v[50:51]
	v_cvt_pk_bf16_f32 v46, v46, v47
	v_cvt_pk_bf16_f32 v47, v48, v49
	global_store_dwordx2 v[102:103], v[46:47], off offset:3072
	global_load_dwordx4 v[46:49], v[112:113], off
	s_nop 0
	global_load_dwordx4 v[50:53], v[110:111], off offset:3072
	v_pk_add_f32 v[54:55], v[148:149], v[148:149] op_sel:[0,1] op_sel_hi:[1,0]
	v_pk_add_f32 v[56:57], v[150:151], v[150:151] op_sel:[0,1] op_sel_hi:[1,0]
	v_mov_b32_e32 v55, v199
	v_mov_b32_e32 v57, v200
	s_waitcnt vmcnt(0) lgkmcnt(0)
	v_pk_add_f32 v[48:49], v[48:49], 1.0 op_sel_hi:[1,0]
	v_pk_add_f32 v[46:47], v[46:47], 1.0 op_sel_hi:[1,0]
	v_pk_fma_f32 v[48:49], v[84:85], v[48:49], v[52:53]
	v_pk_fma_f32 v[46:47], v[82:83], v[46:47], v[50:51]
	v_cvt_pk_bf16_f32 v46, v46, v47
	v_cvt_pk_bf16_f32 v47, v48, v49
	global_store_dwordx2 v[102:103], v[46:47], off offset:3584
	global_load_dwordx4 v[46:49], v[142:143], off
	s_nop 0
	global_load_dwordx4 v[50:53], v[108:109], off
	s_waitcnt vmcnt(0) lgkmcnt(0)
	v_pk_add_f32 v[48:49], v[48:49], 1.0 op_sel_hi:[1,0]
	v_pk_add_f32 v[46:47], v[46:47], 1.0 op_sel_hi:[1,0]
	v_pk_fma_f32 v[48:49], v[88:89], v[48:49], v[52:53]
	v_pk_fma_f32 v[46:47], v[86:87], v[46:47], v[50:51]
	v_cvt_pk_bf16_f32 v46, v46, v47
	v_cvt_pk_bf16_f32 v47, v48, v49
	global_store_dwordx2 v[104:105], v[46:47], off
	global_load_dwordx4 v[46:49], v[140:141], off
	s_nop 0
	global_load_dwordx4 v[50:53], v[108:109], off offset:1024
	s_waitcnt vmcnt(0) lgkmcnt(0)
	v_pk_add_f32 v[48:49], v[48:49], 1.0 op_sel_hi:[1,0]
	v_pk_add_f32 v[46:47], v[46:47], 1.0 op_sel_hi:[1,0]
	v_pk_fma_f32 v[44:45], v[44:45], v[48:49], v[52:53]
	v_pk_fma_f32 v[42:43], v[42:43], v[46:47], v[50:51]
	v_cvt_pk_bf16_f32 v42, v42, v43
	v_cvt_pk_bf16_f32 v43, v44, v45
	global_store_dwordx2 v[104:105], v[42:43], off offset:512
	global_load_dwordx4 v[42:45], v[136:137], off
	s_nop 0
	global_load_dwordx4 v[46:49], v[108:109], off offset:2048
	v_pk_add_f32 v[50:51], v[54:55], v[56:57]
	s_waitcnt vmcnt(0) lgkmcnt(0)
	v_pk_add_f32 v[44:45], v[44:45], 1.0 op_sel_hi:[1,0]
	v_pk_add_f32 v[42:43], v[42:43], 1.0 op_sel_hi:[1,0]
	v_pk_fma_f32 v[40:41], v[40:41], v[44:45], v[48:49]
	v_pk_fma_f32 v[38:39], v[38:39], v[42:43], v[46:47]
	v_cvt_pk_bf16_f32 v38, v38, v39
	v_cvt_pk_bf16_f32 v39, v40, v41
	global_store_dwordx2 v[104:105], v[38:39], off offset:1024
	global_load_dwordx4 v[38:41], v[126:127], off
	s_nop 0
	global_load_dwordx4 v[42:45], v[108:109], off offset:3072
	v_pk_add_f32 v[50:51], v[50:51], v[58:59]
	s_waitcnt vmcnt(0) lgkmcnt(0)
	v_pk_add_f32 v[40:41], v[40:41], 1.0 op_sel_hi:[1,0]
	v_pk_add_f32 v[38:39], v[38:39], 1.0 op_sel_hi:[1,0]
	v_pk_fma_f32 v[36:37], v[36:37], v[40:41], v[44:45]
	v_pk_fma_f32 v[34:35], v[34:35], v[38:39], v[42:43]
	v_cvt_pk_bf16_f32 v34, v34, v35
	v_cvt_pk_bf16_f32 v35, v36, v37
	global_store_dwordx2 v[104:105], v[34:35], off offset:1536
	global_load_dwordx4 v[34:37], v[120:121], off
	s_nop 0
	global_load_dwordx4 v[38:41], v[106:107], off
	v_add_f32_e32 v50, v50, v51
	s_waitcnt lgkmcnt(0)
	s_nop 1
	v_add_f32_dpp v50, v50, v50 quad_perm:[1,0,3,2] row_mask:0xf bank_mask:0xf
	s_waitcnt lgkmcnt(0)
	s_nop 1
	v_add_f32_dpp v50, v50, v50 quad_perm:[2,3,0,1] row_mask:0xf bank_mask:0xf
	s_waitcnt lgkmcnt(0)
	s_nop 1
	v_add_f32_dpp v46, v50, v50 row_half_mirror row_mask:0xf bank_mask:0xf
	s_waitcnt lgkmcnt(0)
	s_nop 1
	v_add_f32_dpp v46, v46, v46 row_mirror row_mask:0xf bank_mask:0xf
	ds_bpermute_b32 v47, v155, v46
	s_waitcnt lgkmcnt(0)
	v_add_f32_e32 v46, v46, v47
	ds_bpermute_b32 v47, v156, v46
	s_waitcnt lgkmcnt(0)
	v_add_f32_e32 v46, v46, v47
	v_fmamk_f32 v46, v46, 0x3a800000, v157
	v_mul_f32_e32 v47, 0x4f800000, v46
	v_cmp_gt_f32_e32 vcc, s21, v46
	s_waitcnt vmcnt(0)
	v_pk_add_f32 v[36:37], v[36:37], 1.0 op_sel_hi:[1,0]
	v_cndmask_b32_e32 v42, v46, v47, vcc
	v_sqrt_f32_e32 v43, v42
	v_pk_add_f32 v[34:35], v[34:35], 1.0 op_sel_hi:[1,0]
	v_add_u32_e32 v44, -1, v43
	v_add_u32_e32 v45, 1, v43
	v_fma_f32 v46, -v44, v43, v42
	v_fma_f32 v47, -v45, v43, v42
	v_cmp_ge_f32_e64 s[6:7], 0, v46
	s_nop 1
	v_cndmask_b32_e64 v43, v43, v44, s[6:7]
	v_cmp_lt_f32_e64 s[6:7], 0, v47
	s_nop 1
	v_cndmask_b32_e64 v43, v43, v45, s[6:7]
	v_mul_f32_e32 v44, 0x37800000, v43
	v_cndmask_b32_e32 v43, v43, v44, vcc
	v_cmp_class_f32_e32 vcc, v42, v158
	s_nop 1
	v_cndmask_b32_e32 v42, v43, v42, vcc
	v_div_scale_f32 v43, s[6:7], v42, v42, 1.0
	v_rcp_f32_e32 v45, v43
	v_div_scale_f32 v44, vcc, 1.0, v42, 1.0
	v_fma_f32 v46, -v43, v45, 1.0
	v_fmac_f32_e32 v45, v46, v45
	v_mul_f32_e32 v46, v44, v45
	v_fma_f32 v47, -v43, v46, v44
	v_fmac_f32_e32 v46, v47, v45
	v_fma_f32 v43, -v43, v46, v44
	v_div_fmas_f32 v43, v43, v45, v46
	v_div_fixup_f32 v42, v43, v42, 1.0
	v_pk_mul_f32 v[32:33], v[32:33], v[42:43] op_sel_hi:[1,0]
	v_pk_mul_f32 v[30:31], v[30:31], v[42:43] op_sel_hi:[1,0]
	v_pk_mul_f32 v[32:33], v[32:33], v[4:5]
	v_pk_mul_f32 v[30:31], v[30:31], v[2:3]
	v_pk_fma_f32 v[32:33], v[32:33], v[36:37], v[40:41]
	v_pk_fma_f32 v[30:31], v[30:31], v[34:35], v[38:39]
	v_cvt_pk_bf16_f32 v30, v30, v31
	v_cvt_pk_bf16_f32 v31, v32, v33
	global_store_dwordx2 v[104:105], v[30:31], off offset:2048
	global_load_dwordx4 v[30:33], v[116:117], off
	s_nop 0
	global_load_dwordx4 v[34:37], v[106:107], off offset:1024
	v_pk_mul_f32 v[28:29], v[28:29], v[42:43] op_sel_hi:[1,0]
	v_pk_mul_f32 v[26:27], v[26:27], v[42:43] op_sel_hi:[1,0]
	v_pk_mul_f32 v[28:29], v[28:29], v[8:9]
	v_pk_mul_f32 v[26:27], v[26:27], v[6:7]
	v_lshl_add_u64 v[38:39], s[44:45], 0, v[98:99]
	v_pk_mul_f32 v[24:25], v[24:25], v[42:43] op_sel_hi:[1,0]
	v_pk_mul_f32 v[22:23], v[22:23], v[42:43] op_sel_hi:[1,0]
	v_pk_mul_f32 v[24:25], v[24:25], v[12:13]
	v_pk_mul_f32 v[22:23], v[22:23], v[10:11]
	v_pk_mul_f32 v[20:21], v[20:21], v[42:43] op_sel_hi:[1,0]
	v_pk_mul_f32 v[18:19], v[18:19], v[42:43] op_sel_hi:[1,0]
	v_pk_mul_f32 v[20:21], v[20:21], v[16:17]
	v_pk_mul_f32 v[18:19], v[18:19], v[14:15]
	s_waitcnt vmcnt(0) lgkmcnt(0)
	v_pk_add_f32 v[32:33], v[32:33], 1.0 op_sel_hi:[1,0]
	v_pk_add_f32 v[30:31], v[30:31], 1.0 op_sel_hi:[1,0]
	v_pk_fma_f32 v[28:29], v[28:29], v[32:33], v[36:37]
	v_pk_fma_f32 v[26:27], v[26:27], v[30:31], v[34:35]
	v_cvt_pk_bf16_f32 v26, v26, v27
	v_cvt_pk_bf16_f32 v27, v28, v29
	global_store_dwordx2 v[104:105], v[26:27], off offset:2560
	global_load_dwordx4 v[26:29], v[38:39], off
	s_nop 0
	global_load_dwordx4 v[30:33], v[106:107], off offset:2048
	v_lshl_add_u64 v[34:35], s[44:45], 0, v[100:101]
	s_waitcnt vmcnt(0) lgkmcnt(0)
	v_pk_add_f32 v[28:29], v[28:29], 1.0 op_sel_hi:[1,0]
	v_pk_add_f32 v[26:27], v[26:27], 1.0 op_sel_hi:[1,0]
	v_pk_fma_f32 v[24:25], v[24:25], v[28:29], v[32:33]
	v_pk_fma_f32 v[22:23], v[22:23], v[26:27], v[30:31]
	v_cvt_pk_bf16_f32 v22, v22, v23
	v_cvt_pk_bf16_f32 v23, v24, v25
	global_store_dwordx2 v[104:105], v[22:23], off offset:3072
	global_load_dwordx4 v[22:25], v[34:35], off
	s_nop 0
	global_load_dwordx4 v[26:29], v[106:107], off offset:3072
	s_waitcnt vmcnt(0) lgkmcnt(0)
	v_pk_add_f32 v[24:25], v[24:25], 1.0 op_sel_hi:[1,0]
	v_pk_add_f32 v[22:23], v[22:23], 1.0 op_sel_hi:[1,0]
	v_pk_fma_f32 v[20:21], v[20:21], v[24:25], v[28:29]
	v_pk_fma_f32 v[18:19], v[18:19], v[22:23], v[26:27]
	v_cvt_pk_bf16_f32 v18, v18, v19
	v_cvt_pk_bf16_f32 v19, v20, v21
	global_store_dwordx2 v[104:105], v[18:19], off offset:3584
	s_cbranch_scc1 .LBB0_3449

.LBB0_3611:
	v_lshl_add_u64 v[18:19], s[38:39], 0, v[94:95]
	v_lshl_add_u64 v[22:23], s[38:39], 0, v[92:93]
	v_add_co_u32_e32 v20, vcc, 0x7800000, v18
	v_add_co_u32_e64 v102, s[6:7], s23, v22
	s_nop 0
	v_addc_co_u32_e32 v21, vcc, 0, v19, vcc
	v_addc_co_u32_e64 v103, s[6:7], 0, v23, s[6:7]
	v_add_co_u32_e64 v104, s[6:7], s24, v22
	v_add_co_u32_e32 v22, vcc, 0x7801000, v18
	s_nop 0
	v_addc_co_u32_e64 v105, s[6:7], 0, v23, s[6:7]
	global_load_dwordx4 v[78:81], v[20:21], off
	global_load_dwordx4 v[74:77], v[20:21], off offset:1024
	global_load_dwordx4 v[70:73], v[20:21], off offset:2048
	global_load_dwordx4 v[66:69], v[20:21], off offset:3072
	v_addc_co_u32_e32 v23, vcc, 0, v19, vcc
	v_add_co_u32_e32 v20, vcc, 0x7802000, v18
	global_load_dwordx4 v[62:65], v[22:23], off
	global_load_dwordx4 v[58:61], v[22:23], off offset:1024
	global_load_dwordx4 v[54:57], v[22:23], off offset:2048
	global_load_dwordx4 v[50:53], v[22:23], off offset:3072
	v_addc_co_u32_e32 v21, vcc, 0, v19, vcc
	v_add_co_u32_e32 v82, vcc, 0x7803000, v18
	global_load_dwordx4 v[46:49], v[20:21], off
	global_load_dwordx4 v[42:45], v[20:21], off offset:1024
	global_load_dwordx4 v[38:41], v[20:21], off offset:2048
	global_load_dwordx4 v[34:37], v[20:21], off offset:3072
	v_addc_co_u32_e32 v83, vcc, 0, v19, vcc
	global_load_dwordx4 v[30:33], v[82:83], off
	global_load_dwordx4 v[26:29], v[82:83], off offset:1024
	global_load_dwordx4 v[22:25], v[82:83], off offset:2048
	global_load_dwordx4 v[18:21], v[82:83], off offset:3072
	s_add_i32 s25, s8, 32
	s_add_i32 s10, s8, 0xffffc022
	s_ashr_i32 s9, s25, 13
	s_cmpk_lt_i32 s25, 0x4000
	s_cselect_b32 s6, s9, s10
	s_addk_i32 s6, 0x82
	s_mul_hi_i32 s7, s6, 0x9000
	s_mul_i32 s6, s6, 0x9000
	s_add_u32 s6, s2, s6
	s_addc_u32 s7, s5, s7
	s_add_u32 s10, s6, 0x1000
	s_addc_u32 s11, s7, 0
	v_lshl_add_u64 v[124:125], s[6:7], 0, v[90:91]
	v_lshl_add_u64 v[86:87], s[10:11], 0, v[90:91]
	global_load_dwordx4 v[82:85], v[124:125], off
	s_add_i32 s6, s8, 0xffffc023
	global_load_dwordx4 v[86:89], v[86:87], off
	s_cmpk_lt_i32 s25, 0x3fff
	s_cselect_b32 s6, s9, s6
	s_addk_i32 s6, 0x82
	s_mul_hi_i32 s7, s6, 0x9000
	s_mul_i32 s6, s6, 0x9000
	s_add_u32 s6, s2, s6
	s_addc_u32 s7, s5, s7
	v_lshl_add_u64 v[138:139], s[10:11], 0, v[96:97]
	v_lshl_add_u64 v[134:135], s[10:11], 0, v[98:99]
	v_lshl_add_u64 v[128:129], s[10:11], 0, v[100:101]
	s_add_u32 s10, s6, 0x1000
	v_lshl_add_u64 v[110:111], s[6:7], 0, v[90:91]
	s_addc_u32 s11, s7, 0
	s_add_i32 s6, s8, 0xffffc024
	s_cmpk_lt_i32 s25, 0x3ffe
	s_cselect_b32 s6, s9, s6
	s_addk_i32 s6, 0x82
	s_mul_hi_i32 s7, s6, 0x9000
	s_mul_i32 s6, s6, 0x9000
	v_lshl_add_u64 v[126:127], s[10:11], 0, v[90:91]
	v_lshl_add_u64 v[120:121], s[10:11], 0, v[96:97]
	v_lshl_add_u64 v[116:117], s[10:11], 0, v[98:99]
	v_lshl_add_u64 v[112:113], s[10:11], 0, v[100:101]
	s_add_u32 s10, s2, s6
	s_addc_u32 s11, s5, s7
	s_add_u32 s6, s10, 0x1000
	s_addc_u32 s7, s11, 0
	s_addk_i32 s8, 0xc025
	s_cmpk_lt_i32 s25, 0x3ffd
	v_lshl_add_u64 v[142:143], s[6:7], 0, v[90:91]
	v_lshl_add_u64 v[140:141], s[6:7], 0, v[96:97]
	v_lshl_add_u64 v[136:137], s[6:7], 0, v[98:99]
	v_lshl_add_u64 v[122:123], s[6:7], 0, v[100:101]
	s_cselect_b32 s6, s9, s8
	s_addk_i32 s6, 0x82
	s_mul_hi_i32 s7, s6, 0x9000
	s_mul_i32 s6, s6, 0x9000
	s_add_u32 s6, s2, s6
	s_addc_u32 s7, s5, s7
	s_add_u32 s20, s6, 0x1000
	v_lshl_add_u64 v[106:107], s[6:7], 0, v[90:91]
	s_addc_u32 s21, s7, 0
	v_lshl_add_u64 v[108:109], s[10:11], 0, v[90:91]
	v_lshl_add_u64 v[118:119], s[20:21], 0, v[90:91]
	v_lshl_add_u64 v[114:115], s[20:21], 0, v[96:97]
	v_lshl_add_u64 v[92:93], v[92:93], 0, s[14:15]
	s_waitcnt vmcnt(0) lgkmcnt(0)
	v_pk_mul_f32 v[144:145], v[80:81], v[80:81]
	v_pk_mul_f32 v[146:147], v[78:79], v[78:79]
	v_pk_mul_f32 v[148:149], v[76:77], v[76:77]
	v_pk_mul_f32 v[150:151], v[74:75], v[74:75]
	v_mul_f32_e32 v158, v71, v71
	v_mul_f32_e32 v160, v73, v73
	v_mul_f32_e32 v171, v68, v68
	v_mul_f32_e32 v173, v69, v69
	v_pk_mov_b32 v[162:163], v[146:147], v[144:145] op_sel:[1,0]
	v_mov_b32_e32 v147, v145
	v_pk_mov_b32 v[144:145], v[150:151], v[148:149] op_sel:[1,0]
	v_mov_b32_e32 v151, v149
	v_pk_fma_f32 v[148:149], v[70:71], v[70:71], v[158:159] op_sel_hi:[1,1,0]
	v_pk_fma_f32 v[158:159], v[72:73], v[72:73], v[160:161] op_sel_hi:[1,1,0]
	v_pk_mul_f32 v[160:161], v[64:65], v[64:65]
	v_pk_mul_f32 v[164:165], v[62:63], v[62:63]
	v_pk_mul_f32 v[166:167], v[60:61], v[60:61]
	v_pk_mul_f32 v[168:169], v[58:59], v[58:59]
	v_mul_f32_e32 v170, v55, v55
	v_mul_f32_e32 v172, v57, v57
	v_pk_add_f32 v[146:147], v[162:163], v[146:147]
	v_pk_add_f32 v[144:145], v[144:145], v[150:151]
	v_mov_b32_e32 v149, v171
	v_mov_b32_e32 v159, v173
	v_pk_mov_b32 v[150:151], v[164:165], v[160:161] op_sel:[1,0]
	v_mov_b32_e32 v165, v161
	v_pk_mov_b32 v[160:161], v[168:169], v[166:167] op_sel:[1,0]
	v_mov_b32_e32 v169, v167
	v_pk_fma_f32 v[162:163], v[54:55], v[54:55], v[170:171] op_sel_hi:[1,1,0]
	v_pk_fma_f32 v[166:167], v[56:57], v[56:57], v[172:173] op_sel_hi:[1,1,0]
	v_pk_mul_f32 v[170:171], v[48:49], v[48:49]
	v_pk_mul_f32 v[172:173], v[46:47], v[46:47]
	v_pk_mul_f32 v[174:175], v[44:45], v[44:45]
	v_pk_mul_f32 v[176:177], v[42:43], v[42:43]
	v_mul_f32_e32 v157, v66, v66
	v_mul_f32_e32 v181, v67, v67
	v_mul_f32_e32 v179, v52, v52
	v_mul_f32_e32 v186, v53, v53
	v_mul_f32_e32 v178, v39, v39
	v_mul_f32_e32 v180, v41, v41
	v_pk_add_f32 v[182:183], v[146:147], v[146:147] op_sel:[0,1] op_sel_hi:[1,0]
	v_pk_add_f32 v[184:185], v[144:145], v[144:145] op_sel:[0,1] op_sel_hi:[1,0]
	v_pk_add_f32 v[158:159], v[148:149], v[158:159]
	v_pk_add_f32 v[144:145], v[150:151], v[164:165]
	v_pk_add_f32 v[146:147], v[160:161], v[168:169]
	v_pk_mov_b32 v[148:149], v[172:173], v[170:171] op_sel:[1,0]
	v_mov_b32_e32 v173, v171
	v_pk_mov_b32 v[150:151], v[176:177], v[174:175] op_sel:[1,0]
	v_mov_b32_e32 v177, v175
	v_mul_f32_e32 v187, v50, v50
	v_mul_f32_e32 v192, v51, v51
	v_mul_f32_e32 v195, v36, v36
	v_mul_f32_e32 v196, v37, v37
	v_mov_b32_e32 v163, v179
	v_mov_b32_e32 v167, v186
	v_pk_fma_f32 v[160:161], v[38:39], v[38:39], v[178:179] op_sel_hi:[1,1,0]
	v_pk_fma_f32 v[164:165], v[40:41], v[40:41], v[180:181] op_sel_hi:[1,1,0]
	v_pk_mul_f32 v[168:169], v[32:33], v[32:33]
	v_pk_mul_f32 v[170:171], v[30:31], v[30:31]
	v_pk_mul_f32 v[174:175], v[28:29], v[28:29]
	v_pk_mul_f32 v[178:179], v[26:27], v[26:27]
	v_mov_b32_e32 v183, v157
	v_mov_b32_e32 v185, v181
	v_pk_add_f32 v[188:189], v[144:145], v[144:145] op_sel:[0,1] op_sel_hi:[1,0]
	v_pk_add_f32 v[190:191], v[146:147], v[146:147] op_sel:[0,1] op_sel_hi:[1,0]
	v_pk_add_f32 v[148:149], v[148:149], v[172:173]
	v_pk_add_f32 v[150:151], v[150:151], v[176:177]
	v_mul_f32_e32 v193, v34, v34
	v_mul_f32_e32 v194, v35, v35
	v_pk_add_f32 v[162:163], v[162:163], v[166:167]
	v_mov_b32_e32 v161, v195
	v_mov_b32_e32 v165, v196
	v_pk_mov_b32 v[166:167], v[170:171], v[168:169] op_sel:[1,0]
	v_mov_b32_e32 v171, v169
	v_pk_mov_b32 v[168:169], v[178:179], v[174:175] op_sel:[1,0]
	v_mov_b32_e32 v179, v175
	v_pk_add_f32 v[172:173], v[182:183], v[184:185]
	v_mov_b32_e32 v189, v187
	v_mov_b32_e32 v191, v192
	v_pk_add_f32 v[174:175], v[148:149], v[148:149] op_sel:[0,1] op_sel_hi:[1,0]
	v_pk_add_f32 v[176:177], v[150:151], v[150:151] op_sel:[0,1] op_sel_hi:[1,0]
	v_pk_add_f32 v[160:161], v[160:161], v[164:165]
	v_pk_add_f32 v[158:159], v[172:173], v[158:159]
	v_pk_add_f32 v[164:165], v[188:189], v[190:191]
	v_mov_b32_e32 v175, v193
	v_mov_b32_e32 v177, v194
	v_add_f32_e32 v157, v158, v159
	v_pk_add_f32 v[158:159], v[164:165], v[162:163]
	v_pk_add_f32 v[162:163], v[174:175], v[176:177]
	v_add_f32_e32 v164, v158, v159
	v_pk_add_f32 v[158:159], v[162:163], v[160:161]
	v_add_f32_e32 v158, v158, v159
	v_pk_add_f32 v[148:149], v[166:167], v[170:171]
	s_waitcnt lgkmcnt(0)
	s_nop 1
	v_add_f32_dpp v157, v157, v157 quad_perm:[1,0,3,2] row_mask:0xf bank_mask:0xf
	s_waitcnt lgkmcnt(0)
	s_nop 1
	v_add_f32_dpp v161, v164, v164 quad_perm:[1,0,3,2] row_mask:0xf bank_mask:0xf
	s_waitcnt lgkmcnt(0)
	s_nop 1
	v_add_f32_dpp v158, v158, v158 quad_perm:[1,0,3,2] row_mask:0xf bank_mask:0xf
	s_waitcnt lgkmcnt(0)
	s_nop 1
	v_add_f32_dpp v157, v157, v157 quad_perm:[2,3,0,1] row_mask:0xf bank_mask:0xf
	s_waitcnt lgkmcnt(0)
	s_nop 1
	v_add_f32_dpp v161, v161, v161 quad_perm:[2,3,0,1] row_mask:0xf bank_mask:0xf
	s_waitcnt lgkmcnt(0)
	s_nop 1
	v_add_f32_dpp v158, v158, v158 quad_perm:[2,3,0,1] row_mask:0xf bank_mask:0xf
	s_waitcnt lgkmcnt(0)
	s_nop 1
	v_add_f32_dpp v157, v157, v157 row_half_mirror row_mask:0xf bank_mask:0xf
	s_waitcnt lgkmcnt(0)
	s_nop 1
	v_add_f32_dpp v161, v161, v161 row_half_mirror row_mask:0xf bank_mask:0xf
	s_waitcnt lgkmcnt(0)
	s_nop 1
	v_add_f32_dpp v158, v158, v158 row_half_mirror row_mask:0xf bank_mask:0xf
	s_waitcnt lgkmcnt(0)
	s_nop 1
	v_add_f32_dpp v157, v157, v157 row_mirror row_mask:0xf bank_mask:0xf
	ds_bpermute_b32 v160, v153, v157
	s_waitcnt lgkmcnt(2)
	s_nop 1
	v_add_f32_dpp v161, v161, v161 row_mirror row_mask:0xf bank_mask:0xf
	ds_bpermute_b32 v162, v153, v161
	s_waitcnt lgkmcnt(2)
	s_nop 1
	v_add_f32_dpp v158, v158, v158 row_mirror row_mask:0xf bank_mask:0xf
	ds_bpermute_b32 v159, v153, v158
	s_waitcnt lgkmcnt(2)
	v_add_f32_e32 v157, v157, v160
	ds_bpermute_b32 v160, v154, v157
	s_waitcnt lgkmcnt(2)
	v_add_f32_e32 v161, v161, v162
	ds_bpermute_b32 v162, v154, v161
	s_waitcnt lgkmcnt(2)
	v_add_f32_e32 v158, v158, v159
	ds_bpermute_b32 v159, v154, v158
	s_waitcnt lgkmcnt(2)
	v_add_f32_e32 v157, v157, v160
	v_fmamk_f32 v157, v157, 0x3a800000, v155
	s_waitcnt lgkmcnt(1)
	v_add_f32_e32 v160, v161, v162
	v_mul_f32_e32 v161, 0x4f800000, v157
	v_cmp_gt_f32_e32 vcc, s3, v157
	v_fmamk_f32 v160, v160, 0x3a800000, v155
	s_waitcnt lgkmcnt(0)
	v_add_f32_e32 v158, v158, v159
	v_cndmask_b32_e32 v157, v157, v161, vcc
	v_mul_f32_e32 v159, 0x4f800000, v160
	v_cmp_gt_f32_e64 s[6:7], s3, v160
	v_sqrt_f32_e32 v161, v157
	v_fmamk_f32 v158, v158, 0x3a800000, v155
	v_cndmask_b32_e64 v159, v160, v159, s[6:7]
	v_mul_f32_e32 v160, 0x4f800000, v158
	v_cmp_gt_f32_e64 s[8:9], s3, v158
	v_sqrt_f32_e32 v162, v159
	v_add_u32_e32 v163, -1, v161
	v_cndmask_b32_e64 v158, v158, v160, s[8:9]
	v_sqrt_f32_e32 v160, v158
	v_add_u32_e32 v164, 1, v161
	v_fma_f32 v165, -v163, v161, v157
	v_fma_f32 v166, -v164, v161, v157
	v_add_u32_e32 v167, -1, v162
	v_cmp_ge_f32_e64 s[10:11], 0, v165
	v_pk_add_f32 v[150:151], v[168:169], v[178:179]
	v_add_u32_e32 v168, 1, v162
	v_cndmask_b32_e64 v161, v161, v163, s[10:11]
	v_fma_f32 v163, -v167, v162, v159
	v_cmp_lt_f32_e64 s[10:11], 0, v166
	v_fma_f32 v165, -v168, v162, v159
	v_add_u32_e32 v169, -1, v160
	v_cndmask_b32_e64 v161, v161, v164, s[10:11]
	v_cmp_ge_f32_e64 s[10:11], 0, v163
	v_add_u32_e32 v170, 1, v160
	v_fma_f32 v163, -v169, v160, v158
	v_cndmask_b32_e64 v162, v162, v167, s[10:11]
	v_cmp_lt_f32_e64 s[10:11], 0, v165
	v_fma_f32 v164, -v170, v160, v158
	v_mul_f32_e32 v165, 0x37800000, v161
	v_cndmask_b32_e64 v162, v162, v168, s[10:11]
	v_cmp_ge_f32_e64 s[10:11], 0, v163
	v_cndmask_b32_e32 v161, v161, v165, vcc
	v_cmp_class_f32_e32 vcc, v157, v156
	v_cndmask_b32_e64 v160, v160, v169, s[10:11]
	v_cmp_lt_f32_e64 s[10:11], 0, v164
	v_mul_f32_e32 v163, 0x37800000, v162
	v_cndmask_b32_e32 v157, v161, v157, vcc
	v_cndmask_b32_e64 v160, v160, v170, s[10:11]
	v_cndmask_b32_e64 v161, v162, v163, s[6:7]
	v_cmp_class_f32_e32 vcc, v159, v156
	v_mul_f32_e32 v162, 0x37800000, v160
	v_div_scale_f32 v163, s[6:7], v157, v157, 1.0
	v_cndmask_b32_e32 v159, v161, v159, vcc
	v_cndmask_b32_e64 v160, v160, v162, s[8:9]
	v_cmp_class_f32_e32 vcc, v158, v156
	v_rcp_f32_e32 v161, v163
	v_div_scale_f32 v162, s[8:9], v159, v159, 1.0
	v_cndmask_b32_e32 v160, v160, v158, vcc
	v_rcp_f32_e32 v166, v162
	v_div_scale_f32 v167, s[10:11], v160, v160, 1.0
	v_rcp_f32_e32 v169, v167
	v_fma_f32 v158, -v163, v161, 1.0
	v_div_scale_f32 v164, s[6:7], 1.0, v157, 1.0
	v_fmac_f32_e32 v161, v158, v161
	v_fma_f32 v158, -v162, v166, 1.0
	v_mul_f32_e32 v170, v164, v161
	v_div_scale_f32 v165, s[8:9], 1.0, v159, 1.0
	v_fmac_f32_e32 v166, v158, v166
	v_fma_f32 v158, -v167, v169, 1.0
	v_fma_f32 v171, -v163, v170, v164
	v_div_scale_f32 v168, s[10:11], 1.0, v160, 1.0
	v_mul_f32_e32 v172, v165, v166
	v_fmac_f32_e32 v169, v158, v169
	v_fmac_f32_e32 v170, v171, v161
	v_fma_f32 v158, -v162, v172, v165
	v_mul_f32_e32 v171, v168, v169
	v_fma_f32 v163, -v163, v170, v164
	s_mov_b64 vcc, s[6:7]
	v_fmac_f32_e32 v172, v158, v166
	v_fma_f32 v158, -v167, v171, v168
	v_div_fmas_f32 v161, v163, v161, v170
	v_fma_f32 v162, -v162, v172, v165
	v_fmac_f32_e32 v171, v158, v169
	v_div_fixup_f32 v158, v161, v157, 1.0
	s_mov_b64 vcc, s[8:9]
	v_div_fmas_f32 v157, v162, v166, v172
	v_fma_f32 v161, -v167, v171, v168
	v_pk_mul_f32 v[80:81], v[80:81], v[158:159] op_sel_hi:[1,0]
	v_pk_mul_f32 v[78:79], v[78:79], v[158:159] op_sel_hi:[1,0]
	s_mov_b64 vcc, s[10:11]
	v_pk_add_f32 v[88:89], v[88:89], 1.0 op_sel_hi:[1,0]
	v_pk_add_f32 v[86:87], v[86:87], 1.0 op_sel_hi:[1,0]
	v_pk_mul_f32 v[76:77], v[76:77], v[158:159] op_sel_hi:[1,0]
	v_pk_mul_f32 v[74:75], v[74:75], v[158:159] op_sel_hi:[1,0]
	v_pk_mul_f32 v[72:73], v[72:73], v[158:159] op_sel_hi:[1,0]
	v_pk_mul_f32 v[70:71], v[70:71], v[158:159] op_sel_hi:[1,0]
	v_pk_mul_f32 v[68:69], v[68:69], v[158:159] op_sel_hi:[1,0]
	v_pk_mul_f32 v[66:67], v[66:67], v[158:159] op_sel_hi:[1,0]
	v_div_fixup_f32 v158, v157, v159, 1.0
	v_div_fmas_f32 v157, v161, v169, v171
	v_pk_mul_f32 v[78:79], v[78:79], v[2:3]
	v_pk_mul_f32 v[80:81], v[80:81], v[4:5]
	v_pk_mul_f32 v[64:65], v[64:65], v[158:159] op_sel_hi:[1,0]
	v_pk_mul_f32 v[62:63], v[62:63], v[158:159] op_sel_hi:[1,0]
	v_pk_mul_f32 v[60:61], v[60:61], v[158:159] op_sel_hi:[1,0]
	v_pk_mul_f32 v[58:59], v[58:59], v[158:159] op_sel_hi:[1,0]
	v_pk_mul_f32 v[56:57], v[56:57], v[158:159] op_sel_hi:[1,0]
	v_pk_mul_f32 v[54:55], v[54:55], v[158:159] op_sel_hi:[1,0]
	v_pk_mul_f32 v[52:53], v[52:53], v[158:159] op_sel_hi:[1,0]
	v_pk_mul_f32 v[158:159], v[50:51], v[158:159] op_sel_hi:[1,0]
	v_div_fixup_f32 v50, v157, v160, 1.0
	v_pk_fma_f32 v[80:81], v[80:81], v[88:89], v[84:85]
	v_pk_fma_f32 v[78:79], v[78:79], v[86:87], v[82:83]
	v_pk_mul_f32 v[86:87], v[52:53], v[16:17]
	v_pk_mul_f32 v[48:49], v[48:49], v[50:51] op_sel_hi:[1,0]
	v_pk_mul_f32 v[46:47], v[46:47], v[50:51] op_sel_hi:[1,0]
	v_pk_mul_f32 v[82:83], v[54:55], v[10:11]
	v_pk_mul_f32 v[84:85], v[158:159], v[14:15]
	v_pk_mul_f32 v[88:89], v[46:47], v[2:3]
	v_pk_mul_f32 v[158:159], v[48:49], v[4:5]
	v_cvt_pk_bf16_f32 v46, v78, v79
	v_cvt_pk_bf16_f32 v47, v80, v81
	global_store_dwordx2 v[102:103], v[46:47], off
	global_load_dwordx4 v[46:49], v[138:139], off
	s_nop 0
	global_load_dwordx4 v[52:55], v[124:125], off offset:1024
	v_pk_mul_f32 v[74:75], v[74:75], v[6:7]
	v_pk_mul_f32 v[76:77], v[76:77], v[8:9]
	v_pk_mul_f32 v[70:71], v[70:71], v[10:11]
	v_pk_mul_f32 v[72:73], v[72:73], v[12:13]
	v_pk_mul_f32 v[66:67], v[66:67], v[14:15]
	v_pk_mul_f32 v[68:69], v[68:69], v[16:17]
	v_pk_mul_f32 v[62:63], v[62:63], v[2:3]
	v_pk_mul_f32 v[64:65], v[64:65], v[4:5]
	v_pk_mul_f32 v[58:59], v[58:59], v[6:7]
	v_pk_mul_f32 v[60:61], v[60:61], v[8:9]
	v_pk_mul_f32 v[56:57], v[56:57], v[12:13]
	v_mul_f32_e32 v180, v23, v23
	v_mul_f32_e32 v186, v25, v25
	v_mul_f32_e32 v197, v18, v18
	v_mul_f32_e32 v198, v19, v19
	v_mul_f32_e32 v199, v20, v20
	v_mul_f32_e32 v200, v21, v21
	v_pk_fma_f32 v[144:145], v[22:23], v[22:23], v[180:181] op_sel_hi:[1,1,0]
	v_pk_fma_f32 v[146:147], v[24:25], v[24:25], v[186:187] op_sel_hi:[1,1,0]
	v_mov_b32_e32 v145, v199
	v_mov_b32_e32 v147, v200
	v_lshl_add_u64 v[94:95], v[94:95], 0, s[18:19]
	s_mov_b32 s8, s25
	s_cmp_lt_i32 s25, s13
	s_waitcnt vmcnt(0) lgkmcnt(0)
	v_pk_add_f32 v[48:49], v[48:49], 1.0 op_sel_hi:[1,0]
	v_pk_add_f32 v[46:47], v[46:47], 1.0 op_sel_hi:[1,0]
	v_pk_fma_f32 v[48:49], v[76:77], v[48:49], v[54:55]
	v_pk_fma_f32 v[46:47], v[74:75], v[46:47], v[52:53]
	v_cvt_pk_bf16_f32 v46, v46, v47
	v_cvt_pk_bf16_f32 v47, v48, v49
	global_store_dwordx2 v[102:103], v[46:47], off offset:512
	global_load_dwordx4 v[46:49], v[134:135], off
	s_nop 0
	global_load_dwordx4 v[52:55], v[124:125], off offset:2048
	s_waitcnt vmcnt(0) lgkmcnt(0)
	v_pk_add_f32 v[48:49], v[48:49], 1.0 op_sel_hi:[1,0]
	v_pk_add_f32 v[46:47], v[46:47], 1.0 op_sel_hi:[1,0]
	v_pk_fma_f32 v[48:49], v[72:73], v[48:49], v[54:55]
	v_pk_fma_f32 v[46:47], v[70:71], v[46:47], v[52:53]
	v_cvt_pk_bf16_f32 v46, v46, v47
	v_cvt_pk_bf16_f32 v47, v48, v49
	global_store_dwordx2 v[102:103], v[46:47], off offset:1024
	global_load_dwordx4 v[46:49], v[128:129], off
	s_nop 0
	global_load_dwordx4 v[52:55], v[124:125], off offset:3072
	s_waitcnt vmcnt(0) lgkmcnt(0)
	v_pk_add_f32 v[48:49], v[48:49], 1.0 op_sel_hi:[1,0]
	v_pk_add_f32 v[46:47], v[46:47], 1.0 op_sel_hi:[1,0]
	v_pk_fma_f32 v[48:49], v[68:69], v[48:49], v[54:55]
	v_pk_fma_f32 v[46:47], v[66:67], v[46:47], v[52:53]
	v_cvt_pk_bf16_f32 v46, v46, v47
	v_cvt_pk_bf16_f32 v47, v48, v49
	global_store_dwordx2 v[102:103], v[46:47], off offset:1536
	global_load_dwordx4 v[46:49], v[126:127], off
	s_nop 0
	global_load_dwordx4 v[52:55], v[110:111], off
	s_waitcnt vmcnt(0) lgkmcnt(0)
	v_pk_add_f32 v[48:49], v[48:49], 1.0 op_sel_hi:[1,0]
	v_pk_add_f32 v[46:47], v[46:47], 1.0 op_sel_hi:[1,0]
	v_pk_fma_f32 v[48:49], v[64:65], v[48:49], v[54:55]
	v_pk_fma_f32 v[46:47], v[62:63], v[46:47], v[52:53]
	v_cvt_pk_bf16_f32 v46, v46, v47
	v_cvt_pk_bf16_f32 v47, v48, v49
	global_store_dwordx2 v[102:103], v[46:47], off offset:2048
	global_load_dwordx4 v[46:49], v[120:121], off
	s_nop 0
	global_load_dwordx4 v[52:55], v[110:111], off offset:1024
	s_waitcnt vmcnt(0) lgkmcnt(0)
	v_pk_add_f32 v[48:49], v[48:49], 1.0 op_sel_hi:[1,0]
	v_pk_add_f32 v[46:47], v[46:47], 1.0 op_sel_hi:[1,0]
	v_pk_fma_f32 v[48:49], v[60:61], v[48:49], v[54:55]
	v_pk_fma_f32 v[46:47], v[58:59], v[46:47], v[52:53]
	v_cvt_pk_bf16_f32 v46, v46, v47
	v_cvt_pk_bf16_f32 v47, v48, v49
	global_store_dwordx2 v[102:103], v[46:47], off offset:2560
	global_load_dwordx4 v[46:49], v[116:117], off
	s_nop 0
	global_load_dwordx4 v[52:55], v[110:111], off offset:2048
	v_pk_add_f32 v[58:59], v[150:151], v[150:151] op_sel:[0,1] op_sel_hi:[1,0]
	v_pk_add_f32 v[60:61], v[144:145], v[146:147]
	v_mov_b32_e32 v59, v198
	s_waitcnt vmcnt(0) lgkmcnt(0)
	v_pk_add_f32 v[48:49], v[48:49], 1.0 op_sel_hi:[1,0]
	v_pk_add_f32 v[46:47], v[46:47], 1.0 op_sel_hi:[1,0]
	v_pk_fma_f32 v[48:49], v[56:57], v[48:49], v[54:55]
	v_pk_fma_f32 v[46:47], v[82:83], v[46:47], v[52:53]
	v_cvt_pk_bf16_f32 v46, v46, v47
	v_cvt_pk_bf16_f32 v47, v48, v49
	global_store_dwordx2 v[102:103], v[46:47], off offset:3072
	global_load_dwordx4 v[46:49], v[112:113], off
	s_nop 0
	global_load_dwordx4 v[52:55], v[110:111], off offset:3072
	v_pk_add_f32 v[56:57], v[148:149], v[148:149] op_sel:[0,1] op_sel_hi:[1,0]
	s_waitcnt vmcnt(0) lgkmcnt(0)
	v_pk_add_f32 v[48:49], v[48:49], 1.0 op_sel_hi:[1,0]
	v_pk_add_f32 v[46:47], v[46:47], 1.0 op_sel_hi:[1,0]
	v_pk_fma_f32 v[48:49], v[86:87], v[48:49], v[54:55]
	v_pk_fma_f32 v[46:47], v[84:85], v[46:47], v[52:53]
	v_cvt_pk_bf16_f32 v46, v46, v47
	v_cvt_pk_bf16_f32 v47, v48, v49
	global_store_dwordx2 v[102:103], v[46:47], off offset:3584
	global_load_dwordx4 v[46:49], v[142:143], off
	s_nop 0
	global_load_dwordx4 v[52:55], v[108:109], off
	v_mov_b32_e32 v57, v197
	s_waitcnt vmcnt(0) lgkmcnt(0)
	v_pk_add_f32 v[48:49], v[48:49], 1.0 op_sel_hi:[1,0]
	v_pk_add_f32 v[46:47], v[46:47], 1.0 op_sel_hi:[1,0]
	v_pk_fma_f32 v[48:49], v[158:159], v[48:49], v[54:55]
	v_pk_fma_f32 v[46:47], v[88:89], v[46:47], v[52:53]
	v_bfe_u32 v51, v46, 16, 1
	v_bfe_u32 v52, v47, 16, 1
	v_add3_u32 v46, v46, v51, s4
	v_add3_u32 v47, v47, v52, s4
	v_lshrrev_b32_e32 v46, 16, v46
	v_and_or_b32 v46, v47, s22, v46
	v_cvt_pk_bf16_f32 v47, v48, v49
	global_store_dwordx2 v[104:105], v[46:47], off
	global_load_dwordx4 v[46:49], v[140:141], off
	s_nop 0
	global_load_dwordx4 v[52:55], v[108:109], off offset:1024
	v_pk_mul_f32 v[44:45], v[44:45], v[50:51] op_sel_hi:[1,0]
	v_pk_mul_f32 v[42:43], v[42:43], v[50:51] op_sel_hi:[1,0]
	v_pk_mul_f32 v[44:45], v[44:45], v[8:9]
	v_pk_mul_f32 v[42:43], v[42:43], v[6:7]
	s_waitcnt vmcnt(0) lgkmcnt(0)
	v_pk_add_f32 v[48:49], v[48:49], 1.0 op_sel_hi:[1,0]
	v_pk_add_f32 v[46:47], v[46:47], 1.0 op_sel_hi:[1,0]
	v_pk_fma_f32 v[44:45], v[44:45], v[48:49], v[54:55]
	v_pk_fma_f32 v[42:43], v[42:43], v[46:47], v[52:53]
	v_cvt_pk_bf16_f32 v42, v42, v43
	v_cvt_pk_bf16_f32 v43, v44, v45
	global_store_dwordx2 v[104:105], v[42:43], off offset:512
	global_load_dwordx4 v[42:45], v[136:137], off
	s_nop 0
	global_load_dwordx4 v[46:49], v[108:109], off offset:2048
	v_pk_add_f32 v[52:53], v[56:57], v[58:59]
	s_waitcnt vmcnt(0) lgkmcnt(0)
	v_pk_add_f32 v[44:45], v[44:45], 1.0 op_sel_hi:[1,0]
	v_pk_add_f32 v[52:53], v[52:53], v[60:61]
	v_pk_add_f32 v[42:43], v[42:43], 1.0 op_sel_hi:[1,0]
	v_add_f32_e32 v51, v52, v53
	s_waitcnt lgkmcnt(0)
	s_nop 1
	v_add_f32_dpp v51, v51, v51 quad_perm:[1,0,3,2] row_mask:0xf bank_mask:0xf
	s_waitcnt lgkmcnt(0)
	s_nop 1
	v_add_f32_dpp v51, v51, v51 quad_perm:[2,3,0,1] row_mask:0xf bank_mask:0xf
	v_pk_mul_f32 v[40:41], v[40:41], v[50:51] op_sel_hi:[1,0]
	v_pk_mul_f32 v[38:39], v[38:39], v[50:51] op_sel_hi:[1,0]
	v_pk_mul_f32 v[40:41], v[40:41], v[12:13]
	v_pk_mul_f32 v[38:39], v[38:39], v[10:11]
	v_pk_fma_f32 v[40:41], v[40:41], v[44:45], v[48:49]
	v_pk_fma_f32 v[38:39], v[38:39], v[42:43], v[46:47]
	v_cvt_pk_bf16_f32 v38, v38, v39
	v_cvt_pk_bf16_f32 v39, v40, v41
	global_store_dwordx2 v[104:105], v[38:39], off offset:1024
	global_load_dwordx4 v[38:41], v[122:123], off
	s_nop 0
	global_load_dwordx4 v[42:45], v[108:109], off offset:3072
	v_pk_mul_f32 v[36:37], v[36:37], v[50:51] op_sel_hi:[1,0]
	v_pk_mul_f32 v[34:35], v[34:35], v[50:51] op_sel_hi:[1,0]
	v_pk_mul_f32 v[36:37], v[36:37], v[16:17]
	v_pk_mul_f32 v[34:35], v[34:35], v[14:15]
	s_waitcnt lgkmcnt(0)
	s_nop 1
	v_add_f32_dpp v46, v51, v51 row_half_mirror row_mask:0xf bank_mask:0xf
	s_waitcnt lgkmcnt(0)
	s_nop 1
	v_add_f32_dpp v46, v46, v46 row_mirror row_mask:0xf bank_mask:0xf
	ds_bpermute_b32 v47, v153, v46
	s_waitcnt lgkmcnt(0)
	v_add_f32_e32 v46, v46, v47
	ds_bpermute_b32 v47, v154, v46
	s_waitcnt lgkmcnt(0)
	v_add_f32_e32 v46, v46, v47
	v_fmamk_f32 v46, v46, 0x3a800000, v155
	v_mul_f32_e32 v47, 0x4f800000, v46
	v_cmp_gt_f32_e32 vcc, s3, v46
	s_waitcnt vmcnt(0)
	v_pk_add_f32 v[40:41], v[40:41], 1.0 op_sel_hi:[1,0]
	v_pk_add_f32 v[38:39], v[38:39], 1.0 op_sel_hi:[1,0]
	v_pk_fma_f32 v[36:37], v[36:37], v[40:41], v[44:45]
	v_pk_fma_f32 v[34:35], v[34:35], v[38:39], v[42:43]
	v_cvt_pk_bf16_f32 v34, v34, v35
	v_cvt_pk_bf16_f32 v35, v36, v37
	global_store_dwordx2 v[104:105], v[34:35], off offset:1536
	global_load_dwordx4 v[34:37], v[118:119], off
	s_nop 0
	global_load_dwordx4 v[38:41], v[106:107], off
	v_cndmask_b32_e32 v42, v46, v47, vcc
	v_sqrt_f32_e32 v43, v42
	s_waitcnt vmcnt(0) lgkmcnt(0)
	v_pk_add_f32 v[36:37], v[36:37], 1.0 op_sel_hi:[1,0]
	v_add_u32_e32 v44, -1, v43
	v_add_u32_e32 v45, 1, v43
	v_fma_f32 v46, -v44, v43, v42
	v_fma_f32 v47, -v45, v43, v42
	v_cmp_ge_f32_e64 s[6:7], 0, v46
	v_pk_add_f32 v[34:35], v[34:35], 1.0 op_sel_hi:[1,0]
	s_nop 0
	v_cndmask_b32_e64 v43, v43, v44, s[6:7]
	v_cmp_lt_f32_e64 s[6:7], 0, v47
	s_nop 1
	v_cndmask_b32_e64 v43, v43, v45, s[6:7]
	v_mul_f32_e32 v44, 0x37800000, v43
	v_cndmask_b32_e32 v43, v43, v44, vcc
	v_cmp_class_f32_e32 vcc, v42, v156
	s_nop 1
	v_cndmask_b32_e32 v42, v43, v42, vcc
	v_div_scale_f32 v43, s[6:7], v42, v42, 1.0
	v_rcp_f32_e32 v45, v43
	v_div_scale_f32 v44, vcc, 1.0, v42, 1.0
	v_fma_f32 v46, -v43, v45, 1.0
	v_fmac_f32_e32 v45, v46, v45
	v_mul_f32_e32 v46, v44, v45
	v_fma_f32 v47, -v43, v46, v44
	v_fmac_f32_e32 v46, v47, v45
	v_fma_f32 v43, -v43, v46, v44
	v_div_fmas_f32 v43, v43, v45, v46
	v_div_fixup_f32 v42, v43, v42, 1.0
	v_pk_mul_f32 v[32:33], v[32:33], v[42:43] op_sel_hi:[1,0]
	v_pk_mul_f32 v[30:31], v[30:31], v[42:43] op_sel_hi:[1,0]
	v_pk_mul_f32 v[32:33], v[32:33], v[4:5]
	v_pk_mul_f32 v[30:31], v[30:31], v[2:3]
	v_pk_fma_f32 v[32:33], v[32:33], v[36:37], v[40:41]
	v_pk_fma_f32 v[30:31], v[30:31], v[34:35], v[38:39]
	v_cvt_pk_bf16_f32 v30, v30, v31
	v_cvt_pk_bf16_f32 v31, v32, v33
	global_store_dwordx2 v[104:105], v[30:31], off offset:2048
	global_load_dwordx4 v[30:33], v[114:115], off
	s_nop 0
	global_load_dwordx4 v[34:37], v[106:107], off offset:1024
	v_pk_mul_f32 v[28:29], v[28:29], v[42:43] op_sel_hi:[1,0]
	v_pk_mul_f32 v[26:27], v[26:27], v[42:43] op_sel_hi:[1,0]
	v_pk_mul_f32 v[28:29], v[28:29], v[8:9]
	v_pk_mul_f32 v[26:27], v[26:27], v[6:7]
	v_lshl_add_u64 v[38:39], s[20:21], 0, v[98:99]
	v_pk_mul_f32 v[24:25], v[24:25], v[42:43] op_sel_hi:[1,0]
	v_pk_mul_f32 v[22:23], v[22:23], v[42:43] op_sel_hi:[1,0]
	v_pk_mul_f32 v[24:25], v[24:25], v[12:13]
	v_pk_mul_f32 v[22:23], v[22:23], v[10:11]
	v_pk_mul_f32 v[20:21], v[20:21], v[42:43] op_sel_hi:[1,0]
	v_pk_mul_f32 v[18:19], v[18:19], v[42:43] op_sel_hi:[1,0]
	v_pk_mul_f32 v[20:21], v[20:21], v[16:17]
	v_pk_mul_f32 v[18:19], v[18:19], v[14:15]
	s_waitcnt vmcnt(0) lgkmcnt(0)
	v_pk_add_f32 v[32:33], v[32:33], 1.0 op_sel_hi:[1,0]
	v_pk_add_f32 v[30:31], v[30:31], 1.0 op_sel_hi:[1,0]
	v_pk_fma_f32 v[28:29], v[28:29], v[32:33], v[36:37]
	v_pk_fma_f32 v[26:27], v[26:27], v[30:31], v[34:35]
	v_cvt_pk_bf16_f32 v26, v26, v27
	v_cvt_pk_bf16_f32 v27, v28, v29
	global_store_dwordx2 v[104:105], v[26:27], off offset:2560
	global_load_dwordx4 v[26:29], v[38:39], off
	s_nop 0
	global_load_dwordx4 v[30:33], v[106:107], off offset:2048
	v_lshl_add_u64 v[34:35], s[20:21], 0, v[100:101]
	s_waitcnt vmcnt(0) lgkmcnt(0)
	v_pk_add_f32 v[28:29], v[28:29], 1.0 op_sel_hi:[1,0]
	v_pk_add_f32 v[26:27], v[26:27], 1.0 op_sel_hi:[1,0]
	v_pk_fma_f32 v[24:25], v[24:25], v[28:29], v[32:33]
	v_pk_fma_f32 v[22:23], v[22:23], v[26:27], v[30:31]
	v_cvt_pk_bf16_f32 v22, v22, v23
	v_cvt_pk_bf16_f32 v23, v24, v25
	global_store_dwordx2 v[104:105], v[22:23], off offset:3072
	global_load_dwordx4 v[22:25], v[34:35], off
	s_nop 0
	global_load_dwordx4 v[26:29], v[106:107], off offset:3072
	s_waitcnt vmcnt(0) lgkmcnt(0)
	v_pk_add_f32 v[24:25], v[24:25], 1.0 op_sel_hi:[1,0]
	v_pk_add_f32 v[22:23], v[22:23], 1.0 op_sel_hi:[1,0]
	v_pk_fma_f32 v[20:21], v[20:21], v[24:25], v[28:29]
	v_pk_fma_f32 v[18:19], v[18:19], v[22:23], v[26:27]
	v_cvt_pk_bf16_f32 v18, v18, v19
	v_cvt_pk_bf16_f32 v19, v20, v21
	global_store_dwordx2 v[104:105], v[18:19], off offset:3584
	s_cbranch_scc1 .LBB0_3611

.LBB0_5351:
	v_mul_f32_e32 v149, v11, v95
	v_fmac_f32_e32 v149, v10, v94
	v_fmac_f32_e32 v149, v12, v96
	v_fmac_f32_e32 v149, v13, v97
	v_sub_u32_e32 v148, 0x800, v144
	v_cvt_f32_u32_e32 v148, v148
	v_cmp_gt_i32_e32 vcc, s2, v144
	s_waitcnt vmcnt(0)
	v_pk_mul_f32 v[154:155], v[12:13], v[92:93]
	s_waitcnt lgkmcnt(0)
	v_add_f32_dpp v149, v149, v149 quad_perm:[1,0,3,2] row_mask:0xf bank_mask:0xf
	v_cmp_gt_i32_e64 s[10:11], s2, v147
	v_pk_mul_f32 v[158:159], v[12:13], v[88:89]
	v_cmp_gt_i32_e64 s[12:13], s2, v146
	v_pk_mul_f32 v[160:161], v[10:11], v[82:83]
	s_waitcnt lgkmcnt(0)
	v_add_f32_dpp v149, v149, v149 quad_perm:[2,3,0,1] row_mask:0xf bank_mask:0xf
	v_cmp_gt_i32_e64 s[14:15], s2, v145
	s_waitcnt lgkmcnt(0)
	v_add_f32_dpp v149, v149, v149 row_half_mirror row_mask:0xf bank_mask:0xf
	s_waitcnt lgkmcnt(0)
	s_nop 0
	v_add_f32_dpp v149, v149, v149 row_mirror row_mask:0xf bank_mask:0xf
	v_fma_f32 v149, -v127, v148, v149
	v_cndmask_b32_e32 v153, v135, v149, vcc
	v_mul_f32_e32 v149, v15, v95
	v_fmac_f32_e32 v149, v14, v94
	v_fmac_f32_e32 v149, v16, v96
	v_fmac_f32_e32 v149, v17, v97
	s_waitcnt lgkmcnt(0)
	s_nop 0
	v_add_f32_dpp v149, v149, v149 quad_perm:[1,0,3,2] row_mask:0xf bank_mask:0xf
	s_waitcnt lgkmcnt(0)
	s_nop 0
	v_add_f32_dpp v149, v149, v149 quad_perm:[2,3,0,1] row_mask:0xf bank_mask:0xf
	s_waitcnt lgkmcnt(0)
	s_nop 0
	v_add_f32_dpp v151, v149, v149 row_half_mirror row_mask:0xf bank_mask:0xf
	v_mul_f32_e32 v149, v19, v95
	v_mul_f32_e32 v95, v23, v95
	v_fmac_f32_e32 v149, v18, v94
	v_fmac_f32_e32 v95, v22, v94
	v_fmac_f32_e32 v149, v20, v96
	v_fmac_f32_e32 v95, v24, v96
	v_fmac_f32_e32 v149, v21, v97
	v_fmac_f32_e32 v95, v25, v97
	v_mul_f32_e32 v97, v11, v91
	v_fmac_f32_e32 v97, v10, v90
	v_add_f32_e32 v97, v154, v97
	v_add_f32_e32 v97, v155, v97
	ds_bpermute_b32 v152, v141, v151
	s_waitcnt lgkmcnt(0)
	v_add_f32_dpp v97, v97, v97 quad_perm:[1,0,3,2] row_mask:0xf bank_mask:0xf
	s_waitcnt lgkmcnt(0)
	s_nop 1
	v_add_f32_dpp v94, v95, v95 quad_perm:[1,0,3,2] row_mask:0xf bank_mask:0xf
	s_waitcnt lgkmcnt(0)
	v_add_f32_dpp v149, v149, v149 quad_perm:[1,0,3,2] row_mask:0xf bank_mask:0xf
	s_waitcnt lgkmcnt(0)
	v_add_f32_dpp v97, v97, v97 quad_perm:[2,3,0,1] row_mask:0xf bank_mask:0xf
	s_waitcnt lgkmcnt(0)
	v_add_f32_dpp v94, v94, v94 quad_perm:[2,3,0,1] row_mask:0xf bank_mask:0xf
	s_waitcnt lgkmcnt(0)
	v_add_f32_dpp v149, v149, v149 quad_perm:[2,3,0,1] row_mask:0xf bank_mask:0xf
	s_waitcnt lgkmcnt(0)
	v_add_f32_dpp v97, v97, v97 row_half_mirror row_mask:0xf bank_mask:0xf
	s_waitcnt lgkmcnt(0)
	v_add_f32_dpp v94, v94, v94 row_half_mirror row_mask:0xf bank_mask:0xf
	v_sub_u32_e32 v95, 0x7fc, v144
	v_cvt_f32_u32_e32 v95, v95
	s_waitcnt lgkmcnt(0)
	v_add_f32_dpp v149, v149, v149 row_half_mirror row_mask:0xf bank_mask:0xf
	s_waitcnt lgkmcnt(0)
	v_add_f32_dpp v97, v97, v97 row_mirror row_mask:0xf bank_mask:0xf
	ds_bpermute_b32 v150, v141, v149
	v_fma_f32 v97, -v127, v95, v97
	v_cndmask_b32_e64 v156, v135, v97, s[10:11]
	v_mul_f32_e32 v97, v15, v91
	v_fmac_f32_e32 v97, v14, v90
	v_fmac_f32_e32 v97, v16, v92
	v_fmac_f32_e32 v97, v17, v93
	v_max3_f32 v162, v153, s33, v156
	ds_bpermute_b32 v96, v141, v94
	s_waitcnt lgkmcnt(0)
	v_add_f32_dpp v97, v97, v97 quad_perm:[1,0,3,2] row_mask:0xf bank_mask:0xf
	s_waitcnt lgkmcnt(0)
	s_nop 0
	v_add_f32_dpp v97, v97, v97 quad_perm:[2,3,0,1] row_mask:0xf bank_mask:0xf
	s_waitcnt lgkmcnt(0)
	s_nop 0
	v_add_f32_dpp v154, v97, v97 row_half_mirror row_mask:0xf bank_mask:0xf
	v_mul_f32_e32 v97, v19, v91
	v_mul_f32_e32 v91, v23, v91
	v_fmac_f32_e32 v97, v18, v90
	v_fmac_f32_e32 v91, v22, v90
	v_fmac_f32_e32 v97, v20, v92
	v_fmac_f32_e32 v91, v24, v92
	v_fmac_f32_e32 v97, v21, v93
	v_fmac_f32_e32 v91, v25, v93
	v_mul_f32_e32 v93, v11, v87
	v_fmac_f32_e32 v93, v10, v86
	v_add_f32_e32 v93, v158, v93
	v_add_f32_e32 v93, v159, v93
	ds_bpermute_b32 v155, v141, v154
	s_waitcnt lgkmcnt(0)
	v_add_f32_dpp v93, v93, v93 quad_perm:[1,0,3,2] row_mask:0xf bank_mask:0xf
	s_waitcnt lgkmcnt(0)
	s_nop 1
	v_add_f32_dpp v90, v91, v91 quad_perm:[1,0,3,2] row_mask:0xf bank_mask:0xf
	s_waitcnt lgkmcnt(0)
	v_add_f32_dpp v97, v97, v97 quad_perm:[1,0,3,2] row_mask:0xf bank_mask:0xf
	s_waitcnt lgkmcnt(0)
	v_add_f32_dpp v93, v93, v93 quad_perm:[2,3,0,1] row_mask:0xf bank_mask:0xf
	s_waitcnt lgkmcnt(0)
	v_add_f32_dpp v90, v90, v90 quad_perm:[2,3,0,1] row_mask:0xf bank_mask:0xf
	s_waitcnt lgkmcnt(0)
	v_add_f32_dpp v97, v97, v97 quad_perm:[2,3,0,1] row_mask:0xf bank_mask:0xf
	s_waitcnt lgkmcnt(0)
	v_add_f32_dpp v93, v93, v93 row_half_mirror row_mask:0xf bank_mask:0xf
	s_waitcnt lgkmcnt(0)
	s_nop 1
	v_add_f32_dpp v91, v90, v90 row_half_mirror row_mask:0xf bank_mask:0xf
	v_sub_u32_e32 v90, 0x7f8, v144
	v_cvt_f32_u32_e32 v90, v90
	s_waitcnt lgkmcnt(0)
	v_add_f32_dpp v97, v97, v97 row_half_mirror row_mask:0xf bank_mask:0xf
	s_waitcnt lgkmcnt(0)
	v_add_f32_dpp v93, v93, v93 row_mirror row_mask:0xf bank_mask:0xf
	ds_bpermute_b32 v147, v141, v97
	v_fma_f32 v93, -v127, v90, v93
	v_cndmask_b32_e64 v159, v135, v93, s[12:13]
	v_mul_f32_e32 v93, v15, v87
	v_fmac_f32_e32 v93, v14, v86
	v_fmac_f32_e32 v93, v16, v88
	v_fmac_f32_e32 v93, v17, v89
	ds_bpermute_b32 v92, v141, v91
	s_waitcnt lgkmcnt(0)
	v_add_f32_dpp v93, v93, v93 quad_perm:[1,0,3,2] row_mask:0xf bank_mask:0xf
	s_waitcnt lgkmcnt(0)
	s_nop 0
	v_add_f32_dpp v93, v93, v93 quad_perm:[2,3,0,1] row_mask:0xf bank_mask:0xf
	s_waitcnt lgkmcnt(0)
	s_nop 0
	v_add_f32_dpp v157, v93, v93 row_half_mirror row_mask:0xf bank_mask:0xf
	v_mul_f32_e32 v93, v19, v87
	v_mul_f32_e32 v87, v23, v87
	v_fmac_f32_e32 v87, v22, v86
	v_fmac_f32_e32 v87, v24, v88
	v_fmac_f32_e32 v87, v25, v89
	v_fmac_f32_e32 v93, v18, v86
	v_fmac_f32_e32 v93, v20, v88
	v_fmac_f32_e32 v93, v21, v89
	v_add_f32_e32 v89, v160, v161
	s_waitcnt lgkmcnt(0)
	s_nop 1
	v_add_f32_dpp v86, v87, v87 quad_perm:[1,0,3,2] row_mask:0xf bank_mask:0xf
	ds_bpermute_b32 v158, v141, v157
	s_waitcnt lgkmcnt(0)
	v_add_f32_dpp v93, v93, v93 quad_perm:[1,0,3,2] row_mask:0xf bank_mask:0xf
	s_waitcnt lgkmcnt(0)
	v_add_f32_dpp v86, v86, v86 quad_perm:[2,3,0,1] row_mask:0xf bank_mask:0xf
	s_waitcnt lgkmcnt(0)
	v_add_f32_dpp v93, v93, v93 quad_perm:[2,3,0,1] row_mask:0xf bank_mask:0xf
	s_waitcnt lgkmcnt(0)
	v_add_f32_dpp v86, v86, v86 row_half_mirror row_mask:0xf bank_mask:0xf
	v_sub_u32_e32 v87, 0x7f4, v144
	v_pk_mul_f32 v[144:145], v[12:13], v[84:85]
	v_cvt_f32_u32_e32 v87, v87
	v_add_f32_e32 v89, v144, v89
	v_add_f32_e32 v89, v145, v89
	s_waitcnt lgkmcnt(0)
	v_add_f32_dpp v93, v93, v93 row_half_mirror row_mask:0xf bank_mask:0xf
	ds_bpermute_b32 v146, v141, v93
	ds_bpermute_b32 v88, v141, v86
	s_waitcnt lgkmcnt(0)
	v_add_f32_dpp v89, v89, v89 quad_perm:[1,0,3,2] row_mask:0xf bank_mask:0xf
	s_waitcnt lgkmcnt(0)
	s_nop 0
	v_add_f32_dpp v89, v89, v89 quad_perm:[2,3,0,1] row_mask:0xf bank_mask:0xf
	s_waitcnt lgkmcnt(0)
	s_nop 0
	v_add_f32_dpp v89, v89, v89 row_half_mirror row_mask:0xf bank_mask:0xf
	s_waitcnt lgkmcnt(0)
	s_nop 0
	v_add_f32_dpp v89, v89, v89 row_mirror row_mask:0xf bank_mask:0xf
	v_fma_f32 v89, -v127, v87, v89
	v_cndmask_b32_e64 v161, v135, v89, s[14:15]
	v_mul_f32_e32 v89, v15, v83
	v_fmac_f32_e32 v89, v14, v82
	v_fmac_f32_e32 v89, v16, v84
	v_fmac_f32_e32 v89, v17, v85
	v_max3_f32 v162, v162, v159, v161
	s_waitcnt lgkmcnt(0)
	v_add_f32_dpp v89, v89, v89 quad_perm:[1,0,3,2] row_mask:0xf bank_mask:0xf
	s_waitcnt lgkmcnt(0)
	s_nop 0
	v_add_f32_dpp v89, v89, v89 quad_perm:[2,3,0,1] row_mask:0xf bank_mask:0xf
	s_waitcnt lgkmcnt(0)
	s_nop 0
	v_add_f32_dpp v145, v89, v89 row_half_mirror row_mask:0xf bank_mask:0xf
	v_mul_f32_e32 v89, v19, v83
	v_mul_f32_e32 v83, v23, v83
	v_fmac_f32_e32 v89, v18, v82
	v_fmac_f32_e32 v83, v22, v82
	v_fmac_f32_e32 v89, v20, v84
	v_fmac_f32_e32 v83, v24, v84
	v_fmac_f32_e32 v89, v21, v85
	v_fmac_f32_e32 v83, v25, v85
	ds_bpermute_b32 v84, v142, v162
	ds_bpermute_b32 v160, v141, v145
	s_waitcnt lgkmcnt(0)
	v_add_f32_dpp v89, v89, v89 quad_perm:[1,0,3,2] row_mask:0xf bank_mask:0xf
	s_waitcnt lgkmcnt(0)
	s_nop 1
	v_add_f32_dpp v82, v83, v83 quad_perm:[1,0,3,2] row_mask:0xf bank_mask:0xf
	s_waitcnt lgkmcnt(0)
	v_max_f32_e32 v84, v84, v84
	v_max_f32_e32 v84, v162, v84
	ds_bpermute_b32 v85, v143, v84
	s_waitcnt lgkmcnt(0)
	v_add_f32_dpp v89, v89, v89 quad_perm:[2,3,0,1] row_mask:0xf bank_mask:0xf
	s_waitcnt lgkmcnt(0)
	v_add_f32_dpp v82, v82, v82 quad_perm:[2,3,0,1] row_mask:0xf bank_mask:0xf
	s_waitcnt lgkmcnt(0)
	v_max_f32_e32 v85, v85, v85
	v_max_f32_e32 v84, v84, v85
	v_cmp_neq_f32_e64 s[16:17], s33, v84
	s_waitcnt lgkmcnt(0)
	v_add_f32_dpp v89, v89, v89 row_half_mirror row_mask:0xf bank_mask:0xf
	s_waitcnt lgkmcnt(0)
	v_add_f32_dpp v82, v82, v82 row_half_mirror row_mask:0xf bank_mask:0xf
	ds_bpermute_b32 v144, v141, v89
	ds_bpermute_b32 v83, v141, v82
	s_and_saveexec_b64 s[24:25], s[16:17]
	s_cbranch_execz .LBB0_5353
	v_max_f32_e32 v84, v84, v84
	v_max_f32_e32 v85, v113, v113
	v_max_f32_e32 v119, v85, v84
	v_sub_f32_e32 v84, v113, v119
	v_mul_f32_e32 v113, 0x3fb8aa3b, v84
	v_sub_f32_e32 v84, v153, v119
	v_mul_f32_e32 v84, 0x3fb8aa3b, v84
	v_sub_f32_e32 v118, v156, v119
	v_exp_f32_e32 v84, v84
	v_mul_f32_e32 v118, 0x3fb8aa3b, v118
	v_exp_f32_e32 v118, v118
	v_exp_f32_e32 v156, v113
	v_add_f32_e32 v153, 0, v84
	v_pk_fma_f32 v[162:163], v[76:77], v[84:85], 0 op_sel_hi:[1,0,0]
	v_pk_fma_f32 v[84:85], v[74:75], v[84:85], 0 op_sel_hi:[1,0,0]
	v_add_f32_e32 v153, v118, v153
	v_pk_fma_f32 v[162:163], v[68:69], v[118:119], v[162:163] op_sel_hi:[1,0,1]
	v_pk_fma_f32 v[84:85], v[66:67], v[118:119], v[84:85] op_sel_hi:[1,0,1]
	v_sub_f32_e32 v118, v159, v119
	v_mul_f32_e32 v118, 0x3fb8aa3b, v118
	v_exp_f32_e32 v118, v118
	s_nop 0
	v_add_f32_e32 v153, v118, v153
	v_pk_fma_f32 v[84:85], v[70:71], v[118:119], v[84:85] op_sel_hi:[1,0,1]
	v_pk_fma_f32 v[162:163], v[72:73], v[118:119], v[162:163] op_sel_hi:[1,0,1]
	v_sub_f32_e32 v118, v161, v119
	v_mul_f32_e32 v118, 0x3fb8aa3b, v118
	v_exp_f32_e32 v118, v118
	s_nop 0
	v_add_f32_e32 v153, v118, v153
	ds_bpermute_b32 v113, v142, v153
	v_pk_fma_f32 v[162:163], v[80:81], v[118:119], v[162:163] op_sel_hi:[1,0,1]
	v_pk_fma_f32 v[84:85], v[78:79], v[118:119], v[84:85] op_sel_hi:[1,0,1]
	ds_bpermute_b32 v164, v142, v162
	ds_bpermute_b32 v165, v142, v163
	s_waitcnt lgkmcnt(0)
	v_add_f32_e32 v113, v153, v113
	ds_bpermute_b32 v118, v143, v113
	s_waitcnt lgkmcnt(0)
	v_pk_add_f32 v[162:163], v[162:163], v[164:165]
	ds_bpermute_b32 v164, v143, v162
	s_waitcnt lgkmcnt(0)
	v_add_f32_e32 v118, v113, v118
	v_fmac_f32_e32 v118, v112, v156
	ds_bpermute_b32 v112, v142, v84
	ds_bpermute_b32 v113, v142, v85
	ds_bpermute_b32 v165, v143, v163
	s_waitcnt lgkmcnt(0)
	v_pk_add_f32 v[84:85], v[84:85], v[112:113]
	ds_bpermute_b32 v112, v143, v84
	ds_bpermute_b32 v113, v143, v85
	s_waitcnt lgkmcnt(0)
	v_pk_add_f32 v[84:85], v[84:85], v[112:113]
	v_pk_add_f32 v[112:113], v[162:163], v[164:165]
	v_pk_fma_f32 v[62:63], v[62:63], v[156:157], v[84:85] op_sel_hi:[1,0,1]
	v_pk_fma_f32 v[64:65], v[64:65], v[156:157], v[112:113] op_sel_hi:[1,0,1]
	v_mov_b32_e32 v112, v118
	v_mov_b32_e32 v113, v119

.LBB0_5544:
	v_lshl_add_u64 v[18:19], s[68:69], 0, v[94:95]
	v_lshl_add_u64 v[22:23], s[68:69], 0, v[92:93]
	v_add_co_u32_e32 v20, vcc, 0x7800000, v18
	v_add_co_u32_e64 v102, s[6:7], s24, v22
	s_nop 0
	v_addc_co_u32_e32 v21, vcc, 0, v19, vcc
	v_addc_co_u32_e64 v103, s[6:7], 0, v23, s[6:7]
	v_add_co_u32_e64 v104, s[6:7], s25, v22
	v_add_co_u32_e32 v22, vcc, 0x7801000, v18
	s_nop 0
	v_addc_co_u32_e64 v105, s[6:7], 0, v23, s[6:7]
	global_load_dwordx4 v[78:81], v[20:21], off
	global_load_dwordx4 v[74:77], v[20:21], off offset:1024
	global_load_dwordx4 v[70:73], v[20:21], off offset:2048
	global_load_dwordx4 v[66:69], v[20:21], off offset:3072
	v_addc_co_u32_e32 v23, vcc, 0, v19, vcc
	v_add_co_u32_e32 v20, vcc, 0x7802000, v18
	global_load_dwordx4 v[62:65], v[22:23], off
	global_load_dwordx4 v[58:61], v[22:23], off offset:1024
	global_load_dwordx4 v[54:57], v[22:23], off offset:2048
	global_load_dwordx4 v[50:53], v[22:23], off offset:3072
	v_addc_co_u32_e32 v21, vcc, 0, v19, vcc
	v_add_co_u32_e32 v82, vcc, 0x7803000, v18
	global_load_dwordx4 v[46:49], v[20:21], off
	global_load_dwordx4 v[42:45], v[20:21], off offset:1024
	global_load_dwordx4 v[38:41], v[20:21], off offset:2048
	global_load_dwordx4 v[34:37], v[20:21], off offset:3072
	v_addc_co_u32_e32 v83, vcc, 0, v19, vcc
	global_load_dwordx4 v[30:33], v[82:83], off
	global_load_dwordx4 v[26:29], v[82:83], off offset:1024
	global_load_dwordx4 v[22:25], v[82:83], off offset:2048
	global_load_dwordx4 v[18:21], v[82:83], off offset:3072
	s_ashr_i32 s8, s12, 13
	s_add_i32 s9, s12, 0xffffc002
	s_cmpk_lt_i32 s12, 0x4000
	s_cselect_b32 s6, s8, s9
	s_addk_i32 s6, 0x82
	s_mul_hi_i32 s7, s6, 0x9000
	s_mul_i32 s6, s6, 0x9000
	s_add_u32 s9, s3, s6
	s_addc_u32 s11, s4, s7
	s_add_u32 s6, s9, 0x6000
	s_addc_u32 s7, s11, 0
	s_add_u32 s10, s9, 0x7000
	s_addc_u32 s11, s11, 0
	v_lshl_add_u64 v[82:83], s[6:7], 0, v[90:91]
	v_lshl_add_u64 v[86:87], s[10:11], 0, v[90:91]
	global_load_dwordx4 v[82:85], v[82:83], off
	v_lshl_add_u64 v[148:149], s[6:7], 0, v[96:97]
	global_load_dwordx4 v[86:89], v[86:87], off
	v_lshl_add_u64 v[142:143], s[6:7], 0, v[98:99]
	v_lshl_add_u64 v[132:133], s[6:7], 0, v[100:101]
	s_add_i32 s6, s12, 0xffffc003
	s_cmpk_lt_i32 s12, 0x3fff
	s_cselect_b32 s6, s8, s6
	s_addk_i32 s6, 0x82
	s_mul_hi_i32 s7, s6, 0x9000
	s_mul_i32 s6, s6, 0x9000
	s_add_u32 s9, s3, s6
	v_lshl_add_u64 v[152:153], s[10:11], 0, v[96:97]
	v_lshl_add_u64 v[146:147], s[10:11], 0, v[98:99]
	v_lshl_add_u64 v[140:141], s[10:11], 0, v[100:101]
	s_addc_u32 s11, s4, s7
	s_add_u32 s6, s9, 0x6000
	s_addc_u32 s7, s11, 0
	s_add_u32 s10, s9, 0x7000
	v_lshl_add_u64 v[134:135], s[6:7], 0, v[90:91]
	v_lshl_add_u64 v[126:127], s[6:7], 0, v[96:97]
	v_lshl_add_u64 v[118:119], s[6:7], 0, v[98:99]
	v_lshl_add_u64 v[114:115], s[6:7], 0, v[100:101]
	s_addc_u32 s11, s11, 0
	s_add_i32 s6, s12, 0xffffc004
	s_cmpk_lt_i32 s12, 0x3ffe
	s_cselect_b32 s6, s8, s6
	s_addk_i32 s6, 0x82
	s_mul_hi_i32 s7, s6, 0x9000
	s_mul_i32 s6, s6, 0x9000
	s_add_u32 s6, s3, s6
	s_addc_u32 s7, s4, s7
	v_lshl_add_u64 v[136:137], s[10:11], 0, v[90:91]
	v_lshl_add_u64 v[130:131], s[10:11], 0, v[96:97]
	v_lshl_add_u64 v[122:123], s[10:11], 0, v[98:99]
	v_lshl_add_u64 v[116:117], s[10:11], 0, v[100:101]
	s_add_u32 s10, s6, 0x6000
	s_addc_u32 s11, s7, 0
	s_add_u32 s6, s6, 0x7000
	s_addc_u32 s7, s7, 0
	s_add_i32 s9, s12, 0xffffc005
	s_cmpk_lt_i32 s12, 0x3ffd
	v_lshl_add_u64 v[156:157], s[6:7], 0, v[90:91]
	v_lshl_add_u64 v[154:155], s[6:7], 0, v[96:97]
	v_lshl_add_u64 v[150:151], s[6:7], 0, v[98:99]
	v_lshl_add_u64 v[138:139], s[6:7], 0, v[100:101]
	s_cselect_b32 s6, s8, s9
	s_addk_i32 s6, 0x82
	s_waitcnt vmcnt(0) lgkmcnt(0)
	v_pk_mul_f32 v[158:159], v[80:81], v[80:81]
	v_pk_mul_f32 v[160:161], v[78:79], v[78:79]
	v_pk_mul_f32 v[162:163], v[76:77], v[76:77]
	v_pk_mul_f32 v[164:165], v[74:75], v[74:75]
	v_mul_f32_e32 v174, v71, v71
	v_mul_f32_e32 v176, v73, v73
	v_mul_f32_e32 v187, v68, v68
	v_mul_f32_e32 v189, v69, v69
	v_pk_mov_b32 v[178:179], v[160:161], v[158:159] op_sel:[1,0]
	v_mov_b32_e32 v161, v159
	v_pk_mov_b32 v[158:159], v[164:165], v[162:163] op_sel:[1,0]
	v_mov_b32_e32 v165, v163
	v_pk_fma_f32 v[162:163], v[70:71], v[70:71], v[174:175] op_sel_hi:[1,1,0]
	v_pk_fma_f32 v[174:175], v[72:73], v[72:73], v[176:177] op_sel_hi:[1,1,0]
	v_pk_mul_f32 v[176:177], v[64:65], v[64:65]
	v_pk_mul_f32 v[180:181], v[62:63], v[62:63]
	v_pk_mul_f32 v[182:183], v[60:61], v[60:61]
	v_pk_mul_f32 v[184:185], v[58:59], v[58:59]
	v_mul_f32_e32 v186, v55, v55
	v_mul_f32_e32 v188, v57, v57
	v_pk_add_f32 v[160:161], v[178:179], v[160:161]
	v_pk_add_f32 v[158:159], v[158:159], v[164:165]
	v_mov_b32_e32 v163, v187
	v_mov_b32_e32 v175, v189
	v_pk_mov_b32 v[164:165], v[180:181], v[176:177] op_sel:[1,0]
	v_mov_b32_e32 v181, v177
	v_pk_mov_b32 v[176:177], v[184:185], v[182:183] op_sel:[1,0]
	v_mov_b32_e32 v185, v183
	v_pk_fma_f32 v[178:179], v[54:55], v[54:55], v[186:187] op_sel_hi:[1,1,0]
	v_pk_fma_f32 v[182:183], v[56:57], v[56:57], v[188:189] op_sel_hi:[1,1,0]
	v_pk_mul_f32 v[186:187], v[48:49], v[48:49]
	v_pk_mul_f32 v[188:189], v[46:47], v[46:47]
	v_pk_mul_f32 v[190:191], v[44:45], v[44:45]
	v_pk_mul_f32 v[192:193], v[42:43], v[42:43]
	v_mul_f32_e32 v197, v66, v66
	v_mul_f32_e32 v203, v67, v67
	v_mul_f32_e32 v195, v52, v52
	v_mul_f32_e32 v202, v53, v53
	v_mul_f32_e32 v194, v39, v39
	v_mul_f32_e32 v196, v41, v41
	v_pk_add_f32 v[198:199], v[160:161], v[160:161] op_sel:[0,1] op_sel_hi:[1,0]
	v_pk_add_f32 v[200:201], v[158:159], v[158:159] op_sel:[0,1] op_sel_hi:[1,0]
	v_pk_add_f32 v[174:175], v[162:163], v[174:175]
	v_pk_add_f32 v[158:159], v[164:165], v[180:181]
	v_pk_add_f32 v[160:161], v[176:177], v[184:185]
	v_pk_mov_b32 v[162:163], v[188:189], v[186:187] op_sel:[1,0]
	v_mov_b32_e32 v189, v187
	v_pk_mov_b32 v[164:165], v[192:193], v[190:191] op_sel:[1,0]
	v_mov_b32_e32 v193, v191
	v_mul_f32_e32 v208, v50, v50
	v_mul_f32_e32 v209, v51, v51
	v_mul_f32_e32 v212, v36, v36
	v_mul_f32_e32 v213, v37, v37
	v_mov_b32_e32 v179, v195
	v_mov_b32_e32 v183, v202
	v_pk_fma_f32 v[176:177], v[38:39], v[38:39], v[194:195] op_sel_hi:[1,1,0]
	v_pk_fma_f32 v[180:181], v[40:41], v[40:41], v[196:197] op_sel_hi:[1,1,0]
	v_pk_mul_f32 v[184:185], v[32:33], v[32:33]
	v_pk_mul_f32 v[186:187], v[30:31], v[30:31]
	v_pk_mul_f32 v[190:191], v[28:29], v[28:29]
	v_pk_mul_f32 v[194:195], v[26:27], v[26:27]
	v_mov_b32_e32 v199, v197
	v_mov_b32_e32 v201, v203
	v_pk_add_f32 v[204:205], v[158:159], v[158:159] op_sel:[0,1] op_sel_hi:[1,0]
	v_pk_add_f32 v[206:207], v[160:161], v[160:161] op_sel:[0,1] op_sel_hi:[1,0]
	v_pk_add_f32 v[162:163], v[162:163], v[188:189]
	v_pk_add_f32 v[164:165], v[164:165], v[192:193]
	v_mul_f32_e32 v210, v34, v34
	v_mul_f32_e32 v211, v35, v35
	v_pk_add_f32 v[178:179], v[178:179], v[182:183]
	v_mov_b32_e32 v177, v212
	v_mov_b32_e32 v181, v213
	v_pk_mov_b32 v[182:183], v[186:187], v[184:185] op_sel:[1,0]
	v_mov_b32_e32 v187, v185
	v_pk_mov_b32 v[184:185], v[194:195], v[190:191] op_sel:[1,0]
	v_mov_b32_e32 v195, v191
	v_pk_add_f32 v[188:189], v[198:199], v[200:201]
	v_mov_b32_e32 v205, v208
	v_mov_b32_e32 v207, v209
	v_pk_add_f32 v[190:191], v[162:163], v[162:163] op_sel:[0,1] op_sel_hi:[1,0]
	v_pk_add_f32 v[192:193], v[164:165], v[164:165] op_sel:[0,1] op_sel_hi:[1,0]
	v_pk_add_f32 v[176:177], v[176:177], v[180:181]
	v_pk_add_f32 v[174:175], v[188:189], v[174:175]
	v_pk_add_f32 v[180:181], v[204:205], v[206:207]
	v_mov_b32_e32 v191, v210
	v_mov_b32_e32 v193, v211
	v_pk_add_f32 v[162:163], v[182:183], v[186:187]
	v_add_f32_e32 v182, v174, v175
	v_pk_add_f32 v[174:175], v[180:181], v[178:179]
	v_pk_add_f32 v[178:179], v[190:191], v[192:193]
	v_add_f32_e32 v180, v174, v175
	v_pk_add_f32 v[174:175], v[178:179], v[176:177]
	v_add_f32_e32 v174, v174, v175
	s_mul_hi_i32 s7, s6, 0x9000
	s_waitcnt lgkmcnt(0)
	s_nop 1
	v_add_f32_dpp v176, v182, v182 quad_perm:[1,0,3,2] row_mask:0xf bank_mask:0xf
	s_waitcnt lgkmcnt(0)
	s_nop 1
	v_add_f32_dpp v175, v180, v180 quad_perm:[1,0,3,2] row_mask:0xf bank_mask:0xf
	s_waitcnt lgkmcnt(0)
	s_nop 1
	v_add_f32_dpp v174, v174, v174 quad_perm:[1,0,3,2] row_mask:0xf bank_mask:0xf
	s_waitcnt lgkmcnt(0)
	s_nop 1
	v_add_f32_dpp v176, v176, v176 quad_perm:[2,3,0,1] row_mask:0xf bank_mask:0xf
	s_waitcnt lgkmcnt(0)
	s_nop 1
	v_add_f32_dpp v175, v175, v175 quad_perm:[2,3,0,1] row_mask:0xf bank_mask:0xf
	s_waitcnt lgkmcnt(0)
	s_nop 1
	v_add_f32_dpp v174, v174, v174 quad_perm:[2,3,0,1] row_mask:0xf bank_mask:0xf
	s_waitcnt lgkmcnt(0)
	s_nop 1
	v_add_f32_dpp v176, v176, v176 row_half_mirror row_mask:0xf bank_mask:0xf
	s_waitcnt lgkmcnt(0)
	s_nop 1
	v_add_f32_dpp v175, v175, v175 row_half_mirror row_mask:0xf bank_mask:0xf
	s_waitcnt lgkmcnt(0)
	s_nop 1
	v_add_f32_dpp v174, v174, v174 row_half_mirror row_mask:0xf bank_mask:0xf
	s_waitcnt lgkmcnt(0)
	s_nop 1
	v_add_f32_dpp v176, v176, v176 row_mirror row_mask:0xf bank_mask:0xf
	ds_bpermute_b32 v178, v170, v176
	s_waitcnt lgkmcnt(2)
	s_nop 1
	v_add_f32_dpp v175, v175, v175 row_mirror row_mask:0xf bank_mask:0xf
	ds_bpermute_b32 v179, v170, v175
	s_waitcnt lgkmcnt(2)
	s_nop 1
	v_add_f32_dpp v174, v174, v174 row_mirror row_mask:0xf bank_mask:0xf
	ds_bpermute_b32 v177, v170, v174
	s_waitcnt lgkmcnt(2)
	v_add_f32_e32 v176, v176, v178
	ds_bpermute_b32 v178, v171, v176
	s_waitcnt lgkmcnt(2)
	v_add_f32_e32 v175, v175, v179
	ds_bpermute_b32 v179, v171, v175
	s_mul_i32 s6, s6, 0x9000
	s_waitcnt lgkmcnt(2)
	v_add_f32_e32 v174, v174, v177
	s_add_u32 s6, s3, s6
	ds_bpermute_b32 v177, v171, v174
	s_addc_u32 s7, s4, s7
	s_waitcnt lgkmcnt(2)
	v_add_f32_e32 v176, v176, v178
	s_add_u32 s18, s6, 0x6000
	v_fmamk_f32 v176, v176, 0x3a800000, v172
	s_addc_u32 s19, s7, 0
	s_waitcnt lgkmcnt(1)
	v_add_f32_e32 v175, v175, v179
	v_mul_f32_e32 v178, 0x4f800000, v176
	v_cmp_gt_f32_e32 vcc, s13, v176
	s_add_u32 s20, s6, 0x7000
	v_fmamk_f32 v175, v175, 0x3a800000, v172
	v_cndmask_b32_e32 v176, v176, v178, vcc
	s_addc_u32 s21, s7, 0
	s_waitcnt lgkmcnt(0)
	v_add_f32_e32 v174, v174, v177
	v_mul_f32_e32 v177, 0x4f800000, v175
	v_cmp_gt_f32_e64 s[6:7], s13, v175
	v_sqrt_f32_e32 v178, v176
	v_fmamk_f32 v174, v174, 0x3a800000, v172
	v_cndmask_b32_e64 v175, v175, v177, s[6:7]
	v_mul_f32_e32 v177, 0x4f800000, v174
	v_cmp_gt_f32_e64 s[8:9], s13, v174
	v_sqrt_f32_e32 v179, v175
	v_add_u32_e32 v180, -1, v178
	v_cndmask_b32_e64 v174, v174, v177, s[8:9]
	v_sqrt_f32_e32 v177, v174
	v_add_u32_e32 v181, 1, v178
	v_fma_f32 v182, -v180, v178, v176
	v_lshl_add_u64 v[112:113], s[10:11], 0, v[90:91]
	v_lshl_add_u64 v[106:107], s[10:11], 0, v[96:97]
	v_lshl_add_u64 v[110:111], s[10:11], 0, v[98:99]
	v_lshl_add_u64 v[108:109], s[10:11], 0, v[100:101]
	v_pk_add_f32 v[164:165], v[184:185], v[194:195]
	v_fma_f32 v183, -v181, v178, v176
	v_add_u32_e32 v184, -1, v179
	v_cmp_ge_f32_e64 s[10:11], 0, v182
	v_add_u32_e32 v185, 1, v179
	v_fma_f32 v182, -v185, v179, v175
	v_cndmask_b32_e64 v178, v178, v180, s[10:11]
	v_fma_f32 v180, -v184, v179, v175
	v_cmp_lt_f32_e64 s[10:11], 0, v183
	v_add_u32_e32 v186, -1, v177
	v_add_u32_e32 v187, 1, v177
	v_cndmask_b32_e64 v178, v178, v181, s[10:11]
	v_cmp_ge_f32_e64 s[10:11], 0, v180
	v_fma_f32 v180, -v186, v177, v174
	v_fma_f32 v181, -v187, v177, v174
	v_cndmask_b32_e64 v179, v179, v184, s[10:11]
	v_cmp_lt_f32_e64 s[10:11], 0, v182
	v_mul_f32_e32 v182, 0x37800000, v178
	v_cndmask_b32_e32 v178, v178, v182, vcc
	v_cndmask_b32_e64 v179, v179, v185, s[10:11]
	v_cmp_ge_f32_e64 s[10:11], 0, v180
	v_cmp_class_f32_e32 vcc, v176, v173
	v_mul_f32_e32 v180, 0x37800000, v179
	v_cndmask_b32_e64 v177, v177, v186, s[10:11]
	v_cmp_lt_f32_e64 s[10:11], 0, v181
	v_cndmask_b32_e32 v176, v178, v176, vcc
	v_cndmask_b32_e64 v178, v179, v180, s[6:7]
	v_cndmask_b32_e64 v177, v177, v187, s[10:11]
	v_cmp_class_f32_e32 vcc, v175, v173
	v_mul_f32_e32 v179, 0x37800000, v177
	v_div_scale_f32 v180, s[6:7], v176, v176, 1.0
	v_cndmask_b32_e32 v175, v178, v175, vcc
	v_cndmask_b32_e64 v177, v177, v179, s[8:9]
	v_cmp_class_f32_e32 vcc, v174, v173
	v_rcp_f32_e32 v178, v180
	v_div_scale_f32 v179, s[8:9], v175, v175, 1.0
	v_cndmask_b32_e32 v177, v177, v174, vcc
	v_rcp_f32_e32 v183, v179
	v_div_scale_f32 v184, s[10:11], v177, v177, 1.0
	v_rcp_f32_e32 v186, v184
	v_fma_f32 v174, -v180, v178, 1.0
	v_div_scale_f32 v181, s[6:7], 1.0, v176, 1.0
	v_fmac_f32_e32 v178, v174, v178
	v_fma_f32 v174, -v179, v183, 1.0
	v_mul_f32_e32 v187, v181, v178
	v_div_scale_f32 v182, s[8:9], 1.0, v175, 1.0
	v_fmac_f32_e32 v183, v174, v183
	v_fma_f32 v174, -v184, v186, 1.0
	v_fma_f32 v188, -v180, v187, v181
	v_div_scale_f32 v185, s[10:11], 1.0, v177, 1.0
	v_mul_f32_e32 v189, v182, v183
	v_fmac_f32_e32 v186, v174, v186
	v_fmac_f32_e32 v187, v188, v178
	v_fma_f32 v174, -v179, v189, v182
	v_mul_f32_e32 v188, v185, v186
	v_fma_f32 v180, -v180, v187, v181
	s_mov_b64 vcc, s[6:7]
	v_fmac_f32_e32 v189, v174, v183
	v_fma_f32 v174, -v184, v188, v185
	v_div_fmas_f32 v178, v180, v178, v187
	v_fma_f32 v179, -v179, v189, v182
	v_fmac_f32_e32 v188, v174, v186
	v_div_fixup_f32 v174, v178, v176, 1.0
	s_mov_b64 vcc, s[8:9]
	v_div_fmas_f32 v176, v179, v183, v189
	v_fma_f32 v178, -v184, v188, v185
	v_pk_mul_f32 v[80:81], v[80:81], v[174:175] op_sel_hi:[1,0]
	v_pk_mul_f32 v[78:79], v[78:79], v[174:175] op_sel_hi:[1,0]
	s_mov_b64 vcc, s[10:11]
	v_pk_add_f32 v[88:89], v[88:89], 1.0 op_sel_hi:[1,0]
	v_pk_add_f32 v[86:87], v[86:87], 1.0 op_sel_hi:[1,0]
	v_pk_mul_f32 v[76:77], v[76:77], v[174:175] op_sel_hi:[1,0]
	v_pk_mul_f32 v[74:75], v[74:75], v[174:175] op_sel_hi:[1,0]
	v_pk_mul_f32 v[72:73], v[72:73], v[174:175] op_sel_hi:[1,0]
	v_pk_mul_f32 v[70:71], v[70:71], v[174:175] op_sel_hi:[1,0]
	v_pk_mul_f32 v[68:69], v[68:69], v[174:175] op_sel_hi:[1,0]
	v_pk_mul_f32 v[66:67], v[66:67], v[174:175] op_sel_hi:[1,0]
	v_div_fixup_f32 v174, v176, v175, 1.0
	v_div_fmas_f32 v176, v178, v186, v188
	v_pk_mul_f32 v[78:79], v[2:3], v[78:79]
	v_pk_mul_f32 v[80:81], v[4:5], v[80:81]
	v_pk_mul_f32 v[64:65], v[64:65], v[174:175] op_sel_hi:[1,0]
	v_pk_mul_f32 v[62:63], v[62:63], v[174:175] op_sel_hi:[1,0]
	v_pk_mul_f32 v[60:61], v[60:61], v[174:175] op_sel_hi:[1,0]
	v_pk_mul_f32 v[58:59], v[58:59], v[174:175] op_sel_hi:[1,0]
	v_pk_mul_f32 v[56:57], v[56:57], v[174:175] op_sel_hi:[1,0]
	v_pk_mul_f32 v[54:55], v[54:55], v[174:175] op_sel_hi:[1,0]
	v_pk_mul_f32 v[52:53], v[52:53], v[174:175] op_sel_hi:[1,0]
	v_pk_mul_f32 v[174:175], v[50:51], v[174:175] op_sel_hi:[1,0]
	v_div_fixup_f32 v50, v176, v177, 1.0
	v_pk_fma_f32 v[80:81], v[88:89], v[80:81], v[84:85]
	v_pk_fma_f32 v[78:79], v[86:87], v[78:79], v[82:83]
	v_pk_mul_f32 v[86:87], v[16:17], v[52:53]
	v_pk_mul_f32 v[48:49], v[48:49], v[50:51] op_sel_hi:[1,0]
	v_pk_mul_f32 v[46:47], v[46:47], v[50:51] op_sel_hi:[1,0]
	v_pk_mul_f32 v[82:83], v[10:11], v[54:55]
	v_pk_mul_f32 v[84:85], v[14:15], v[174:175]
	v_pk_mul_f32 v[88:89], v[2:3], v[46:47]
	v_pk_mul_f32 v[174:175], v[4:5], v[48:49]
	v_cvt_pk_bf16_f32 v46, v78, v79
	v_cvt_pk_bf16_f32 v47, v80, v81
	global_store_dwordx2 v[102:103], v[46:47], off
	global_load_dwordx4 v[46:49], v[152:153], off
	s_nop 0
	global_load_dwordx4 v[52:55], v[148:149], off
	v_pk_mul_f32 v[74:75], v[6:7], v[74:75]
	v_pk_mul_f32 v[76:77], v[8:9], v[76:77]
	v_pk_mul_f32 v[70:71], v[10:11], v[70:71]
	v_pk_mul_f32 v[72:73], v[12:13], v[72:73]
	v_pk_mul_f32 v[66:67], v[66:67], v[14:15]
	v_pk_mul_f32 v[68:69], v[68:69], v[16:17]
	v_pk_mul_f32 v[62:63], v[2:3], v[62:63]
	v_pk_mul_f32 v[64:65], v[4:5], v[64:65]
	v_pk_mul_f32 v[58:59], v[6:7], v[58:59]
	v_pk_mul_f32 v[60:61], v[8:9], v[60:61]
	v_pk_mul_f32 v[56:57], v[12:13], v[56:57]
	v_mul_f32_e32 v196, v23, v23
	v_mul_f32_e32 v202, v25, v25
	v_mul_f32_e32 v214, v18, v18
	v_mul_f32_e32 v215, v19, v19
	v_mul_f32_e32 v216, v20, v20
	v_mul_f32_e32 v217, v21, v21
	v_pk_fma_f32 v[158:159], v[22:23], v[22:23], v[196:197] op_sel_hi:[1,1,0]
	v_pk_fma_f32 v[160:161], v[24:25], v[24:25], v[202:203] op_sel_hi:[1,1,0]
	v_mov_b32_e32 v159, v216
	v_mov_b32_e32 v161, v217
	v_lshl_add_u64 v[144:145], s[20:21], 0, v[90:91]
	v_lshl_add_u64 v[128:129], s[18:19], 0, v[90:91]
	v_lshl_add_u64 v[124:125], s[20:21], 0, v[96:97]
	v_lshl_add_u64 v[120:121], s[18:19], 0, v[96:97]
	s_add_i32 s12, s12, 32
	v_lshl_add_u64 v[92:93], v[92:93], 0, s[14:15]
	v_lshl_add_u64 v[94:95], v[94:95], 0, s[16:17]
	s_cmp_lt_i32 s12, s2
	s_waitcnt vmcnt(0) lgkmcnt(0)
	v_pk_add_f32 v[48:49], v[48:49], 1.0 op_sel_hi:[1,0]
	v_pk_add_f32 v[46:47], v[46:47], 1.0 op_sel_hi:[1,0]
	v_pk_fma_f32 v[48:49], v[48:49], v[76:77], v[54:55]
	v_pk_fma_f32 v[46:47], v[46:47], v[74:75], v[52:53]
	v_cvt_pk_bf16_f32 v46, v46, v47
	v_cvt_pk_bf16_f32 v47, v48, v49
	global_store_dwordx2 v[102:103], v[46:47], off offset:512
	global_load_dwordx4 v[46:49], v[146:147], off
	s_nop 0
	global_load_dwordx4 v[52:55], v[142:143], off
	s_waitcnt vmcnt(0) lgkmcnt(0)
	v_pk_add_f32 v[48:49], v[48:49], 1.0 op_sel_hi:[1,0]
	v_pk_add_f32 v[46:47], v[46:47], 1.0 op_sel_hi:[1,0]
	v_pk_fma_f32 v[48:49], v[72:73], v[48:49], v[54:55]
	v_pk_fma_f32 v[46:47], v[70:71], v[46:47], v[52:53]
	v_cvt_pk_bf16_f32 v46, v46, v47
	v_cvt_pk_bf16_f32 v47, v48, v49
	global_store_dwordx2 v[102:103], v[46:47], off offset:1024
	global_load_dwordx4 v[46:49], v[140:141], off
	s_nop 0
	global_load_dwordx4 v[52:55], v[132:133], off
	s_waitcnt vmcnt(0) lgkmcnt(0)
	v_pk_add_f32 v[48:49], v[48:49], 1.0 op_sel_hi:[1,0]
	v_pk_add_f32 v[46:47], v[46:47], 1.0 op_sel_hi:[1,0]
	v_pk_fma_f32 v[48:49], v[68:69], v[48:49], v[54:55]
	v_pk_fma_f32 v[46:47], v[66:67], v[46:47], v[52:53]
	v_cvt_pk_bf16_f32 v46, v46, v47
	v_cvt_pk_bf16_f32 v47, v48, v49
	global_store_dwordx2 v[102:103], v[46:47], off offset:1536
	global_load_dwordx4 v[46:49], v[136:137], off
	s_nop 0
	global_load_dwordx4 v[52:55], v[134:135], off
	s_waitcnt vmcnt(0) lgkmcnt(0)
	v_pk_add_f32 v[48:49], v[48:49], 1.0 op_sel_hi:[1,0]
	v_pk_add_f32 v[46:47], v[46:47], 1.0 op_sel_hi:[1,0]
	v_pk_fma_f32 v[48:49], v[48:49], v[64:65], v[54:55]
	v_pk_fma_f32 v[46:47], v[46:47], v[62:63], v[52:53]
	v_cvt_pk_bf16_f32 v46, v46, v47
	v_cvt_pk_bf16_f32 v47, v48, v49
	global_store_dwordx2 v[102:103], v[46:47], off offset:2048
	global_load_dwordx4 v[46:49], v[130:131], off
	s_nop 0
	global_load_dwordx4 v[52:55], v[126:127], off
	s_waitcnt vmcnt(0) lgkmcnt(0)
	v_pk_add_f32 v[48:49], v[48:49], 1.0 op_sel_hi:[1,0]
	v_pk_add_f32 v[46:47], v[46:47], 1.0 op_sel_hi:[1,0]
	v_pk_fma_f32 v[48:49], v[48:49], v[60:61], v[54:55]
	v_pk_fma_f32 v[46:47], v[46:47], v[58:59], v[52:53]
	v_cvt_pk_bf16_f32 v46, v46, v47
	v_cvt_pk_bf16_f32 v47, v48, v49
	global_store_dwordx2 v[102:103], v[46:47], off offset:2560
	global_load_dwordx4 v[46:49], v[122:123], off
	s_nop 0
	global_load_dwordx4 v[52:55], v[118:119], off
	v_pk_add_f32 v[58:59], v[164:165], v[164:165] op_sel:[0,1] op_sel_hi:[1,0]
	v_pk_add_f32 v[60:61], v[158:159], v[160:161]
	v_mov_b32_e32 v59, v215
	s_waitcnt vmcnt(0) lgkmcnt(0)
	v_pk_add_f32 v[48:49], v[48:49], 1.0 op_sel_hi:[1,0]
	v_pk_add_f32 v[46:47], v[46:47], 1.0 op_sel_hi:[1,0]
	v_pk_fma_f32 v[48:49], v[48:49], v[56:57], v[54:55]
	v_pk_fma_f32 v[46:47], v[46:47], v[82:83], v[52:53]
	v_cvt_pk_bf16_f32 v46, v46, v47
	v_cvt_pk_bf16_f32 v47, v48, v49
	global_store_dwordx2 v[102:103], v[46:47], off offset:3072
	global_load_dwordx4 v[46:49], v[116:117], off
	s_nop 0
	global_load_dwordx4 v[52:55], v[114:115], off
	v_pk_add_f32 v[56:57], v[162:163], v[162:163] op_sel:[0,1] op_sel_hi:[1,0]
	s_waitcnt vmcnt(0) lgkmcnt(0)
	v_pk_add_f32 v[48:49], v[48:49], 1.0 op_sel_hi:[1,0]
	v_pk_add_f32 v[46:47], v[46:47], 1.0 op_sel_hi:[1,0]
	v_pk_fma_f32 v[48:49], v[86:87], v[48:49], v[54:55]
	v_pk_fma_f32 v[46:47], v[84:85], v[46:47], v[52:53]
	v_cvt_pk_bf16_f32 v46, v46, v47
	v_cvt_pk_bf16_f32 v47, v48, v49
	global_store_dwordx2 v[102:103], v[46:47], off offset:3584
	global_load_dwordx4 v[46:49], v[156:157], off
	s_nop 0
	global_load_dwordx4 v[52:55], v[112:113], off
	v_mov_b32_e32 v57, v214
	s_waitcnt vmcnt(0) lgkmcnt(0)
	v_pk_add_f32 v[48:49], v[48:49], 1.0 op_sel_hi:[1,0]
	v_pk_add_f32 v[46:47], v[46:47], 1.0 op_sel_hi:[1,0]
	v_pk_fma_f32 v[48:49], v[48:49], v[174:175], v[54:55]
	v_pk_fma_f32 v[46:47], v[46:47], v[88:89], v[52:53]
	v_bfe_u32 v51, v46, 16, 1
	v_bfe_u32 v52, v47, 16, 1
	v_add3_u32 v46, v46, v51, s22
	v_add3_u32 v47, v47, v52, s22
	v_lshrrev_b32_e32 v46, 16, v46
	v_and_or_b32 v46, v47, s23, v46
	v_cvt_pk_bf16_f32 v47, v48, v49
	global_store_dwordx2 v[104:105], v[46:47], off
	global_load_dwordx4 v[46:49], v[154:155], off
	s_nop 0
	global_load_dwordx4 v[52:55], v[106:107], off
	v_pk_mul_f32 v[44:45], v[44:45], v[50:51] op_sel_hi:[1,0]
	v_pk_mul_f32 v[42:43], v[42:43], v[50:51] op_sel_hi:[1,0]
	v_pk_mul_f32 v[44:45], v[8:9], v[44:45]
	v_pk_mul_f32 v[42:43], v[6:7], v[42:43]
	s_waitcnt vmcnt(0) lgkmcnt(0)
	v_pk_add_f32 v[48:49], v[48:49], 1.0 op_sel_hi:[1,0]
	v_pk_add_f32 v[46:47], v[46:47], 1.0 op_sel_hi:[1,0]
	v_pk_fma_f32 v[44:45], v[48:49], v[44:45], v[54:55]
	v_pk_fma_f32 v[42:43], v[46:47], v[42:43], v[52:53]
	v_cvt_pk_bf16_f32 v42, v42, v43
	v_cvt_pk_bf16_f32 v43, v44, v45
	global_store_dwordx2 v[104:105], v[42:43], off offset:512
	global_load_dwordx4 v[42:45], v[150:151], off
	s_nop 0
	global_load_dwordx4 v[46:49], v[110:111], off
	v_pk_add_f32 v[52:53], v[56:57], v[58:59]
	s_waitcnt vmcnt(0) lgkmcnt(0)
	v_pk_add_f32 v[44:45], v[44:45], 1.0 op_sel_hi:[1,0]
	v_pk_add_f32 v[52:53], v[52:53], v[60:61]
	v_pk_add_f32 v[42:43], v[42:43], 1.0 op_sel_hi:[1,0]
	v_add_f32_e32 v51, v52, v53
	s_waitcnt lgkmcnt(0)
	s_nop 1
	v_add_f32_dpp v51, v51, v51 quad_perm:[1,0,3,2] row_mask:0xf bank_mask:0xf
	s_waitcnt lgkmcnt(0)
	s_nop 1
	v_add_f32_dpp v51, v51, v51 quad_perm:[2,3,0,1] row_mask:0xf bank_mask:0xf
	v_pk_mul_f32 v[40:41], v[40:41], v[50:51] op_sel_hi:[1,0]
	v_pk_mul_f32 v[38:39], v[38:39], v[50:51] op_sel_hi:[1,0]
	v_pk_mul_f32 v[40:41], v[12:13], v[40:41]
	v_pk_mul_f32 v[38:39], v[10:11], v[38:39]
	v_pk_fma_f32 v[40:41], v[44:45], v[40:41], v[48:49]
	v_pk_fma_f32 v[38:39], v[42:43], v[38:39], v[46:47]
	v_cvt_pk_bf16_f32 v38, v38, v39
	v_cvt_pk_bf16_f32 v39, v40, v41
	global_store_dwordx2 v[104:105], v[38:39], off offset:1024
	global_load_dwordx4 v[38:41], v[138:139], off
	s_nop 0
	global_load_dwordx4 v[42:45], v[108:109], off
	v_pk_mul_f32 v[36:37], v[36:37], v[50:51] op_sel_hi:[1,0]
	v_pk_mul_f32 v[34:35], v[34:35], v[50:51] op_sel_hi:[1,0]
	v_pk_mul_f32 v[36:37], v[16:17], v[36:37]
	v_pk_mul_f32 v[34:35], v[14:15], v[34:35]
	s_waitcnt lgkmcnt(0)
	s_nop 1
	v_add_f32_dpp v46, v51, v51 row_half_mirror row_mask:0xf bank_mask:0xf
	s_waitcnt lgkmcnt(0)
	s_nop 1
	v_add_f32_dpp v46, v46, v46 row_mirror row_mask:0xf bank_mask:0xf
	ds_bpermute_b32 v47, v170, v46
	s_waitcnt lgkmcnt(0)
	v_add_f32_e32 v46, v46, v47
	ds_bpermute_b32 v47, v171, v46
	s_waitcnt lgkmcnt(0)
	v_add_f32_e32 v46, v46, v47
	v_fmamk_f32 v46, v46, 0x3a800000, v172
	v_mul_f32_e32 v47, 0x4f800000, v46
	v_cmp_gt_f32_e32 vcc, s13, v46
	s_waitcnt vmcnt(0)
	v_pk_add_f32 v[40:41], v[40:41], 1.0 op_sel_hi:[1,0]
	v_pk_add_f32 v[38:39], v[38:39], 1.0 op_sel_hi:[1,0]
	v_pk_fma_f32 v[36:37], v[36:37], v[40:41], v[44:45]
	v_pk_fma_f32 v[34:35], v[34:35], v[38:39], v[42:43]
	v_cvt_pk_bf16_f32 v34, v34, v35
	v_cvt_pk_bf16_f32 v35, v36, v37
	global_store_dwordx2 v[104:105], v[34:35], off offset:1536
	global_load_dwordx4 v[34:37], v[144:145], off
	s_nop 0
	global_load_dwordx4 v[38:41], v[128:129], off
	v_cndmask_b32_e32 v42, v46, v47, vcc
	v_sqrt_f32_e32 v43, v42
	s_waitcnt vmcnt(0) lgkmcnt(0)
	v_pk_add_f32 v[36:37], v[36:37], 1.0 op_sel_hi:[1,0]
	v_add_u32_e32 v44, -1, v43
	v_add_u32_e32 v45, 1, v43
	v_fma_f32 v46, -v44, v43, v42
	v_fma_f32 v47, -v45, v43, v42
	v_cmp_ge_f32_e64 s[6:7], 0, v46
	v_pk_add_f32 v[34:35], v[34:35], 1.0 op_sel_hi:[1,0]
	s_nop 0
	v_cndmask_b32_e64 v43, v43, v44, s[6:7]
	v_cmp_lt_f32_e64 s[6:7], 0, v47
	s_nop 1
	v_cndmask_b32_e64 v43, v43, v45, s[6:7]
	v_mul_f32_e32 v44, 0x37800000, v43
	v_cndmask_b32_e32 v43, v43, v44, vcc
	v_cmp_class_f32_e32 vcc, v42, v173
	s_nop 1
	v_cndmask_b32_e32 v42, v43, v42, vcc
	v_div_scale_f32 v43, s[6:7], v42, v42, 1.0
	v_rcp_f32_e32 v45, v43
	v_div_scale_f32 v44, vcc, 1.0, v42, 1.0
	v_fma_f32 v46, -v43, v45, 1.0
	v_fmac_f32_e32 v45, v46, v45
	v_mul_f32_e32 v46, v44, v45
	v_fma_f32 v47, -v43, v46, v44
	v_fmac_f32_e32 v46, v47, v45
	v_fma_f32 v43, -v43, v46, v44
	v_div_fmas_f32 v43, v43, v45, v46
	v_div_fixup_f32 v42, v43, v42, 1.0
	v_pk_mul_f32 v[32:33], v[32:33], v[42:43] op_sel_hi:[1,0]
	v_pk_mul_f32 v[30:31], v[30:31], v[42:43] op_sel_hi:[1,0]
	v_pk_mul_f32 v[32:33], v[4:5], v[32:33]
	v_pk_mul_f32 v[30:31], v[2:3], v[30:31]
	v_pk_fma_f32 v[32:33], v[36:37], v[32:33], v[40:41]
	v_pk_fma_f32 v[30:31], v[34:35], v[30:31], v[38:39]
	v_cvt_pk_bf16_f32 v30, v30, v31
	v_cvt_pk_bf16_f32 v31, v32, v33
	global_store_dwordx2 v[104:105], v[30:31], off offset:2048
	global_load_dwordx4 v[30:33], v[124:125], off
	s_nop 0
	global_load_dwordx4 v[34:37], v[120:121], off
	v_pk_mul_f32 v[28:29], v[28:29], v[42:43] op_sel_hi:[1,0]
	v_pk_mul_f32 v[26:27], v[26:27], v[42:43] op_sel_hi:[1,0]
	v_pk_mul_f32 v[28:29], v[8:9], v[28:29]
	v_pk_mul_f32 v[26:27], v[6:7], v[26:27]
	v_lshl_add_u64 v[40:41], s[20:21], 0, v[98:99]
	v_lshl_add_u64 v[38:39], s[18:19], 0, v[98:99]
	v_pk_mul_f32 v[24:25], v[24:25], v[42:43] op_sel_hi:[1,0]
	v_pk_mul_f32 v[22:23], v[22:23], v[42:43] op_sel_hi:[1,0]
	v_pk_mul_f32 v[24:25], v[12:13], v[24:25]
	v_pk_mul_f32 v[22:23], v[10:11], v[22:23]
	v_pk_mul_f32 v[20:21], v[20:21], v[42:43] op_sel_hi:[1,0]
	v_pk_mul_f32 v[18:19], v[18:19], v[42:43] op_sel_hi:[1,0]
	v_pk_mul_f32 v[20:21], v[16:17], v[20:21]
	v_pk_mul_f32 v[18:19], v[14:15], v[18:19]
	s_waitcnt vmcnt(0) lgkmcnt(0)
	v_pk_add_f32 v[32:33], v[32:33], 1.0 op_sel_hi:[1,0]
	v_pk_add_f32 v[30:31], v[30:31], 1.0 op_sel_hi:[1,0]
	v_pk_fma_f32 v[28:29], v[32:33], v[28:29], v[36:37]
	v_pk_fma_f32 v[26:27], v[30:31], v[26:27], v[34:35]
	v_cvt_pk_bf16_f32 v26, v26, v27
	v_cvt_pk_bf16_f32 v27, v28, v29
	global_store_dwordx2 v[104:105], v[26:27], off offset:2560
	global_load_dwordx4 v[26:29], v[40:41], off
	s_nop 0
	global_load_dwordx4 v[30:33], v[38:39], off
	v_lshl_add_u64 v[36:37], s[20:21], 0, v[100:101]
	v_lshl_add_u64 v[34:35], s[18:19], 0, v[100:101]
	s_waitcnt vmcnt(0) lgkmcnt(0)
	v_pk_add_f32 v[28:29], v[28:29], 1.0 op_sel_hi:[1,0]
	v_pk_add_f32 v[26:27], v[26:27], 1.0 op_sel_hi:[1,0]
	v_pk_fma_f32 v[24:25], v[28:29], v[24:25], v[32:33]
	v_pk_fma_f32 v[22:23], v[26:27], v[22:23], v[30:31]
	v_cvt_pk_bf16_f32 v22, v22, v23
	v_cvt_pk_bf16_f32 v23, v24, v25
	global_store_dwordx2 v[104:105], v[22:23], off offset:3072
	global_load_dwordx4 v[22:25], v[36:37], off
	s_nop 0
	global_load_dwordx4 v[26:29], v[34:35], off
	s_waitcnt vmcnt(0) lgkmcnt(0)
	v_pk_add_f32 v[24:25], v[24:25], 1.0 op_sel_hi:[1,0]
	v_pk_add_f32 v[22:23], v[22:23], 1.0 op_sel_hi:[1,0]
	v_pk_fma_f32 v[20:21], v[20:21], v[24:25], v[28:29]
	v_pk_fma_f32 v[18:19], v[18:19], v[22:23], v[26:27]
	v_cvt_pk_bf16_f32 v18, v18, v19
	v_cvt_pk_bf16_f32 v19, v20, v21
	global_store_dwordx2 v[104:105], v[18:19], off offset:3584
	s_cbranch_scc1 .LBB0_5544

.LBB0_5693:
	v_lshl_add_u64 v[18:19], s[68:69], 0, v[94:95]
	v_lshl_add_u64 v[22:23], s[68:69], 0, v[92:93]
	v_add_co_u32_e32 v20, vcc, 0x7800000, v18
	v_add_co_u32_e64 v102, s[6:7], s22, v22
	s_nop 0
	v_addc_co_u32_e32 v21, vcc, 0, v19, vcc
	v_addc_co_u32_e64 v103, s[6:7], 0, v23, s[6:7]
	v_add_co_u32_e64 v104, s[6:7], s23, v22
	v_add_co_u32_e32 v22, vcc, 0x7801000, v18
	s_nop 0
	v_addc_co_u32_e64 v105, s[6:7], 0, v23, s[6:7]
	global_load_dwordx4 v[78:81], v[20:21], off
	global_load_dwordx4 v[74:77], v[20:21], off offset:1024
	global_load_dwordx4 v[70:73], v[20:21], off offset:2048
	global_load_dwordx4 v[66:69], v[20:21], off offset:3072
	v_addc_co_u32_e32 v23, vcc, 0, v19, vcc
	v_add_co_u32_e32 v20, vcc, 0x7802000, v18
	global_load_dwordx4 v[62:65], v[22:23], off
	global_load_dwordx4 v[58:61], v[22:23], off offset:1024
	global_load_dwordx4 v[54:57], v[22:23], off offset:2048
	global_load_dwordx4 v[50:53], v[22:23], off offset:3072
	v_addc_co_u32_e32 v21, vcc, 0, v19, vcc
	v_add_co_u32_e32 v82, vcc, 0x7803000, v18
	global_load_dwordx4 v[46:49], v[20:21], off
	global_load_dwordx4 v[42:45], v[20:21], off offset:1024
	global_load_dwordx4 v[38:41], v[20:21], off offset:2048
	global_load_dwordx4 v[34:37], v[20:21], off offset:3072
	v_addc_co_u32_e32 v83, vcc, 0, v19, vcc
	global_load_dwordx4 v[30:33], v[82:83], off
	global_load_dwordx4 v[26:29], v[82:83], off offset:1024
	global_load_dwordx4 v[22:25], v[82:83], off offset:2048
	global_load_dwordx4 v[18:21], v[82:83], off offset:3072
	s_add_i32 s24, s8, 32
	s_add_i32 s10, s8, 0xffffc022
	s_ashr_i32 s9, s24, 13
	s_cmpk_lt_i32 s24, 0x4000
	s_cselect_b32 s6, s9, s10
	s_addk_i32 s6, 0x82
	s_mul_hi_i32 s7, s6, 0x9000
	s_mul_i32 s6, s6, 0x9000
	s_add_u32 s10, s4, s6
	s_addc_u32 s11, s5, s7
	s_add_u32 s6, s10, 0x6000
	s_addc_u32 s7, s11, 0
	s_add_u32 s10, s10, 0x7000
	s_addc_u32 s11, s11, 0
	v_lshl_add_u64 v[82:83], s[6:7], 0, v[90:91]
	v_lshl_add_u64 v[86:87], s[10:11], 0, v[90:91]
	global_load_dwordx4 v[82:85], v[82:83], off
	v_lshl_add_u64 v[148:149], s[6:7], 0, v[96:97]
	global_load_dwordx4 v[86:89], v[86:87], off
	v_lshl_add_u64 v[142:143], s[6:7], 0, v[98:99]
	v_lshl_add_u64 v[132:133], s[6:7], 0, v[100:101]
	s_add_i32 s6, s8, 0xffffc023
	s_cmpk_lt_i32 s24, 0x3fff
	s_cselect_b32 s6, s9, s6
	s_addk_i32 s6, 0x82
	s_mul_hi_i32 s7, s6, 0x9000
	s_mul_i32 s6, s6, 0x9000
	v_lshl_add_u64 v[152:153], s[10:11], 0, v[96:97]
	v_lshl_add_u64 v[146:147], s[10:11], 0, v[98:99]
	v_lshl_add_u64 v[140:141], s[10:11], 0, v[100:101]
	s_add_u32 s10, s4, s6
	s_addc_u32 s11, s5, s7
	s_add_u32 s6, s10, 0x6000
	s_addc_u32 s7, s11, 0
	s_add_u32 s10, s10, 0x7000
	v_lshl_add_u64 v[134:135], s[6:7], 0, v[90:91]
	v_lshl_add_u64 v[126:127], s[6:7], 0, v[96:97]
	v_lshl_add_u64 v[118:119], s[6:7], 0, v[98:99]
	v_lshl_add_u64 v[114:115], s[6:7], 0, v[100:101]
	s_addc_u32 s11, s11, 0
	s_add_i32 s6, s8, 0xffffc024
	s_cmpk_lt_i32 s24, 0x3ffe
	s_cselect_b32 s6, s9, s6
	s_addk_i32 s6, 0x82
	s_mul_hi_i32 s7, s6, 0x9000
	s_mul_i32 s6, s6, 0x9000
	s_add_u32 s6, s4, s6
	s_addc_u32 s7, s5, s7
	v_lshl_add_u64 v[136:137], s[10:11], 0, v[90:91]
	v_lshl_add_u64 v[130:131], s[10:11], 0, v[96:97]
	v_lshl_add_u64 v[122:123], s[10:11], 0, v[98:99]
	v_lshl_add_u64 v[116:117], s[10:11], 0, v[100:101]
	s_add_u32 s10, s6, 0x6000
	s_addc_u32 s11, s7, 0
	s_add_u32 s6, s6, 0x7000
	s_addc_u32 s7, s7, 0
	s_addk_i32 s8, 0xc025
	s_cmpk_lt_i32 s24, 0x3ffd
	v_lshl_add_u64 v[156:157], s[6:7], 0, v[90:91]
	v_lshl_add_u64 v[154:155], s[6:7], 0, v[96:97]
	v_lshl_add_u64 v[150:151], s[6:7], 0, v[98:99]
	v_lshl_add_u64 v[138:139], s[6:7], 0, v[100:101]
	s_cselect_b32 s6, s9, s8
	s_waitcnt vmcnt(0) lgkmcnt(0)
	v_pk_mul_f32 v[158:159], v[80:81], v[80:81]
	v_pk_mul_f32 v[160:161], v[78:79], v[78:79]
	v_pk_mul_f32 v[162:163], v[76:77], v[76:77]
	v_pk_mul_f32 v[164:165], v[74:75], v[74:75]
	v_mul_f32_e32 v174, v71, v71
	v_mul_f32_e32 v176, v73, v73
	v_mul_f32_e32 v187, v68, v68
	v_mul_f32_e32 v189, v69, v69
	v_pk_mov_b32 v[178:179], v[160:161], v[158:159] op_sel:[1,0]
	v_mov_b32_e32 v161, v159
	v_pk_mov_b32 v[158:159], v[164:165], v[162:163] op_sel:[1,0]
	v_mov_b32_e32 v165, v163
	v_pk_fma_f32 v[162:163], v[70:71], v[70:71], v[174:175] op_sel_hi:[1,1,0]
	v_pk_fma_f32 v[174:175], v[72:73], v[72:73], v[176:177] op_sel_hi:[1,1,0]
	v_pk_mul_f32 v[176:177], v[64:65], v[64:65]
	v_pk_mul_f32 v[180:181], v[62:63], v[62:63]
	v_pk_mul_f32 v[182:183], v[60:61], v[60:61]
	v_pk_mul_f32 v[184:185], v[58:59], v[58:59]
	v_mul_f32_e32 v186, v55, v55
	v_mul_f32_e32 v188, v57, v57
	v_pk_add_f32 v[160:161], v[178:179], v[160:161]
	v_pk_add_f32 v[158:159], v[158:159], v[164:165]
	v_mov_b32_e32 v163, v187
	v_mov_b32_e32 v175, v189
	v_pk_mov_b32 v[164:165], v[180:181], v[176:177] op_sel:[1,0]
	v_mov_b32_e32 v181, v177
	v_pk_mov_b32 v[176:177], v[184:185], v[182:183] op_sel:[1,0]
	v_mov_b32_e32 v185, v183
	v_pk_fma_f32 v[178:179], v[54:55], v[54:55], v[186:187] op_sel_hi:[1,1,0]
	v_pk_fma_f32 v[182:183], v[56:57], v[56:57], v[188:189] op_sel_hi:[1,1,0]
	v_pk_mul_f32 v[186:187], v[48:49], v[48:49]
	v_pk_mul_f32 v[188:189], v[46:47], v[46:47]
	v_pk_mul_f32 v[190:191], v[44:45], v[44:45]
	v_pk_mul_f32 v[192:193], v[42:43], v[42:43]
	v_mul_f32_e32 v173, v66, v66
	v_mul_f32_e32 v197, v67, v67
	v_mul_f32_e32 v195, v52, v52
	v_mul_f32_e32 v202, v53, v53
	v_mul_f32_e32 v194, v39, v39
	v_mul_f32_e32 v196, v41, v41
	v_pk_add_f32 v[198:199], v[160:161], v[160:161] op_sel:[0,1] op_sel_hi:[1,0]
	v_pk_add_f32 v[200:201], v[158:159], v[158:159] op_sel:[0,1] op_sel_hi:[1,0]
	v_pk_add_f32 v[174:175], v[162:163], v[174:175]
	v_pk_add_f32 v[158:159], v[164:165], v[180:181]
	v_pk_add_f32 v[160:161], v[176:177], v[184:185]
	v_pk_mov_b32 v[162:163], v[188:189], v[186:187] op_sel:[1,0]
	v_mov_b32_e32 v189, v187
	v_pk_mov_b32 v[164:165], v[192:193], v[190:191] op_sel:[1,0]
	v_mov_b32_e32 v193, v191
	v_mul_f32_e32 v203, v50, v50
	v_mul_f32_e32 v208, v51, v51
	v_mul_f32_e32 v211, v36, v36
	v_mul_f32_e32 v212, v37, v37
	v_mov_b32_e32 v179, v195
	v_mov_b32_e32 v183, v202
	v_pk_fma_f32 v[176:177], v[38:39], v[38:39], v[194:195] op_sel_hi:[1,1,0]
	v_pk_fma_f32 v[180:181], v[40:41], v[40:41], v[196:197] op_sel_hi:[1,1,0]
	v_pk_mul_f32 v[184:185], v[32:33], v[32:33]
	v_pk_mul_f32 v[186:187], v[30:31], v[30:31]
	v_pk_mul_f32 v[190:191], v[28:29], v[28:29]
	v_pk_mul_f32 v[194:195], v[26:27], v[26:27]
	v_mov_b32_e32 v199, v173
	v_mov_b32_e32 v201, v197
	v_pk_add_f32 v[204:205], v[158:159], v[158:159] op_sel:[0,1] op_sel_hi:[1,0]
	v_pk_add_f32 v[206:207], v[160:161], v[160:161] op_sel:[0,1] op_sel_hi:[1,0]
	v_pk_add_f32 v[162:163], v[162:163], v[188:189]
	v_pk_add_f32 v[164:165], v[164:165], v[192:193]
	v_mul_f32_e32 v209, v34, v34
	v_mul_f32_e32 v210, v35, v35
	v_pk_add_f32 v[178:179], v[178:179], v[182:183]
	v_mov_b32_e32 v177, v211
	v_mov_b32_e32 v181, v212
	v_pk_mov_b32 v[182:183], v[186:187], v[184:185] op_sel:[1,0]
	v_mov_b32_e32 v187, v185
	v_pk_mov_b32 v[184:185], v[194:195], v[190:191] op_sel:[1,0]
	v_mov_b32_e32 v195, v191
	v_pk_add_f32 v[188:189], v[198:199], v[200:201]
	v_mov_b32_e32 v205, v203
	v_mov_b32_e32 v207, v208
	v_pk_add_f32 v[190:191], v[162:163], v[162:163] op_sel:[0,1] op_sel_hi:[1,0]
	v_pk_add_f32 v[192:193], v[164:165], v[164:165] op_sel:[0,1] op_sel_hi:[1,0]
	v_pk_add_f32 v[176:177], v[176:177], v[180:181]
	v_pk_add_f32 v[174:175], v[188:189], v[174:175]
	v_pk_add_f32 v[180:181], v[204:205], v[206:207]
	v_mov_b32_e32 v191, v209
	v_mov_b32_e32 v193, v210
	v_add_f32_e32 v173, v174, v175
	v_pk_add_f32 v[174:175], v[180:181], v[178:179]
	v_pk_add_f32 v[178:179], v[190:191], v[192:193]
	v_add_f32_e32 v180, v174, v175
	v_pk_add_f32 v[174:175], v[178:179], v[176:177]
	v_add_f32_e32 v174, v174, v175
	s_addk_i32 s6, 0x82
	s_waitcnt lgkmcnt(0)
	s_nop 1
	v_add_f32_dpp v173, v173, v173 quad_perm:[1,0,3,2] row_mask:0xf bank_mask:0xf
	s_waitcnt lgkmcnt(0)
	s_nop 1
	v_add_f32_dpp v175, v180, v180 quad_perm:[1,0,3,2] row_mask:0xf bank_mask:0xf
	s_waitcnt lgkmcnt(0)
	s_nop 1
	v_add_f32_dpp v174, v174, v174 quad_perm:[1,0,3,2] row_mask:0xf bank_mask:0xf
	s_waitcnt lgkmcnt(0)
	s_nop 1
	v_add_f32_dpp v173, v173, v173 quad_perm:[2,3,0,1] row_mask:0xf bank_mask:0xf
	s_waitcnt lgkmcnt(0)
	s_nop 1
	v_add_f32_dpp v175, v175, v175 quad_perm:[2,3,0,1] row_mask:0xf bank_mask:0xf
	s_waitcnt lgkmcnt(0)
	s_nop 1
	v_add_f32_dpp v174, v174, v174 quad_perm:[2,3,0,1] row_mask:0xf bank_mask:0xf
	s_waitcnt lgkmcnt(0)
	s_nop 1
	v_add_f32_dpp v173, v173, v173 row_half_mirror row_mask:0xf bank_mask:0xf
	s_waitcnt lgkmcnt(0)
	s_nop 1
	v_add_f32_dpp v175, v175, v175 row_half_mirror row_mask:0xf bank_mask:0xf
	s_waitcnt lgkmcnt(0)
	s_nop 1
	v_add_f32_dpp v174, v174, v174 row_half_mirror row_mask:0xf bank_mask:0xf
	s_waitcnt lgkmcnt(0)
	s_nop 1
	v_add_f32_dpp v173, v173, v173 row_mirror row_mask:0xf bank_mask:0xf
	ds_bpermute_b32 v176, v169, v173
	s_waitcnt lgkmcnt(2)
	s_nop 1
	v_add_f32_dpp v175, v175, v175 row_mirror row_mask:0xf bank_mask:0xf
	ds_bpermute_b32 v178, v169, v175
	s_waitcnt lgkmcnt(2)
	s_nop 1
	v_add_f32_dpp v174, v174, v174 row_mirror row_mask:0xf bank_mask:0xf
	ds_bpermute_b32 v177, v169, v174
	s_waitcnt lgkmcnt(2)
	v_add_f32_e32 v173, v173, v176
	ds_bpermute_b32 v176, v170, v173
	s_waitcnt lgkmcnt(2)
	v_add_f32_e32 v175, v175, v178
	ds_bpermute_b32 v178, v170, v175
	s_mul_hi_i32 s7, s6, 0x9000
	s_mul_i32 s6, s6, 0x9000
	s_waitcnt lgkmcnt(2)
	v_add_f32_e32 v174, v174, v177
	s_add_u32 s6, s4, s6
	ds_bpermute_b32 v177, v170, v174
	s_addc_u32 s7, s5, s7
	s_waitcnt lgkmcnt(2)
	v_add_f32_e32 v173, v173, v176
	s_add_u32 s16, s6, 0x6000
	v_fmamk_f32 v173, v173, 0x3a800000, v171
	s_addc_u32 s17, s7, 0
	s_waitcnt lgkmcnt(1)
	v_add_f32_e32 v175, v175, v178
	v_mul_f32_e32 v176, 0x4f800000, v173
	v_cmp_gt_f32_e32 vcc, s2, v173
	s_add_u32 s18, s6, 0x7000
	v_fmamk_f32 v175, v175, 0x3a800000, v171
	v_cndmask_b32_e32 v173, v173, v176, vcc
	s_addc_u32 s19, s7, 0
	s_waitcnt lgkmcnt(0)
	v_add_f32_e32 v174, v174, v177
	v_mul_f32_e32 v176, 0x4f800000, v175
	v_cmp_gt_f32_e64 s[6:7], s2, v175
	v_sqrt_f32_e32 v177, v173
	v_fmamk_f32 v174, v174, 0x3a800000, v171
	v_cndmask_b32_e64 v175, v175, v176, s[6:7]
	v_mul_f32_e32 v176, 0x4f800000, v174
	v_cmp_gt_f32_e64 s[8:9], s2, v174
	v_sqrt_f32_e32 v178, v175
	v_add_u32_e32 v179, -1, v177
	v_cndmask_b32_e64 v174, v174, v176, s[8:9]
	v_sqrt_f32_e32 v176, v174
	v_add_u32_e32 v180, 1, v177
	v_fma_f32 v181, -v179, v177, v173
	v_lshl_add_u64 v[112:113], s[10:11], 0, v[90:91]
	v_lshl_add_u64 v[106:107], s[10:11], 0, v[96:97]
	v_lshl_add_u64 v[110:111], s[10:11], 0, v[98:99]
	v_lshl_add_u64 v[108:109], s[10:11], 0, v[100:101]
	v_pk_add_f32 v[162:163], v[182:183], v[186:187]
	v_fma_f32 v182, -v180, v177, v173
	v_add_u32_e32 v183, -1, v178
	v_cmp_ge_f32_e64 s[10:11], 0, v181
	v_pk_add_f32 v[164:165], v[184:185], v[194:195]
	v_add_u32_e32 v184, 1, v178
	v_cndmask_b32_e64 v177, v177, v179, s[10:11]
	v_fma_f32 v179, -v183, v178, v175
	v_cmp_lt_f32_e64 s[10:11], 0, v182
	v_fma_f32 v181, -v184, v178, v175
	v_add_u32_e32 v185, -1, v176
	v_cndmask_b32_e64 v177, v177, v180, s[10:11]
	v_cmp_ge_f32_e64 s[10:11], 0, v179
	v_add_u32_e32 v186, 1, v176
	v_fma_f32 v179, -v185, v176, v174
	v_cndmask_b32_e64 v178, v178, v183, s[10:11]
	v_cmp_lt_f32_e64 s[10:11], 0, v181
	v_fma_f32 v180, -v186, v176, v174
	v_mul_f32_e32 v181, 0x37800000, v177
	v_cndmask_b32_e64 v178, v178, v184, s[10:11]
	v_cmp_ge_f32_e64 s[10:11], 0, v179
	v_cndmask_b32_e32 v177, v177, v181, vcc
	v_cmp_class_f32_e32 vcc, v173, v172
	v_cndmask_b32_e64 v176, v176, v185, s[10:11]
	v_cmp_lt_f32_e64 s[10:11], 0, v180
	v_mul_f32_e32 v179, 0x37800000, v178
	v_cndmask_b32_e32 v173, v177, v173, vcc
	v_cndmask_b32_e64 v176, v176, v186, s[10:11]
	v_cndmask_b32_e64 v177, v178, v179, s[6:7]
	v_cmp_class_f32_e32 vcc, v175, v172
	v_mul_f32_e32 v178, 0x37800000, v176
	v_div_scale_f32 v179, s[6:7], v173, v173, 1.0
	v_cndmask_b32_e32 v175, v177, v175, vcc
	v_cndmask_b32_e64 v176, v176, v178, s[8:9]
	v_cmp_class_f32_e32 vcc, v174, v172
	v_rcp_f32_e32 v177, v179
	v_div_scale_f32 v178, s[8:9], v175, v175, 1.0
	v_cndmask_b32_e32 v176, v176, v174, vcc
	v_rcp_f32_e32 v182, v178
	v_div_scale_f32 v183, s[10:11], v176, v176, 1.0
	v_rcp_f32_e32 v185, v183
	v_fma_f32 v174, -v179, v177, 1.0
	v_div_scale_f32 v180, s[6:7], 1.0, v173, 1.0
	v_fmac_f32_e32 v177, v174, v177
	v_fma_f32 v174, -v178, v182, 1.0
	v_mul_f32_e32 v186, v180, v177
	v_div_scale_f32 v181, s[8:9], 1.0, v175, 1.0
	v_fmac_f32_e32 v182, v174, v182
	v_fma_f32 v174, -v183, v185, 1.0
	v_fma_f32 v187, -v179, v186, v180
	v_div_scale_f32 v184, s[10:11], 1.0, v176, 1.0
	v_mul_f32_e32 v188, v181, v182
	v_fmac_f32_e32 v185, v174, v185
	v_fmac_f32_e32 v186, v187, v177
	v_fma_f32 v174, -v178, v188, v181
	v_mul_f32_e32 v187, v184, v185
	v_fma_f32 v179, -v179, v186, v180
	s_mov_b64 vcc, s[6:7]
	v_fmac_f32_e32 v188, v174, v182
	v_fma_f32 v174, -v183, v187, v184
	v_div_fmas_f32 v177, v179, v177, v186
	v_fma_f32 v178, -v178, v188, v181
	v_fmac_f32_e32 v187, v174, v185
	v_div_fixup_f32 v174, v177, v173, 1.0
	s_mov_b64 vcc, s[8:9]
	v_div_fmas_f32 v173, v178, v182, v188
	v_fma_f32 v177, -v183, v187, v184
	v_pk_mul_f32 v[80:81], v[80:81], v[174:175] op_sel_hi:[1,0]
	v_pk_mul_f32 v[78:79], v[78:79], v[174:175] op_sel_hi:[1,0]
	s_mov_b64 vcc, s[10:11]
	v_pk_add_f32 v[88:89], v[88:89], 1.0 op_sel_hi:[1,0]
	v_pk_add_f32 v[86:87], v[86:87], 1.0 op_sel_hi:[1,0]
	v_pk_mul_f32 v[76:77], v[76:77], v[174:175] op_sel_hi:[1,0]
	v_pk_mul_f32 v[74:75], v[74:75], v[174:175] op_sel_hi:[1,0]
	v_pk_mul_f32 v[72:73], v[72:73], v[174:175] op_sel_hi:[1,0]
	v_pk_mul_f32 v[70:71], v[70:71], v[174:175] op_sel_hi:[1,0]
	v_pk_mul_f32 v[68:69], v[68:69], v[174:175] op_sel_hi:[1,0]
	v_pk_mul_f32 v[66:67], v[66:67], v[174:175] op_sel_hi:[1,0]
	v_div_fixup_f32 v174, v173, v175, 1.0
	v_div_fmas_f32 v173, v177, v185, v187
	v_pk_mul_f32 v[78:79], v[2:3], v[78:79]
	v_pk_mul_f32 v[80:81], v[4:5], v[80:81]
	v_pk_mul_f32 v[64:65], v[64:65], v[174:175] op_sel_hi:[1,0]
	v_pk_mul_f32 v[62:63], v[62:63], v[174:175] op_sel_hi:[1,0]
	v_pk_mul_f32 v[60:61], v[60:61], v[174:175] op_sel_hi:[1,0]
	v_pk_mul_f32 v[58:59], v[58:59], v[174:175] op_sel_hi:[1,0]
	v_pk_mul_f32 v[56:57], v[56:57], v[174:175] op_sel_hi:[1,0]
	v_pk_mul_f32 v[54:55], v[54:55], v[174:175] op_sel_hi:[1,0]
	v_pk_mul_f32 v[52:53], v[52:53], v[174:175] op_sel_hi:[1,0]
	v_pk_mul_f32 v[174:175], v[50:51], v[174:175] op_sel_hi:[1,0]
	v_div_fixup_f32 v50, v173, v176, 1.0
	v_pk_fma_f32 v[80:81], v[88:89], v[80:81], v[84:85]
	v_pk_fma_f32 v[78:79], v[86:87], v[78:79], v[82:83]
	v_pk_mul_f32 v[86:87], v[16:17], v[52:53]
	v_pk_mul_f32 v[48:49], v[48:49], v[50:51] op_sel_hi:[1,0]
	v_pk_mul_f32 v[46:47], v[46:47], v[50:51] op_sel_hi:[1,0]
	v_pk_mul_f32 v[82:83], v[10:11], v[54:55]
	v_pk_mul_f32 v[84:85], v[14:15], v[174:175]
	v_pk_mul_f32 v[88:89], v[2:3], v[46:47]
	v_pk_mul_f32 v[174:175], v[4:5], v[48:49]
	v_cvt_pk_bf16_f32 v46, v78, v79
	v_cvt_pk_bf16_f32 v47, v80, v81
	global_store_dwordx2 v[102:103], v[46:47], off
	global_load_dwordx4 v[46:49], v[152:153], off
	s_nop 0
	global_load_dwordx4 v[52:55], v[148:149], off
	v_pk_mul_f32 v[74:75], v[6:7], v[74:75]
	v_pk_mul_f32 v[76:77], v[8:9], v[76:77]
	v_pk_mul_f32 v[70:71], v[10:11], v[70:71]
	v_pk_mul_f32 v[72:73], v[12:13], v[72:73]
	v_pk_mul_f32 v[66:67], v[66:67], v[14:15]
	v_pk_mul_f32 v[68:69], v[68:69], v[16:17]
	v_pk_mul_f32 v[62:63], v[2:3], v[62:63]
	v_pk_mul_f32 v[64:65], v[4:5], v[64:65]
	v_pk_mul_f32 v[58:59], v[6:7], v[58:59]
	v_pk_mul_f32 v[60:61], v[8:9], v[60:61]
	v_pk_mul_f32 v[56:57], v[12:13], v[56:57]
	v_mul_f32_e32 v196, v23, v23
	v_mul_f32_e32 v202, v25, v25
	v_mul_f32_e32 v213, v18, v18
	v_mul_f32_e32 v214, v19, v19
	v_mul_f32_e32 v215, v20, v20
	v_mul_f32_e32 v216, v21, v21
	v_pk_fma_f32 v[158:159], v[22:23], v[22:23], v[196:197] op_sel_hi:[1,1,0]
	v_pk_fma_f32 v[160:161], v[24:25], v[24:25], v[202:203] op_sel_hi:[1,1,0]
	v_mov_b32_e32 v159, v215
	v_mov_b32_e32 v161, v216
	v_lshl_add_u64 v[144:145], s[18:19], 0, v[90:91]
	v_lshl_add_u64 v[128:129], s[16:17], 0, v[90:91]
	v_lshl_add_u64 v[124:125], s[18:19], 0, v[96:97]
	v_lshl_add_u64 v[120:121], s[16:17], 0, v[96:97]
	v_lshl_add_u64 v[92:93], v[92:93], 0, s[12:13]
	v_lshl_add_u64 v[94:95], v[94:95], 0, s[14:15]
	s_mov_b32 s8, s24
	s_cmp_lt_i32 s24, s20
	s_waitcnt vmcnt(0) lgkmcnt(0)
	v_pk_add_f32 v[48:49], v[48:49], 1.0 op_sel_hi:[1,0]
	v_pk_add_f32 v[46:47], v[46:47], 1.0 op_sel_hi:[1,0]
	v_pk_fma_f32 v[48:49], v[48:49], v[76:77], v[54:55]
	v_pk_fma_f32 v[46:47], v[46:47], v[74:75], v[52:53]
	v_cvt_pk_bf16_f32 v46, v46, v47
	v_cvt_pk_bf16_f32 v47, v48, v49
	global_store_dwordx2 v[102:103], v[46:47], off offset:512
	global_load_dwordx4 v[46:49], v[146:147], off
	s_nop 0
	global_load_dwordx4 v[52:55], v[142:143], off
	s_waitcnt vmcnt(0) lgkmcnt(0)
	v_pk_add_f32 v[48:49], v[48:49], 1.0 op_sel_hi:[1,0]
	v_pk_add_f32 v[46:47], v[46:47], 1.0 op_sel_hi:[1,0]
	v_pk_fma_f32 v[48:49], v[72:73], v[48:49], v[54:55]
	v_pk_fma_f32 v[46:47], v[70:71], v[46:47], v[52:53]
	v_cvt_pk_bf16_f32 v46, v46, v47
	v_cvt_pk_bf16_f32 v47, v48, v49
	global_store_dwordx2 v[102:103], v[46:47], off offset:1024
	global_load_dwordx4 v[46:49], v[140:141], off
	s_nop 0
	global_load_dwordx4 v[52:55], v[132:133], off
	s_waitcnt vmcnt(0) lgkmcnt(0)
	v_pk_add_f32 v[48:49], v[48:49], 1.0 op_sel_hi:[1,0]
	v_pk_add_f32 v[46:47], v[46:47], 1.0 op_sel_hi:[1,0]
	v_pk_fma_f32 v[48:49], v[68:69], v[48:49], v[54:55]
	v_pk_fma_f32 v[46:47], v[66:67], v[46:47], v[52:53]
	v_cvt_pk_bf16_f32 v46, v46, v47
	v_cvt_pk_bf16_f32 v47, v48, v49
	global_store_dwordx2 v[102:103], v[46:47], off offset:1536
	global_load_dwordx4 v[46:49], v[136:137], off
	s_nop 0
	global_load_dwordx4 v[52:55], v[134:135], off
	s_waitcnt vmcnt(0) lgkmcnt(0)
	v_pk_add_f32 v[48:49], v[48:49], 1.0 op_sel_hi:[1,0]
	v_pk_add_f32 v[46:47], v[46:47], 1.0 op_sel_hi:[1,0]
	v_pk_fma_f32 v[48:49], v[48:49], v[64:65], v[54:55]
	v_pk_fma_f32 v[46:47], v[46:47], v[62:63], v[52:53]
	v_cvt_pk_bf16_f32 v46, v46, v47
	v_cvt_pk_bf16_f32 v47, v48, v49
	global_store_dwordx2 v[102:103], v[46:47], off offset:2048
	global_load_dwordx4 v[46:49], v[130:131], off
	s_nop 0
	global_load_dwordx4 v[52:55], v[126:127], off
	s_waitcnt vmcnt(0) lgkmcnt(0)
	v_pk_add_f32 v[48:49], v[48:49], 1.0 op_sel_hi:[1,0]
	v_pk_add_f32 v[46:47], v[46:47], 1.0 op_sel_hi:[1,0]
	v_pk_fma_f32 v[48:49], v[48:49], v[60:61], v[54:55]
	v_pk_fma_f32 v[46:47], v[46:47], v[58:59], v[52:53]
	v_cvt_pk_bf16_f32 v46, v46, v47
	v_cvt_pk_bf16_f32 v47, v48, v49
	global_store_dwordx2 v[102:103], v[46:47], off offset:2560
	global_load_dwordx4 v[46:49], v[122:123], off
	s_nop 0
	global_load_dwordx4 v[52:55], v[118:119], off
	v_pk_add_f32 v[58:59], v[164:165], v[164:165] op_sel:[0,1] op_sel_hi:[1,0]
	v_pk_add_f32 v[60:61], v[158:159], v[160:161]
	v_mov_b32_e32 v59, v214
	s_waitcnt vmcnt(0) lgkmcnt(0)
	v_pk_add_f32 v[48:49], v[48:49], 1.0 op_sel_hi:[1,0]
	v_pk_add_f32 v[46:47], v[46:47], 1.0 op_sel_hi:[1,0]
	v_pk_fma_f32 v[48:49], v[48:49], v[56:57], v[54:55]
	v_pk_fma_f32 v[46:47], v[46:47], v[82:83], v[52:53]
	v_cvt_pk_bf16_f32 v46, v46, v47
	v_cvt_pk_bf16_f32 v47, v48, v49
	global_store_dwordx2 v[102:103], v[46:47], off offset:3072
	global_load_dwordx4 v[46:49], v[116:117], off
	s_nop 0
	global_load_dwordx4 v[52:55], v[114:115], off
	v_pk_add_f32 v[56:57], v[162:163], v[162:163] op_sel:[0,1] op_sel_hi:[1,0]
	s_waitcnt vmcnt(0) lgkmcnt(0)
	v_pk_add_f32 v[48:49], v[48:49], 1.0 op_sel_hi:[1,0]
	v_pk_add_f32 v[46:47], v[46:47], 1.0 op_sel_hi:[1,0]
	v_pk_fma_f32 v[48:49], v[86:87], v[48:49], v[54:55]
	v_pk_fma_f32 v[46:47], v[84:85], v[46:47], v[52:53]
	v_cvt_pk_bf16_f32 v46, v46, v47
	v_cvt_pk_bf16_f32 v47, v48, v49
	global_store_dwordx2 v[102:103], v[46:47], off offset:3584
	global_load_dwordx4 v[46:49], v[156:157], off
	s_nop 0
	global_load_dwordx4 v[52:55], v[112:113], off
	v_mov_b32_e32 v57, v213
	s_waitcnt vmcnt(0) lgkmcnt(0)
	v_pk_add_f32 v[48:49], v[48:49], 1.0 op_sel_hi:[1,0]
	v_pk_add_f32 v[46:47], v[46:47], 1.0 op_sel_hi:[1,0]
	v_pk_fma_f32 v[48:49], v[48:49], v[174:175], v[54:55]
	v_pk_fma_f32 v[46:47], v[46:47], v[88:89], v[52:53]
	v_bfe_u32 v51, v46, 16, 1
	v_bfe_u32 v52, v47, 16, 1
	v_add3_u32 v46, v46, v51, s3
	v_add3_u32 v47, v47, v52, s3
	v_lshrrev_b32_e32 v46, 16, v46
	v_and_or_b32 v46, v47, s21, v46
	v_cvt_pk_bf16_f32 v47, v48, v49
	global_store_dwordx2 v[104:105], v[46:47], off
	global_load_dwordx4 v[46:49], v[154:155], off
	s_nop 0
	global_load_dwordx4 v[52:55], v[106:107], off
	v_pk_mul_f32 v[44:45], v[44:45], v[50:51] op_sel_hi:[1,0]
	v_pk_mul_f32 v[42:43], v[42:43], v[50:51] op_sel_hi:[1,0]
	v_pk_mul_f32 v[44:45], v[8:9], v[44:45]
	v_pk_mul_f32 v[42:43], v[6:7], v[42:43]
	s_waitcnt vmcnt(0) lgkmcnt(0)
	v_pk_add_f32 v[48:49], v[48:49], 1.0 op_sel_hi:[1,0]
	v_pk_add_f32 v[46:47], v[46:47], 1.0 op_sel_hi:[1,0]
	v_pk_fma_f32 v[44:45], v[48:49], v[44:45], v[54:55]
	v_pk_fma_f32 v[42:43], v[46:47], v[42:43], v[52:53]
	v_cvt_pk_bf16_f32 v42, v42, v43
	v_cvt_pk_bf16_f32 v43, v44, v45
	global_store_dwordx2 v[104:105], v[42:43], off offset:512
	global_load_dwordx4 v[42:45], v[150:151], off
	s_nop 0
	global_load_dwordx4 v[46:49], v[110:111], off
	v_pk_add_f32 v[52:53], v[56:57], v[58:59]
	s_waitcnt vmcnt(0) lgkmcnt(0)
	v_pk_add_f32 v[44:45], v[44:45], 1.0 op_sel_hi:[1,0]
	v_pk_add_f32 v[52:53], v[52:53], v[60:61]
	v_pk_add_f32 v[42:43], v[42:43], 1.0 op_sel_hi:[1,0]
	v_add_f32_e32 v51, v52, v53
	s_waitcnt lgkmcnt(0)
	s_nop 1
	v_add_f32_dpp v51, v51, v51 quad_perm:[1,0,3,2] row_mask:0xf bank_mask:0xf
	s_waitcnt lgkmcnt(0)
	s_nop 1
	v_add_f32_dpp v51, v51, v51 quad_perm:[2,3,0,1] row_mask:0xf bank_mask:0xf
	v_pk_mul_f32 v[40:41], v[40:41], v[50:51] op_sel_hi:[1,0]
	v_pk_mul_f32 v[38:39], v[38:39], v[50:51] op_sel_hi:[1,0]
	v_pk_mul_f32 v[40:41], v[12:13], v[40:41]
	v_pk_mul_f32 v[38:39], v[10:11], v[38:39]
	v_pk_fma_f32 v[40:41], v[44:45], v[40:41], v[48:49]
	v_pk_fma_f32 v[38:39], v[42:43], v[38:39], v[46:47]
	v_cvt_pk_bf16_f32 v38, v38, v39
	v_cvt_pk_bf16_f32 v39, v40, v41
	global_store_dwordx2 v[104:105], v[38:39], off offset:1024
	global_load_dwordx4 v[38:41], v[138:139], off
	s_nop 0
	global_load_dwordx4 v[42:45], v[108:109], off
	v_pk_mul_f32 v[36:37], v[36:37], v[50:51] op_sel_hi:[1,0]
	v_pk_mul_f32 v[34:35], v[34:35], v[50:51] op_sel_hi:[1,0]
	v_pk_mul_f32 v[36:37], v[16:17], v[36:37]
	v_pk_mul_f32 v[34:35], v[14:15], v[34:35]
	s_waitcnt lgkmcnt(0)
	s_nop 1
	v_add_f32_dpp v46, v51, v51 row_half_mirror row_mask:0xf bank_mask:0xf
	s_waitcnt lgkmcnt(0)
	s_nop 1
	v_add_f32_dpp v46, v46, v46 row_mirror row_mask:0xf bank_mask:0xf
	ds_bpermute_b32 v47, v169, v46
	s_waitcnt lgkmcnt(0)
	v_add_f32_e32 v46, v46, v47
	ds_bpermute_b32 v47, v170, v46
	s_waitcnt lgkmcnt(0)
	v_add_f32_e32 v46, v46, v47
	v_fmamk_f32 v46, v46, 0x3a800000, v171
	v_mul_f32_e32 v47, 0x4f800000, v46
	v_cmp_gt_f32_e32 vcc, s2, v46
	s_waitcnt vmcnt(0)
	v_pk_add_f32 v[40:41], v[40:41], 1.0 op_sel_hi:[1,0]
	v_pk_add_f32 v[38:39], v[38:39], 1.0 op_sel_hi:[1,0]
	v_pk_fma_f32 v[36:37], v[36:37], v[40:41], v[44:45]
	v_pk_fma_f32 v[34:35], v[34:35], v[38:39], v[42:43]
	v_cvt_pk_bf16_f32 v34, v34, v35
	v_cvt_pk_bf16_f32 v35, v36, v37
	global_store_dwordx2 v[104:105], v[34:35], off offset:1536
	global_load_dwordx4 v[34:37], v[144:145], off
	s_nop 0
	global_load_dwordx4 v[38:41], v[128:129], off
	v_cndmask_b32_e32 v42, v46, v47, vcc
	v_sqrt_f32_e32 v43, v42
	s_waitcnt vmcnt(0) lgkmcnt(0)
	v_pk_add_f32 v[36:37], v[36:37], 1.0 op_sel_hi:[1,0]
	v_add_u32_e32 v44, -1, v43
	v_add_u32_e32 v45, 1, v43
	v_fma_f32 v46, -v44, v43, v42
	v_fma_f32 v47, -v45, v43, v42
	v_cmp_ge_f32_e64 s[6:7], 0, v46
	v_pk_add_f32 v[34:35], v[34:35], 1.0 op_sel_hi:[1,0]
	s_nop 0
	v_cndmask_b32_e64 v43, v43, v44, s[6:7]
	v_cmp_lt_f32_e64 s[6:7], 0, v47
	s_nop 1
	v_cndmask_b32_e64 v43, v43, v45, s[6:7]
	v_mul_f32_e32 v44, 0x37800000, v43
	v_cndmask_b32_e32 v43, v43, v44, vcc
	v_cmp_class_f32_e32 vcc, v42, v172
	s_nop 1
	v_cndmask_b32_e32 v42, v43, v42, vcc
	v_div_scale_f32 v43, s[6:7], v42, v42, 1.0
	v_rcp_f32_e32 v45, v43
	v_div_scale_f32 v44, vcc, 1.0, v42, 1.0
	v_fma_f32 v46, -v43, v45, 1.0
	v_fmac_f32_e32 v45, v46, v45
	v_mul_f32_e32 v46, v44, v45
	v_fma_f32 v47, -v43, v46, v44
	v_fmac_f32_e32 v46, v47, v45
	v_fma_f32 v43, -v43, v46, v44
	v_div_fmas_f32 v43, v43, v45, v46
	v_div_fixup_f32 v42, v43, v42, 1.0
	v_pk_mul_f32 v[32:33], v[32:33], v[42:43] op_sel_hi:[1,0]
	v_pk_mul_f32 v[30:31], v[30:31], v[42:43] op_sel_hi:[1,0]
	v_pk_mul_f32 v[32:33], v[4:5], v[32:33]
	v_pk_mul_f32 v[30:31], v[2:3], v[30:31]
	v_pk_fma_f32 v[32:33], v[36:37], v[32:33], v[40:41]
	v_pk_fma_f32 v[30:31], v[34:35], v[30:31], v[38:39]
	v_cvt_pk_bf16_f32 v30, v30, v31
	v_cvt_pk_bf16_f32 v31, v32, v33
	global_store_dwordx2 v[104:105], v[30:31], off offset:2048
	global_load_dwordx4 v[30:33], v[124:125], off
	s_nop 0
	global_load_dwordx4 v[34:37], v[120:121], off
	v_pk_mul_f32 v[28:29], v[28:29], v[42:43] op_sel_hi:[1,0]
	v_pk_mul_f32 v[26:27], v[26:27], v[42:43] op_sel_hi:[1,0]
	v_pk_mul_f32 v[28:29], v[8:9], v[28:29]
	v_pk_mul_f32 v[26:27], v[6:7], v[26:27]
	v_lshl_add_u64 v[40:41], s[18:19], 0, v[98:99]
	v_lshl_add_u64 v[38:39], s[16:17], 0, v[98:99]
	v_pk_mul_f32 v[24:25], v[24:25], v[42:43] op_sel_hi:[1,0]
	v_pk_mul_f32 v[22:23], v[22:23], v[42:43] op_sel_hi:[1,0]
	v_pk_mul_f32 v[24:25], v[12:13], v[24:25]
	v_pk_mul_f32 v[22:23], v[10:11], v[22:23]
	v_pk_mul_f32 v[20:21], v[20:21], v[42:43] op_sel_hi:[1,0]
	v_pk_mul_f32 v[18:19], v[18:19], v[42:43] op_sel_hi:[1,0]
	v_pk_mul_f32 v[20:21], v[16:17], v[20:21]
	v_pk_mul_f32 v[18:19], v[14:15], v[18:19]
	s_waitcnt vmcnt(0) lgkmcnt(0)
	v_pk_add_f32 v[32:33], v[32:33], 1.0 op_sel_hi:[1,0]
	v_pk_add_f32 v[30:31], v[30:31], 1.0 op_sel_hi:[1,0]
	v_pk_fma_f32 v[28:29], v[32:33], v[28:29], v[36:37]
	v_pk_fma_f32 v[26:27], v[30:31], v[26:27], v[34:35]
	v_cvt_pk_bf16_f32 v26, v26, v27
	v_cvt_pk_bf16_f32 v27, v28, v29
	global_store_dwordx2 v[104:105], v[26:27], off offset:2560
	global_load_dwordx4 v[26:29], v[40:41], off
	s_nop 0
	global_load_dwordx4 v[30:33], v[38:39], off
	v_lshl_add_u64 v[36:37], s[18:19], 0, v[100:101]
	v_lshl_add_u64 v[34:35], s[16:17], 0, v[100:101]
	s_waitcnt vmcnt(0) lgkmcnt(0)
	v_pk_add_f32 v[28:29], v[28:29], 1.0 op_sel_hi:[1,0]
	v_pk_add_f32 v[26:27], v[26:27], 1.0 op_sel_hi:[1,0]
	v_pk_fma_f32 v[24:25], v[28:29], v[24:25], v[32:33]
	v_pk_fma_f32 v[22:23], v[26:27], v[22:23], v[30:31]
	v_cvt_pk_bf16_f32 v22, v22, v23
	v_cvt_pk_bf16_f32 v23, v24, v25
	global_store_dwordx2 v[104:105], v[22:23], off offset:3072
	global_load_dwordx4 v[22:25], v[36:37], off
	s_nop 0
	global_load_dwordx4 v[26:29], v[34:35], off
	s_waitcnt vmcnt(0) lgkmcnt(0)
	v_pk_add_f32 v[24:25], v[24:25], 1.0 op_sel_hi:[1,0]
	v_pk_add_f32 v[22:23], v[22:23], 1.0 op_sel_hi:[1,0]
	v_pk_fma_f32 v[20:21], v[20:21], v[24:25], v[28:29]
	v_pk_fma_f32 v[18:19], v[18:19], v[22:23], v[26:27]
	v_cvt_pk_bf16_f32 v18, v18, v19
	v_cvt_pk_bf16_f32 v19, v20, v21
	global_store_dwordx2 v[104:105], v[18:19], off offset:3584
	s_cbranch_scc1 .LBB0_5693

.LBB0_5801:
	v_lshl_add_u64 v[18:19], v[84:85], 0, s[24:25]
	v_add_co_u32_e32 v20, vcc, 0x7800000, v18
	s_add_u32 s6, s38, s24
	s_nop 0
	v_addc_co_u32_e32 v21, vcc, 0, v19, vcc
	v_add_co_u32_e32 v22, vcc, 0x7801000, v18
	global_load_dwordx4 v[78:81], v[20:21], off
	global_load_dwordx4 v[70:73], v[20:21], off offset:1024
	global_load_dwordx4 v[66:69], v[20:21], off offset:3072
	global_load_dwordx4 v[74:77], v[20:21], off offset:2048
	v_addc_co_u32_e32 v23, vcc, 0, v19, vcc
	v_add_co_u32_e32 v20, vcc, 0x7802000, v18
	global_load_dwordx4 v[62:65], v[22:23], off
	global_load_dwordx4 v[54:57], v[22:23], off offset:1024
	global_load_dwordx4 v[50:53], v[22:23], off offset:3072
	global_load_dwordx4 v[58:61], v[22:23], off offset:2048
	v_addc_co_u32_e32 v21, vcc, 0, v19, vcc
	v_add_co_u32_e32 v86, vcc, 0x7803000, v18
	global_load_dwordx4 v[46:49], v[20:21], off
	global_load_dwordx4 v[42:45], v[20:21], off offset:1024
	global_load_dwordx4 v[38:41], v[20:21], off offset:2048
	global_load_dwordx4 v[34:37], v[20:21], off offset:3072
	v_addc_co_u32_e32 v87, vcc, 0, v19, vcc
	global_load_dwordx4 v[30:33], v[86:87], off
	global_load_dwordx4 v[26:29], v[86:87], off offset:1024
	global_load_dwordx4 v[22:25], v[86:87], off offset:2048
	global_load_dwordx4 v[18:21], v[86:87], off offset:3072
	s_addc_u32 s7, s39, s25
	s_add_i32 s22, s20, 0xffffc000
	s_lshl_b64 s[8:9], s[22:23], 12
	s_add_u32 s8, s28, s8
	s_addc_u32 s9, s29, s9
	s_cmpk_lt_i32 s20, 0x4000
	s_cselect_b32 s9, s7, s9
	s_cselect_b32 s8, s6, s8
	s_add_u32 s10, s6, 0x1000
	s_addc_u32 s11, s7, 0
	s_add_i32 s22, s20, 0xffffc001
	v_lshl_add_u64 v[92:93], s[8:9], 0, v[82:83]
	s_lshl_b64 s[8:9], s[22:23], 12
	s_add_u32 s8, s28, s8
	s_addc_u32 s9, s29, s9
	s_cmpk_lt_i32 s20, 0x3fff
	s_cselect_b32 s9, s11, s9
	s_cselect_b32 s8, s10, s8
	s_add_u32 s10, s6, 0x2000
	s_addc_u32 s11, s7, 0
	s_add_i32 s22, s20, 0xffffc002
	v_lshl_add_u64 v[90:91], s[8:9], 0, v[82:83]
	s_lshl_b64 s[8:9], s[22:23], 12
	s_add_u32 s8, s28, s8
	s_addc_u32 s9, s29, s9
	s_cmpk_lt_i32 s20, 0x3ffe
	s_cselect_b32 s9, s11, s9
	s_cselect_b32 s8, s10, s8
	s_add_u32 s10, s6, 0x3000
	v_lshl_add_u64 v[88:89], s[8:9], 0, v[82:83]
	s_addc_u32 s8, s7, 0
	s_add_i32 s22, s20, 0xffffc003
	s_lshl_b64 s[6:7], s[22:23], 12
	s_add_u32 s6, s28, s6
	s_addc_u32 s7, s29, s7
	s_cmpk_lt_i32 s20, 0x3ffd
	s_cselect_b32 s7, s8, s7
	s_cselect_b32 s6, s10, s6
	v_lshl_add_u64 v[86:87], s[6:7], 0, v[82:83]
	s_add_i32 s20, s20, 32
	s_add_u32 s38, s38, 0x20000
	s_addc_u32 s39, s39, 0
	v_lshl_add_u64 v[84:85], v[84:85], 0, s[26:27]
	s_cmp_lt_i32 s20, s5
	s_waitcnt vmcnt(0) lgkmcnt(0)
	v_pk_mul_f32 v[102:103], v[80:81], v[80:81]
	v_pk_mul_f32 v[104:105], v[78:79], v[78:79]
	v_pk_mul_f32 v[106:107], v[72:73], v[72:73]
	v_pk_mul_f32 v[108:109], v[70:71], v[70:71]
	v_mul_f32_e32 v110, v75, v75
	v_mul_f32_e32 v112, v77, v77
	v_pk_mov_b32 v[114:115], v[104:105], v[102:103] op_sel:[1,0]
	v_mov_b32_e32 v105, v103
	v_pk_mov_b32 v[102:103], v[108:109], v[106:107] op_sel:[1,0]
	v_mov_b32_e32 v109, v107
	v_mul_f32_e32 v123, v68, v68
	v_mul_f32_e32 v125, v69, v69
	v_pk_fma_f32 v[106:107], v[74:75], v[74:75], v[110:111] op_sel_hi:[1,1,0]
	v_pk_fma_f32 v[110:111], v[76:77], v[76:77], v[112:113] op_sel_hi:[1,1,0]
	v_pk_mul_f32 v[112:113], v[64:65], v[64:65]
	v_pk_mul_f32 v[116:117], v[62:63], v[62:63]
	v_pk_mul_f32 v[118:119], v[56:57], v[56:57]
	v_pk_mul_f32 v[120:121], v[54:55], v[54:55]
	v_mul_f32_e32 v122, v59, v59
	v_mul_f32_e32 v124, v61, v61
	v_pk_add_f32 v[104:105], v[114:115], v[104:105]
	v_pk_add_f32 v[102:103], v[102:103], v[108:109]
	v_mul_f32_e32 v101, v66, v66
	v_mul_f32_e32 v137, v67, v67
	v_mul_f32_e32 v131, v52, v52
	v_mul_f32_e32 v133, v53, v53
	v_mov_b32_e32 v107, v123
	v_mov_b32_e32 v111, v125
	v_pk_mov_b32 v[108:109], v[116:117], v[112:113] op_sel:[1,0]
	v_mov_b32_e32 v117, v113
	v_pk_mov_b32 v[112:113], v[120:121], v[118:119] op_sel:[1,0]
	v_mov_b32_e32 v121, v119
	v_pk_fma_f32 v[114:115], v[58:59], v[58:59], v[122:123] op_sel_hi:[1,1,0]
	v_pk_fma_f32 v[118:119], v[60:61], v[60:61], v[124:125] op_sel_hi:[1,1,0]
	v_pk_mul_f32 v[122:123], v[48:49], v[48:49]
	v_pk_mul_f32 v[124:125], v[46:47], v[46:47]
	v_pk_mul_f32 v[126:127], v[44:45], v[44:45]
	v_pk_mul_f32 v[128:129], v[42:43], v[42:43]
	v_mul_f32_e32 v130, v39, v39
	v_mul_f32_e32 v132, v41, v41
	v_pk_add_f32 v[104:105], v[104:105], v[104:105] op_sel:[0,1] op_sel_hi:[1,0]
	v_pk_add_f32 v[102:103], v[102:103], v[102:103] op_sel:[0,1] op_sel_hi:[1,0]
	v_mul_f32_e32 v143, v36, v36
	v_mul_f32_e32 v144, v37, v37
	v_pk_add_f32 v[106:107], v[106:107], v[110:111]
	v_pk_add_f32 v[108:109], v[108:109], v[116:117]
	v_pk_add_f32 v[110:111], v[112:113], v[120:121]
	v_mov_b32_e32 v115, v131
	v_mov_b32_e32 v119, v133
	v_pk_mov_b32 v[112:113], v[124:125], v[122:123] op_sel:[1,0]
	v_mov_b32_e32 v125, v123
	v_pk_mov_b32 v[116:117], v[128:129], v[126:127] op_sel:[1,0]
	v_mov_b32_e32 v129, v127
	v_pk_fma_f32 v[120:121], v[38:39], v[38:39], v[130:131] op_sel_hi:[1,1,0]
	v_pk_fma_f32 v[122:123], v[40:41], v[40:41], v[132:133] op_sel_hi:[1,1,0]
	v_pk_mul_f32 v[126:127], v[32:33], v[32:33]
	v_pk_mul_f32 v[130:131], v[30:31], v[30:31]
	v_pk_mul_f32 v[132:133], v[28:29], v[28:29]
	v_pk_mul_f32 v[134:135], v[26:27], v[26:27]
	v_mov_b32_e32 v105, v101
	v_mov_b32_e32 v103, v137
	v_mul_f32_e32 v139, v50, v50
	v_mul_f32_e32 v140, v51, v51
	v_pk_add_f32 v[108:109], v[108:109], v[108:109] op_sel:[0,1] op_sel_hi:[1,0]
	v_pk_add_f32 v[110:111], v[110:111], v[110:111] op_sel:[0,1] op_sel_hi:[1,0]
	v_pk_add_f32 v[114:115], v[114:115], v[118:119]
	v_pk_add_f32 v[112:113], v[112:113], v[124:125]
	v_pk_add_f32 v[116:117], v[116:117], v[128:129]
	v_mov_b32_e32 v121, v143
	v_mov_b32_e32 v123, v144
	v_pk_mov_b32 v[118:119], v[130:131], v[126:127] op_sel:[1,0]
	v_mov_b32_e32 v131, v127
	v_pk_mov_b32 v[124:125], v[134:135], v[132:133] op_sel:[1,0]
	v_mov_b32_e32 v135, v133
	v_pk_add_f32 v[102:103], v[104:105], v[102:103]
	v_mul_f32_e32 v141, v34, v34
	v_mul_f32_e32 v142, v35, v35
	v_mul_f32_e32 v136, v23, v23
	v_mul_f32_e32 v138, v25, v25
	v_mov_b32_e32 v109, v139
	v_mov_b32_e32 v111, v140
	v_pk_add_f32 v[104:105], v[112:113], v[112:113] op_sel:[0,1] op_sel_hi:[1,0]
	v_pk_add_f32 v[112:113], v[116:117], v[116:117] op_sel:[0,1] op_sel_hi:[1,0]
	v_pk_add_f32 v[116:117], v[120:121], v[122:123]
	v_pk_add_f32 v[118:119], v[118:119], v[130:131]
	v_pk_add_f32 v[120:121], v[124:125], v[134:135]
	v_pk_add_f32 v[102:103], v[102:103], v[106:107]
	v_mul_f32_e32 v145, v18, v18
	v_mul_f32_e32 v146, v19, v19
	v_mul_f32_e32 v147, v20, v20
	v_mul_f32_e32 v148, v21, v21
	v_pk_fma_f32 v[126:127], v[22:23], v[22:23], v[136:137] op_sel_hi:[1,1,0]
	v_pk_fma_f32 v[128:129], v[24:25], v[24:25], v[138:139] op_sel_hi:[1,1,0]
	v_pk_add_f32 v[106:107], v[108:109], v[110:111]
	v_mov_b32_e32 v105, v141
	v_mov_b32_e32 v113, v142
	v_pk_add_f32 v[108:109], v[118:119], v[118:119] op_sel:[0,1] op_sel_hi:[1,0]
	v_pk_add_f32 v[110:111], v[120:121], v[120:121] op_sel:[0,1] op_sel_hi:[1,0]
	v_add_f32_e32 v101, v102, v103
	v_mov_b32_e32 v127, v147
	v_mov_b32_e32 v129, v148
	v_pk_add_f32 v[102:103], v[106:107], v[114:115]
	v_pk_add_f32 v[104:105], v[104:105], v[112:113]
	v_mov_b32_e32 v109, v145
	v_mov_b32_e32 v111, v146
	v_pk_add_f32 v[118:119], v[126:127], v[128:129]
	v_add_f32_e32 v106, v102, v103
	v_pk_add_f32 v[102:103], v[104:105], v[116:117]
	v_pk_add_f32 v[104:105], v[108:109], v[110:111]
	v_add_f32_e32 v108, v102, v103
	v_pk_add_f32 v[102:103], v[104:105], v[118:119]
	v_add_f32_e32 v102, v102, v103
	s_waitcnt lgkmcnt(0)
	s_nop 1
	v_add_f32_dpp v101, v101, v101 quad_perm:[1,0,3,2] row_mask:0xf bank_mask:0xf
	s_waitcnt lgkmcnt(0)
	s_nop 1
	v_add_f32_dpp v104, v106, v106 quad_perm:[1,0,3,2] row_mask:0xf bank_mask:0xf
	s_waitcnt lgkmcnt(0)
	s_nop 1
	v_add_f32_dpp v103, v108, v108 quad_perm:[1,0,3,2] row_mask:0xf bank_mask:0xf
	s_waitcnt lgkmcnt(2)
	s_nop 1
	v_add_f32_dpp v102, v102, v102 quad_perm:[1,0,3,2] row_mask:0xf bank_mask:0xf
	s_waitcnt lgkmcnt(0)
	s_nop 1
	v_add_f32_dpp v101, v101, v101 quad_perm:[2,3,0,1] row_mask:0xf bank_mask:0xf
	s_waitcnt lgkmcnt(0)
	s_nop 1
	v_add_f32_dpp v104, v104, v104 quad_perm:[2,3,0,1] row_mask:0xf bank_mask:0xf
	s_waitcnt lgkmcnt(0)
	s_nop 1
	v_add_f32_dpp v103, v103, v103 quad_perm:[2,3,0,1] row_mask:0xf bank_mask:0xf
	s_waitcnt lgkmcnt(2)
	s_nop 1
	v_add_f32_dpp v102, v102, v102 quad_perm:[2,3,0,1] row_mask:0xf bank_mask:0xf
	s_waitcnt lgkmcnt(0)
	s_nop 1
	v_add_f32_dpp v101, v101, v101 row_half_mirror row_mask:0xf bank_mask:0xf
	s_waitcnt lgkmcnt(0)
	s_nop 1
	v_add_f32_dpp v104, v104, v104 row_half_mirror row_mask:0xf bank_mask:0xf
	s_waitcnt lgkmcnt(0)
	s_nop 1
	v_add_f32_dpp v103, v103, v103 row_half_mirror row_mask:0xf bank_mask:0xf
	s_waitcnt lgkmcnt(2)
	s_nop 1
	v_add_f32_dpp v102, v102, v102 row_half_mirror row_mask:0xf bank_mask:0xf
	s_waitcnt lgkmcnt(0)
	s_nop 1
	v_add_f32_dpp v101, v101, v101 row_mirror row_mask:0xf bank_mask:0xf
	ds_bpermute_b32 v107, v97, v101
	s_waitcnt lgkmcnt(3)
	s_nop 1
	v_add_f32_dpp v104, v104, v104 row_mirror row_mask:0xf bank_mask:0xf
	ds_bpermute_b32 v106, v97, v104
	s_waitcnt lgkmcnt(3)
	s_nop 1
	v_add_f32_dpp v103, v103, v103 row_mirror row_mask:0xf bank_mask:0xf
	s_waitcnt lgkmcnt(2)
	s_nop 1
	v_add_f32_dpp v102, v102, v102 row_mirror row_mask:0xf bank_mask:0xf
	ds_bpermute_b32 v108, v97, v103
	ds_bpermute_b32 v105, v97, v102
	s_waitcnt lgkmcnt(3)
	v_add_f32_e32 v101, v101, v107
	ds_bpermute_b32 v107, v98, v101
	s_waitcnt lgkmcnt(3)
	v_add_f32_e32 v104, v104, v106
	ds_bpermute_b32 v106, v98, v104
	s_waitcnt lgkmcnt(3)
	v_add_f32_e32 v103, v103, v108
	s_waitcnt lgkmcnt(2)
	v_add_f32_e32 v102, v102, v105
	ds_bpermute_b32 v108, v98, v103
	ds_bpermute_b32 v105, v98, v102
	s_waitcnt lgkmcnt(3)
	v_add_f32_e32 v101, v101, v107
	v_fmamk_f32 v101, v101, 0x3a800000, v99
	s_waitcnt lgkmcnt(2)
	v_add_f32_e32 v104, v104, v106
	v_mul_f32_e32 v106, 0x4f800000, v101
	v_cmp_gt_f32_e32 vcc, s21, v101
	v_fmamk_f32 v104, v104, 0x3a800000, v99
	s_waitcnt lgkmcnt(1)
	v_add_f32_e32 v103, v103, v108
	v_cndmask_b32_e32 v101, v101, v106, vcc
	v_mul_f32_e32 v106, 0x4f800000, v104
	v_cmp_gt_f32_e64 s[6:7], s21, v104
	s_waitcnt lgkmcnt(0)
	v_add_f32_e32 v102, v102, v105
	v_sqrt_f32_e32 v105, v101
	v_fmamk_f32 v103, v103, 0x3a800000, v99
	v_cndmask_b32_e64 v104, v104, v106, s[6:7]
	v_mul_f32_e32 v106, 0x4f800000, v103
	v_cmp_gt_f32_e64 s[8:9], s21, v103
	v_fmamk_f32 v102, v102, 0x3a800000, v99
	v_sqrt_f32_e32 v107, v104
	v_cndmask_b32_e64 v103, v103, v106, s[8:9]
	v_mul_f32_e32 v106, 0x4f800000, v102
	v_cmp_gt_f32_e64 s[10:11], s21, v102
	v_sqrt_f32_e32 v108, v103
	v_add_u32_e32 v109, -1, v105
	v_cndmask_b32_e64 v102, v102, v106, s[10:11]
	v_sqrt_f32_e32 v106, v102
	v_add_u32_e32 v110, 1, v105
	v_fma_f32 v111, -v109, v105, v101
	v_fma_f32 v112, -v110, v105, v101
	v_add_u32_e32 v113, -1, v107
	v_cmp_ge_f32_e64 s[12:13], 0, v111
	v_add_u32_e32 v114, 1, v107
	v_fma_f32 v111, -v114, v107, v104
	v_cndmask_b32_e64 v105, v105, v109, s[12:13]
	v_fma_f32 v109, -v113, v107, v104
	v_cmp_lt_f32_e64 s[12:13], 0, v112
	v_add_u32_e32 v115, -1, v108
	v_add_u32_e32 v116, 1, v108
	v_cndmask_b32_e64 v105, v105, v110, s[12:13]
	v_cmp_ge_f32_e64 s[12:13], 0, v109
	v_fma_f32 v109, -v115, v108, v103
	v_fma_f32 v110, -v116, v108, v103
	v_cndmask_b32_e64 v107, v107, v113, s[12:13]
	v_cmp_lt_f32_e64 s[12:13], 0, v111
	v_add_u32_e32 v111, -1, v106
	v_add_u32_e32 v112, 1, v106
	v_mul_f32_e32 v113, 0x37800000, v105
	v_cndmask_b32_e64 v107, v107, v114, s[12:13]
	v_cmp_ge_f32_e64 s[12:13], 0, v109
	v_fma_f32 v109, -v111, v106, v102
	v_cndmask_b32_e32 v105, v105, v113, vcc
	v_cndmask_b32_e64 v108, v108, v115, s[12:13]
	v_cmp_lt_f32_e64 s[12:13], 0, v110
	v_fma_f32 v110, -v112, v106, v102
	v_cmp_ge_f32_e32 vcc, 0, v109
	v_mul_f32_e32 v113, 0x37800000, v107
	v_cndmask_b32_e64 v108, v108, v116, s[12:13]
	v_cndmask_b32_e32 v106, v106, v111, vcc
	v_cmp_lt_f32_e32 vcc, 0, v110
	v_cmp_class_f32_e64 s[12:13], v101, v100
	s_nop 0
	v_cndmask_b32_e32 v106, v106, v112, vcc
	v_cndmask_b32_e64 v101, v105, v101, s[12:13]
	v_cndmask_b32_e64 v105, v107, v113, s[6:7]
	v_cmp_class_f32_e64 s[6:7], v104, v100
	v_mul_f32_e32 v107, 0x37800000, v108
	v_div_scale_f32 v109, s[12:13], v101, v101, 1.0
	v_cndmask_b32_e64 v111, v105, v104, s[6:7]
	v_cndmask_b32_e64 v104, v108, v107, s[8:9]
	v_cmp_class_f32_e64 s[6:7], v103, v100
	v_mul_f32_e32 v105, 0x37800000, v106
	v_rcp_f32_e32 v107, v109
	v_div_scale_f32 v108, s[8:9], v111, v111, 1.0
	v_cndmask_b32_e64 v113, v104, v103, s[6:7]
	v_cndmask_b32_e64 v103, v106, v105, s[10:11]
	v_cmp_class_f32_e64 s[6:7], v102, v100
	v_rcp_f32_e32 v104, v108
	v_div_scale_f32 v105, s[10:11], v113, v113, 1.0
	v_cndmask_b32_e64 v114, v103, v102, s[6:7]
	v_rcp_f32_e32 v115, v105
	v_div_scale_f32 v116, s[6:7], v114, v114, 1.0
	v_rcp_f32_e32 v118, v116
	v_fma_f32 v102, -v109, v107, 1.0
	v_div_scale_f32 v110, vcc, 1.0, v101, 1.0
	v_fmac_f32_e32 v107, v102, v107
	v_fma_f32 v102, -v108, v104, 1.0
	v_div_scale_f32 v112, s[8:9], 1.0, v111, 1.0
	v_mul_f32_e32 v103, v110, v107
	v_fmac_f32_e32 v104, v102, v104
	v_fma_f32 v102, -v105, v115, 1.0
	v_div_scale_f32 v106, s[10:11], 1.0, v113, 1.0
	v_fma_f32 v119, -v109, v103, v110
	v_mul_f32_e32 v120, v112, v104
	v_fmac_f32_e32 v115, v102, v115
	v_fma_f32 v102, -v116, v118, 1.0
	v_div_scale_f32 v117, s[6:7], 1.0, v114, 1.0
	v_fmac_f32_e32 v103, v119, v107
	v_fma_f32 v119, -v108, v120, v112
	v_mul_f32_e32 v121, v106, v115
	v_fmac_f32_e32 v118, v102, v118
	v_fma_f32 v102, -v109, v103, v110
	v_fmac_f32_e32 v120, v119, v104
	v_fma_f32 v109, -v105, v121, v106
	v_mul_f32_e32 v110, v117, v118
	v_div_fmas_f32 v102, v102, v107, v103
	v_fma_f32 v103, -v108, v120, v112
	v_fmac_f32_e32 v121, v109, v115
	v_fma_f32 v107, -v116, v110, v117
	s_mov_b64 vcc, s[8:9]
	v_div_fixup_f32 v102, v102, v101, 1.0
	v_div_fmas_f32 v101, v103, v104, v120
	v_fma_f32 v108, -v105, v121, v106
	v_fmac_f32_e32 v110, v107, v118
	s_mov_b64 vcc, s[10:11]
	v_pk_mul_f32 v[78:79], v[78:79], v[102:103] op_sel_hi:[1,0]
	v_pk_mul_f32 v[80:81], v[80:81], v[102:103] op_sel_hi:[1,0]
	v_pk_mul_f32 v[70:71], v[70:71], v[102:103] op_sel_hi:[1,0]
	v_pk_mul_f32 v[72:73], v[72:73], v[102:103] op_sel_hi:[1,0]
	v_pk_mul_f32 v[74:75], v[74:75], v[102:103] op_sel_hi:[1,0]
	v_pk_mul_f32 v[76:77], v[76:77], v[102:103] op_sel_hi:[1,0]
	v_pk_mul_f32 v[104:105], v[66:67], v[102:103] op_sel_hi:[1,0]
	v_pk_mul_f32 v[102:103], v[68:69], v[102:103] op_sel_hi:[1,0]
	v_div_fixup_f32 v106, v101, v111, 1.0
	v_div_fmas_f32 v101, v108, v115, v121
	v_fma_f32 v107, -v116, v110, v117
	s_mov_b64 vcc, s[6:7]
	v_pk_mul_f32 v[68:69], v[80:81], v[4:5]
	v_pk_mul_f32 v[66:67], v[78:79], v[2:3]
	v_pk_mul_f32 v[74:75], v[74:75], v[10:11]
	v_pk_mul_f32 v[80:81], v[102:103], v[16:17]
	v_pk_mul_f32 v[78:79], v[104:105], v[14:15]
	v_pk_mul_f32 v[62:63], v[62:63], v[106:107] op_sel_hi:[1,0]
	v_pk_mul_f32 v[64:65], v[64:65], v[106:107] op_sel_hi:[1,0]
	v_pk_mul_f32 v[54:55], v[54:55], v[106:107] op_sel_hi:[1,0]
	v_pk_mul_f32 v[56:57], v[56:57], v[106:107] op_sel_hi:[1,0]
	v_pk_mul_f32 v[58:59], v[58:59], v[106:107] op_sel_hi:[1,0]
	v_pk_mul_f32 v[60:61], v[60:61], v[106:107] op_sel_hi:[1,0]
	v_pk_mul_f32 v[102:103], v[50:51], v[106:107] op_sel_hi:[1,0]
	v_pk_mul_f32 v[104:105], v[52:53], v[106:107] op_sel_hi:[1,0]
	v_div_fixup_f32 v106, v101, v113, 1.0
	v_div_fmas_f32 v101, v107, v118, v110
	v_pk_mul_f32 v[72:73], v[72:73], v[8:9]
	v_pk_mul_f32 v[70:71], v[70:71], v[6:7]
	v_pk_mul_f32 v[76:77], v[76:77], v[12:13]
	global_store_dwordx4 v[92:93], v[66:69], off
	global_store_dwordx4 v[92:93], v[70:73], off offset:1024
	global_store_dwordx4 v[92:93], v[74:77], off offset:2048
	global_store_dwordx4 v[92:93], v[78:81], off offset:3072
	v_pk_mul_f32 v[52:53], v[64:65], v[4:5]
	v_div_fixup_f32 v74, v101, v114, 1.0
	v_pk_mul_f32 v[50:51], v[62:63], v[2:3]
	v_pk_mul_f32 v[56:57], v[56:57], v[8:9]
	v_pk_mul_f32 v[54:55], v[54:55], v[6:7]
	v_pk_mul_f32 v[46:47], v[46:47], v[106:107] op_sel_hi:[1,0]
	v_pk_mul_f32 v[48:49], v[48:49], v[106:107] op_sel_hi:[1,0]
	v_pk_mul_f32 v[30:31], v[30:31], v[74:75] op_sel_hi:[1,0]
	v_pk_mul_f32 v[32:33], v[32:33], v[74:75] op_sel_hi:[1,0]
	v_pk_mul_f32 v[60:61], v[60:61], v[12:13]
	v_pk_mul_f32 v[58:59], v[58:59], v[10:11]
	v_pk_mul_f32 v[64:65], v[104:105], v[16:17]
	v_pk_mul_f32 v[62:63], v[102:103], v[14:15]
	v_pk_mul_f32 v[42:43], v[42:43], v[106:107] op_sel_hi:[1,0]
	v_pk_mul_f32 v[44:45], v[44:45], v[106:107] op_sel_hi:[1,0]
	v_pk_mul_f32 v[66:67], v[38:39], v[106:107] op_sel_hi:[1,0]
	v_pk_mul_f32 v[68:69], v[40:41], v[106:107] op_sel_hi:[1,0]
	v_pk_mul_f32 v[70:71], v[34:35], v[106:107] op_sel_hi:[1,0]
	v_pk_mul_f32 v[72:73], v[36:37], v[106:107] op_sel_hi:[1,0]
	global_store_dwordx4 v[90:91], v[50:53], off
	global_store_dwordx4 v[90:91], v[54:57], off offset:1024
	global_store_dwordx4 v[90:91], v[58:61], off offset:2048
	global_store_dwordx4 v[90:91], v[62:65], off offset:3072
	v_pk_mul_f32 v[36:37], v[48:49], v[4:5]
	v_pk_mul_f32 v[34:35], v[46:47], v[2:3]
	v_pk_mul_f32 v[26:27], v[26:27], v[74:75] op_sel_hi:[1,0]
	v_pk_mul_f32 v[28:29], v[28:29], v[74:75] op_sel_hi:[1,0]
	v_pk_mul_f32 v[50:51], v[22:23], v[74:75] op_sel_hi:[1,0]
	v_pk_mul_f32 v[52:53], v[24:25], v[74:75] op_sel_hi:[1,0]
	v_pk_mul_f32 v[54:55], v[18:19], v[74:75] op_sel_hi:[1,0]
	v_pk_mul_f32 v[56:57], v[20:21], v[74:75] op_sel_hi:[1,0]
	v_pk_mul_f32 v[20:21], v[32:33], v[4:5]
	v_pk_mul_f32 v[18:19], v[30:31], v[2:3]
	v_pk_mul_f32 v[40:41], v[44:45], v[8:9]
	v_pk_mul_f32 v[38:39], v[42:43], v[6:7]
	v_pk_mul_f32 v[44:45], v[68:69], v[12:13]
	v_pk_mul_f32 v[42:43], v[66:67], v[10:11]
	v_pk_mul_f32 v[48:49], v[72:73], v[16:17]
	v_pk_mul_f32 v[46:47], v[70:71], v[14:15]
	global_store_dwordx4 v[88:89], v[34:37], off
	global_store_dwordx4 v[88:89], v[38:41], off offset:1024
	global_store_dwordx4 v[88:89], v[42:45], off offset:2048
	global_store_dwordx4 v[88:89], v[46:49], off offset:3072
	v_pk_mul_f32 v[24:25], v[28:29], v[8:9]
	v_pk_mul_f32 v[22:23], v[26:27], v[6:7]
	v_pk_mul_f32 v[28:29], v[52:53], v[12:13]
	v_pk_mul_f32 v[26:27], v[50:51], v[10:11]
	v_pk_mul_f32 v[32:33], v[56:57], v[16:17]
	v_pk_mul_f32 v[30:31], v[54:55], v[14:15]
	global_store_dwordx4 v[86:87], v[18:21], off
	global_store_dwordx4 v[86:87], v[22:25], off offset:1024
	global_store_dwordx4 v[86:87], v[26:29], off offset:2048
	global_store_dwordx4 v[86:87], v[30:33], off offset:3072
	s_cbranch_scc1 .LBB0_5801

.LBB0_5948:
	v_lshl_add_u64 v[16:17], v[82:83], 0, s[10:11]
	v_add_co_u32_e32 v18, vcc, 0x7800000, v16
	s_add_i32 s0, s17, 32
	s_nop 0
	v_addc_co_u32_e32 v19, vcc, 0, v17, vcc
	v_add_co_u32_e32 v20, vcc, 0x7801000, v16
	global_load_dwordx4 v[76:79], v[18:19], off
	global_load_dwordx4 v[68:71], v[18:19], off offset:1024
	global_load_dwordx4 v[64:67], v[18:19], off offset:3072
	global_load_dwordx4 v[72:75], v[18:19], off offset:2048
	v_addc_co_u32_e32 v21, vcc, 0, v17, vcc
	v_add_co_u32_e32 v18, vcc, 0x7802000, v16
	global_load_dwordx4 v[60:63], v[20:21], off
	global_load_dwordx4 v[52:55], v[20:21], off offset:1024
	global_load_dwordx4 v[48:51], v[20:21], off offset:3072
	global_load_dwordx4 v[56:59], v[20:21], off offset:2048
	v_addc_co_u32_e32 v19, vcc, 0, v17, vcc
	v_add_co_u32_e32 v84, vcc, 0x7803000, v16
	global_load_dwordx4 v[44:47], v[18:19], off
	global_load_dwordx4 v[40:43], v[18:19], off offset:1024
	global_load_dwordx4 v[36:39], v[18:19], off offset:2048
	global_load_dwordx4 v[32:35], v[18:19], off offset:3072
	v_addc_co_u32_e32 v85, vcc, 0, v17, vcc
	global_load_dwordx4 v[28:31], v[84:85], off
	global_load_dwordx4 v[24:27], v[84:85], off offset:1024
	global_load_dwordx4 v[20:23], v[84:85], off offset:2048
	global_load_dwordx4 v[16:19], v[84:85], off offset:3072
	s_add_u32 s1, s68, s10
	s_addc_u32 s4, s69, s11
	s_add_i32 s8, s17, 0xffffc020
	s_lshl_b64 s[2:3], s[8:9], 12
	s_add_u32 s2, s15, s2
	s_addc_u32 s3, s16, s3
	s_cmpk_lt_i32 s0, 0x4000
	s_cselect_b32 s3, s4, s3
	s_cselect_b32 s2, s1, s2
	s_add_u32 s5, s1, 0x1000
	s_addc_u32 s6, s4, 0
	s_add_i32 s8, s17, 0xffffc021
	v_lshl_add_u64 v[90:91], s[2:3], 0, v[80:81]
	s_lshl_b64 s[2:3], s[8:9], 12
	s_add_u32 s2, s15, s2
	s_addc_u32 s3, s16, s3
	s_cmpk_lt_i32 s0, 0x3fff
	s_cselect_b32 s3, s6, s3
	s_cselect_b32 s2, s5, s2
	s_add_u32 s5, s1, 0x2000
	s_addc_u32 s6, s4, 0
	s_add_i32 s8, s17, 0xffffc022
	v_lshl_add_u64 v[88:89], s[2:3], 0, v[80:81]
	s_lshl_b64 s[2:3], s[8:9], 12
	s_add_u32 s2, s15, s2
	s_addc_u32 s3, s16, s3
	s_cmpk_lt_i32 s0, 0x3ffe
	s_cselect_b32 s3, s6, s3
	s_cselect_b32 s2, s5, s2
	s_add_u32 s1, s1, 0x3000
	s_addc_u32 s4, s4, 0
	s_add_i32 s8, s17, 0xffffc023
	v_lshl_add_u64 v[84:85], s[2:3], 0, v[80:81]
	s_lshl_b64 s[2:3], s[8:9], 12
	s_add_u32 s2, s15, s2
	s_addc_u32 s3, s16, s3
	s_cmpk_lt_i32 s0, 0x3ffd
	s_cselect_b32 s3, s4, s3
	s_cselect_b32 s2, s1, s2
	s_add_u32 s68, s68, 0x20000
	s_addc_u32 s69, s69, 0
	s_mov_b32 s17, s0
	s_cmp_lt_i32 s0, s14
	v_lshl_add_u64 v[86:87], s[2:3], 0, v[80:81]
	v_lshl_add_u64 v[82:83], v[82:83], 0, s[12:13]
	s_waitcnt vmcnt(0) lgkmcnt(0)
	v_pk_mul_f32 v[100:101], v[78:79], v[78:79]
	v_pk_mul_f32 v[102:103], v[76:77], v[76:77]
	v_pk_mul_f32 v[104:105], v[70:71], v[70:71]
	v_pk_mul_f32 v[106:107], v[68:69], v[68:69]
	v_mul_f32_e32 v108, v73, v73
	v_mul_f32_e32 v110, v75, v75
	v_pk_mov_b32 v[112:113], v[102:103], v[100:101] op_sel:[1,0]
	v_mov_b32_e32 v103, v101
	v_pk_mov_b32 v[100:101], v[106:107], v[104:105] op_sel:[1,0]
	v_mov_b32_e32 v107, v105
	v_mul_f32_e32 v121, v66, v66
	v_mul_f32_e32 v123, v67, v67
	v_pk_fma_f32 v[104:105], v[72:73], v[72:73], v[108:109] op_sel_hi:[1,1,0]
	v_pk_fma_f32 v[108:109], v[74:75], v[74:75], v[110:111] op_sel_hi:[1,1,0]
	v_pk_mul_f32 v[110:111], v[62:63], v[62:63]
	v_pk_mul_f32 v[114:115], v[60:61], v[60:61]
	v_pk_mul_f32 v[116:117], v[54:55], v[54:55]
	v_pk_mul_f32 v[118:119], v[52:53], v[52:53]
	v_mul_f32_e32 v120, v57, v57
	v_mul_f32_e32 v122, v59, v59
	v_pk_add_f32 v[102:103], v[112:113], v[102:103]
	v_pk_add_f32 v[100:101], v[100:101], v[106:107]
	v_mul_f32_e32 v135, v64, v64
	v_mul_f32_e32 v137, v65, v65
	v_mul_f32_e32 v129, v50, v50
	v_mul_f32_e32 v131, v51, v51
	v_mov_b32_e32 v105, v121
	v_mov_b32_e32 v109, v123
	v_pk_mov_b32 v[106:107], v[114:115], v[110:111] op_sel:[1,0]
	v_mov_b32_e32 v115, v111
	v_pk_mov_b32 v[110:111], v[118:119], v[116:117] op_sel:[1,0]
	v_mov_b32_e32 v119, v117
	v_pk_fma_f32 v[112:113], v[56:57], v[56:57], v[120:121] op_sel_hi:[1,1,0]
	v_pk_fma_f32 v[116:117], v[58:59], v[58:59], v[122:123] op_sel_hi:[1,1,0]
	v_pk_mul_f32 v[120:121], v[46:47], v[46:47]
	v_pk_mul_f32 v[122:123], v[44:45], v[44:45]
	v_pk_mul_f32 v[124:125], v[42:43], v[42:43]
	v_pk_mul_f32 v[126:127], v[40:41], v[40:41]
	v_mul_f32_e32 v128, v37, v37
	v_mul_f32_e32 v130, v39, v39
	v_pk_add_f32 v[102:103], v[102:103], v[102:103] op_sel:[0,1] op_sel_hi:[1,0]
	v_pk_add_f32 v[100:101], v[100:101], v[100:101] op_sel:[0,1] op_sel_hi:[1,0]
	v_mul_f32_e32 v142, v34, v34
	v_mul_f32_e32 v143, v35, v35
	v_pk_add_f32 v[104:105], v[104:105], v[108:109]
	v_pk_add_f32 v[106:107], v[106:107], v[114:115]
	v_pk_add_f32 v[108:109], v[110:111], v[118:119]
	v_mov_b32_e32 v113, v129
	v_mov_b32_e32 v117, v131
	v_pk_mov_b32 v[110:111], v[122:123], v[120:121] op_sel:[1,0]
	v_mov_b32_e32 v123, v121
	v_pk_mov_b32 v[114:115], v[126:127], v[124:125] op_sel:[1,0]
	v_mov_b32_e32 v127, v125
	v_pk_fma_f32 v[118:119], v[36:37], v[36:37], v[128:129] op_sel_hi:[1,1,0]
	v_pk_fma_f32 v[120:121], v[38:39], v[38:39], v[130:131] op_sel_hi:[1,1,0]
	v_pk_mul_f32 v[124:125], v[30:31], v[30:31]
	v_pk_mul_f32 v[128:129], v[28:29], v[28:29]
	v_pk_mul_f32 v[130:131], v[26:27], v[26:27]
	v_pk_mul_f32 v[132:133], v[24:25], v[24:25]
	v_mov_b32_e32 v103, v135
	v_mov_b32_e32 v101, v137
	v_mul_f32_e32 v138, v48, v48
	v_mul_f32_e32 v139, v49, v49
	v_pk_add_f32 v[106:107], v[106:107], v[106:107] op_sel:[0,1] op_sel_hi:[1,0]
	v_pk_add_f32 v[108:109], v[108:109], v[108:109] op_sel:[0,1] op_sel_hi:[1,0]
	v_pk_add_f32 v[112:113], v[112:113], v[116:117]
	v_pk_add_f32 v[110:111], v[110:111], v[122:123]
	v_pk_add_f32 v[114:115], v[114:115], v[126:127]
	v_mov_b32_e32 v119, v142
	v_mov_b32_e32 v121, v143
	v_pk_mov_b32 v[116:117], v[128:129], v[124:125] op_sel:[1,0]
	v_mov_b32_e32 v129, v125
	v_pk_mov_b32 v[122:123], v[132:133], v[130:131] op_sel:[1,0]
	v_mov_b32_e32 v133, v131
	v_pk_add_f32 v[100:101], v[102:103], v[100:101]
	v_mul_f32_e32 v140, v32, v32
	v_mul_f32_e32 v141, v33, v33
	v_mul_f32_e32 v134, v21, v21
	v_mul_f32_e32 v136, v23, v23
	v_mov_b32_e32 v107, v138
	v_mov_b32_e32 v109, v139
	v_pk_add_f32 v[102:103], v[110:111], v[110:111] op_sel:[0,1] op_sel_hi:[1,0]
	v_pk_add_f32 v[110:111], v[114:115], v[114:115] op_sel:[0,1] op_sel_hi:[1,0]
	v_pk_add_f32 v[114:115], v[118:119], v[120:121]
	v_pk_add_f32 v[116:117], v[116:117], v[128:129]
	v_pk_add_f32 v[118:119], v[122:123], v[132:133]
	v_pk_add_f32 v[100:101], v[100:101], v[104:105]
	v_mul_f32_e32 v144, v16, v16
	v_mul_f32_e32 v145, v17, v17
	v_mul_f32_e32 v146, v18, v18
	v_mul_f32_e32 v147, v19, v19
	v_pk_fma_f32 v[124:125], v[20:21], v[20:21], v[134:135] op_sel_hi:[1,1,0]
	v_pk_fma_f32 v[126:127], v[22:23], v[22:23], v[136:137] op_sel_hi:[1,1,0]
	v_pk_add_f32 v[104:105], v[106:107], v[108:109]
	v_mov_b32_e32 v103, v140
	v_mov_b32_e32 v111, v141
	v_pk_add_f32 v[106:107], v[116:117], v[116:117] op_sel:[0,1] op_sel_hi:[1,0]
	v_pk_add_f32 v[108:109], v[118:119], v[118:119] op_sel:[0,1] op_sel_hi:[1,0]
	v_add_f32_e32 v118, v100, v101
	v_mov_b32_e32 v125, v146
	v_mov_b32_e32 v127, v147
	v_pk_add_f32 v[100:101], v[104:105], v[112:113]
	v_pk_add_f32 v[102:103], v[102:103], v[110:111]
	v_mov_b32_e32 v107, v144
	v_mov_b32_e32 v109, v145
	v_pk_add_f32 v[116:117], v[124:125], v[126:127]
	v_add_f32_e32 v104, v100, v101
	v_pk_add_f32 v[100:101], v[102:103], v[114:115]
	v_pk_add_f32 v[102:103], v[106:107], v[108:109]
	v_add_f32_e32 v106, v100, v101
	v_pk_add_f32 v[100:101], v[102:103], v[116:117]
	v_add_f32_e32 v100, v100, v101
	s_waitcnt lgkmcnt(0)
	s_nop 1
	v_add_f32_dpp v105, v118, v118 quad_perm:[1,0,3,2] row_mask:0xf bank_mask:0xf
	s_waitcnt lgkmcnt(0)
	s_nop 1
	v_add_f32_dpp v102, v104, v104 quad_perm:[1,0,3,2] row_mask:0xf bank_mask:0xf
	s_waitcnt lgkmcnt(0)
	s_nop 1
	v_add_f32_dpp v101, v106, v106 quad_perm:[1,0,3,2] row_mask:0xf bank_mask:0xf
	s_waitcnt lgkmcnt(2)
	s_nop 1
	v_add_f32_dpp v100, v100, v100 quad_perm:[1,0,3,2] row_mask:0xf bank_mask:0xf
	s_waitcnt lgkmcnt(0)
	s_nop 1
	v_add_f32_dpp v105, v105, v105 quad_perm:[2,3,0,1] row_mask:0xf bank_mask:0xf
	s_waitcnt lgkmcnt(0)
	s_nop 1
	v_add_f32_dpp v102, v102, v102 quad_perm:[2,3,0,1] row_mask:0xf bank_mask:0xf
	s_waitcnt lgkmcnt(0)
	s_nop 1
	v_add_f32_dpp v101, v101, v101 quad_perm:[2,3,0,1] row_mask:0xf bank_mask:0xf
	s_waitcnt lgkmcnt(2)
	s_nop 1
	v_add_f32_dpp v100, v100, v100 quad_perm:[2,3,0,1] row_mask:0xf bank_mask:0xf
	s_waitcnt lgkmcnt(0)
	s_nop 1
	v_add_f32_dpp v105, v105, v105 row_half_mirror row_mask:0xf bank_mask:0xf
	s_waitcnt lgkmcnt(0)
	s_nop 1
	v_add_f32_dpp v102, v102, v102 row_half_mirror row_mask:0xf bank_mask:0xf
	s_waitcnt lgkmcnt(0)
	s_nop 1
	v_add_f32_dpp v101, v101, v101 row_half_mirror row_mask:0xf bank_mask:0xf
	s_waitcnt lgkmcnt(2)
	s_nop 1
	v_add_f32_dpp v100, v100, v100 row_half_mirror row_mask:0xf bank_mask:0xf
	s_waitcnt lgkmcnt(0)
	s_nop 1
	v_add_f32_dpp v105, v105, v105 row_mirror row_mask:0xf bank_mask:0xf
	ds_bpermute_b32 v107, v96, v105
	s_waitcnt lgkmcnt(3)
	s_nop 1
	v_add_f32_dpp v102, v102, v102 row_mirror row_mask:0xf bank_mask:0xf
	ds_bpermute_b32 v104, v96, v102
	s_waitcnt lgkmcnt(3)
	s_nop 1
	v_add_f32_dpp v101, v101, v101 row_mirror row_mask:0xf bank_mask:0xf
	s_waitcnt lgkmcnt(2)
	s_nop 1
	v_add_f32_dpp v100, v100, v100 row_mirror row_mask:0xf bank_mask:0xf
	ds_bpermute_b32 v106, v96, v101
	ds_bpermute_b32 v103, v96, v100
	s_waitcnt lgkmcnt(3)
	v_add_f32_e32 v105, v105, v107
	ds_bpermute_b32 v107, v97, v105
	s_waitcnt lgkmcnt(3)
	v_add_f32_e32 v102, v102, v104
	ds_bpermute_b32 v104, v97, v102
	s_waitcnt lgkmcnt(3)
	v_add_f32_e32 v101, v101, v106
	s_waitcnt lgkmcnt(2)
	v_add_f32_e32 v100, v100, v103
	ds_bpermute_b32 v106, v97, v101
	ds_bpermute_b32 v103, v97, v100
	s_waitcnt lgkmcnt(3)
	v_add_f32_e32 v105, v105, v107
	v_fmamk_f32 v105, v105, 0x3a800000, v98
	s_waitcnt lgkmcnt(2)
	v_add_f32_e32 v102, v102, v104
	v_mul_f32_e32 v104, 0x4f800000, v105
	v_cmp_gt_f32_e32 vcc, s18, v105
	v_fmamk_f32 v102, v102, 0x3a800000, v98
	s_waitcnt lgkmcnt(1)
	v_add_f32_e32 v101, v101, v106
	v_cndmask_b32_e32 v104, v105, v104, vcc
	v_mul_f32_e32 v105, 0x4f800000, v102
	v_cmp_gt_f32_e64 s[0:1], s18, v102
	s_waitcnt lgkmcnt(0)
	v_add_f32_e32 v100, v100, v103
	v_sqrt_f32_e32 v103, v104
	v_fmamk_f32 v101, v101, 0x3a800000, v98
	v_cndmask_b32_e64 v102, v102, v105, s[0:1]
	v_mul_f32_e32 v105, 0x4f800000, v101
	v_cmp_gt_f32_e64 s[2:3], s18, v101
	v_fmamk_f32 v100, v100, 0x3a800000, v98
	v_sqrt_f32_e32 v106, v102
	v_cndmask_b32_e64 v101, v101, v105, s[2:3]
	v_mul_f32_e32 v105, 0x4f800000, v100
	v_cmp_gt_f32_e64 s[4:5], s18, v100
	v_sqrt_f32_e32 v107, v101
	v_add_u32_e32 v108, -1, v103
	v_cndmask_b32_e64 v100, v100, v105, s[4:5]
	v_sqrt_f32_e32 v105, v100
	v_add_u32_e32 v109, 1, v103
	v_fma_f32 v110, -v108, v103, v104
	v_fma_f32 v111, -v109, v103, v104
	v_add_u32_e32 v112, -1, v106
	v_cmp_ge_f32_e64 s[6:7], 0, v110
	v_add_u32_e32 v113, 1, v106
	v_fma_f32 v110, -v113, v106, v102
	v_cndmask_b32_e64 v103, v103, v108, s[6:7]
	v_fma_f32 v108, -v112, v106, v102
	v_cmp_lt_f32_e64 s[6:7], 0, v111
	v_add_u32_e32 v114, -1, v107
	v_add_u32_e32 v115, 1, v107
	v_cndmask_b32_e64 v103, v103, v109, s[6:7]
	v_cmp_ge_f32_e64 s[6:7], 0, v108
	v_fma_f32 v108, -v114, v107, v101
	v_fma_f32 v109, -v115, v107, v101
	v_cndmask_b32_e64 v106, v106, v112, s[6:7]
	v_cmp_lt_f32_e64 s[6:7], 0, v110
	v_add_u32_e32 v110, -1, v105
	v_add_u32_e32 v111, 1, v105
	v_mul_f32_e32 v112, 0x37800000, v103
	v_cndmask_b32_e64 v106, v106, v113, s[6:7]
	v_cmp_ge_f32_e64 s[6:7], 0, v108
	v_fma_f32 v108, -v110, v105, v100
	v_cndmask_b32_e32 v103, v103, v112, vcc
	v_cndmask_b32_e64 v107, v107, v114, s[6:7]
	v_cmp_lt_f32_e64 s[6:7], 0, v109
	v_fma_f32 v109, -v111, v105, v100
	v_cmp_ge_f32_e32 vcc, 0, v108
	v_mul_f32_e32 v112, 0x37800000, v106
	v_cndmask_b32_e64 v107, v107, v115, s[6:7]
	v_cndmask_b32_e32 v105, v105, v110, vcc
	v_cmp_lt_f32_e32 vcc, 0, v109
	v_cmp_class_f32_e64 s[6:7], v104, v99
	s_nop 0
	v_cndmask_b32_e32 v105, v105, v111, vcc
	v_cndmask_b32_e64 v103, v103, v104, s[6:7]
	v_cndmask_b32_e64 v104, v106, v112, s[0:1]
	v_cmp_class_f32_e64 s[0:1], v102, v99
	v_mul_f32_e32 v106, 0x37800000, v107
	v_div_scale_f32 v108, s[6:7], v103, v103, 1.0
	v_cndmask_b32_e64 v104, v104, v102, s[0:1]
	v_cndmask_b32_e64 v102, v107, v106, s[2:3]
	v_cmp_class_f32_e64 s[0:1], v101, v99
	v_mul_f32_e32 v106, 0x37800000, v105
	v_rcp_f32_e32 v107, v108
	v_div_scale_f32 v110, s[2:3], v104, v104, 1.0
	v_cndmask_b32_e64 v112, v102, v101, s[0:1]
	v_cndmask_b32_e64 v101, v105, v106, s[4:5]
	v_cmp_class_f32_e64 s[0:1], v100, v99
	v_rcp_f32_e32 v102, v110
	v_div_scale_f32 v105, s[4:5], v112, v112, 1.0
	v_cndmask_b32_e64 v113, v101, v100, s[0:1]
	v_rcp_f32_e32 v114, v105
	v_div_scale_f32 v115, s[0:1], v113, v113, 1.0
	v_rcp_f32_e32 v117, v115
	v_fma_f32 v100, -v108, v107, 1.0
	v_div_scale_f32 v109, vcc, 1.0, v103, 1.0
	v_fmac_f32_e32 v107, v100, v107
	v_fma_f32 v100, -v110, v102, 1.0
	v_div_scale_f32 v111, s[2:3], 1.0, v104, 1.0
	v_mul_f32_e32 v101, v109, v107
	v_fmac_f32_e32 v102, v100, v102
	v_fma_f32 v100, -v105, v114, 1.0
	v_div_scale_f32 v106, s[4:5], 1.0, v112, 1.0
	v_fma_f32 v118, -v108, v101, v109
	v_mul_f32_e32 v119, v111, v102
	v_fmac_f32_e32 v114, v100, v114
	v_fma_f32 v100, -v115, v117, 1.0
	v_div_scale_f32 v116, s[0:1], 1.0, v113, 1.0
	v_fmac_f32_e32 v101, v118, v107
	v_fma_f32 v118, -v110, v119, v111
	v_mul_f32_e32 v120, v106, v114
	v_fmac_f32_e32 v117, v100, v117
	v_fma_f32 v100, -v108, v101, v109
	v_fmac_f32_e32 v119, v118, v102
	v_fma_f32 v108, -v105, v120, v106
	v_mul_f32_e32 v109, v116, v117
	v_div_fmas_f32 v100, v100, v107, v101
	v_fma_f32 v101, -v110, v119, v111
	v_fmac_f32_e32 v120, v108, v114
	v_fma_f32 v107, -v115, v109, v116
	s_mov_b64 vcc, s[2:3]
	v_div_fixup_f32 v100, v100, v103, 1.0
	v_div_fmas_f32 v108, v101, v102, v119
	v_fma_f32 v105, -v105, v120, v106
	v_fmac_f32_e32 v109, v107, v117
	s_mov_b64 vcc, s[4:5]
	v_pk_mul_f32 v[76:77], v[76:77], v[100:101] op_sel_hi:[1,0]
	v_pk_mul_f32 v[78:79], v[78:79], v[100:101] op_sel_hi:[1,0]
	v_pk_mul_f32 v[68:69], v[68:69], v[100:101] op_sel_hi:[1,0]
	v_pk_mul_f32 v[70:71], v[70:71], v[100:101] op_sel_hi:[1,0]
	v_pk_mul_f32 v[72:73], v[72:73], v[100:101] op_sel_hi:[1,0]
	v_pk_mul_f32 v[74:75], v[74:75], v[100:101] op_sel_hi:[1,0]
	v_pk_mul_f32 v[102:103], v[64:65], v[100:101] op_sel_hi:[1,0]
	v_pk_mul_f32 v[100:101], v[66:67], v[100:101] op_sel_hi:[1,0]
	v_div_fixup_f32 v104, v108, v104, 1.0
	v_div_fmas_f32 v105, v105, v114, v120
	v_fma_f32 v106, -v115, v109, v116
	s_mov_b64 vcc, s[0:1]
	v_pk_mul_f32 v[66:67], v[78:79], v[2:3]
	v_pk_mul_f32 v[64:65], v[76:77], v[0:1]
	v_pk_mul_f32 v[72:73], v[72:73], v[8:9]
	v_pk_mul_f32 v[78:79], v[100:101], v[14:15]
	v_pk_mul_f32 v[76:77], v[102:103], v[12:13]
	v_pk_mul_f32 v[60:61], v[60:61], v[104:105] op_sel_hi:[1,0]
	v_pk_mul_f32 v[62:63], v[62:63], v[104:105] op_sel_hi:[1,0]
	v_pk_mul_f32 v[52:53], v[52:53], v[104:105] op_sel_hi:[1,0]
	v_pk_mul_f32 v[54:55], v[54:55], v[104:105] op_sel_hi:[1,0]
	v_pk_mul_f32 v[56:57], v[56:57], v[104:105] op_sel_hi:[1,0]
	v_pk_mul_f32 v[58:59], v[58:59], v[104:105] op_sel_hi:[1,0]
	v_pk_mul_f32 v[100:101], v[48:49], v[104:105] op_sel_hi:[1,0]
	v_pk_mul_f32 v[102:103], v[50:51], v[104:105] op_sel_hi:[1,0]
	v_div_fixup_f32 v104, v105, v112, 1.0
	v_div_fmas_f32 v105, v106, v117, v109
	v_pk_mul_f32 v[70:71], v[70:71], v[6:7]
	v_pk_mul_f32 v[68:69], v[68:69], v[4:5]
	v_pk_mul_f32 v[74:75], v[74:75], v[10:11]
	global_store_dwordx4 v[90:91], v[64:67], off
	global_store_dwordx4 v[90:91], v[68:71], off offset:1024
	global_store_dwordx4 v[90:91], v[72:75], off offset:2048
	global_store_dwordx4 v[90:91], v[76:79], off offset:3072
	v_pk_mul_f32 v[50:51], v[62:63], v[2:3]
	v_div_fixup_f32 v72, v105, v113, 1.0
	v_pk_mul_f32 v[48:49], v[60:61], v[0:1]
	v_pk_mul_f32 v[54:55], v[54:55], v[6:7]
	v_pk_mul_f32 v[52:53], v[52:53], v[4:5]
	v_pk_mul_f32 v[44:45], v[44:45], v[104:105] op_sel_hi:[1,0]
	v_pk_mul_f32 v[46:47], v[46:47], v[104:105] op_sel_hi:[1,0]
	v_pk_mul_f32 v[28:29], v[28:29], v[72:73] op_sel_hi:[1,0]
	v_pk_mul_f32 v[30:31], v[30:31], v[72:73] op_sel_hi:[1,0]
	v_pk_mul_f32 v[58:59], v[58:59], v[10:11]
	v_pk_mul_f32 v[56:57], v[56:57], v[8:9]
	v_pk_mul_f32 v[62:63], v[102:103], v[14:15]
	v_pk_mul_f32 v[60:61], v[100:101], v[12:13]
	v_pk_mul_f32 v[40:41], v[40:41], v[104:105] op_sel_hi:[1,0]
	v_pk_mul_f32 v[42:43], v[42:43], v[104:105] op_sel_hi:[1,0]
	v_pk_mul_f32 v[64:65], v[36:37], v[104:105] op_sel_hi:[1,0]
	v_pk_mul_f32 v[66:67], v[38:39], v[104:105] op_sel_hi:[1,0]
	v_pk_mul_f32 v[68:69], v[32:33], v[104:105] op_sel_hi:[1,0]
	v_pk_mul_f32 v[70:71], v[34:35], v[104:105] op_sel_hi:[1,0]
	global_store_dwordx4 v[88:89], v[48:51], off
	global_store_dwordx4 v[88:89], v[52:55], off offset:1024
	global_store_dwordx4 v[88:89], v[56:59], off offset:2048
	global_store_dwordx4 v[88:89], v[60:63], off offset:3072
	v_pk_mul_f32 v[34:35], v[46:47], v[2:3]
	v_pk_mul_f32 v[32:33], v[44:45], v[0:1]
	v_pk_mul_f32 v[24:25], v[24:25], v[72:73] op_sel_hi:[1,0]
	v_pk_mul_f32 v[26:27], v[26:27], v[72:73] op_sel_hi:[1,0]
	v_pk_mul_f32 v[48:49], v[20:21], v[72:73] op_sel_hi:[1,0]
	v_pk_mul_f32 v[50:51], v[22:23], v[72:73] op_sel_hi:[1,0]
	v_pk_mul_f32 v[52:53], v[16:17], v[72:73] op_sel_hi:[1,0]
	v_pk_mul_f32 v[54:55], v[18:19], v[72:73] op_sel_hi:[1,0]
	v_pk_mul_f32 v[18:19], v[30:31], v[2:3]
	v_pk_mul_f32 v[16:17], v[28:29], v[0:1]
	v_pk_mul_f32 v[38:39], v[42:43], v[6:7]
	v_pk_mul_f32 v[36:37], v[40:41], v[4:5]
	v_pk_mul_f32 v[42:43], v[66:67], v[10:11]
	v_pk_mul_f32 v[40:41], v[64:65], v[8:9]
	v_pk_mul_f32 v[46:47], v[70:71], v[14:15]
	v_pk_mul_f32 v[44:45], v[68:69], v[12:13]
	global_store_dwordx4 v[84:85], v[32:35], off
	global_store_dwordx4 v[84:85], v[36:39], off offset:1024
	global_store_dwordx4 v[84:85], v[40:43], off offset:2048
	global_store_dwordx4 v[84:85], v[44:47], off offset:3072
	v_pk_mul_f32 v[22:23], v[26:27], v[6:7]
	v_pk_mul_f32 v[20:21], v[24:25], v[4:5]
	v_pk_mul_f32 v[26:27], v[50:51], v[10:11]
	v_pk_mul_f32 v[24:25], v[48:49], v[8:9]
	v_pk_mul_f32 v[30:31], v[54:55], v[14:15]
	v_pk_mul_f32 v[28:29], v[52:53], v[12:13]
	global_store_dwordx4 v[86:87], v[16:19], off
	global_store_dwordx4 v[86:87], v[20:23], off offset:1024
	global_store_dwordx4 v[86:87], v[24:27], off offset:2048
	global_store_dwordx4 v[86:87], v[28:31], off offset:3072
	s_cbranch_scc1 .LBB0_5948
